# v3 + hipcc per-phase s_setprio flips removed from the 16 GEMM loops, one static s_setprio 1 for waves 4-7 at kernel entry (reset to 0 inside the scan producer paths)
# speedup vs baseline: 1.0077x; 1.0077x over previous
; #define LAS __attribute__((address_space(3)))
; __global__ void __launch_bounds__(NTHREADS, 2) fwd_megakernel(Args args) {
;     extern __shared__ __attribute__((aligned(16))) unsigned char lds_raw[];
;     LAS unsigned char* lds = (LAS unsigned char*)lds_raw;
;     cg::grid_group grid = cg::this_grid();
;     const int bid = blockIdx.x, G = gridDim.x;
;     const int NPB = G - NSB, pb = bid - NSB;
;     unsigned* ctr = (unsigned*)(args.ws + WS_CTR);
;     if (bid == 0 && threadIdx.x == 0) __hip_atomic_store(ctr, 0u, __ATOMIC_RELAXED, __HIP_MEMORY_SCOPE_AGENT);
_Z14fwd_megakernel4Args:
	v_readfirstlane_b32 s3, v0
	s_nop 3
	s_bfe_u32 s3, s3, 0x40006
	s_cmp_ge_u32 s3, 4
	s_cbranch_scc0 .Lprio_skip
	s_setprio 1
.Lprio_skip:
	s_load_dwordx16 s[4:19], s[0:1], 0x0
	s_load_dwordx2 s[90:91], s[0:1], 0x100
	s_load_dword s69, s[0:1], 0x108
	s_mov_b32 s68, s2
	s_add_u32 s2, s0, 0x108
	s_addc_u32 s3, s1, 0
	s_waitcnt lgkmcnt(0)
	v_writelane_b32 v248, s4, 0
	v_and_b32_e32 v199, 0x3ff, v0
	v_writelane_b32 v249, s2, 0
	v_writelane_b32 v248, s5, 1
	v_writelane_b32 v248, s6, 2
	v_writelane_b32 v248, s7, 3
	v_writelane_b32 v248, s8, 4
	v_writelane_b32 v248, s9, 5
	v_writelane_b32 v248, s10, 6
	v_writelane_b32 v248, s11, 7
	v_writelane_b32 v248, s12, 8
	v_writelane_b32 v248, s13, 9
	v_writelane_b32 v248, s14, 10
	v_writelane_b32 v248, s15, 11
	v_writelane_b32 v248, s16, 12
	v_writelane_b32 v248, s17, 13
	v_writelane_b32 v248, s18, 14
	v_writelane_b32 v248, s19, 15
	s_load_dwordx16 s[4:19], s[0:1], 0x40
	v_or_b32_e32 v1, s68, v199
	v_writelane_b32 v249, s3, 1
	s_mov_b32 s93, 0
	v_cmp_eq_u32_e32 vcc, 0, v1
	s_waitcnt lgkmcnt(0)
	v_writelane_b32 v248, s4, 16
	s_nop 1
	v_writelane_b32 v248, s5, 17
	v_writelane_b32 v248, s6, 18
	v_writelane_b32 v248, s7, 19
	v_writelane_b32 v248, s8, 20
	v_writelane_b32 v248, s9, 21
	v_writelane_b32 v248, s10, 22
	v_writelane_b32 v248, s11, 23
	v_writelane_b32 v248, s12, 24
	v_writelane_b32 v248, s13, 25
	v_writelane_b32 v248, s14, 26
	v_writelane_b32 v248, s15, 27
	v_writelane_b32 v248, s16, 28
	v_writelane_b32 v248, s17, 29
	v_writelane_b32 v248, s18, 30
	v_writelane_b32 v248, s19, 31
	s_load_dwordx16 s[4:19], s[0:1], 0x80
	s_waitcnt lgkmcnt(0)
	v_writelane_b32 v248, s4, 32
	s_nop 1
	v_writelane_b32 v248, s5, 33
	v_writelane_b32 v248, s6, 34
	v_writelane_b32 v248, s7, 35
	v_writelane_b32 v248, s8, 36
	v_writelane_b32 v248, s9, 37
	v_writelane_b32 v248, s10, 38
	v_writelane_b32 v248, s11, 39
	v_writelane_b32 v248, s12, 40
	v_writelane_b32 v248, s13, 41
	v_writelane_b32 v248, s14, 42
	v_writelane_b32 v248, s15, 43
	v_writelane_b32 v248, s16, 44
	v_writelane_b32 v248, s17, 45
	v_writelane_b32 v248, s18, 46
	v_writelane_b32 v248, s19, 47
	s_load_dwordx16 s[4:19], s[0:1], 0xc0
	s_waitcnt lgkmcnt(0)
	v_writelane_b32 v248, s4, 48
	s_nop 1
	v_writelane_b32 v248, s5, 49
	v_writelane_b32 v248, s6, 50
	v_writelane_b32 v248, s7, 51
	v_writelane_b32 v248, s8, 52
	v_writelane_b32 v248, s9, 53
	v_writelane_b32 v248, s10, 54
	v_writelane_b32 v248, s11, 55
	v_writelane_b32 v248, s12, 56
	v_writelane_b32 v248, s13, 57
	v_writelane_b32 v248, s14, 58
	v_writelane_b32 v248, s15, 59
	v_writelane_b32 v248, s16, 60
	v_writelane_b32 v248, s17, 61
	v_writelane_b32 v248, s18, 62
	v_writelane_b32 v248, s19, 63
	s_and_saveexec_b64 s[0:1], vcc
	s_cbranch_execz .LBB0_2
	v_mov_b32_e32 v1, 0
	global_store_dword v1, v1, s[90:91] offset:256 sc1

; #define PG8_STAGE(bufoff, gbase, voff) do { _Pragma("unroll") for (int _i = 0; _i < 2; ++_i) \
;         __builtin_amdgcn_global_load_lds((const unsigned*)((const char*)(gbase) + (voff)[_i]), (LAS unsigned*)(lds + (bufoff) + ldsw + _i * 8192), 16, 0, 0); } while (0)
; #define PG8_LDA(dst, b, h) do { _Pragma("unroll") for (int m = 0; m < 4; ++m) _Pragma("unroll") for (int k = 0; k < 2; ++k) dst[m][k] = *(const LAS h16x8*)(lds + PG8_SA(b, h) + aoff + m * 2048 + k * 1024); } while (0)
; #define PG8_LDB(dst, b, h) do { _Pragma("unroll") for (int n = 0; n < 2; ++n) _Pragma("unroll") for (int k = 0; k < 2; ++k) dst[n][k] = *(const LAS h16x8*)(lds + PG8_SB(b, h) + boff + n * 2048 + k * 1024); } while (0)
; #define PG8_MMA(ai, bj, At, Bt) do { __builtin_amdgcn_s_setprio(1); _Pragma("unroll") for (int m = 0; m < 4; ++m) _Pragma("unroll") for (int n = 0; n < 2; ++n) _Pragma("unroll") for (int k = 0; k < 2; ++k) \
;         acc[ai][bj][m][n] = __builtin_amdgcn_mfma_f32_16x16x32_f16(Bt[n][k], At[m][k], acc[ai][bj][m][n], 0, 0, 0); __builtin_amdgcn_s_setprio(0); } while (0)
; #define PG8_WAIT_V(n) asm volatile("s_waitcnt vmcnt(" #n ")" ::: "memory")
; #define PG8_WAIT_L(n) asm volatile("s_waitcnt lgkmcnt(" #n ")" ::: "memory")
; #define PG8_BAR __builtin_amdgcn_s_barrier()
; #define PG8_SCHED __builtin_amdgcn_sched_barrier(0)
; template <class Epi>
; __device__ __forceinline__ void gemm_phase(LAS unsigned char* lds, const Gemm g, const StaticOrder& S, const Epi& E, const int tid) {
;     ...
;         for (int t = 0; t < nt; t += 2) {
;             const bool last = (t == nt - 2);
;             const char* a1 = cA + (size_t)(t + 1) * kstep;
;             const char* a2 = last ? nA : cA + (size_t)(t + 2) * kstep; const char* b2 = last ? nB : cB + (size_t)(t + 2) * kstep;
;             const char* a3 = a2 + kstep; const char* b3 = b2 + kstep;
;             PG8_LDB(B0, 0, 0); PG8_LDB(B1, 0, 1); PG8_SCHED; PG8_LDA(At, 0, 0); PG8_STAGE(PG8_SA(1, 1), a1 + hstepA, voffA);
;             PG8_WAIT_V(8); PG8_WAIT_L(0); PG8_BAR; PG8_MMA(0, 0, At, B0); PG8_MMA(0, 1, At, B1); PG8_BAR; PG8_SCHED;
;             PG8_LDA(At, 0, 1); PG8_STAGE(PG8_SB(0, 0), b2, voffB); PG8_STAGE(PG8_SB(0, 1), b2 + hstepB, voffB); PG8_STAGE(PG8_SA(0, 0), a2, voffA);
;             PG8_WAIT_V(8); PG8_WAIT_L(0); PG8_BAR; PG8_MMA(1, 0, At, B0); PG8_MMA(1, 1, At, B1); PG8_BAR; PG8_SCHED;
.LBB0_180:
	s_add_u32 s22, s20, 0xfffc0080
	s_addc_u32 s23, s21, -1
	s_add_i32 s31, 0, 0x10000
	s_cmp_eq_u32 s42, 12
	s_cselect_b32 s25, s15, s23
	s_cselect_b32 s24, s40, s22
	s_cselect_b32 s23, s13, s3
	s_cselect_b32 s22, s41, s2
	s_add_i32 s43, 0, 0x14000
	v_add_u32_e32 v140, s31, v195
	v_add_u32_e32 v154, s43, v195
	ds_read_b128 v[128:131], v140
	ds_read_b128 v[132:135], v140 offset:1024
	ds_read_b128 v[136:139], v140 offset:2048
	ds_read_b128 v[140:143], v140 offset:3072
	ds_read_b128 v[174:177], v154
	ds_read_b128 v[178:181], v154 offset:1024
	ds_read_b128 v[182:185], v154 offset:2048
	ds_read_b128 v[190:193], v154 offset:3072
	v_lshl_add_u64 v[154:155], s[20:21], 0, v[170:171]
	s_add_i32 m0, s27, 0xc000
	ds_read_b128 v[212:215], v211
	ds_read_b128 v[216:219], v211 offset:1024
	ds_read_b128 v[220:223], v211 offset:2048
	ds_read_b128 v[224:227], v211 offset:3072
	ds_read_b128 v[228:231], v211 offset:4096
	ds_read_b128 v[232:235], v211 offset:5120
	ds_read_b128 v[236:239], v211 offset:6144
	ds_read_b128 v[240:243], v211 offset:7168
	global_load_lds_dwordx4 v[154:155], off
	v_lshl_add_u64 v[154:155], s[20:21], 0, v[172:173]
	s_add_i32 m0, s27, 0xe000
	s_nop 0
	global_load_lds_dwordx4 v[154:155], off
	s_waitcnt vmcnt(8)
	s_waitcnt lgkmcnt(0)
	s_barrier
	s_waitcnt lgkmcnt(0)
	v_mfma_f32_16x16x32_f16 v[124:127], v[128:131], v[212:215], v[124:127]
	v_mfma_f32_16x16x32_f16 v[116:119], v[136:139], v[212:215], v[116:119]
	v_mfma_f32_16x16x32_f16 v[108:111], v[128:131], v[220:223], v[108:111]
	v_mfma_f32_16x16x32_f16 v[100:103], v[136:139], v[220:223], v[100:103]
	v_mfma_f32_16x16x32_f16 v[92:95], v[128:131], v[228:231], v[92:95]
	v_mfma_f32_16x16x32_f16 v[84:87], v[136:139], v[228:231], v[84:87]
	v_mfma_f32_16x16x32_f16 v[76:79], v[128:131], v[236:239], v[76:79]
	v_mfma_f32_16x16x32_f16 v[68:71], v[136:139], v[236:239], v[68:71]
	v_mfma_f32_16x16x32_f16 v[124:127], v[132:135], v[216:219], v[124:127]
	v_mfma_f32_16x16x32_f16 v[116:119], v[140:143], v[216:219], v[116:119]
	v_mfma_f32_16x16x32_f16 v[108:111], v[132:135], v[224:227], v[108:111]
	v_mfma_f32_16x16x32_f16 v[100:103], v[140:143], v[224:227], v[100:103]
	v_mfma_f32_16x16x32_f16 v[92:95], v[132:135], v[232:235], v[92:95]
	v_mfma_f32_16x16x32_f16 v[84:87], v[140:143], v[232:235], v[84:87]
	v_mfma_f32_16x16x32_f16 v[76:79], v[132:135], v[240:243], v[76:79]
	v_mfma_f32_16x16x32_f16 v[68:71], v[140:143], v[240:243], v[68:71]
	v_mfma_f32_16x16x32_f16 v[120:123], v[174:177], v[212:215], v[120:123]
	v_mfma_f32_16x16x32_f16 v[112:115], v[182:185], v[212:215], v[112:115]
	v_mfma_f32_16x16x32_f16 v[104:107], v[174:177], v[220:223], v[104:107]
	v_mfma_f32_16x16x32_f16 v[96:99], v[182:185], v[220:223], v[96:99]
	v_mfma_f32_16x16x32_f16 v[88:91], v[174:177], v[228:231], v[88:91]
	v_mfma_f32_16x16x32_f16 v[80:83], v[182:185], v[228:231], v[80:83]
	v_mfma_f32_16x16x32_f16 v[72:75], v[174:177], v[236:239], v[72:75]
	v_mfma_f32_16x16x32_f16 v[64:67], v[182:185], v[236:239], v[64:67]
	v_mfma_f32_16x16x32_f16 v[120:123], v[178:181], v[216:219], v[120:123]
	v_mfma_f32_16x16x32_f16 v[112:115], v[190:193], v[216:219], v[112:115]
	v_mfma_f32_16x16x32_f16 v[104:107], v[178:181], v[224:227], v[104:107]
	v_mfma_f32_16x16x32_f16 v[96:99], v[190:193], v[224:227], v[96:99]
	v_mfma_f32_16x16x32_f16 v[88:91], v[178:181], v[232:235], v[88:91]
	v_mfma_f32_16x16x32_f16 v[80:83], v[190:193], v[232:235], v[80:83]
	v_mfma_f32_16x16x32_f16 v[72:75], v[178:181], v[240:243], v[72:75]
	v_mfma_f32_16x16x32_f16 v[64:67], v[190:193], v[240:243], v[64:67]
	s_barrier
	s_add_i32 s31, s31, s26
	v_lshl_add_u64 v[154:155], s[22:23], 0, v[152:153]
	s_mov_b32 m0, s31
	ds_read_b128 v[212:215], v211 offset:16384
	ds_read_b128 v[216:219], v211 offset:17408
	ds_read_b128 v[220:223], v211 offset:18432
	ds_read_b128 v[224:227], v211 offset:19456
	ds_read_b128 v[228:231], v211 offset:20480
	ds_read_b128 v[232:235], v211 offset:21504
	ds_read_b128 v[236:239], v211 offset:22528
	ds_read_b128 v[240:243], v211 offset:23552
	global_load_lds_dwordx4 v[154:155], off
	s_add_i32 m0, s31, 0x2000
	s_add_u32 s44, s22, 0x40000
	v_lshl_add_u64 v[156:157], s[22:23], 0, v[144:145]
	s_addc_u32 s45, s23, 0
	s_add_i32 s31, s43, s26
	global_load_lds_dwordx4 v[156:157], off
	v_lshl_add_u64 v[162:163], s[44:45], 0, v[152:153]
	s_mov_b32 m0, s31
	v_lshl_add_u64 v[164:165], s[24:25], 0, v[146:147]
	global_load_lds_dwordx4 v[162:163], off
	v_lshl_add_u64 v[162:163], s[44:45], 0, v[144:145]
	s_add_i32 m0, s31, 0x2000
	s_nop 0
	global_load_lds_dwordx4 v[162:163], off
	v_lshl_add_u64 v[162:163], s[24:25], 0, v[148:149]
	s_mov_b32 m0, s27
	s_nop 0
	global_load_lds_dwordx4 v[162:163], off
	s_mov_b32 m0, s28
	s_nop 0
	global_load_lds_dwordx4 v[164:165], off
	s_waitcnt vmcnt(8)
	s_waitcnt lgkmcnt(0)
	s_barrier
; #define PG8_STAGE(bufoff, gbase, voff) do { _Pragma("unroll") for (int _i = 0; _i < 2; ++_i) \
;         __builtin_amdgcn_global_load_lds((const unsigned*)((const char*)(gbase) + (voff)[_i]), (LAS unsigned*)(lds + (bufoff) + ldsw + _i * 8192), 16, 0, 0); } while (0)
; #define PG8_LDA(dst, b, h) do { _Pragma("unroll") for (int m = 0; m < 4; ++m) _Pragma("unroll") for (int k = 0; k < 2; ++k) dst[m][k] = *(const LAS h16x8*)(lds + PG8_SA(b, h) + aoff + m * 2048 + k * 1024); } while (0)
; #define PG8_LDB(dst, b, h) do { _Pragma("unroll") for (int n = 0; n < 2; ++n) _Pragma("unroll") for (int k = 0; k < 2; ++k) dst[n][k] = *(const LAS h16x8*)(lds + PG8_SB(b, h) + boff + n * 2048 + k * 1024); } while (0)
; #define PG8_MMA(ai, bj, At, Bt) do { __builtin_amdgcn_s_setprio(1); _Pragma("unroll") for (int m = 0; m < 4; ++m) _Pragma("unroll") for (int n = 0; n < 2; ++n) _Pragma("unroll") for (int k = 0; k < 2; ++k) \
;         acc[ai][bj][m][n] = __builtin_amdgcn_mfma_f32_16x16x32_f16(Bt[n][k], At[m][k], acc[ai][bj][m][n], 0, 0, 0); __builtin_amdgcn_s_setprio(0); } while (0)
; #define PG8_WAIT_V(n) asm volatile("s_waitcnt vmcnt(" #n ")" ::: "memory")
; #define PG8_WAIT_L(n) asm volatile("s_waitcnt lgkmcnt(" #n ")" ::: "memory")
; #define PG8_BAR __builtin_amdgcn_s_barrier()
; #define PG8_SCHED __builtin_amdgcn_sched_barrier(0)
; template <class Epi>
; __device__ __forceinline__ void gemm_phase(LAS unsigned char* lds, const Gemm g, const StaticOrder& S, const Epi& E, const int tid) {
;     ...
;             PG8_WAIT_V(8); PG8_WAIT_L(0); PG8_BAR; PG8_MMA(1, 0, At, B0); PG8_MMA(1, 1, At, B1); PG8_BAR; PG8_SCHED;
;             PG8_LDB(B0, 1, 0); PG8_LDB(B1, 1, 1); PG8_SCHED; PG8_LDA(At, 1, 0); PG8_STAGE(PG8_SA(0, 1), a2 + hstepA, voffA);
;             PG8_WAIT_V(8); PG8_WAIT_L(0); PG8_BAR; PG8_MMA(0, 0, At, B0); PG8_MMA(0, 1, At, B1); PG8_BAR; PG8_SCHED;
	s_waitcnt lgkmcnt(0)
	v_mfma_f32_16x16x32_f16 v[60:63], v[128:131], v[212:215], v[60:63]
	v_mfma_f32_16x16x32_f16 v[52:55], v[136:139], v[212:215], v[52:55]
	v_mfma_f32_16x16x32_f16 v[44:47], v[128:131], v[220:223], v[44:47]
	v_mfma_f32_16x16x32_f16 v[36:39], v[136:139], v[220:223], v[36:39]
	v_mfma_f32_16x16x32_f16 v[28:31], v[128:131], v[228:231], v[28:31]
	v_mfma_f32_16x16x32_f16 v[20:23], v[136:139], v[228:231], v[20:23]
	v_mfma_f32_16x16x32_f16 v[12:15], v[128:131], v[236:239], v[12:15]
	v_mfma_f32_16x16x32_f16 v[4:7], v[136:139], v[236:239], v[4:7]
	v_mfma_f32_16x16x32_f16 v[60:63], v[132:135], v[216:219], v[60:63]
	v_mfma_f32_16x16x32_f16 v[52:55], v[140:143], v[216:219], v[52:55]
	v_mfma_f32_16x16x32_f16 v[44:47], v[132:135], v[224:227], v[44:47]
	v_mfma_f32_16x16x32_f16 v[36:39], v[140:143], v[224:227], v[36:39]
	v_mfma_f32_16x16x32_f16 v[28:31], v[132:135], v[232:235], v[28:31]
	v_mfma_f32_16x16x32_f16 v[20:23], v[140:143], v[232:235], v[20:23]
	v_mfma_f32_16x16x32_f16 v[12:15], v[132:135], v[240:243], v[12:15]
	v_mfma_f32_16x16x32_f16 v[4:7], v[140:143], v[240:243], v[4:7]
	v_mfma_f32_16x16x32_f16 v[56:59], v[174:177], v[212:215], v[56:59]
	v_mfma_f32_16x16x32_f16 v[48:51], v[182:185], v[212:215], v[48:51]
	v_mfma_f32_16x16x32_f16 v[40:43], v[174:177], v[220:223], v[40:43]
	v_mfma_f32_16x16x32_f16 v[32:35], v[182:185], v[220:223], v[32:35]
	v_mfma_f32_16x16x32_f16 v[24:27], v[174:177], v[228:231], v[24:27]
	v_mfma_f32_16x16x32_f16 v[16:19], v[182:185], v[228:231], v[16:19]
	v_mfma_f32_16x16x32_f16 v[8:11], v[174:177], v[236:239], v[8:11]
	v_mfma_f32_16x16x32_f16 v[0:3], v[182:185], v[236:239], v[0:3]
	v_mfma_f32_16x16x32_f16 v[56:59], v[178:181], v[216:219], v[56:59]
	v_mfma_f32_16x16x32_f16 v[48:51], v[190:193], v[216:219], v[48:51]
	v_mfma_f32_16x16x32_f16 v[40:43], v[178:181], v[224:227], v[40:43]
	v_mfma_f32_16x16x32_f16 v[32:35], v[190:193], v[224:227], v[32:35]
	v_mfma_f32_16x16x32_f16 v[24:27], v[178:181], v[232:235], v[24:27]
	v_mfma_f32_16x16x32_f16 v[16:19], v[190:193], v[232:235], v[16:19]
	v_mfma_f32_16x16x32_f16 v[8:11], v[178:181], v[240:243], v[8:11]
	v_mfma_f32_16x16x32_f16 v[0:3], v[190:193], v[240:243], v[0:3]
	s_barrier
	s_add_i32 s31, 0, 0x18000
	s_add_i32 s43, 0, 0x1c000
	v_add_u32_e32 v140, s31, v195
	v_add_u32_e32 v166, s43, v195
	ds_read_b128 v[128:131], v140
	ds_read_b128 v[132:135], v140 offset:1024
	ds_read_b128 v[136:139], v140 offset:2048
	ds_read_b128 v[140:143], v140 offset:3072
	ds_read_b128 v[174:177], v166
	ds_read_b128 v[178:181], v166 offset:1024
	ds_read_b128 v[182:185], v166 offset:2048
	ds_read_b128 v[190:193], v166 offset:3072
	s_add_u32 s24, s24, 0x40000
	s_addc_u32 s25, s25, 0
	s_mov_b32 m0, s29
	v_lshl_add_u64 v[166:167], s[24:25], 0, v[148:149]
	ds_read_b128 v[212:215], v211 offset:32768
	ds_read_b128 v[216:219], v211 offset:33792
	ds_read_b128 v[220:223], v211 offset:34816
	ds_read_b128 v[224:227], v211 offset:35840
	ds_read_b128 v[228:231], v211 offset:36864
	ds_read_b128 v[232:235], v211 offset:37888
	ds_read_b128 v[236:239], v211 offset:38912
	ds_read_b128 v[240:243], v211 offset:39936
	global_load_lds_dwordx4 v[166:167], off
	v_lshl_add_u64 v[166:167], s[24:25], 0, v[146:147]
	s_mov_b32 m0, s34
	s_nop 0
	global_load_lds_dwordx4 v[166:167], off
	s_waitcnt vmcnt(8)
	s_waitcnt lgkmcnt(0)
	s_barrier
	s_waitcnt lgkmcnt(0)
	v_mfma_f32_16x16x32_f16 v[124:127], v[128:131], v[212:215], v[124:127]
	v_mfma_f32_16x16x32_f16 v[116:119], v[136:139], v[212:215], v[116:119]
	v_mfma_f32_16x16x32_f16 v[108:111], v[128:131], v[220:223], v[108:111]
	v_mfma_f32_16x16x32_f16 v[100:103], v[136:139], v[220:223], v[100:103]
	v_mfma_f32_16x16x32_f16 v[92:95], v[128:131], v[228:231], v[92:95]
	v_mfma_f32_16x16x32_f16 v[84:87], v[136:139], v[228:231], v[84:87]
	v_mfma_f32_16x16x32_f16 v[76:79], v[128:131], v[236:239], v[76:79]
	v_mfma_f32_16x16x32_f16 v[68:71], v[136:139], v[236:239], v[68:71]
	v_mfma_f32_16x16x32_f16 v[124:127], v[132:135], v[216:219], v[124:127]
	v_mfma_f32_16x16x32_f16 v[116:119], v[140:143], v[216:219], v[116:119]
	v_mfma_f32_16x16x32_f16 v[108:111], v[132:135], v[224:227], v[108:111]
	v_mfma_f32_16x16x32_f16 v[100:103], v[140:143], v[224:227], v[100:103]
	v_mfma_f32_16x16x32_f16 v[92:95], v[132:135], v[232:235], v[92:95]
	v_mfma_f32_16x16x32_f16 v[84:87], v[140:143], v[232:235], v[84:87]
	v_mfma_f32_16x16x32_f16 v[76:79], v[132:135], v[240:243], v[76:79]
	v_mfma_f32_16x16x32_f16 v[68:71], v[140:143], v[240:243], v[68:71]
	v_mfma_f32_16x16x32_f16 v[120:123], v[174:177], v[212:215], v[120:123]
	v_mfma_f32_16x16x32_f16 v[112:115], v[182:185], v[212:215], v[112:115]
	v_mfma_f32_16x16x32_f16 v[104:107], v[174:177], v[220:223], v[104:107]
	v_mfma_f32_16x16x32_f16 v[96:99], v[182:185], v[220:223], v[96:99]
	v_mfma_f32_16x16x32_f16 v[88:91], v[174:177], v[228:231], v[88:91]
	v_mfma_f32_16x16x32_f16 v[80:83], v[182:185], v[228:231], v[80:83]
	v_mfma_f32_16x16x32_f16 v[72:75], v[174:177], v[236:239], v[72:75]
	v_mfma_f32_16x16x32_f16 v[64:67], v[182:185], v[236:239], v[64:67]
	v_mfma_f32_16x16x32_f16 v[120:123], v[178:181], v[216:219], v[120:123]
	v_mfma_f32_16x16x32_f16 v[112:115], v[190:193], v[216:219], v[112:115]
	v_mfma_f32_16x16x32_f16 v[104:107], v[178:181], v[224:227], v[104:107]
	v_mfma_f32_16x16x32_f16 v[96:99], v[190:193], v[224:227], v[96:99]
	v_mfma_f32_16x16x32_f16 v[88:91], v[178:181], v[232:235], v[88:91]
	v_mfma_f32_16x16x32_f16 v[80:83], v[190:193], v[232:235], v[80:83]
	v_mfma_f32_16x16x32_f16 v[72:75], v[178:181], v[240:243], v[72:75]
	v_mfma_f32_16x16x32_f16 v[64:67], v[190:193], v[240:243], v[64:67]
	s_barrier
; #define PG8_STAGE(bufoff, gbase, voff) do { _Pragma("unroll") for (int _i = 0; _i < 2; ++_i) \
;         __builtin_amdgcn_global_load_lds((const unsigned*)((const char*)(gbase) + (voff)[_i]), (LAS unsigned*)(lds + (bufoff) + ldsw + _i * 8192), 16, 0, 0); } while (0)
; #define PG8_LDA(dst, b, h) do { _Pragma("unroll") for (int m = 0; m < 4; ++m) _Pragma("unroll") for (int k = 0; k < 2; ++k) dst[m][k] = *(const LAS h16x8*)(lds + PG8_SA(b, h) + aoff + m * 2048 + k * 1024); } while (0)
; #define PG8_MMA(ai, bj, At, Bt) do { __builtin_amdgcn_s_setprio(1); _Pragma("unroll") for (int m = 0; m < 4; ++m) _Pragma("unroll") for (int n = 0; n < 2; ++n) _Pragma("unroll") for (int k = 0; k < 2; ++k) \
;         acc[ai][bj][m][n] = __builtin_amdgcn_mfma_f32_16x16x32_f16(Bt[n][k], At[m][k], acc[ai][bj][m][n], 0, 0, 0); __builtin_amdgcn_s_setprio(0); } while (0)
; #define PG8_WAIT_V(n) asm volatile("s_waitcnt vmcnt(" #n ")" ::: "memory")
; #define PG8_WAIT_L(n) asm volatile("s_waitcnt lgkmcnt(" #n ")" ::: "memory")
; #define PG8_BAR __builtin_amdgcn_s_barrier()
; #define PG8_SCHED __builtin_amdgcn_sched_barrier(0)
; template <class Epi>
; __device__ __forceinline__ void gemm_phase(LAS unsigned char* lds, const Gemm g, const StaticOrder& S, const Epi& E, const int tid) {
;     ...
;             PG8_LDA(At, 1, 1); PG8_STAGE(PG8_SB(1, 0), b3, voffB); PG8_STAGE(PG8_SB(1, 1), b3 + hstepB, voffB); PG8_STAGE(PG8_SA(1, 0), a3, voffA);
;             PG8_WAIT_V(8); PG8_WAIT_L(0); PG8_BAR; PG8_MMA(1, 0, At, B0); PG8_MMA(1, 1, At, B1); PG8_BAR; PG8_SCHED;
;         }
;         if (wr == 0) PG8_BAR;
	s_add_i32 s24, s31, s26
	v_lshl_add_u64 v[154:155], v[154:155], 0, s[0:1]
	s_mov_b32 m0, s24
	ds_read_b128 v[212:215], v211 offset:49152
	ds_read_b128 v[216:219], v211 offset:50176
	ds_read_b128 v[220:223], v211 offset:51200
	ds_read_b128 v[224:227], v211 offset:52224
	ds_read_b128 v[228:231], v211 offset:53248
	ds_read_b128 v[232:235], v211 offset:54272
	ds_read_b128 v[236:239], v211 offset:55296
	ds_read_b128 v[240:243], v211 offset:56320
	global_load_lds_dwordx4 v[154:155], off
	s_add_i32 m0, s24, 0x2000
	s_add_u32 s22, s22, 0x40080
	v_lshl_add_u64 v[154:155], v[156:157], 0, s[0:1]
	s_addc_u32 s23, s23, 0
	s_add_i32 s24, s43, s26
	global_load_lds_dwordx4 v[154:155], off
	v_lshl_add_u64 v[154:155], s[22:23], 0, v[152:153]
	s_mov_b32 m0, s24
	s_nop 0
	global_load_lds_dwordx4 v[154:155], off
	v_lshl_add_u64 v[154:155], s[22:23], 0, v[144:145]
	s_add_i32 m0, s24, 0x2000
	s_nop 0
	global_load_lds_dwordx4 v[154:155], off
	v_lshl_add_u64 v[154:155], v[162:163], 0, s[0:1]
	s_mov_b32 m0, s35
	s_nop 0
	global_load_lds_dwordx4 v[154:155], off
	v_lshl_add_u64 v[154:155], v[164:165], 0, s[0:1]
	s_mov_b32 m0, s36
	s_nop 0
	global_load_lds_dwordx4 v[154:155], off
	s_waitcnt vmcnt(8)
	s_waitcnt lgkmcnt(0)
	s_barrier
	s_waitcnt lgkmcnt(0)
	v_mfma_f32_16x16x32_f16 v[60:63], v[128:131], v[212:215], v[60:63]
	v_mfma_f32_16x16x32_f16 v[52:55], v[136:139], v[212:215], v[52:55]
	v_mfma_f32_16x16x32_f16 v[44:47], v[128:131], v[220:223], v[44:47]
	v_mfma_f32_16x16x32_f16 v[36:39], v[136:139], v[220:223], v[36:39]
	v_mfma_f32_16x16x32_f16 v[28:31], v[128:131], v[228:231], v[28:31]
	v_mfma_f32_16x16x32_f16 v[20:23], v[136:139], v[228:231], v[20:23]
	v_mfma_f32_16x16x32_f16 v[12:15], v[128:131], v[236:239], v[12:15]
	v_mfma_f32_16x16x32_f16 v[4:7], v[136:139], v[236:239], v[4:7]
	v_mfma_f32_16x16x32_f16 v[60:63], v[132:135], v[216:219], v[60:63]
	v_mfma_f32_16x16x32_f16 v[52:55], v[140:143], v[216:219], v[52:55]
	v_mfma_f32_16x16x32_f16 v[44:47], v[132:135], v[224:227], v[44:47]
	v_mfma_f32_16x16x32_f16 v[36:39], v[140:143], v[224:227], v[36:39]
	v_mfma_f32_16x16x32_f16 v[28:31], v[132:135], v[232:235], v[28:31]
	v_mfma_f32_16x16x32_f16 v[20:23], v[140:143], v[232:235], v[20:23]
	v_mfma_f32_16x16x32_f16 v[12:15], v[132:135], v[240:243], v[12:15]
	v_mfma_f32_16x16x32_f16 v[4:7], v[140:143], v[240:243], v[4:7]
	v_mfma_f32_16x16x32_f16 v[56:59], v[174:177], v[212:215], v[56:59]
	v_mfma_f32_16x16x32_f16 v[48:51], v[182:185], v[212:215], v[48:51]
	v_mfma_f32_16x16x32_f16 v[40:43], v[174:177], v[220:223], v[40:43]
	v_mfma_f32_16x16x32_f16 v[32:35], v[182:185], v[220:223], v[32:35]
	v_mfma_f32_16x16x32_f16 v[24:27], v[174:177], v[228:231], v[24:27]
	v_mfma_f32_16x16x32_f16 v[16:19], v[182:185], v[228:231], v[16:19]
	v_mfma_f32_16x16x32_f16 v[8:11], v[174:177], v[236:239], v[8:11]
	v_mfma_f32_16x16x32_f16 v[0:3], v[182:185], v[236:239], v[0:3]
	v_mfma_f32_16x16x32_f16 v[56:59], v[178:181], v[216:219], v[56:59]
	v_mfma_f32_16x16x32_f16 v[48:51], v[190:193], v[216:219], v[48:51]
	v_mfma_f32_16x16x32_f16 v[40:43], v[178:181], v[224:227], v[40:43]
	v_mfma_f32_16x16x32_f16 v[32:35], v[190:193], v[224:227], v[32:35]
	v_mfma_f32_16x16x32_f16 v[24:27], v[178:181], v[232:235], v[24:27]
	v_mfma_f32_16x16x32_f16 v[16:19], v[190:193], v[232:235], v[16:19]
	v_mfma_f32_16x16x32_f16 v[8:11], v[178:181], v[240:243], v[8:11]
	v_mfma_f32_16x16x32_f16 v[0:3], v[190:193], v[240:243], v[0:3]
	s_barrier
	s_add_i32 s42, s42, 2
	s_add_u32 s20, s20, 0x100
	s_addc_u32 s21, s21, 0
	s_add_u32 s2, s2, 0x100
	s_addc_u32 s3, s3, 0
	s_cmp_gt_u32 s42, 13
	s_cbranch_scc0 .LBB0_180
	s_and_b64 vcc, exec, s[8:9]
	s_cbranch_vccz .LBB0_183
	s_barrier

; #define PG8_STAGE(bufoff, gbase, voff) do { _Pragma("unroll") for (int _i = 0; _i < 2; ++_i) \
;         __builtin_amdgcn_global_load_lds((const unsigned*)((const char*)(gbase) + (voff)[_i]), (LAS unsigned*)(lds + (bufoff) + ldsw + _i * 8192), 16, 0, 0); } while (0)
; #define PG8_LDA(dst, b, h) do { _Pragma("unroll") for (int m = 0; m < 4; ++m) _Pragma("unroll") for (int k = 0; k < 2; ++k) dst[m][k] = *(const LAS h16x8*)(lds + PG8_SA(b, h) + aoff + m * 2048 + k * 1024); } while (0)
; #define PG8_LDB(dst, b, h) do { _Pragma("unroll") for (int n = 0; n < 2; ++n) _Pragma("unroll") for (int k = 0; k < 2; ++k) dst[n][k] = *(const LAS h16x8*)(lds + PG8_SB(b, h) + boff + n * 2048 + k * 1024); } while (0)
; #define PG8_MMA(ai, bj, At, Bt) do { __builtin_amdgcn_s_setprio(1); _Pragma("unroll") for (int m = 0; m < 4; ++m) _Pragma("unroll") for (int n = 0; n < 2; ++n) _Pragma("unroll") for (int k = 0; k < 2; ++k) \
;         acc[ai][bj][m][n] = __builtin_amdgcn_mfma_f32_16x16x32_f16(Bt[n][k], At[m][k], acc[ai][bj][m][n], 0, 0, 0); __builtin_amdgcn_s_setprio(0); } while (0)
; #define PG8_WAIT_V(n) asm volatile("s_waitcnt vmcnt(" #n ")" ::: "memory")
; #define PG8_WAIT_L(n) asm volatile("s_waitcnt lgkmcnt(" #n ")" ::: "memory")
; #define PG8_BAR __builtin_amdgcn_s_barrier()
; #define PG8_SCHED __builtin_amdgcn_sched_barrier(0)
; template <class Epi>
; __device__ __forceinline__ void gemm_phase(LAS unsigned char* lds, const Gemm g, const StaticOrder& S, const Epi& E, const int tid) {
;     ...
;         for (int t = 0; t < nt; t += 2) {
;             const bool last = (t == nt - 2);
;             const char* a1 = cA + (size_t)(t + 1) * kstep;
;             const char* a2 = last ? nA : cA + (size_t)(t + 2) * kstep; const char* b2 = last ? nB : cB + (size_t)(t + 2) * kstep;
;             const char* a3 = a2 + kstep; const char* b3 = b2 + kstep;
;             PG8_LDB(B0, 0, 0); PG8_LDB(B1, 0, 1); PG8_SCHED; PG8_LDA(At, 0, 0); PG8_STAGE(PG8_SA(1, 1), a1 + hstepA, voffA);
;             PG8_WAIT_V(8); PG8_WAIT_L(0); PG8_BAR; PG8_MMA(0, 0, At, B0); PG8_MMA(0, 1, At, B1); PG8_BAR; PG8_SCHED;
;             PG8_LDA(At, 0, 1); PG8_STAGE(PG8_SB(0, 0), b2, voffB); PG8_STAGE(PG8_SB(0, 1), b2 + hstepB, voffB); PG8_STAGE(PG8_SA(0, 0), a2, voffA);
;             PG8_WAIT_V(8); PG8_WAIT_L(0); PG8_BAR; PG8_MMA(1, 0, At, B0); PG8_MMA(1, 1, At, B1); PG8_BAR; PG8_SCHED;
.LBB0_214:
	s_add_u32 s18, s16, 0x100
	s_addc_u32 s19, s17, 0
	s_add_i32 s31, 0, 0x10000
	s_cmp_eq_u32 s45, 40
	s_cselect_b32 s23, s11, s19
	s_cselect_b32 s22, s10, s18
	s_cselect_b32 s21, s15, s3
	s_cselect_b32 s20, s14, s2
	s_add_i32 s46, 0, 0x14000
	v_add_u32_e32 v140, s31, v185
	v_add_u32_e32 v154, s46, v185
	ds_read_b128 v[128:131], v140
	ds_read_b128 v[132:135], v140 offset:1024
	ds_read_b128 v[136:139], v140 offset:2048
	ds_read_b128 v[140:143], v140 offset:3072
	ds_read_b128 v[144:147], v154
	ds_read_b128 v[148:151], v154 offset:1024
	ds_read_b128 v[176:179], v154 offset:2048
	ds_read_b128 v[180:183], v154 offset:3072
	v_lshl_add_u64 v[154:155], s[16:17], 0, v[172:173]
	s_add_i32 m0, s29, 0xc000
	ds_read_b128 v[188:191], v187
	ds_read_b128 v[192:195], v187 offset:1024
	ds_read_b128 v[210:213], v187 offset:2048
	ds_read_b128 v[214:217], v187 offset:3072
	ds_read_b128 v[218:221], v187 offset:4096
	ds_read_b128 v[222:225], v187 offset:5120
	ds_read_b128 v[226:229], v187 offset:6144
	ds_read_b128 v[230:233], v187 offset:7168
	global_load_lds_dwordx4 v[154:155], off
	v_lshl_add_u64 v[154:155], s[16:17], 0, v[174:175]
	s_add_i32 m0, s29, 0xe000
	s_nop 0
	global_load_lds_dwordx4 v[154:155], off
	s_waitcnt vmcnt(8)
	s_waitcnt lgkmcnt(0)
	s_barrier
	s_waitcnt lgkmcnt(0)
	v_mfma_f32_16x16x32_f16 v[124:127], v[128:131], v[188:191], v[124:127]
	v_mfma_f32_16x16x32_f16 v[120:123], v[136:139], v[188:191], v[120:123]
	v_mfma_f32_16x16x32_f16 v[108:111], v[128:131], v[210:213], v[108:111]
	v_mfma_f32_16x16x32_f16 v[104:107], v[136:139], v[210:213], v[104:107]
	v_mfma_f32_16x16x32_f16 v[92:95], v[128:131], v[218:221], v[92:95]
	v_mfma_f32_16x16x32_f16 v[88:91], v[136:139], v[218:221], v[88:91]
	v_mfma_f32_16x16x32_f16 v[76:79], v[128:131], v[226:229], v[76:79]
	v_mfma_f32_16x16x32_f16 v[72:75], v[136:139], v[226:229], v[72:75]
	v_mfma_f32_16x16x32_f16 v[124:127], v[132:135], v[192:195], v[124:127]
	v_mfma_f32_16x16x32_f16 v[120:123], v[140:143], v[192:195], v[120:123]
	v_mfma_f32_16x16x32_f16 v[108:111], v[132:135], v[214:217], v[108:111]
	v_mfma_f32_16x16x32_f16 v[104:107], v[140:143], v[214:217], v[104:107]
	v_mfma_f32_16x16x32_f16 v[92:95], v[132:135], v[222:225], v[92:95]
	v_mfma_f32_16x16x32_f16 v[88:91], v[140:143], v[222:225], v[88:91]
	v_mfma_f32_16x16x32_f16 v[76:79], v[132:135], v[230:233], v[76:79]
	v_mfma_f32_16x16x32_f16 v[72:75], v[140:143], v[230:233], v[72:75]
	v_mfma_f32_16x16x32_f16 v[116:119], v[144:147], v[188:191], v[116:119]
	v_mfma_f32_16x16x32_f16 v[112:115], v[176:179], v[188:191], v[112:115]
	v_mfma_f32_16x16x32_f16 v[100:103], v[144:147], v[210:213], v[100:103]
	v_mfma_f32_16x16x32_f16 v[96:99], v[176:179], v[210:213], v[96:99]
	v_mfma_f32_16x16x32_f16 v[84:87], v[144:147], v[218:221], v[84:87]
	v_mfma_f32_16x16x32_f16 v[80:83], v[176:179], v[218:221], v[80:83]
	v_mfma_f32_16x16x32_f16 v[68:71], v[144:147], v[226:229], v[68:71]
	v_mfma_f32_16x16x32_f16 v[64:67], v[176:179], v[226:229], v[64:67]
	v_mfma_f32_16x16x32_f16 v[116:119], v[148:151], v[192:195], v[116:119]
	v_mfma_f32_16x16x32_f16 v[112:115], v[180:183], v[192:195], v[112:115]
	v_mfma_f32_16x16x32_f16 v[100:103], v[148:151], v[214:217], v[100:103]
	v_mfma_f32_16x16x32_f16 v[96:99], v[180:183], v[214:217], v[96:99]
	v_mfma_f32_16x16x32_f16 v[84:87], v[148:151], v[222:225], v[84:87]
	v_mfma_f32_16x16x32_f16 v[80:83], v[180:183], v[222:225], v[80:83]
	v_mfma_f32_16x16x32_f16 v[68:71], v[148:151], v[230:233], v[68:71]
	v_mfma_f32_16x16x32_f16 v[64:67], v[180:183], v[230:233], v[64:67]
	s_barrier
	s_add_i32 s16, s31, s28
	v_lshl_add_u64 v[154:155], s[20:21], 0, v[152:153]
	s_mov_b32 m0, s16
	ds_read_b128 v[188:191], v187 offset:16384
	ds_read_b128 v[192:195], v187 offset:17408
	ds_read_b128 v[210:213], v187 offset:18432
	ds_read_b128 v[214:217], v187 offset:19456
	ds_read_b128 v[218:221], v187 offset:20480
	ds_read_b128 v[222:225], v187 offset:21504
	ds_read_b128 v[226:229], v187 offset:22528
	ds_read_b128 v[230:233], v187 offset:23552
	global_load_lds_dwordx4 v[154:155], off
	s_add_i32 m0, s16, 0x2000
	s_add_u32 s16, s20, 0xb0000
	v_lshl_add_u64 v[156:157], s[20:21], 0, v[170:171]
	s_addc_u32 s17, s21, 0
	s_add_i32 s31, s46, s28
	global_load_lds_dwordx4 v[156:157], off
	v_lshl_add_u64 v[162:163], s[16:17], 0, v[152:153]
	s_mov_b32 m0, s31
	v_lshl_add_u64 v[164:165], s[22:23], 0, v[170:171]
	global_load_lds_dwordx4 v[162:163], off
	v_lshl_add_u64 v[162:163], s[16:17], 0, v[170:171]
	s_add_i32 m0, s31, 0x2000
	s_nop 0
	global_load_lds_dwordx4 v[162:163], off
	v_lshl_add_u64 v[162:163], s[22:23], 0, v[152:153]
	s_mov_b32 m0, s29
	s_nop 0
	global_load_lds_dwordx4 v[162:163], off
	s_mov_b32 m0, s34
	s_nop 0
	global_load_lds_dwordx4 v[164:165], off
	s_waitcnt vmcnt(8)
	s_waitcnt lgkmcnt(0)
	s_barrier
; #define PG8_STAGE(bufoff, gbase, voff) do { _Pragma("unroll") for (int _i = 0; _i < 2; ++_i) \
;         __builtin_amdgcn_global_load_lds((const unsigned*)((const char*)(gbase) + (voff)[_i]), (LAS unsigned*)(lds + (bufoff) + ldsw + _i * 8192), 16, 0, 0); } while (0)
; #define PG8_LDA(dst, b, h) do { _Pragma("unroll") for (int m = 0; m < 4; ++m) _Pragma("unroll") for (int k = 0; k < 2; ++k) dst[m][k] = *(const LAS h16x8*)(lds + PG8_SA(b, h) + aoff + m * 2048 + k * 1024); } while (0)
; #define PG8_LDB(dst, b, h) do { _Pragma("unroll") for (int n = 0; n < 2; ++n) _Pragma("unroll") for (int k = 0; k < 2; ++k) dst[n][k] = *(const LAS h16x8*)(lds + PG8_SB(b, h) + boff + n * 2048 + k * 1024); } while (0)
; #define PG8_MMA(ai, bj, At, Bt) do { __builtin_amdgcn_s_setprio(1); _Pragma("unroll") for (int m = 0; m < 4; ++m) _Pragma("unroll") for (int n = 0; n < 2; ++n) _Pragma("unroll") for (int k = 0; k < 2; ++k) \
;         acc[ai][bj][m][n] = __builtin_amdgcn_mfma_f32_16x16x32_f16(Bt[n][k], At[m][k], acc[ai][bj][m][n], 0, 0, 0); __builtin_amdgcn_s_setprio(0); } while (0)
; #define PG8_WAIT_V(n) asm volatile("s_waitcnt vmcnt(" #n ")" ::: "memory")
; #define PG8_WAIT_L(n) asm volatile("s_waitcnt lgkmcnt(" #n ")" ::: "memory")
; #define PG8_BAR __builtin_amdgcn_s_barrier()
; #define PG8_SCHED __builtin_amdgcn_sched_barrier(0)
; template <class Epi>
; __device__ __forceinline__ void gemm_phase(LAS unsigned char* lds, const Gemm g, const StaticOrder& S, const Epi& E, const int tid) {
;     ...
;             PG8_WAIT_V(8); PG8_WAIT_L(0); PG8_BAR; PG8_MMA(1, 0, At, B0); PG8_MMA(1, 1, At, B1); PG8_BAR; PG8_SCHED;
;             PG8_LDB(B0, 1, 0); PG8_LDB(B1, 1, 1); PG8_SCHED; PG8_LDA(At, 1, 0); PG8_STAGE(PG8_SA(0, 1), a2 + hstepA, voffA);
;             PG8_WAIT_V(8); PG8_WAIT_L(0); PG8_BAR; PG8_MMA(0, 0, At, B0); PG8_MMA(0, 1, At, B1); PG8_BAR; PG8_SCHED;
	s_waitcnt lgkmcnt(0)
	v_mfma_f32_16x16x32_f16 v[60:63], v[128:131], v[188:191], v[60:63]
	v_mfma_f32_16x16x32_f16 v[56:59], v[136:139], v[188:191], v[56:59]
	v_mfma_f32_16x16x32_f16 v[44:47], v[128:131], v[210:213], v[44:47]
	v_mfma_f32_16x16x32_f16 v[40:43], v[136:139], v[210:213], v[40:43]
	v_mfma_f32_16x16x32_f16 v[28:31], v[128:131], v[218:221], v[28:31]
	v_mfma_f32_16x16x32_f16 v[24:27], v[136:139], v[218:221], v[24:27]
	v_mfma_f32_16x16x32_f16 v[12:15], v[128:131], v[226:229], v[12:15]
	v_mfma_f32_16x16x32_f16 v[8:11], v[136:139], v[226:229], v[8:11]
	v_mfma_f32_16x16x32_f16 v[60:63], v[132:135], v[192:195], v[60:63]
	v_mfma_f32_16x16x32_f16 v[56:59], v[140:143], v[192:195], v[56:59]
	v_mfma_f32_16x16x32_f16 v[44:47], v[132:135], v[214:217], v[44:47]
	v_mfma_f32_16x16x32_f16 v[40:43], v[140:143], v[214:217], v[40:43]
	v_mfma_f32_16x16x32_f16 v[28:31], v[132:135], v[222:225], v[28:31]
	v_mfma_f32_16x16x32_f16 v[24:27], v[140:143], v[222:225], v[24:27]
	v_mfma_f32_16x16x32_f16 v[12:15], v[132:135], v[230:233], v[12:15]
	v_mfma_f32_16x16x32_f16 v[8:11], v[140:143], v[230:233], v[8:11]
	v_mfma_f32_16x16x32_f16 v[52:55], v[144:147], v[188:191], v[52:55]
	v_mfma_f32_16x16x32_f16 v[48:51], v[176:179], v[188:191], v[48:51]
	v_mfma_f32_16x16x32_f16 v[36:39], v[144:147], v[210:213], v[36:39]
	v_mfma_f32_16x16x32_f16 v[32:35], v[176:179], v[210:213], v[32:35]
	v_mfma_f32_16x16x32_f16 v[20:23], v[144:147], v[218:221], v[20:23]
	v_mfma_f32_16x16x32_f16 v[16:19], v[176:179], v[218:221], v[16:19]
	v_mfma_f32_16x16x32_f16 v[4:7], v[144:147], v[226:229], v[4:7]
	v_mfma_f32_16x16x32_f16 v[0:3], v[176:179], v[226:229], v[0:3]
	v_mfma_f32_16x16x32_f16 v[52:55], v[148:151], v[192:195], v[52:55]
	v_mfma_f32_16x16x32_f16 v[48:51], v[180:183], v[192:195], v[48:51]
	v_mfma_f32_16x16x32_f16 v[36:39], v[148:151], v[214:217], v[36:39]
	v_mfma_f32_16x16x32_f16 v[32:35], v[180:183], v[214:217], v[32:35]
	v_mfma_f32_16x16x32_f16 v[20:23], v[148:151], v[222:225], v[20:23]
	v_mfma_f32_16x16x32_f16 v[16:19], v[180:183], v[222:225], v[16:19]
	v_mfma_f32_16x16x32_f16 v[4:7], v[148:151], v[230:233], v[4:7]
	v_mfma_f32_16x16x32_f16 v[0:3], v[180:183], v[230:233], v[0:3]
	s_barrier
	s_add_i32 s31, 0, 0x18000
	s_add_i32 s46, 0, 0x1c000
	v_add_u32_e32 v140, s31, v185
	v_add_u32_e32 v166, s46, v185
	ds_read_b128 v[128:131], v140
	ds_read_b128 v[132:135], v140 offset:1024
	ds_read_b128 v[136:139], v140 offset:2048
	ds_read_b128 v[140:143], v140 offset:3072
	ds_read_b128 v[144:147], v166
	ds_read_b128 v[148:151], v166 offset:1024
	ds_read_b128 v[176:179], v166 offset:2048
	ds_read_b128 v[180:183], v166 offset:3072
	s_add_u32 s16, s22, 0xb0000
	s_addc_u32 s17, s23, 0
	s_mov_b32 m0, s35
	v_lshl_add_u64 v[166:167], s[16:17], 0, v[152:153]
	ds_read_b128 v[188:191], v187 offset:32768
	ds_read_b128 v[192:195], v187 offset:33792
	ds_read_b128 v[210:213], v187 offset:34816
	ds_read_b128 v[214:217], v187 offset:35840
	ds_read_b128 v[218:221], v187 offset:36864
	ds_read_b128 v[222:225], v187 offset:37888
	ds_read_b128 v[226:229], v187 offset:38912
	ds_read_b128 v[230:233], v187 offset:39936
	global_load_lds_dwordx4 v[166:167], off
	v_lshl_add_u64 v[166:167], s[16:17], 0, v[170:171]
	s_mov_b32 m0, s36
	s_nop 0
	global_load_lds_dwordx4 v[166:167], off
	s_waitcnt vmcnt(8)
	s_waitcnt lgkmcnt(0)
	s_barrier
	s_waitcnt lgkmcnt(0)
	v_mfma_f32_16x16x32_f16 v[124:127], v[128:131], v[188:191], v[124:127]
	v_mfma_f32_16x16x32_f16 v[120:123], v[136:139], v[188:191], v[120:123]
	v_mfma_f32_16x16x32_f16 v[108:111], v[128:131], v[210:213], v[108:111]
	v_mfma_f32_16x16x32_f16 v[104:107], v[136:139], v[210:213], v[104:107]
	v_mfma_f32_16x16x32_f16 v[92:95], v[128:131], v[218:221], v[92:95]
	v_mfma_f32_16x16x32_f16 v[88:91], v[136:139], v[218:221], v[88:91]
	v_mfma_f32_16x16x32_f16 v[76:79], v[128:131], v[226:229], v[76:79]
	v_mfma_f32_16x16x32_f16 v[72:75], v[136:139], v[226:229], v[72:75]
	v_mfma_f32_16x16x32_f16 v[124:127], v[132:135], v[192:195], v[124:127]
	v_mfma_f32_16x16x32_f16 v[120:123], v[140:143], v[192:195], v[120:123]
	v_mfma_f32_16x16x32_f16 v[108:111], v[132:135], v[214:217], v[108:111]
	v_mfma_f32_16x16x32_f16 v[104:107], v[140:143], v[214:217], v[104:107]
	v_mfma_f32_16x16x32_f16 v[92:95], v[132:135], v[222:225], v[92:95]
	v_mfma_f32_16x16x32_f16 v[88:91], v[140:143], v[222:225], v[88:91]
	v_mfma_f32_16x16x32_f16 v[76:79], v[132:135], v[230:233], v[76:79]
	v_mfma_f32_16x16x32_f16 v[72:75], v[140:143], v[230:233], v[72:75]
	v_mfma_f32_16x16x32_f16 v[116:119], v[144:147], v[188:191], v[116:119]
	v_mfma_f32_16x16x32_f16 v[112:115], v[176:179], v[188:191], v[112:115]
	v_mfma_f32_16x16x32_f16 v[100:103], v[144:147], v[210:213], v[100:103]
	v_mfma_f32_16x16x32_f16 v[96:99], v[176:179], v[210:213], v[96:99]
	v_mfma_f32_16x16x32_f16 v[84:87], v[144:147], v[218:221], v[84:87]
	v_mfma_f32_16x16x32_f16 v[80:83], v[176:179], v[218:221], v[80:83]
	v_mfma_f32_16x16x32_f16 v[68:71], v[144:147], v[226:229], v[68:71]
	v_mfma_f32_16x16x32_f16 v[64:67], v[176:179], v[226:229], v[64:67]
	v_mfma_f32_16x16x32_f16 v[116:119], v[148:151], v[192:195], v[116:119]
	v_mfma_f32_16x16x32_f16 v[112:115], v[180:183], v[192:195], v[112:115]
	v_mfma_f32_16x16x32_f16 v[100:103], v[148:151], v[214:217], v[100:103]
	v_mfma_f32_16x16x32_f16 v[96:99], v[180:183], v[214:217], v[96:99]
	v_mfma_f32_16x16x32_f16 v[84:87], v[148:151], v[222:225], v[84:87]
	v_mfma_f32_16x16x32_f16 v[80:83], v[180:183], v[222:225], v[80:83]
	v_mfma_f32_16x16x32_f16 v[68:71], v[148:151], v[230:233], v[68:71]
	v_mfma_f32_16x16x32_f16 v[64:67], v[180:183], v[230:233], v[64:67]
	s_barrier
; #define PG8_STAGE(bufoff, gbase, voff) do { _Pragma("unroll") for (int _i = 0; _i < 2; ++_i) \
;         __builtin_amdgcn_global_load_lds((const unsigned*)((const char*)(gbase) + (voff)[_i]), (LAS unsigned*)(lds + (bufoff) + ldsw + _i * 8192), 16, 0, 0); } while (0)
; #define PG8_LDA(dst, b, h) do { _Pragma("unroll") for (int m = 0; m < 4; ++m) _Pragma("unroll") for (int k = 0; k < 2; ++k) dst[m][k] = *(const LAS h16x8*)(lds + PG8_SA(b, h) + aoff + m * 2048 + k * 1024); } while (0)
; #define PG8_MMA(ai, bj, At, Bt) do { __builtin_amdgcn_s_setprio(1); _Pragma("unroll") for (int m = 0; m < 4; ++m) _Pragma("unroll") for (int n = 0; n < 2; ++n) _Pragma("unroll") for (int k = 0; k < 2; ++k) \
;         acc[ai][bj][m][n] = __builtin_amdgcn_mfma_f32_16x16x32_f16(Bt[n][k], At[m][k], acc[ai][bj][m][n], 0, 0, 0); __builtin_amdgcn_s_setprio(0); } while (0)
; #define PG8_WAIT_V(n) asm volatile("s_waitcnt vmcnt(" #n ")" ::: "memory")
; #define PG8_WAIT_L(n) asm volatile("s_waitcnt lgkmcnt(" #n ")" ::: "memory")
; #define PG8_BAR __builtin_amdgcn_s_barrier()
; #define PG8_SCHED __builtin_amdgcn_sched_barrier(0)
; template <class Epi>
; __device__ __forceinline__ void gemm_phase(LAS unsigned char* lds, const Gemm g, const StaticOrder& S, const Epi& E, const int tid) {
;     ...
;             PG8_LDA(At, 1, 1); PG8_STAGE(PG8_SB(1, 0), b3, voffB); PG8_STAGE(PG8_SB(1, 1), b3 + hstepB, voffB); PG8_STAGE(PG8_SA(1, 0), a3, voffA);
;             PG8_WAIT_V(8); PG8_WAIT_L(0); PG8_BAR; PG8_MMA(1, 0, At, B0); PG8_MMA(1, 1, At, B1); PG8_BAR; PG8_SCHED;
;         }
;         if (wr == 0) PG8_BAR;
	s_add_i32 s16, s31, s28
	v_lshl_add_u64 v[154:155], v[154:155], 0, s[0:1]
	s_mov_b32 m0, s16
	ds_read_b128 v[188:191], v187 offset:49152
	ds_read_b128 v[192:195], v187 offset:50176
	ds_read_b128 v[210:213], v187 offset:51200
	ds_read_b128 v[214:217], v187 offset:52224
	ds_read_b128 v[218:221], v187 offset:53248
	ds_read_b128 v[222:225], v187 offset:54272
	ds_read_b128 v[226:229], v187 offset:55296
	ds_read_b128 v[230:233], v187 offset:56320
	global_load_lds_dwordx4 v[154:155], off
	s_add_i32 m0, s16, 0x2000
	s_add_u32 s16, s20, 0xb0080
	v_lshl_add_u64 v[154:155], v[156:157], 0, s[0:1]
	s_addc_u32 s17, s21, 0
	s_add_i32 s20, s46, s28
	global_load_lds_dwordx4 v[154:155], off
	v_lshl_add_u64 v[154:155], s[16:17], 0, v[152:153]
	s_mov_b32 m0, s20
	s_nop 0
	global_load_lds_dwordx4 v[154:155], off
	v_lshl_add_u64 v[154:155], s[16:17], 0, v[170:171]
	s_add_i32 m0, s20, 0x2000
	s_nop 0
	global_load_lds_dwordx4 v[154:155], off
	v_lshl_add_u64 v[154:155], v[162:163], 0, s[0:1]
	s_mov_b32 m0, s37
	s_nop 0
	global_load_lds_dwordx4 v[154:155], off
	v_lshl_add_u64 v[154:155], v[164:165], 0, s[0:1]
	s_mov_b32 m0, s38
	s_nop 0
	global_load_lds_dwordx4 v[154:155], off
	s_waitcnt vmcnt(8)
	s_waitcnt lgkmcnt(0)
	s_barrier
	s_waitcnt lgkmcnt(0)
	v_mfma_f32_16x16x32_f16 v[60:63], v[128:131], v[188:191], v[60:63]
	v_mfma_f32_16x16x32_f16 v[56:59], v[136:139], v[188:191], v[56:59]
	v_mfma_f32_16x16x32_f16 v[44:47], v[128:131], v[210:213], v[44:47]
	v_mfma_f32_16x16x32_f16 v[40:43], v[136:139], v[210:213], v[40:43]
	v_mfma_f32_16x16x32_f16 v[28:31], v[128:131], v[218:221], v[28:31]
	v_mfma_f32_16x16x32_f16 v[24:27], v[136:139], v[218:221], v[24:27]
	v_mfma_f32_16x16x32_f16 v[12:15], v[128:131], v[226:229], v[12:15]
	v_mfma_f32_16x16x32_f16 v[8:11], v[136:139], v[226:229], v[8:11]
	v_mfma_f32_16x16x32_f16 v[60:63], v[132:135], v[192:195], v[60:63]
	v_mfma_f32_16x16x32_f16 v[56:59], v[140:143], v[192:195], v[56:59]
	v_mfma_f32_16x16x32_f16 v[44:47], v[132:135], v[214:217], v[44:47]
	v_mfma_f32_16x16x32_f16 v[40:43], v[140:143], v[214:217], v[40:43]
	v_mfma_f32_16x16x32_f16 v[28:31], v[132:135], v[222:225], v[28:31]
	v_mfma_f32_16x16x32_f16 v[24:27], v[140:143], v[222:225], v[24:27]
	v_mfma_f32_16x16x32_f16 v[12:15], v[132:135], v[230:233], v[12:15]
	v_mfma_f32_16x16x32_f16 v[8:11], v[140:143], v[230:233], v[8:11]
	v_mfma_f32_16x16x32_f16 v[52:55], v[144:147], v[188:191], v[52:55]
	v_mfma_f32_16x16x32_f16 v[48:51], v[176:179], v[188:191], v[48:51]
	v_mfma_f32_16x16x32_f16 v[36:39], v[144:147], v[210:213], v[36:39]
	v_mfma_f32_16x16x32_f16 v[32:35], v[176:179], v[210:213], v[32:35]
	v_mfma_f32_16x16x32_f16 v[20:23], v[144:147], v[218:221], v[20:23]
	v_mfma_f32_16x16x32_f16 v[16:19], v[176:179], v[218:221], v[16:19]
	v_mfma_f32_16x16x32_f16 v[4:7], v[144:147], v[226:229], v[4:7]
	v_mfma_f32_16x16x32_f16 v[0:3], v[176:179], v[226:229], v[0:3]
	v_mfma_f32_16x16x32_f16 v[52:55], v[148:151], v[192:195], v[52:55]
	v_mfma_f32_16x16x32_f16 v[48:51], v[180:183], v[192:195], v[48:51]
	v_mfma_f32_16x16x32_f16 v[36:39], v[148:151], v[214:217], v[36:39]
	v_mfma_f32_16x16x32_f16 v[32:35], v[180:183], v[214:217], v[32:35]
	v_mfma_f32_16x16x32_f16 v[20:23], v[148:151], v[222:225], v[20:23]
	v_mfma_f32_16x16x32_f16 v[16:19], v[180:183], v[222:225], v[16:19]
	v_mfma_f32_16x16x32_f16 v[4:7], v[148:151], v[230:233], v[4:7]
	v_mfma_f32_16x16x32_f16 v[0:3], v[180:183], v[230:233], v[0:3]
	s_barrier
	s_add_i32 s45, s45, 2
	s_add_u32 s2, s2, 0x100
	s_addc_u32 s3, s3, 0
	s_cmp_gt_u32 s45, 41
	s_mov_b64 s[16:17], s[18:19]
	s_cbranch_scc0 .LBB0_214
	s_and_b64 vcc, exec, s[12:13]
	s_cbranch_vccz .LBB0_217
	s_barrier

; #define PG8_STAGE(bufoff, gbase, voff) do { _Pragma("unroll") for (int _i = 0; _i < 2; ++_i) \
;         __builtin_amdgcn_global_load_lds((const unsigned*)((const char*)(gbase) + (voff)[_i]), (LAS unsigned*)(lds + (bufoff) + ldsw + _i * 8192), 16, 0, 0); } while (0)
; #define PG8_LDA(dst, b, h) do { _Pragma("unroll") for (int m = 0; m < 4; ++m) _Pragma("unroll") for (int k = 0; k < 2; ++k) dst[m][k] = *(const LAS h16x8*)(lds + PG8_SA(b, h) + aoff + m * 2048 + k * 1024); } while (0)
; #define PG8_LDB(dst, b, h) do { _Pragma("unroll") for (int n = 0; n < 2; ++n) _Pragma("unroll") for (int k = 0; k < 2; ++k) dst[n][k] = *(const LAS h16x8*)(lds + PG8_SB(b, h) + boff + n * 2048 + k * 1024); } while (0)
; #define PG8_MMA(ai, bj, At, Bt) do { __builtin_amdgcn_s_setprio(1); _Pragma("unroll") for (int m = 0; m < 4; ++m) _Pragma("unroll") for (int n = 0; n < 2; ++n) _Pragma("unroll") for (int k = 0; k < 2; ++k) \
;         acc[ai][bj][m][n] = __builtin_amdgcn_mfma_f32_16x16x32_f16(Bt[n][k], At[m][k], acc[ai][bj][m][n], 0, 0, 0); __builtin_amdgcn_s_setprio(0); } while (0)
; #define PG8_WAIT_V(n) asm volatile("s_waitcnt vmcnt(" #n ")" ::: "memory")
; #define PG8_WAIT_L(n) asm volatile("s_waitcnt lgkmcnt(" #n ")" ::: "memory")
; #define PG8_BAR __builtin_amdgcn_s_barrier()
; #define PG8_SCHED __builtin_amdgcn_sched_barrier(0)
; template <class Epi>
; __device__ __forceinline__ void gemm_phase(LAS unsigned char* lds, const Gemm g, const StaticOrder& S, const Epi& E, const int tid) {
;     ...
;             const bool last = (t == nt - 2);
;             const char* a1 = cA + (size_t)(t + 1) * kstep;
;             const char* a2 = last ? nA : cA + (size_t)(t + 2) * kstep; const char* b2 = last ? nB : cB + (size_t)(t + 2) * kstep;
;             const char* a3 = a2 + kstep; const char* b3 = b2 + kstep;
;             PG8_LDB(B0, 0, 0); PG8_LDB(B1, 0, 1); PG8_SCHED; PG8_LDA(At, 0, 0); PG8_STAGE(PG8_SA(1, 1), a1 + hstepA, voffA);
;             PG8_WAIT_V(8); PG8_WAIT_L(0); PG8_BAR; PG8_MMA(0, 0, At, B0); PG8_MMA(0, 1, At, B1); PG8_BAR; PG8_SCHED;
;             PG8_LDA(At, 0, 1); PG8_STAGE(PG8_SB(0, 0), b2, voffB); PG8_STAGE(PG8_SB(0, 1), b2 + hstepB, voffB); PG8_STAGE(PG8_SA(0, 0), a2, voffA);
;             PG8_WAIT_V(8); PG8_WAIT_L(0); PG8_BAR; PG8_MMA(1, 0, At, B0); PG8_MMA(1, 1, At, B1); PG8_BAR; PG8_SCHED;
.LBB0_256:
	s_add_u32 s20, s8, 0xfffc0080
	s_addc_u32 s21, s9, -1
	s_add_i32 s31, 0, 0x10000
	s_cmp_eq_u32 s44, 12
	s_cselect_b32 s23, s15, s21
	s_cselect_b32 s22, s42, s20
	v_add_u32_e32 v154, s31, v163
	s_cselect_b32 s21, s13, s3
	s_cselect_b32 s20, s43, s2
	s_add_i32 s45, 0, 0x14000
	ds_read_b128 v[140:143], v154
	ds_read_b128 v[144:147], v154 offset:1024
	ds_read_b128 v[148:151], v154 offset:2048
	ds_read_b128 v[170:173], v154 offset:3072
	v_add_u32_e32 v154, s45, v163
	ds_read_b128 v[174:177], v154
	ds_read_b128 v[180:183], v154 offset:1024
	ds_read_b128 v[184:187], v154 offset:2048
	ds_read_b128 v[188:191], v154 offset:3072
	v_lshl_add_u64 v[154:155], s[8:9], 0, v[136:137]
	s_add_i32 m0, s29, 0xc000
	ds_read_b128 v[192:195], v179
	ds_read_b128 v[210:213], v179 offset:1024
	ds_read_b128 v[214:217], v179 offset:2048
	ds_read_b128 v[218:221], v179 offset:3072
	ds_read_b128 v[222:225], v179 offset:4096
	ds_read_b128 v[226:229], v179 offset:5120
	ds_read_b128 v[230:233], v179 offset:6144
	ds_read_b128 v[234:237], v179 offset:7168
	global_load_lds_dwordx4 v[154:155], off
	v_lshl_add_u64 v[154:155], s[8:9], 0, v[138:139]
	s_add_i32 m0, s29, 0xe000
	s_nop 0
	global_load_lds_dwordx4 v[154:155], off
	s_waitcnt vmcnt(8)
	s_waitcnt lgkmcnt(0)
	s_barrier
	s_waitcnt lgkmcnt(0)
	v_mfma_f32_16x16x32_f16 v[124:127], v[140:143], v[192:195], v[124:127]
	v_mfma_f32_16x16x32_f16 v[120:123], v[148:151], v[192:195], v[120:123]
	v_mfma_f32_16x16x32_f16 v[112:115], v[140:143], v[214:217], v[112:115]
	v_mfma_f32_16x16x32_f16 v[104:107], v[148:151], v[214:217], v[104:107]
	v_mfma_f32_16x16x32_f16 v[96:99], v[140:143], v[222:225], v[96:99]
	v_mfma_f32_16x16x32_f16 v[88:91], v[148:151], v[222:225], v[88:91]
	v_mfma_f32_16x16x32_f16 v[80:83], v[140:143], v[230:233], v[80:83]
	v_mfma_f32_16x16x32_f16 v[72:75], v[148:151], v[230:233], v[72:75]
	v_mfma_f32_16x16x32_f16 v[124:127], v[144:147], v[210:213], v[124:127]
	v_mfma_f32_16x16x32_f16 v[120:123], v[170:173], v[210:213], v[120:123]
	v_mfma_f32_16x16x32_f16 v[112:115], v[144:147], v[218:221], v[112:115]
	v_mfma_f32_16x16x32_f16 v[104:107], v[170:173], v[218:221], v[104:107]
	v_mfma_f32_16x16x32_f16 v[96:99], v[144:147], v[226:229], v[96:99]
	v_mfma_f32_16x16x32_f16 v[88:91], v[170:173], v[226:229], v[88:91]
	v_mfma_f32_16x16x32_f16 v[80:83], v[144:147], v[234:237], v[80:83]
	v_mfma_f32_16x16x32_f16 v[72:75], v[170:173], v[234:237], v[72:75]
	v_mfma_f32_16x16x32_f16 v[116:119], v[174:177], v[192:195], v[116:119]
	v_mfma_f32_16x16x32_f16 v[108:111], v[184:187], v[192:195], v[108:111]
	v_mfma_f32_16x16x32_f16 v[100:103], v[174:177], v[214:217], v[100:103]
	v_mfma_f32_16x16x32_f16 v[92:95], v[184:187], v[214:217], v[92:95]
	v_mfma_f32_16x16x32_f16 v[84:87], v[174:177], v[222:225], v[84:87]
	v_mfma_f32_16x16x32_f16 v[76:79], v[184:187], v[222:225], v[76:79]
	v_mfma_f32_16x16x32_f16 v[68:71], v[174:177], v[230:233], v[68:71]
	v_mfma_f32_16x16x32_f16 v[64:67], v[184:187], v[230:233], v[64:67]
	v_mfma_f32_16x16x32_f16 v[116:119], v[180:183], v[210:213], v[116:119]
	v_mfma_f32_16x16x32_f16 v[108:111], v[188:191], v[210:213], v[108:111]
	v_mfma_f32_16x16x32_f16 v[100:103], v[180:183], v[218:221], v[100:103]
	v_mfma_f32_16x16x32_f16 v[92:95], v[188:191], v[218:221], v[92:95]
	v_mfma_f32_16x16x32_f16 v[84:87], v[180:183], v[226:229], v[84:87]
	v_mfma_f32_16x16x32_f16 v[76:79], v[188:191], v[226:229], v[76:79]
	v_mfma_f32_16x16x32_f16 v[68:71], v[180:183], v[234:237], v[68:71]
	v_mfma_f32_16x16x32_f16 v[64:67], v[188:191], v[234:237], v[64:67]
	s_barrier
	s_add_i32 s31, s31, s28
	v_lshl_add_u64 v[154:155], s[20:21], 0, v[152:153]
	s_mov_b32 m0, s31
	ds_read_b128 v[192:195], v179 offset:16384
	ds_read_b128 v[210:213], v179 offset:17408
	ds_read_b128 v[214:217], v179 offset:18432
	ds_read_b128 v[218:221], v179 offset:19456
	ds_read_b128 v[222:225], v179 offset:20480
	ds_read_b128 v[226:229], v179 offset:21504
	ds_read_b128 v[230:233], v179 offset:22528
	ds_read_b128 v[234:237], v179 offset:23552
	global_load_lds_dwordx4 v[154:155], off
	s_add_i32 m0, s31, 0x2000
	s_add_u32 s46, s20, 0x40000
	v_lshl_add_u64 v[156:157], s[20:21], 0, v[128:129]
	s_addc_u32 s47, s21, 0
	s_add_i32 s31, s45, s28
	global_load_lds_dwordx4 v[156:157], off
	v_lshl_add_u64 v[164:165], s[46:47], 0, v[152:153]
	s_mov_b32 m0, s31
	v_lshl_add_u64 v[166:167], s[22:23], 0, v[130:131]
	global_load_lds_dwordx4 v[164:165], off
	v_lshl_add_u64 v[164:165], s[46:47], 0, v[128:129]
	s_add_i32 m0, s31, 0x2000
	s_nop 0
	global_load_lds_dwordx4 v[164:165], off
	v_lshl_add_u64 v[164:165], s[22:23], 0, v[132:133]
	s_mov_b32 m0, s29
	s_nop 0
	global_load_lds_dwordx4 v[164:165], off
	s_mov_b32 m0, s34
	s_nop 0
	global_load_lds_dwordx4 v[166:167], off
	s_waitcnt vmcnt(8)
	s_waitcnt lgkmcnt(0)
	s_barrier
; #define PG8_STAGE(bufoff, gbase, voff) do { _Pragma("unroll") for (int _i = 0; _i < 2; ++_i) \
;         __builtin_amdgcn_global_load_lds((const unsigned*)((const char*)(gbase) + (voff)[_i]), (LAS unsigned*)(lds + (bufoff) + ldsw + _i * 8192), 16, 0, 0); } while (0)
; #define PG8_LDA(dst, b, h) do { _Pragma("unroll") for (int m = 0; m < 4; ++m) _Pragma("unroll") for (int k = 0; k < 2; ++k) dst[m][k] = *(const LAS h16x8*)(lds + PG8_SA(b, h) + aoff + m * 2048 + k * 1024); } while (0)
; #define PG8_LDB(dst, b, h) do { _Pragma("unroll") for (int n = 0; n < 2; ++n) _Pragma("unroll") for (int k = 0; k < 2; ++k) dst[n][k] = *(const LAS h16x8*)(lds + PG8_SB(b, h) + boff + n * 2048 + k * 1024); } while (0)
; #define PG8_MMA(ai, bj, At, Bt) do { __builtin_amdgcn_s_setprio(1); _Pragma("unroll") for (int m = 0; m < 4; ++m) _Pragma("unroll") for (int n = 0; n < 2; ++n) _Pragma("unroll") for (int k = 0; k < 2; ++k) \
;         acc[ai][bj][m][n] = __builtin_amdgcn_mfma_f32_16x16x32_f16(Bt[n][k], At[m][k], acc[ai][bj][m][n], 0, 0, 0); __builtin_amdgcn_s_setprio(0); } while (0)
; #define PG8_WAIT_V(n) asm volatile("s_waitcnt vmcnt(" #n ")" ::: "memory")
; #define PG8_WAIT_L(n) asm volatile("s_waitcnt lgkmcnt(" #n ")" ::: "memory")
; #define PG8_BAR __builtin_amdgcn_s_barrier()
; #define PG8_SCHED __builtin_amdgcn_sched_barrier(0)
; template <class Epi>
; __device__ __forceinline__ void gemm_phase(LAS unsigned char* lds, const Gemm g, const StaticOrder& S, const Epi& E, const int tid) {
;     ...
;             PG8_WAIT_V(8); PG8_WAIT_L(0); PG8_BAR; PG8_MMA(1, 0, At, B0); PG8_MMA(1, 1, At, B1); PG8_BAR; PG8_SCHED;
;             PG8_LDB(B0, 1, 0); PG8_LDB(B1, 1, 1); PG8_SCHED; PG8_LDA(At, 1, 0); PG8_STAGE(PG8_SA(0, 1), a2 + hstepA, voffA);
;             PG8_WAIT_V(8); PG8_WAIT_L(0); PG8_BAR; PG8_MMA(0, 0, At, B0); PG8_MMA(0, 1, At, B1); PG8_BAR; PG8_SCHED;
	s_waitcnt lgkmcnt(0)
	v_mfma_f32_16x16x32_f16 v[60:63], v[140:143], v[192:195], v[60:63]
	v_mfma_f32_16x16x32_f16 v[56:59], v[148:151], v[192:195], v[56:59]
	v_mfma_f32_16x16x32_f16 v[48:51], v[140:143], v[214:217], v[48:51]
	v_mfma_f32_16x16x32_f16 v[40:43], v[148:151], v[214:217], v[40:43]
	v_mfma_f32_16x16x32_f16 v[32:35], v[140:143], v[222:225], v[32:35]
	v_mfma_f32_16x16x32_f16 v[24:27], v[148:151], v[222:225], v[24:27]
	v_mfma_f32_16x16x32_f16 v[16:19], v[140:143], v[230:233], v[16:19]
	v_mfma_f32_16x16x32_f16 v[8:11], v[148:151], v[230:233], v[8:11]
	v_mfma_f32_16x16x32_f16 v[60:63], v[144:147], v[210:213], v[60:63]
	v_mfma_f32_16x16x32_f16 v[56:59], v[170:173], v[210:213], v[56:59]
	v_mfma_f32_16x16x32_f16 v[48:51], v[144:147], v[218:221], v[48:51]
	v_mfma_f32_16x16x32_f16 v[40:43], v[170:173], v[218:221], v[40:43]
	v_mfma_f32_16x16x32_f16 v[32:35], v[144:147], v[226:229], v[32:35]
	v_mfma_f32_16x16x32_f16 v[24:27], v[170:173], v[226:229], v[24:27]
	v_mfma_f32_16x16x32_f16 v[16:19], v[144:147], v[234:237], v[16:19]
	v_mfma_f32_16x16x32_f16 v[8:11], v[170:173], v[234:237], v[8:11]
	v_mfma_f32_16x16x32_f16 v[52:55], v[174:177], v[192:195], v[52:55]
	v_mfma_f32_16x16x32_f16 v[44:47], v[184:187], v[192:195], v[44:47]
	v_mfma_f32_16x16x32_f16 v[36:39], v[174:177], v[214:217], v[36:39]
	v_mfma_f32_16x16x32_f16 v[28:31], v[184:187], v[214:217], v[28:31]
	v_mfma_f32_16x16x32_f16 v[20:23], v[174:177], v[222:225], v[20:23]
	v_mfma_f32_16x16x32_f16 v[12:15], v[184:187], v[222:225], v[12:15]
	v_mfma_f32_16x16x32_f16 v[4:7], v[174:177], v[230:233], v[4:7]
	v_mfma_f32_16x16x32_f16 v[0:3], v[184:187], v[230:233], v[0:3]
	v_mfma_f32_16x16x32_f16 v[52:55], v[180:183], v[210:213], v[52:55]
	v_mfma_f32_16x16x32_f16 v[44:47], v[188:191], v[210:213], v[44:47]
	v_mfma_f32_16x16x32_f16 v[36:39], v[180:183], v[218:221], v[36:39]
	v_mfma_f32_16x16x32_f16 v[28:31], v[188:191], v[218:221], v[28:31]
	v_mfma_f32_16x16x32_f16 v[20:23], v[180:183], v[226:229], v[20:23]
	v_mfma_f32_16x16x32_f16 v[12:15], v[188:191], v[226:229], v[12:15]
	v_mfma_f32_16x16x32_f16 v[4:7], v[180:183], v[234:237], v[4:7]
	v_mfma_f32_16x16x32_f16 v[0:3], v[188:191], v[234:237], v[0:3]
	s_barrier
	s_add_i32 s31, 0, 0x18000
	s_add_i32 s45, 0, 0x1c000
	v_add_u32_e32 v170, s31, v163
	v_add_u32_e32 v188, s45, v163
	ds_read_b128 v[140:143], v170
	ds_read_b128 v[144:147], v170 offset:1024
	ds_read_b128 v[148:151], v170 offset:2048
	ds_read_b128 v[170:173], v170 offset:3072
	ds_read_b128 v[174:177], v188
	ds_read_b128 v[180:183], v188 offset:1024
	ds_read_b128 v[184:187], v188 offset:2048
	ds_read_b128 v[188:191], v188 offset:3072
	s_add_u32 s22, s22, 0x40000
	s_addc_u32 s23, s23, 0
	s_mov_b32 m0, s35
	v_lshl_add_u64 v[196:197], s[22:23], 0, v[132:133]
	ds_read_b128 v[192:195], v179 offset:32768
	ds_read_b128 v[210:213], v179 offset:33792
	ds_read_b128 v[214:217], v179 offset:34816
	ds_read_b128 v[218:221], v179 offset:35840
	ds_read_b128 v[222:225], v179 offset:36864
	ds_read_b128 v[226:229], v179 offset:37888
	ds_read_b128 v[230:233], v179 offset:38912
	ds_read_b128 v[234:237], v179 offset:39936
	global_load_lds_dwordx4 v[196:197], off
	v_lshl_add_u64 v[196:197], s[22:23], 0, v[130:131]
	s_mov_b32 m0, s36
	s_nop 0
	global_load_lds_dwordx4 v[196:197], off
	s_waitcnt vmcnt(8)
	s_waitcnt lgkmcnt(0)
	s_barrier
	s_waitcnt lgkmcnt(0)
	v_mfma_f32_16x16x32_f16 v[124:127], v[140:143], v[192:195], v[124:127]
	v_mfma_f32_16x16x32_f16 v[120:123], v[148:151], v[192:195], v[120:123]
	v_mfma_f32_16x16x32_f16 v[112:115], v[140:143], v[214:217], v[112:115]
	v_mfma_f32_16x16x32_f16 v[104:107], v[148:151], v[214:217], v[104:107]
	v_mfma_f32_16x16x32_f16 v[96:99], v[140:143], v[222:225], v[96:99]
	v_mfma_f32_16x16x32_f16 v[88:91], v[148:151], v[222:225], v[88:91]
	v_mfma_f32_16x16x32_f16 v[80:83], v[140:143], v[230:233], v[80:83]
	v_mfma_f32_16x16x32_f16 v[72:75], v[148:151], v[230:233], v[72:75]
	v_mfma_f32_16x16x32_f16 v[124:127], v[144:147], v[210:213], v[124:127]
	v_mfma_f32_16x16x32_f16 v[120:123], v[170:173], v[210:213], v[120:123]
	v_mfma_f32_16x16x32_f16 v[112:115], v[144:147], v[218:221], v[112:115]
	v_mfma_f32_16x16x32_f16 v[104:107], v[170:173], v[218:221], v[104:107]
	v_mfma_f32_16x16x32_f16 v[96:99], v[144:147], v[226:229], v[96:99]
	v_mfma_f32_16x16x32_f16 v[88:91], v[170:173], v[226:229], v[88:91]
	v_mfma_f32_16x16x32_f16 v[80:83], v[144:147], v[234:237], v[80:83]
	v_mfma_f32_16x16x32_f16 v[72:75], v[170:173], v[234:237], v[72:75]
	v_mfma_f32_16x16x32_f16 v[116:119], v[174:177], v[192:195], v[116:119]
	v_mfma_f32_16x16x32_f16 v[108:111], v[184:187], v[192:195], v[108:111]
	v_mfma_f32_16x16x32_f16 v[100:103], v[174:177], v[214:217], v[100:103]
	v_mfma_f32_16x16x32_f16 v[92:95], v[184:187], v[214:217], v[92:95]
	v_mfma_f32_16x16x32_f16 v[84:87], v[174:177], v[222:225], v[84:87]
	v_mfma_f32_16x16x32_f16 v[76:79], v[184:187], v[222:225], v[76:79]
	v_mfma_f32_16x16x32_f16 v[68:71], v[174:177], v[230:233], v[68:71]
	v_mfma_f32_16x16x32_f16 v[64:67], v[184:187], v[230:233], v[64:67]
	v_mfma_f32_16x16x32_f16 v[116:119], v[180:183], v[210:213], v[116:119]
	v_mfma_f32_16x16x32_f16 v[108:111], v[188:191], v[210:213], v[108:111]
	v_mfma_f32_16x16x32_f16 v[100:103], v[180:183], v[218:221], v[100:103]
	v_mfma_f32_16x16x32_f16 v[92:95], v[188:191], v[218:221], v[92:95]
	v_mfma_f32_16x16x32_f16 v[84:87], v[180:183], v[226:229], v[84:87]
	v_mfma_f32_16x16x32_f16 v[76:79], v[188:191], v[226:229], v[76:79]
	v_mfma_f32_16x16x32_f16 v[68:71], v[180:183], v[234:237], v[68:71]
	v_mfma_f32_16x16x32_f16 v[64:67], v[188:191], v[234:237], v[64:67]
	s_barrier
; #define PG8_STAGE(bufoff, gbase, voff) do { _Pragma("unroll") for (int _i = 0; _i < 2; ++_i) \
;         __builtin_amdgcn_global_load_lds((const unsigned*)((const char*)(gbase) + (voff)[_i]), (LAS unsigned*)(lds + (bufoff) + ldsw + _i * 8192), 16, 0, 0); } while (0)
; #define PG8_LDA(dst, b, h) do { _Pragma("unroll") for (int m = 0; m < 4; ++m) _Pragma("unroll") for (int k = 0; k < 2; ++k) dst[m][k] = *(const LAS h16x8*)(lds + PG8_SA(b, h) + aoff + m * 2048 + k * 1024); } while (0)
; #define PG8_MMA(ai, bj, At, Bt) do { __builtin_amdgcn_s_setprio(1); _Pragma("unroll") for (int m = 0; m < 4; ++m) _Pragma("unroll") for (int n = 0; n < 2; ++n) _Pragma("unroll") for (int k = 0; k < 2; ++k) \
;         acc[ai][bj][m][n] = __builtin_amdgcn_mfma_f32_16x16x32_f16(Bt[n][k], At[m][k], acc[ai][bj][m][n], 0, 0, 0); __builtin_amdgcn_s_setprio(0); } while (0)
; #define PG8_WAIT_V(n) asm volatile("s_waitcnt vmcnt(" #n ")" ::: "memory")
; #define PG8_WAIT_L(n) asm volatile("s_waitcnt lgkmcnt(" #n ")" ::: "memory")
; #define PG8_BAR __builtin_amdgcn_s_barrier()
; #define PG8_SCHED __builtin_amdgcn_sched_barrier(0)
; template <class Epi>
; __device__ __forceinline__ void gemm_phase(LAS unsigned char* lds, const Gemm g, const StaticOrder& S, const Epi& E, const int tid) {
;     ...
;             PG8_LDA(At, 1, 1); PG8_STAGE(PG8_SB(1, 0), b3, voffB); PG8_STAGE(PG8_SB(1, 1), b3 + hstepB, voffB); PG8_STAGE(PG8_SA(1, 0), a3, voffA);
;             PG8_WAIT_V(8); PG8_WAIT_L(0); PG8_BAR; PG8_MMA(1, 0, At, B0); PG8_MMA(1, 1, At, B1); PG8_BAR; PG8_SCHED;
;         }
;         if (wr == 0) PG8_BAR;
	s_add_i32 s22, s31, s28
	v_lshl_add_u64 v[154:155], v[154:155], 0, s[0:1]
	s_mov_b32 m0, s22
	ds_read_b128 v[192:195], v179 offset:49152
	ds_read_b128 v[210:213], v179 offset:50176
	ds_read_b128 v[214:217], v179 offset:51200
	ds_read_b128 v[218:221], v179 offset:52224
	ds_read_b128 v[222:225], v179 offset:53248
	ds_read_b128 v[226:229], v179 offset:54272
	ds_read_b128 v[230:233], v179 offset:55296
	ds_read_b128 v[234:237], v179 offset:56320
	global_load_lds_dwordx4 v[154:155], off
	s_add_i32 m0, s22, 0x2000
	s_add_u32 s20, s20, 0x40080
	v_lshl_add_u64 v[154:155], v[156:157], 0, s[0:1]
	s_addc_u32 s21, s21, 0
	s_add_i32 s22, s45, s28
	global_load_lds_dwordx4 v[154:155], off
	v_lshl_add_u64 v[154:155], s[20:21], 0, v[152:153]
	s_mov_b32 m0, s22
	s_nop 0
	global_load_lds_dwordx4 v[154:155], off
	v_lshl_add_u64 v[154:155], s[20:21], 0, v[128:129]
	s_add_i32 m0, s22, 0x2000
	s_nop 0
	global_load_lds_dwordx4 v[154:155], off
	v_lshl_add_u64 v[154:155], v[164:165], 0, s[0:1]
	s_mov_b32 m0, s37
	s_nop 0
	global_load_lds_dwordx4 v[154:155], off
	v_lshl_add_u64 v[154:155], v[166:167], 0, s[0:1]
	s_mov_b32 m0, s38
	s_nop 0
	global_load_lds_dwordx4 v[154:155], off
	s_waitcnt vmcnt(8)
	s_waitcnt lgkmcnt(0)
	s_barrier
	s_waitcnt lgkmcnt(0)
	v_mfma_f32_16x16x32_f16 v[60:63], v[140:143], v[192:195], v[60:63]
	v_mfma_f32_16x16x32_f16 v[56:59], v[148:151], v[192:195], v[56:59]
	v_mfma_f32_16x16x32_f16 v[48:51], v[140:143], v[214:217], v[48:51]
	v_mfma_f32_16x16x32_f16 v[40:43], v[148:151], v[214:217], v[40:43]
	v_mfma_f32_16x16x32_f16 v[32:35], v[140:143], v[222:225], v[32:35]
	v_mfma_f32_16x16x32_f16 v[24:27], v[148:151], v[222:225], v[24:27]
	v_mfma_f32_16x16x32_f16 v[16:19], v[140:143], v[230:233], v[16:19]
	v_mfma_f32_16x16x32_f16 v[8:11], v[148:151], v[230:233], v[8:11]
	v_mfma_f32_16x16x32_f16 v[60:63], v[144:147], v[210:213], v[60:63]
	v_mfma_f32_16x16x32_f16 v[56:59], v[170:173], v[210:213], v[56:59]
	v_mfma_f32_16x16x32_f16 v[48:51], v[144:147], v[218:221], v[48:51]
	v_mfma_f32_16x16x32_f16 v[40:43], v[170:173], v[218:221], v[40:43]
	v_mfma_f32_16x16x32_f16 v[32:35], v[144:147], v[226:229], v[32:35]
	v_mfma_f32_16x16x32_f16 v[24:27], v[170:173], v[226:229], v[24:27]
	v_mfma_f32_16x16x32_f16 v[16:19], v[144:147], v[234:237], v[16:19]
	v_mfma_f32_16x16x32_f16 v[8:11], v[170:173], v[234:237], v[8:11]
	v_mfma_f32_16x16x32_f16 v[52:55], v[174:177], v[192:195], v[52:55]
	v_mfma_f32_16x16x32_f16 v[44:47], v[184:187], v[192:195], v[44:47]
	v_mfma_f32_16x16x32_f16 v[36:39], v[174:177], v[214:217], v[36:39]
	v_mfma_f32_16x16x32_f16 v[28:31], v[184:187], v[214:217], v[28:31]
	v_mfma_f32_16x16x32_f16 v[20:23], v[174:177], v[222:225], v[20:23]
	v_mfma_f32_16x16x32_f16 v[12:15], v[184:187], v[222:225], v[12:15]
	v_mfma_f32_16x16x32_f16 v[4:7], v[174:177], v[230:233], v[4:7]
	v_mfma_f32_16x16x32_f16 v[0:3], v[184:187], v[230:233], v[0:3]
	v_mfma_f32_16x16x32_f16 v[52:55], v[180:183], v[210:213], v[52:55]
	v_mfma_f32_16x16x32_f16 v[44:47], v[188:191], v[210:213], v[44:47]
	v_mfma_f32_16x16x32_f16 v[36:39], v[180:183], v[218:221], v[36:39]
	v_mfma_f32_16x16x32_f16 v[28:31], v[188:191], v[218:221], v[28:31]
	v_mfma_f32_16x16x32_f16 v[20:23], v[180:183], v[226:229], v[20:23]
	v_mfma_f32_16x16x32_f16 v[12:15], v[188:191], v[226:229], v[12:15]
	v_mfma_f32_16x16x32_f16 v[4:7], v[180:183], v[234:237], v[4:7]
	v_mfma_f32_16x16x32_f16 v[0:3], v[188:191], v[234:237], v[0:3]
	s_barrier
	s_add_i32 s44, s44, 2
	s_add_u32 s8, s8, 0x100
	s_addc_u32 s9, s9, 0
	s_add_u32 s2, s2, 0x100
	s_addc_u32 s3, s3, 0
	s_cmp_gt_u32 s44, 13
	s_cbranch_scc0 .LBB0_256
	s_and_b64 vcc, exec, s[10:11]
	s_cbranch_vccz .LBB0_259
	s_barrier

; #define PG8_STAGE(bufoff, gbase, voff) do { _Pragma("unroll") for (int _i = 0; _i < 2; ++_i) \
;         __builtin_amdgcn_global_load_lds((const unsigned*)((const char*)(gbase) + (voff)[_i]), (LAS unsigned*)(lds + (bufoff) + ldsw + _i * 8192), 16, 0, 0); } while (0)
; #define PG8_LDA(dst, b, h) do { _Pragma("unroll") for (int m = 0; m < 4; ++m) _Pragma("unroll") for (int k = 0; k < 2; ++k) dst[m][k] = *(const LAS h16x8*)(lds + PG8_SA(b, h) + aoff + m * 2048 + k * 1024); } while (0)
; #define PG8_LDB(dst, b, h) do { _Pragma("unroll") for (int n = 0; n < 2; ++n) _Pragma("unroll") for (int k = 0; k < 2; ++k) dst[n][k] = *(const LAS h16x8*)(lds + PG8_SB(b, h) + boff + n * 2048 + k * 1024); } while (0)
; #define PG8_MMA(ai, bj, At, Bt) do { __builtin_amdgcn_s_setprio(1); _Pragma("unroll") for (int m = 0; m < 4; ++m) _Pragma("unroll") for (int n = 0; n < 2; ++n) _Pragma("unroll") for (int k = 0; k < 2; ++k) \
;         acc[ai][bj][m][n] = __builtin_amdgcn_mfma_f32_16x16x32_f16(Bt[n][k], At[m][k], acc[ai][bj][m][n], 0, 0, 0); __builtin_amdgcn_s_setprio(0); } while (0)
; #define PG8_WAIT_V(n) asm volatile("s_waitcnt vmcnt(" #n ")" ::: "memory")
; #define PG8_WAIT_L(n) asm volatile("s_waitcnt lgkmcnt(" #n ")" ::: "memory")
; #define PG8_BAR __builtin_amdgcn_s_barrier()
; #define PG8_SCHED __builtin_amdgcn_sched_barrier(0)
; template <class Epi>
; __device__ __forceinline__ void gemm_phase(LAS unsigned char* lds, const Gemm g, const StaticOrder& S, const Epi& E, const int tid) {
;     ...
;             const bool last = (t == nt - 2);
;             const char* a1 = cA + (size_t)(t + 1) * kstep;
;             const char* a2 = last ? nA : cA + (size_t)(t + 2) * kstep; const char* b2 = last ? nB : cB + (size_t)(t + 2) * kstep;
;             const char* a3 = a2 + kstep; const char* b3 = b2 + kstep;
;             PG8_LDB(B0, 0, 0); PG8_LDB(B1, 0, 1); PG8_SCHED; PG8_LDA(At, 0, 0); PG8_STAGE(PG8_SA(1, 1), a1 + hstepA, voffA);
;             PG8_WAIT_V(8); PG8_WAIT_L(0); PG8_BAR; PG8_MMA(0, 0, At, B0); PG8_MMA(0, 1, At, B1); PG8_BAR; PG8_SCHED;
;             PG8_LDA(At, 0, 1); PG8_STAGE(PG8_SB(0, 0), b2, voffB); PG8_STAGE(PG8_SB(0, 1), b2 + hstepB, voffB); PG8_STAGE(PG8_SA(0, 0), a2, voffA);
;             PG8_WAIT_V(8); PG8_WAIT_L(0); PG8_BAR; PG8_MMA(1, 0, At, B0); PG8_MMA(1, 1, At, B1); PG8_BAR; PG8_SCHED;
.LBB0_307:
	s_add_u32 s20, s18, 0xfffc0080
	s_addc_u32 s21, s19, -1
	s_add_i32 s31, 0, 0x10000
	s_cmp_eq_u32 s44, 12
	s_cselect_b32 s23, s13, s21
	s_cselect_b32 s22, s42, s20
	s_cselect_b32 s21, s11, s3
	s_cselect_b32 s20, s43, s2
	s_add_i32 s45, 0, 0x14000
	v_add_u32_e32 v140, s31, v195
	v_add_u32_e32 v166, s45, v195
	ds_read_b128 v[128:131], v140
	ds_read_b128 v[132:135], v140 offset:1024
	ds_read_b128 v[136:139], v140 offset:2048
	ds_read_b128 v[140:143], v140 offset:3072
	ds_read_b128 v[154:157], v166
	ds_read_b128 v[162:165], v166 offset:1024
	ds_read_b128 v[174:177], v166 offset:2048
	ds_read_b128 v[178:181], v166 offset:3072
	v_lshl_add_u64 v[166:167], s[18:19], 0, v[170:171]
	s_add_i32 m0, s29, 0xc000
	ds_read_b128 v[182:185], v211
	ds_read_b128 v[190:193], v211 offset:1024
	ds_read_b128 v[212:215], v211 offset:2048
	ds_read_b128 v[216:219], v211 offset:3072
	ds_read_b128 v[220:223], v211 offset:4096
	ds_read_b128 v[224:227], v211 offset:5120
	ds_read_b128 v[228:231], v211 offset:6144
	ds_read_b128 v[232:235], v211 offset:7168
	global_load_lds_dwordx4 v[166:167], off
	v_lshl_add_u64 v[166:167], s[18:19], 0, v[172:173]
	s_add_i32 m0, s29, 0xe000
	s_nop 0
	global_load_lds_dwordx4 v[166:167], off
	s_waitcnt vmcnt(8)
	s_waitcnt lgkmcnt(0)
	s_barrier
	s_waitcnt lgkmcnt(0)
	v_mfma_f32_16x16x32_f16 v[124:127], v[128:131], v[182:185], v[124:127]
	v_mfma_f32_16x16x32_f16 v[116:119], v[136:139], v[182:185], v[116:119]
	v_mfma_f32_16x16x32_f16 v[108:111], v[128:131], v[212:215], v[108:111]
	v_mfma_f32_16x16x32_f16 v[100:103], v[136:139], v[212:215], v[100:103]
	v_mfma_f32_16x16x32_f16 v[92:95], v[128:131], v[220:223], v[92:95]
	v_mfma_f32_16x16x32_f16 v[84:87], v[136:139], v[220:223], v[84:87]
	v_mfma_f32_16x16x32_f16 v[76:79], v[128:131], v[228:231], v[76:79]
	v_mfma_f32_16x16x32_f16 v[68:71], v[136:139], v[228:231], v[68:71]
	v_mfma_f32_16x16x32_f16 v[124:127], v[132:135], v[190:193], v[124:127]
	v_mfma_f32_16x16x32_f16 v[116:119], v[140:143], v[190:193], v[116:119]
	v_mfma_f32_16x16x32_f16 v[108:111], v[132:135], v[216:219], v[108:111]
	v_mfma_f32_16x16x32_f16 v[100:103], v[140:143], v[216:219], v[100:103]
	v_mfma_f32_16x16x32_f16 v[92:95], v[132:135], v[224:227], v[92:95]
	v_mfma_f32_16x16x32_f16 v[84:87], v[140:143], v[224:227], v[84:87]
	v_mfma_f32_16x16x32_f16 v[76:79], v[132:135], v[232:235], v[76:79]
	v_mfma_f32_16x16x32_f16 v[68:71], v[140:143], v[232:235], v[68:71]
	v_mfma_f32_16x16x32_f16 v[120:123], v[154:157], v[182:185], v[120:123]
	v_mfma_f32_16x16x32_f16 v[112:115], v[174:177], v[182:185], v[112:115]
	v_mfma_f32_16x16x32_f16 v[104:107], v[154:157], v[212:215], v[104:107]
	v_mfma_f32_16x16x32_f16 v[96:99], v[174:177], v[212:215], v[96:99]
	v_mfma_f32_16x16x32_f16 v[88:91], v[154:157], v[220:223], v[88:91]
	v_mfma_f32_16x16x32_f16 v[80:83], v[174:177], v[220:223], v[80:83]
	v_mfma_f32_16x16x32_f16 v[72:75], v[154:157], v[228:231], v[72:75]
	v_mfma_f32_16x16x32_f16 v[64:67], v[174:177], v[228:231], v[64:67]
	v_mfma_f32_16x16x32_f16 v[120:123], v[162:165], v[190:193], v[120:123]
	v_mfma_f32_16x16x32_f16 v[112:115], v[178:181], v[190:193], v[112:115]
	v_mfma_f32_16x16x32_f16 v[104:107], v[162:165], v[216:219], v[104:107]
	v_mfma_f32_16x16x32_f16 v[96:99], v[178:181], v[216:219], v[96:99]
	v_mfma_f32_16x16x32_f16 v[88:91], v[162:165], v[224:227], v[88:91]
	v_mfma_f32_16x16x32_f16 v[80:83], v[178:181], v[224:227], v[80:83]
	v_mfma_f32_16x16x32_f16 v[72:75], v[162:165], v[232:235], v[72:75]
	v_mfma_f32_16x16x32_f16 v[64:67], v[178:181], v[232:235], v[64:67]
	s_barrier
	s_add_i32 s31, s31, s28
	v_lshl_add_u64 v[166:167], s[20:21], 0, v[152:153]
	s_mov_b32 m0, s31
	ds_read_b128 v[182:185], v211 offset:16384
	ds_read_b128 v[190:193], v211 offset:17408
	ds_read_b128 v[212:215], v211 offset:18432
	ds_read_b128 v[216:219], v211 offset:19456
	ds_read_b128 v[220:223], v211 offset:20480
	ds_read_b128 v[224:227], v211 offset:21504
	ds_read_b128 v[228:231], v211 offset:22528
	ds_read_b128 v[232:235], v211 offset:23552
	global_load_lds_dwordx4 v[166:167], off
	s_add_i32 m0, s31, 0x2000
	s_add_u32 s46, s20, 0x40000
	v_lshl_add_u64 v[186:187], s[20:21], 0, v[144:145]
	s_addc_u32 s47, s21, 0
	s_add_i32 s31, s45, s28
	global_load_lds_dwordx4 v[186:187], off
	v_lshl_add_u64 v[204:205], s[46:47], 0, v[152:153]
	s_mov_b32 m0, s31
	v_lshl_add_u64 v[236:237], s[22:23], 0, v[146:147]
	global_load_lds_dwordx4 v[204:205], off
	v_lshl_add_u64 v[204:205], s[46:47], 0, v[144:145]
	s_add_i32 m0, s31, 0x2000
	s_nop 0
	global_load_lds_dwordx4 v[204:205], off
	v_lshl_add_u64 v[204:205], s[22:23], 0, v[148:149]
	s_mov_b32 m0, s29
	s_nop 0
	global_load_lds_dwordx4 v[204:205], off
	s_mov_b32 m0, s34
	s_nop 0
	global_load_lds_dwordx4 v[236:237], off
	s_waitcnt vmcnt(8)
	s_waitcnt lgkmcnt(0)
	s_barrier
; #define PG8_STAGE(bufoff, gbase, voff) do { _Pragma("unroll") for (int _i = 0; _i < 2; ++_i) \
;         __builtin_amdgcn_global_load_lds((const unsigned*)((const char*)(gbase) + (voff)[_i]), (LAS unsigned*)(lds + (bufoff) + ldsw + _i * 8192), 16, 0, 0); } while (0)
; #define PG8_LDA(dst, b, h) do { _Pragma("unroll") for (int m = 0; m < 4; ++m) _Pragma("unroll") for (int k = 0; k < 2; ++k) dst[m][k] = *(const LAS h16x8*)(lds + PG8_SA(b, h) + aoff + m * 2048 + k * 1024); } while (0)
; #define PG8_LDB(dst, b, h) do { _Pragma("unroll") for (int n = 0; n < 2; ++n) _Pragma("unroll") for (int k = 0; k < 2; ++k) dst[n][k] = *(const LAS h16x8*)(lds + PG8_SB(b, h) + boff + n * 2048 + k * 1024); } while (0)
; #define PG8_MMA(ai, bj, At, Bt) do { __builtin_amdgcn_s_setprio(1); _Pragma("unroll") for (int m = 0; m < 4; ++m) _Pragma("unroll") for (int n = 0; n < 2; ++n) _Pragma("unroll") for (int k = 0; k < 2; ++k) \
;         acc[ai][bj][m][n] = __builtin_amdgcn_mfma_f32_16x16x32_f16(Bt[n][k], At[m][k], acc[ai][bj][m][n], 0, 0, 0); __builtin_amdgcn_s_setprio(0); } while (0)
; #define PG8_WAIT_V(n) asm volatile("s_waitcnt vmcnt(" #n ")" ::: "memory")
; #define PG8_WAIT_L(n) asm volatile("s_waitcnt lgkmcnt(" #n ")" ::: "memory")
; #define PG8_BAR __builtin_amdgcn_s_barrier()
; #define PG8_SCHED __builtin_amdgcn_sched_barrier(0)
; template <class Epi>
; __device__ __forceinline__ void gemm_phase(LAS unsigned char* lds, const Gemm g, const StaticOrder& S, const Epi& E, const int tid) {
;     ...
;             PG8_WAIT_V(8); PG8_WAIT_L(0); PG8_BAR; PG8_MMA(1, 0, At, B0); PG8_MMA(1, 1, At, B1); PG8_BAR; PG8_SCHED;
;             PG8_LDB(B0, 1, 0); PG8_LDB(B1, 1, 1); PG8_SCHED; PG8_LDA(At, 1, 0); PG8_STAGE(PG8_SA(0, 1), a2 + hstepA, voffA);
;             PG8_WAIT_V(8); PG8_WAIT_L(0); PG8_BAR; PG8_MMA(0, 0, At, B0); PG8_MMA(0, 1, At, B1); PG8_BAR; PG8_SCHED;
	s_waitcnt lgkmcnt(0)
	v_mfma_f32_16x16x32_f16 v[60:63], v[128:131], v[182:185], v[60:63]
	v_mfma_f32_16x16x32_f16 v[52:55], v[136:139], v[182:185], v[52:55]
	v_mfma_f32_16x16x32_f16 v[44:47], v[128:131], v[212:215], v[44:47]
	v_mfma_f32_16x16x32_f16 v[36:39], v[136:139], v[212:215], v[36:39]
	v_mfma_f32_16x16x32_f16 v[28:31], v[128:131], v[220:223], v[28:31]
	v_mfma_f32_16x16x32_f16 v[20:23], v[136:139], v[220:223], v[20:23]
	v_mfma_f32_16x16x32_f16 v[12:15], v[128:131], v[228:231], v[12:15]
	v_mfma_f32_16x16x32_f16 v[4:7], v[136:139], v[228:231], v[4:7]
	v_mfma_f32_16x16x32_f16 v[60:63], v[132:135], v[190:193], v[60:63]
	v_mfma_f32_16x16x32_f16 v[52:55], v[140:143], v[190:193], v[52:55]
	v_mfma_f32_16x16x32_f16 v[44:47], v[132:135], v[216:219], v[44:47]
	v_mfma_f32_16x16x32_f16 v[36:39], v[140:143], v[216:219], v[36:39]
	v_mfma_f32_16x16x32_f16 v[28:31], v[132:135], v[224:227], v[28:31]
	v_mfma_f32_16x16x32_f16 v[20:23], v[140:143], v[224:227], v[20:23]
	v_mfma_f32_16x16x32_f16 v[12:15], v[132:135], v[232:235], v[12:15]
	v_mfma_f32_16x16x32_f16 v[4:7], v[140:143], v[232:235], v[4:7]
	v_mfma_f32_16x16x32_f16 v[56:59], v[154:157], v[182:185], v[56:59]
	v_mfma_f32_16x16x32_f16 v[48:51], v[174:177], v[182:185], v[48:51]
	v_mfma_f32_16x16x32_f16 v[40:43], v[154:157], v[212:215], v[40:43]
	v_mfma_f32_16x16x32_f16 v[32:35], v[174:177], v[212:215], v[32:35]
	v_mfma_f32_16x16x32_f16 v[24:27], v[154:157], v[220:223], v[24:27]
	v_mfma_f32_16x16x32_f16 v[16:19], v[174:177], v[220:223], v[16:19]
	v_mfma_f32_16x16x32_f16 v[8:11], v[154:157], v[228:231], v[8:11]
	v_mfma_f32_16x16x32_f16 v[0:3], v[174:177], v[228:231], v[0:3]
	v_mfma_f32_16x16x32_f16 v[56:59], v[162:165], v[190:193], v[56:59]
	v_mfma_f32_16x16x32_f16 v[48:51], v[178:181], v[190:193], v[48:51]
	v_mfma_f32_16x16x32_f16 v[40:43], v[162:165], v[216:219], v[40:43]
	v_mfma_f32_16x16x32_f16 v[32:35], v[178:181], v[216:219], v[32:35]
	v_mfma_f32_16x16x32_f16 v[24:27], v[162:165], v[224:227], v[24:27]
	v_mfma_f32_16x16x32_f16 v[16:19], v[178:181], v[224:227], v[16:19]
	v_mfma_f32_16x16x32_f16 v[8:11], v[162:165], v[232:235], v[8:11]
	v_mfma_f32_16x16x32_f16 v[0:3], v[178:181], v[232:235], v[0:3]
	s_barrier
	s_add_i32 s31, 0, 0x18000
	s_add_i32 s45, 0, 0x1c000
	v_add_u32_e32 v140, s31, v195
	v_add_u32_e32 v178, s45, v195
	ds_read_b128 v[128:131], v140
	ds_read_b128 v[132:135], v140 offset:1024
	ds_read_b128 v[136:139], v140 offset:2048
	ds_read_b128 v[140:143], v140 offset:3072
	ds_read_b128 v[154:157], v178
	ds_read_b128 v[162:165], v178 offset:1024
	ds_read_b128 v[174:177], v178 offset:2048
	ds_read_b128 v[178:181], v178 offset:3072
	s_add_u32 s22, s22, 0x40000
	s_addc_u32 s23, s23, 0
	s_mov_b32 m0, s35
	v_lshl_add_u64 v[238:239], s[22:23], 0, v[148:149]
	ds_read_b128 v[182:185], v211 offset:32768
	ds_read_b128 v[190:193], v211 offset:33792
	ds_read_b128 v[212:215], v211 offset:34816
	ds_read_b128 v[216:219], v211 offset:35840
	ds_read_b128 v[220:223], v211 offset:36864
	ds_read_b128 v[224:227], v211 offset:37888
	ds_read_b128 v[228:231], v211 offset:38912
	ds_read_b128 v[232:235], v211 offset:39936
	global_load_lds_dwordx4 v[238:239], off
	v_lshl_add_u64 v[238:239], s[22:23], 0, v[146:147]
	s_mov_b32 m0, s36
	s_nop 0
	global_load_lds_dwordx4 v[238:239], off
	s_waitcnt vmcnt(8)
	s_waitcnt lgkmcnt(0)
	s_barrier
	s_waitcnt lgkmcnt(0)
	v_mfma_f32_16x16x32_f16 v[124:127], v[128:131], v[182:185], v[124:127]
	v_mfma_f32_16x16x32_f16 v[116:119], v[136:139], v[182:185], v[116:119]
	v_mfma_f32_16x16x32_f16 v[108:111], v[128:131], v[212:215], v[108:111]
	v_mfma_f32_16x16x32_f16 v[100:103], v[136:139], v[212:215], v[100:103]
	v_mfma_f32_16x16x32_f16 v[92:95], v[128:131], v[220:223], v[92:95]
	v_mfma_f32_16x16x32_f16 v[84:87], v[136:139], v[220:223], v[84:87]
	v_mfma_f32_16x16x32_f16 v[76:79], v[128:131], v[228:231], v[76:79]
	v_mfma_f32_16x16x32_f16 v[68:71], v[136:139], v[228:231], v[68:71]
	v_mfma_f32_16x16x32_f16 v[124:127], v[132:135], v[190:193], v[124:127]
	v_mfma_f32_16x16x32_f16 v[116:119], v[140:143], v[190:193], v[116:119]
	v_mfma_f32_16x16x32_f16 v[108:111], v[132:135], v[216:219], v[108:111]
	v_mfma_f32_16x16x32_f16 v[100:103], v[140:143], v[216:219], v[100:103]
	v_mfma_f32_16x16x32_f16 v[92:95], v[132:135], v[224:227], v[92:95]
	v_mfma_f32_16x16x32_f16 v[84:87], v[140:143], v[224:227], v[84:87]
	v_mfma_f32_16x16x32_f16 v[76:79], v[132:135], v[232:235], v[76:79]
	v_mfma_f32_16x16x32_f16 v[68:71], v[140:143], v[232:235], v[68:71]
	v_mfma_f32_16x16x32_f16 v[120:123], v[154:157], v[182:185], v[120:123]
	v_mfma_f32_16x16x32_f16 v[112:115], v[174:177], v[182:185], v[112:115]
	v_mfma_f32_16x16x32_f16 v[104:107], v[154:157], v[212:215], v[104:107]
	v_mfma_f32_16x16x32_f16 v[96:99], v[174:177], v[212:215], v[96:99]
	v_mfma_f32_16x16x32_f16 v[88:91], v[154:157], v[220:223], v[88:91]
	v_mfma_f32_16x16x32_f16 v[80:83], v[174:177], v[220:223], v[80:83]
	v_mfma_f32_16x16x32_f16 v[72:75], v[154:157], v[228:231], v[72:75]
	v_mfma_f32_16x16x32_f16 v[64:67], v[174:177], v[228:231], v[64:67]
	v_mfma_f32_16x16x32_f16 v[120:123], v[162:165], v[190:193], v[120:123]
	v_mfma_f32_16x16x32_f16 v[112:115], v[178:181], v[190:193], v[112:115]
	v_mfma_f32_16x16x32_f16 v[104:107], v[162:165], v[216:219], v[104:107]
	v_mfma_f32_16x16x32_f16 v[96:99], v[178:181], v[216:219], v[96:99]
	v_mfma_f32_16x16x32_f16 v[88:91], v[162:165], v[224:227], v[88:91]
	v_mfma_f32_16x16x32_f16 v[80:83], v[178:181], v[224:227], v[80:83]
	v_mfma_f32_16x16x32_f16 v[72:75], v[162:165], v[232:235], v[72:75]
	v_mfma_f32_16x16x32_f16 v[64:67], v[178:181], v[232:235], v[64:67]
	s_barrier
; #define PG8_STAGE(bufoff, gbase, voff) do { _Pragma("unroll") for (int _i = 0; _i < 2; ++_i) \
;         __builtin_amdgcn_global_load_lds((const unsigned*)((const char*)(gbase) + (voff)[_i]), (LAS unsigned*)(lds + (bufoff) + ldsw + _i * 8192), 16, 0, 0); } while (0)
; #define PG8_LDA(dst, b, h) do { _Pragma("unroll") for (int m = 0; m < 4; ++m) _Pragma("unroll") for (int k = 0; k < 2; ++k) dst[m][k] = *(const LAS h16x8*)(lds + PG8_SA(b, h) + aoff + m * 2048 + k * 1024); } while (0)
; #define PG8_MMA(ai, bj, At, Bt) do { __builtin_amdgcn_s_setprio(1); _Pragma("unroll") for (int m = 0; m < 4; ++m) _Pragma("unroll") for (int n = 0; n < 2; ++n) _Pragma("unroll") for (int k = 0; k < 2; ++k) \
;         acc[ai][bj][m][n] = __builtin_amdgcn_mfma_f32_16x16x32_f16(Bt[n][k], At[m][k], acc[ai][bj][m][n], 0, 0, 0); __builtin_amdgcn_s_setprio(0); } while (0)
; #define PG8_WAIT_V(n) asm volatile("s_waitcnt vmcnt(" #n ")" ::: "memory")
; #define PG8_WAIT_L(n) asm volatile("s_waitcnt lgkmcnt(" #n ")" ::: "memory")
; #define PG8_BAR __builtin_amdgcn_s_barrier()
; #define PG8_SCHED __builtin_amdgcn_sched_barrier(0)
; template <class Epi>
; __device__ __forceinline__ void gemm_phase(LAS unsigned char* lds, const Gemm g, const StaticOrder& S, const Epi& E, const int tid) {
;     ...
;             PG8_LDA(At, 1, 1); PG8_STAGE(PG8_SB(1, 0), b3, voffB); PG8_STAGE(PG8_SB(1, 1), b3 + hstepB, voffB); PG8_STAGE(PG8_SA(1, 0), a3, voffA);
;             PG8_WAIT_V(8); PG8_WAIT_L(0); PG8_BAR; PG8_MMA(1, 0, At, B0); PG8_MMA(1, 1, At, B1); PG8_BAR; PG8_SCHED;
;         }
;         if (wr == 0) PG8_BAR;
	s_add_i32 s22, s31, s28
	v_lshl_add_u64 v[166:167], v[166:167], 0, s[0:1]
	s_mov_b32 m0, s22
	ds_read_b128 v[182:185], v211 offset:49152
	ds_read_b128 v[190:193], v211 offset:50176
	ds_read_b128 v[212:215], v211 offset:51200
	ds_read_b128 v[216:219], v211 offset:52224
	ds_read_b128 v[220:223], v211 offset:53248
	ds_read_b128 v[224:227], v211 offset:54272
	ds_read_b128 v[228:231], v211 offset:55296
	ds_read_b128 v[232:235], v211 offset:56320
	global_load_lds_dwordx4 v[166:167], off
	s_add_i32 m0, s22, 0x2000
	s_add_u32 s20, s20, 0x40080
	v_lshl_add_u64 v[166:167], v[186:187], 0, s[0:1]
	s_addc_u32 s21, s21, 0
	s_add_i32 s22, s45, s28
	global_load_lds_dwordx4 v[166:167], off
	v_lshl_add_u64 v[166:167], s[20:21], 0, v[152:153]
	s_mov_b32 m0, s22
	s_nop 0
	global_load_lds_dwordx4 v[166:167], off
	v_lshl_add_u64 v[166:167], s[20:21], 0, v[144:145]
	s_add_i32 m0, s22, 0x2000
	s_nop 0
	global_load_lds_dwordx4 v[166:167], off
	v_lshl_add_u64 v[166:167], v[204:205], 0, s[0:1]
	s_mov_b32 m0, s37
	s_nop 0
	global_load_lds_dwordx4 v[166:167], off
	v_lshl_add_u64 v[166:167], v[236:237], 0, s[0:1]
	s_mov_b32 m0, s38
	s_nop 0
	global_load_lds_dwordx4 v[166:167], off
	s_waitcnt vmcnt(8)
	s_waitcnt lgkmcnt(0)
	s_barrier
	s_waitcnt lgkmcnt(0)
	v_mfma_f32_16x16x32_f16 v[60:63], v[128:131], v[182:185], v[60:63]
	v_mfma_f32_16x16x32_f16 v[52:55], v[136:139], v[182:185], v[52:55]
	v_mfma_f32_16x16x32_f16 v[44:47], v[128:131], v[212:215], v[44:47]
	v_mfma_f32_16x16x32_f16 v[36:39], v[136:139], v[212:215], v[36:39]
	v_mfma_f32_16x16x32_f16 v[28:31], v[128:131], v[220:223], v[28:31]
	v_mfma_f32_16x16x32_f16 v[20:23], v[136:139], v[220:223], v[20:23]
	v_mfma_f32_16x16x32_f16 v[12:15], v[128:131], v[228:231], v[12:15]
	v_mfma_f32_16x16x32_f16 v[4:7], v[136:139], v[228:231], v[4:7]
	v_mfma_f32_16x16x32_f16 v[60:63], v[132:135], v[190:193], v[60:63]
	v_mfma_f32_16x16x32_f16 v[52:55], v[140:143], v[190:193], v[52:55]
	v_mfma_f32_16x16x32_f16 v[44:47], v[132:135], v[216:219], v[44:47]
	v_mfma_f32_16x16x32_f16 v[36:39], v[140:143], v[216:219], v[36:39]
	v_mfma_f32_16x16x32_f16 v[28:31], v[132:135], v[224:227], v[28:31]
	v_mfma_f32_16x16x32_f16 v[20:23], v[140:143], v[224:227], v[20:23]
	v_mfma_f32_16x16x32_f16 v[12:15], v[132:135], v[232:235], v[12:15]
	v_mfma_f32_16x16x32_f16 v[4:7], v[140:143], v[232:235], v[4:7]
	v_mfma_f32_16x16x32_f16 v[56:59], v[154:157], v[182:185], v[56:59]
	v_mfma_f32_16x16x32_f16 v[48:51], v[174:177], v[182:185], v[48:51]
	v_mfma_f32_16x16x32_f16 v[40:43], v[154:157], v[212:215], v[40:43]
	v_mfma_f32_16x16x32_f16 v[32:35], v[174:177], v[212:215], v[32:35]
	v_mfma_f32_16x16x32_f16 v[24:27], v[154:157], v[220:223], v[24:27]
	v_mfma_f32_16x16x32_f16 v[16:19], v[174:177], v[220:223], v[16:19]
	v_mfma_f32_16x16x32_f16 v[8:11], v[154:157], v[228:231], v[8:11]
	v_mfma_f32_16x16x32_f16 v[0:3], v[174:177], v[228:231], v[0:3]
	v_mfma_f32_16x16x32_f16 v[56:59], v[162:165], v[190:193], v[56:59]
	v_mfma_f32_16x16x32_f16 v[48:51], v[178:181], v[190:193], v[48:51]
	v_mfma_f32_16x16x32_f16 v[40:43], v[162:165], v[216:219], v[40:43]
	v_mfma_f32_16x16x32_f16 v[32:35], v[178:181], v[216:219], v[32:35]
	v_mfma_f32_16x16x32_f16 v[24:27], v[162:165], v[224:227], v[24:27]
	v_mfma_f32_16x16x32_f16 v[16:19], v[178:181], v[224:227], v[16:19]
	v_mfma_f32_16x16x32_f16 v[8:11], v[162:165], v[232:235], v[8:11]
	v_mfma_f32_16x16x32_f16 v[0:3], v[178:181], v[232:235], v[0:3]
	s_barrier
	s_add_i32 s44, s44, 2
	s_add_u32 s18, s18, 0x100
	s_addc_u32 s19, s19, 0
	s_add_u32 s2, s2, 0x100
	s_addc_u32 s3, s3, 0
	s_cmp_gt_u32 s44, 13
	s_cbranch_scc0 .LBB0_307
	s_and_b64 vcc, exec, s[8:9]
	s_cbranch_vccz .LBB0_310
	s_barrier

; #define PG8_STAGE(bufoff, gbase, voff) do { _Pragma("unroll") for (int _i = 0; _i < 2; ++_i) \
;         __builtin_amdgcn_global_load_lds((const unsigned*)((const char*)(gbase) + (voff)[_i]), (LAS unsigned*)(lds + (bufoff) + ldsw + _i * 8192), 16, 0, 0); } while (0)
; #define PG8_LDA(dst, b, h) do { _Pragma("unroll") for (int m = 0; m < 4; ++m) _Pragma("unroll") for (int k = 0; k < 2; ++k) dst[m][k] = *(const LAS h16x8*)(lds + PG8_SA(b, h) + aoff + m * 2048 + k * 1024); } while (0)
; #define PG8_LDB(dst, b, h) do { _Pragma("unroll") for (int n = 0; n < 2; ++n) _Pragma("unroll") for (int k = 0; k < 2; ++k) dst[n][k] = *(const LAS h16x8*)(lds + PG8_SB(b, h) + boff + n * 2048 + k * 1024); } while (0)
; #define PG8_MMA(ai, bj, At, Bt) do { __builtin_amdgcn_s_setprio(1); _Pragma("unroll") for (int m = 0; m < 4; ++m) _Pragma("unroll") for (int n = 0; n < 2; ++n) _Pragma("unroll") for (int k = 0; k < 2; ++k) \
;         acc[ai][bj][m][n] = __builtin_amdgcn_mfma_f32_16x16x32_f16(Bt[n][k], At[m][k], acc[ai][bj][m][n], 0, 0, 0); __builtin_amdgcn_s_setprio(0); } while (0)
; #define PG8_WAIT_V(n) asm volatile("s_waitcnt vmcnt(" #n ")" ::: "memory")
; #define PG8_WAIT_L(n) asm volatile("s_waitcnt lgkmcnt(" #n ")" ::: "memory")
; #define PG8_BAR __builtin_amdgcn_s_barrier()
; #define PG8_SCHED __builtin_amdgcn_sched_barrier(0)
; template <class Epi>
; __device__ __forceinline__ void gemm_phase(LAS unsigned char* lds, const Gemm g, const StaticOrder& S, const Epi& E, const int tid) {
;     ...
;             const bool last = (t == nt - 2);
;             const char* a1 = cA + (size_t)(t + 1) * kstep;
;             const char* a2 = last ? nA : cA + (size_t)(t + 2) * kstep; const char* b2 = last ? nB : cB + (size_t)(t + 2) * kstep;
;             const char* a3 = a2 + kstep; const char* b3 = b2 + kstep;
;             PG8_LDB(B0, 0, 0); PG8_LDB(B1, 0, 1); PG8_SCHED; PG8_LDA(At, 0, 0); PG8_STAGE(PG8_SA(1, 1), a1 + hstepA, voffA);
;             PG8_WAIT_V(8); PG8_WAIT_L(0); PG8_BAR; PG8_MMA(0, 0, At, B0); PG8_MMA(0, 1, At, B1); PG8_BAR; PG8_SCHED;
;             PG8_LDA(At, 0, 1); PG8_STAGE(PG8_SB(0, 0), b2, voffB); PG8_STAGE(PG8_SB(0, 1), b2 + hstepB, voffB); PG8_STAGE(PG8_SA(0, 0), a2, voffA);
;             PG8_WAIT_V(8); PG8_WAIT_L(0); PG8_BAR; PG8_MMA(1, 0, At, B0); PG8_MMA(1, 1, At, B1); PG8_BAR; PG8_SCHED;
.LBB0_336:
	s_add_u32 s18, s16, 0x100
	s_addc_u32 s19, s17, 0
	s_add_i32 s31, 0, 0x10000
	s_cmp_eq_u32 s46, 40
	s_cselect_b32 s23, s11, s19
	s_cselect_b32 s22, s10, s18
	s_cselect_b32 s21, s15, s3
	s_cselect_b32 s20, s14, s2
	s_add_i32 s47, 0, 0x14000
	v_add_u32_e32 v140, s31, v185
	v_add_u32_e32 v162, s47, v185
	ds_read_b128 v[128:131], v140
	ds_read_b128 v[132:135], v140 offset:1024
	ds_read_b128 v[136:139], v140 offset:2048
	ds_read_b128 v[140:143], v140 offset:3072
	ds_read_b128 v[144:147], v162
	ds_read_b128 v[148:151], v162 offset:1024
	ds_read_b128 v[154:157], v162 offset:2048
	ds_read_b128 v[162:165], v162 offset:3072
	v_lshl_add_u64 v[166:167], s[16:17], 0, v[172:173]
	s_add_i32 m0, s34, 0xc000
	ds_read_b128 v[176:179], v187
	ds_read_b128 v[180:183], v187 offset:1024
	ds_read_b128 v[188:191], v187 offset:2048
	ds_read_b128 v[192:195], v187 offset:3072
	ds_read_b128 v[210:213], v187 offset:4096
	ds_read_b128 v[214:217], v187 offset:5120
	ds_read_b128 v[218:221], v187 offset:6144
	ds_read_b128 v[222:225], v187 offset:7168
	global_load_lds_dwordx4 v[166:167], off
	v_lshl_add_u64 v[166:167], s[16:17], 0, v[174:175]
	s_add_i32 m0, s34, 0xe000
	s_nop 0
	global_load_lds_dwordx4 v[166:167], off
	s_waitcnt vmcnt(8)
	s_waitcnt lgkmcnt(0)
	s_barrier
	s_waitcnt lgkmcnt(0)
	v_mfma_f32_16x16x32_f16 v[124:127], v[128:131], v[176:179], v[124:127]
	v_mfma_f32_16x16x32_f16 v[120:123], v[136:139], v[176:179], v[120:123]
	v_mfma_f32_16x16x32_f16 v[108:111], v[128:131], v[188:191], v[108:111]
	v_mfma_f32_16x16x32_f16 v[104:107], v[136:139], v[188:191], v[104:107]
	v_mfma_f32_16x16x32_f16 v[92:95], v[128:131], v[210:213], v[92:95]
	v_mfma_f32_16x16x32_f16 v[88:91], v[136:139], v[210:213], v[88:91]
	v_mfma_f32_16x16x32_f16 v[76:79], v[128:131], v[218:221], v[76:79]
	v_mfma_f32_16x16x32_f16 v[72:75], v[136:139], v[218:221], v[72:75]
	v_mfma_f32_16x16x32_f16 v[124:127], v[132:135], v[180:183], v[124:127]
	v_mfma_f32_16x16x32_f16 v[120:123], v[140:143], v[180:183], v[120:123]
	v_mfma_f32_16x16x32_f16 v[108:111], v[132:135], v[192:195], v[108:111]
	v_mfma_f32_16x16x32_f16 v[104:107], v[140:143], v[192:195], v[104:107]
	v_mfma_f32_16x16x32_f16 v[92:95], v[132:135], v[214:217], v[92:95]
	v_mfma_f32_16x16x32_f16 v[88:91], v[140:143], v[214:217], v[88:91]
	v_mfma_f32_16x16x32_f16 v[76:79], v[132:135], v[222:225], v[76:79]
	v_mfma_f32_16x16x32_f16 v[72:75], v[140:143], v[222:225], v[72:75]
	v_mfma_f32_16x16x32_f16 v[116:119], v[144:147], v[176:179], v[116:119]
	v_mfma_f32_16x16x32_f16 v[112:115], v[154:157], v[176:179], v[112:115]
	v_mfma_f32_16x16x32_f16 v[100:103], v[144:147], v[188:191], v[100:103]
	v_mfma_f32_16x16x32_f16 v[96:99], v[154:157], v[188:191], v[96:99]
	v_mfma_f32_16x16x32_f16 v[84:87], v[144:147], v[210:213], v[84:87]
	v_mfma_f32_16x16x32_f16 v[80:83], v[154:157], v[210:213], v[80:83]
	v_mfma_f32_16x16x32_f16 v[68:71], v[144:147], v[218:221], v[68:71]
	v_mfma_f32_16x16x32_f16 v[64:67], v[154:157], v[218:221], v[64:67]
	v_mfma_f32_16x16x32_f16 v[116:119], v[148:151], v[180:183], v[116:119]
	v_mfma_f32_16x16x32_f16 v[112:115], v[162:165], v[180:183], v[112:115]
	v_mfma_f32_16x16x32_f16 v[100:103], v[148:151], v[192:195], v[100:103]
	v_mfma_f32_16x16x32_f16 v[96:99], v[162:165], v[192:195], v[96:99]
	v_mfma_f32_16x16x32_f16 v[84:87], v[148:151], v[214:217], v[84:87]
	v_mfma_f32_16x16x32_f16 v[80:83], v[162:165], v[214:217], v[80:83]
	v_mfma_f32_16x16x32_f16 v[68:71], v[148:151], v[222:225], v[68:71]
	v_mfma_f32_16x16x32_f16 v[64:67], v[162:165], v[222:225], v[64:67]
	s_barrier
	s_add_i32 s16, s31, s29
	v_lshl_add_u64 v[166:167], s[20:21], 0, v[152:153]
	s_mov_b32 m0, s16
	ds_read_b128 v[176:179], v187 offset:16384
	ds_read_b128 v[180:183], v187 offset:17408
	ds_read_b128 v[188:191], v187 offset:18432
	ds_read_b128 v[192:195], v187 offset:19456
	ds_read_b128 v[210:213], v187 offset:20480
	ds_read_b128 v[214:217], v187 offset:21504
	ds_read_b128 v[218:221], v187 offset:22528
	ds_read_b128 v[222:225], v187 offset:23552
	global_load_lds_dwordx4 v[166:167], off
	s_add_i32 m0, s16, 0x2000
	s_add_u32 s16, s20, 0xb0000
	v_lshl_add_u64 v[196:197], s[20:21], 0, v[170:171]
	s_addc_u32 s17, s21, 0
	s_add_i32 s31, s47, s29
	global_load_lds_dwordx4 v[196:197], off
	v_lshl_add_u64 v[204:205], s[16:17], 0, v[152:153]
	s_mov_b32 m0, s31
	v_lshl_add_u64 v[226:227], s[22:23], 0, v[170:171]
	global_load_lds_dwordx4 v[204:205], off
	v_lshl_add_u64 v[204:205], s[16:17], 0, v[170:171]
	s_add_i32 m0, s31, 0x2000
	s_nop 0
	global_load_lds_dwordx4 v[204:205], off
	v_lshl_add_u64 v[204:205], s[22:23], 0, v[152:153]
	s_mov_b32 m0, s34
	s_nop 0
	global_load_lds_dwordx4 v[204:205], off
	s_mov_b32 m0, s35
	s_nop 0
	global_load_lds_dwordx4 v[226:227], off
	s_waitcnt vmcnt(8)
	s_waitcnt lgkmcnt(0)
	s_barrier
; #define PG8_STAGE(bufoff, gbase, voff) do { _Pragma("unroll") for (int _i = 0; _i < 2; ++_i) \
;         __builtin_amdgcn_global_load_lds((const unsigned*)((const char*)(gbase) + (voff)[_i]), (LAS unsigned*)(lds + (bufoff) + ldsw + _i * 8192), 16, 0, 0); } while (0)
; #define PG8_LDA(dst, b, h) do { _Pragma("unroll") for (int m = 0; m < 4; ++m) _Pragma("unroll") for (int k = 0; k < 2; ++k) dst[m][k] = *(const LAS h16x8*)(lds + PG8_SA(b, h) + aoff + m * 2048 + k * 1024); } while (0)
; #define PG8_LDB(dst, b, h) do { _Pragma("unroll") for (int n = 0; n < 2; ++n) _Pragma("unroll") for (int k = 0; k < 2; ++k) dst[n][k] = *(const LAS h16x8*)(lds + PG8_SB(b, h) + boff + n * 2048 + k * 1024); } while (0)
; #define PG8_MMA(ai, bj, At, Bt) do { __builtin_amdgcn_s_setprio(1); _Pragma("unroll") for (int m = 0; m < 4; ++m) _Pragma("unroll") for (int n = 0; n < 2; ++n) _Pragma("unroll") for (int k = 0; k < 2; ++k) \
;         acc[ai][bj][m][n] = __builtin_amdgcn_mfma_f32_16x16x32_f16(Bt[n][k], At[m][k], acc[ai][bj][m][n], 0, 0, 0); __builtin_amdgcn_s_setprio(0); } while (0)
; #define PG8_WAIT_V(n) asm volatile("s_waitcnt vmcnt(" #n ")" ::: "memory")
; #define PG8_WAIT_L(n) asm volatile("s_waitcnt lgkmcnt(" #n ")" ::: "memory")
; #define PG8_BAR __builtin_amdgcn_s_barrier()
; #define PG8_SCHED __builtin_amdgcn_sched_barrier(0)
; template <class Epi>
; __device__ __forceinline__ void gemm_phase(LAS unsigned char* lds, const Gemm g, const StaticOrder& S, const Epi& E, const int tid) {
;     ...
;             PG8_WAIT_V(8); PG8_WAIT_L(0); PG8_BAR; PG8_MMA(1, 0, At, B0); PG8_MMA(1, 1, At, B1); PG8_BAR; PG8_SCHED;
;             PG8_LDB(B0, 1, 0); PG8_LDB(B1, 1, 1); PG8_SCHED; PG8_LDA(At, 1, 0); PG8_STAGE(PG8_SA(0, 1), a2 + hstepA, voffA);
;             PG8_WAIT_V(8); PG8_WAIT_L(0); PG8_BAR; PG8_MMA(0, 0, At, B0); PG8_MMA(0, 1, At, B1); PG8_BAR; PG8_SCHED;
	s_waitcnt lgkmcnt(0)
	v_mfma_f32_16x16x32_f16 v[60:63], v[128:131], v[176:179], v[60:63]
	v_mfma_f32_16x16x32_f16 v[56:59], v[136:139], v[176:179], v[56:59]
	v_mfma_f32_16x16x32_f16 v[44:47], v[128:131], v[188:191], v[44:47]
	v_mfma_f32_16x16x32_f16 v[40:43], v[136:139], v[188:191], v[40:43]
	v_mfma_f32_16x16x32_f16 v[28:31], v[128:131], v[210:213], v[28:31]
	v_mfma_f32_16x16x32_f16 v[24:27], v[136:139], v[210:213], v[24:27]
	v_mfma_f32_16x16x32_f16 v[12:15], v[128:131], v[218:221], v[12:15]
	v_mfma_f32_16x16x32_f16 v[8:11], v[136:139], v[218:221], v[8:11]
	v_mfma_f32_16x16x32_f16 v[60:63], v[132:135], v[180:183], v[60:63]
	v_mfma_f32_16x16x32_f16 v[56:59], v[140:143], v[180:183], v[56:59]
	v_mfma_f32_16x16x32_f16 v[44:47], v[132:135], v[192:195], v[44:47]
	v_mfma_f32_16x16x32_f16 v[40:43], v[140:143], v[192:195], v[40:43]
	v_mfma_f32_16x16x32_f16 v[28:31], v[132:135], v[214:217], v[28:31]
	v_mfma_f32_16x16x32_f16 v[24:27], v[140:143], v[214:217], v[24:27]
	v_mfma_f32_16x16x32_f16 v[12:15], v[132:135], v[222:225], v[12:15]
	v_mfma_f32_16x16x32_f16 v[8:11], v[140:143], v[222:225], v[8:11]
	v_mfma_f32_16x16x32_f16 v[52:55], v[144:147], v[176:179], v[52:55]
	v_mfma_f32_16x16x32_f16 v[48:51], v[154:157], v[176:179], v[48:51]
	v_mfma_f32_16x16x32_f16 v[36:39], v[144:147], v[188:191], v[36:39]
	v_mfma_f32_16x16x32_f16 v[32:35], v[154:157], v[188:191], v[32:35]
	v_mfma_f32_16x16x32_f16 v[20:23], v[144:147], v[210:213], v[20:23]
	v_mfma_f32_16x16x32_f16 v[16:19], v[154:157], v[210:213], v[16:19]
	v_mfma_f32_16x16x32_f16 v[4:7], v[144:147], v[218:221], v[4:7]
	v_mfma_f32_16x16x32_f16 v[0:3], v[154:157], v[218:221], v[0:3]
	v_mfma_f32_16x16x32_f16 v[52:55], v[148:151], v[180:183], v[52:55]
	v_mfma_f32_16x16x32_f16 v[48:51], v[162:165], v[180:183], v[48:51]
	v_mfma_f32_16x16x32_f16 v[36:39], v[148:151], v[192:195], v[36:39]
	v_mfma_f32_16x16x32_f16 v[32:35], v[162:165], v[192:195], v[32:35]
	v_mfma_f32_16x16x32_f16 v[20:23], v[148:151], v[214:217], v[20:23]
	v_mfma_f32_16x16x32_f16 v[16:19], v[162:165], v[214:217], v[16:19]
	v_mfma_f32_16x16x32_f16 v[4:7], v[148:151], v[222:225], v[4:7]
	v_mfma_f32_16x16x32_f16 v[0:3], v[162:165], v[222:225], v[0:3]
	s_barrier
	s_add_i32 s31, 0, 0x18000
	s_add_i32 s47, 0, 0x1c000
	v_add_u32_e32 v140, s31, v185
	v_add_u32_e32 v162, s47, v185
	ds_read_b128 v[128:131], v140
	ds_read_b128 v[132:135], v140 offset:1024
	ds_read_b128 v[136:139], v140 offset:2048
	ds_read_b128 v[140:143], v140 offset:3072
	ds_read_b128 v[144:147], v162
	ds_read_b128 v[148:151], v162 offset:1024
	ds_read_b128 v[154:157], v162 offset:2048
	ds_read_b128 v[162:165], v162 offset:3072
	s_add_u32 s16, s22, 0xb0000
	s_addc_u32 s17, s23, 0
	s_mov_b32 m0, s36
	v_lshl_add_u64 v[228:229], s[16:17], 0, v[152:153]
	ds_read_b128 v[176:179], v187 offset:32768
	ds_read_b128 v[180:183], v187 offset:33792
	ds_read_b128 v[188:191], v187 offset:34816
	ds_read_b128 v[192:195], v187 offset:35840
	ds_read_b128 v[210:213], v187 offset:36864
	ds_read_b128 v[214:217], v187 offset:37888
	ds_read_b128 v[218:221], v187 offset:38912
	ds_read_b128 v[222:225], v187 offset:39936
	global_load_lds_dwordx4 v[228:229], off
	v_lshl_add_u64 v[228:229], s[16:17], 0, v[170:171]
	s_mov_b32 m0, s37
	s_nop 0
	global_load_lds_dwordx4 v[228:229], off
	s_waitcnt vmcnt(8)
	s_waitcnt lgkmcnt(0)
	s_barrier
	s_waitcnt lgkmcnt(0)
	v_mfma_f32_16x16x32_f16 v[124:127], v[128:131], v[176:179], v[124:127]
	v_mfma_f32_16x16x32_f16 v[120:123], v[136:139], v[176:179], v[120:123]
	v_mfma_f32_16x16x32_f16 v[108:111], v[128:131], v[188:191], v[108:111]
	v_mfma_f32_16x16x32_f16 v[104:107], v[136:139], v[188:191], v[104:107]
	v_mfma_f32_16x16x32_f16 v[92:95], v[128:131], v[210:213], v[92:95]
	v_mfma_f32_16x16x32_f16 v[88:91], v[136:139], v[210:213], v[88:91]
	v_mfma_f32_16x16x32_f16 v[76:79], v[128:131], v[218:221], v[76:79]
	v_mfma_f32_16x16x32_f16 v[72:75], v[136:139], v[218:221], v[72:75]
	v_mfma_f32_16x16x32_f16 v[124:127], v[132:135], v[180:183], v[124:127]
	v_mfma_f32_16x16x32_f16 v[120:123], v[140:143], v[180:183], v[120:123]
	v_mfma_f32_16x16x32_f16 v[108:111], v[132:135], v[192:195], v[108:111]
	v_mfma_f32_16x16x32_f16 v[104:107], v[140:143], v[192:195], v[104:107]
	v_mfma_f32_16x16x32_f16 v[92:95], v[132:135], v[214:217], v[92:95]
	v_mfma_f32_16x16x32_f16 v[88:91], v[140:143], v[214:217], v[88:91]
	v_mfma_f32_16x16x32_f16 v[76:79], v[132:135], v[222:225], v[76:79]
	v_mfma_f32_16x16x32_f16 v[72:75], v[140:143], v[222:225], v[72:75]
	v_mfma_f32_16x16x32_f16 v[116:119], v[144:147], v[176:179], v[116:119]
	v_mfma_f32_16x16x32_f16 v[112:115], v[154:157], v[176:179], v[112:115]
	v_mfma_f32_16x16x32_f16 v[100:103], v[144:147], v[188:191], v[100:103]
	v_mfma_f32_16x16x32_f16 v[96:99], v[154:157], v[188:191], v[96:99]
	v_mfma_f32_16x16x32_f16 v[84:87], v[144:147], v[210:213], v[84:87]
	v_mfma_f32_16x16x32_f16 v[80:83], v[154:157], v[210:213], v[80:83]
	v_mfma_f32_16x16x32_f16 v[68:71], v[144:147], v[218:221], v[68:71]
	v_mfma_f32_16x16x32_f16 v[64:67], v[154:157], v[218:221], v[64:67]
	v_mfma_f32_16x16x32_f16 v[116:119], v[148:151], v[180:183], v[116:119]
	v_mfma_f32_16x16x32_f16 v[112:115], v[162:165], v[180:183], v[112:115]
	v_mfma_f32_16x16x32_f16 v[100:103], v[148:151], v[192:195], v[100:103]
	v_mfma_f32_16x16x32_f16 v[96:99], v[162:165], v[192:195], v[96:99]
	v_mfma_f32_16x16x32_f16 v[84:87], v[148:151], v[214:217], v[84:87]
	v_mfma_f32_16x16x32_f16 v[80:83], v[162:165], v[214:217], v[80:83]
	v_mfma_f32_16x16x32_f16 v[68:71], v[148:151], v[222:225], v[68:71]
	v_mfma_f32_16x16x32_f16 v[64:67], v[162:165], v[222:225], v[64:67]
	s_barrier
; #define PG8_STAGE(bufoff, gbase, voff) do { _Pragma("unroll") for (int _i = 0; _i < 2; ++_i) \
;         __builtin_amdgcn_global_load_lds((const unsigned*)((const char*)(gbase) + (voff)[_i]), (LAS unsigned*)(lds + (bufoff) + ldsw + _i * 8192), 16, 0, 0); } while (0)
; #define PG8_LDA(dst, b, h) do { _Pragma("unroll") for (int m = 0; m < 4; ++m) _Pragma("unroll") for (int k = 0; k < 2; ++k) dst[m][k] = *(const LAS h16x8*)(lds + PG8_SA(b, h) + aoff + m * 2048 + k * 1024); } while (0)
; #define PG8_MMA(ai, bj, At, Bt) do { __builtin_amdgcn_s_setprio(1); _Pragma("unroll") for (int m = 0; m < 4; ++m) _Pragma("unroll") for (int n = 0; n < 2; ++n) _Pragma("unroll") for (int k = 0; k < 2; ++k) \
;         acc[ai][bj][m][n] = __builtin_amdgcn_mfma_f32_16x16x32_f16(Bt[n][k], At[m][k], acc[ai][bj][m][n], 0, 0, 0); __builtin_amdgcn_s_setprio(0); } while (0)
; #define PG8_WAIT_V(n) asm volatile("s_waitcnt vmcnt(" #n ")" ::: "memory")
; #define PG8_WAIT_L(n) asm volatile("s_waitcnt lgkmcnt(" #n ")" ::: "memory")
; #define PG8_BAR __builtin_amdgcn_s_barrier()
; #define PG8_SCHED __builtin_amdgcn_sched_barrier(0)
; template <class Epi>
; __device__ __forceinline__ void gemm_phase(LAS unsigned char* lds, const Gemm g, const StaticOrder& S, const Epi& E, const int tid) {
;     ...
;             PG8_LDA(At, 1, 1); PG8_STAGE(PG8_SB(1, 0), b3, voffB); PG8_STAGE(PG8_SB(1, 1), b3 + hstepB, voffB); PG8_STAGE(PG8_SA(1, 0), a3, voffA);
;             PG8_WAIT_V(8); PG8_WAIT_L(0); PG8_BAR; PG8_MMA(1, 0, At, B0); PG8_MMA(1, 1, At, B1); PG8_BAR; PG8_SCHED;
;         }
;         if (wr == 0) PG8_BAR;
	s_add_i32 s16, s31, s29
	v_lshl_add_u64 v[166:167], v[166:167], 0, s[0:1]
	s_mov_b32 m0, s16
	ds_read_b128 v[176:179], v187 offset:49152
	ds_read_b128 v[180:183], v187 offset:50176
	ds_read_b128 v[188:191], v187 offset:51200
	ds_read_b128 v[192:195], v187 offset:52224
	ds_read_b128 v[210:213], v187 offset:53248
	ds_read_b128 v[214:217], v187 offset:54272
	ds_read_b128 v[218:221], v187 offset:55296
	ds_read_b128 v[222:225], v187 offset:56320
	global_load_lds_dwordx4 v[166:167], off
	s_add_i32 m0, s16, 0x2000
	s_add_u32 s16, s20, 0xb0080
	v_lshl_add_u64 v[166:167], v[196:197], 0, s[0:1]
	s_addc_u32 s17, s21, 0
	s_add_i32 s20, s47, s29
	global_load_lds_dwordx4 v[166:167], off
	v_lshl_add_u64 v[166:167], s[16:17], 0, v[152:153]
	s_mov_b32 m0, s20
	s_nop 0
	global_load_lds_dwordx4 v[166:167], off
	v_lshl_add_u64 v[166:167], s[16:17], 0, v[170:171]
	s_add_i32 m0, s20, 0x2000
	s_nop 0
	global_load_lds_dwordx4 v[166:167], off
	v_lshl_add_u64 v[166:167], v[204:205], 0, s[0:1]
	s_mov_b32 m0, s38
	s_nop 0
	global_load_lds_dwordx4 v[166:167], off
	v_lshl_add_u64 v[166:167], v[226:227], 0, s[0:1]
	s_mov_b32 m0, s39
	s_nop 0
	global_load_lds_dwordx4 v[166:167], off
	s_waitcnt vmcnt(8)
	s_waitcnt lgkmcnt(0)
	s_barrier
	s_waitcnt lgkmcnt(0)
	v_mfma_f32_16x16x32_f16 v[60:63], v[128:131], v[176:179], v[60:63]
	v_mfma_f32_16x16x32_f16 v[56:59], v[136:139], v[176:179], v[56:59]
	v_mfma_f32_16x16x32_f16 v[44:47], v[128:131], v[188:191], v[44:47]
	v_mfma_f32_16x16x32_f16 v[40:43], v[136:139], v[188:191], v[40:43]
	v_mfma_f32_16x16x32_f16 v[28:31], v[128:131], v[210:213], v[28:31]
	v_mfma_f32_16x16x32_f16 v[24:27], v[136:139], v[210:213], v[24:27]
	v_mfma_f32_16x16x32_f16 v[12:15], v[128:131], v[218:221], v[12:15]
	v_mfma_f32_16x16x32_f16 v[8:11], v[136:139], v[218:221], v[8:11]
	v_mfma_f32_16x16x32_f16 v[60:63], v[132:135], v[180:183], v[60:63]
	v_mfma_f32_16x16x32_f16 v[56:59], v[140:143], v[180:183], v[56:59]
	v_mfma_f32_16x16x32_f16 v[44:47], v[132:135], v[192:195], v[44:47]
	v_mfma_f32_16x16x32_f16 v[40:43], v[140:143], v[192:195], v[40:43]
	v_mfma_f32_16x16x32_f16 v[28:31], v[132:135], v[214:217], v[28:31]
	v_mfma_f32_16x16x32_f16 v[24:27], v[140:143], v[214:217], v[24:27]
	v_mfma_f32_16x16x32_f16 v[12:15], v[132:135], v[222:225], v[12:15]
	v_mfma_f32_16x16x32_f16 v[8:11], v[140:143], v[222:225], v[8:11]
	v_mfma_f32_16x16x32_f16 v[52:55], v[144:147], v[176:179], v[52:55]
	v_mfma_f32_16x16x32_f16 v[48:51], v[154:157], v[176:179], v[48:51]
	v_mfma_f32_16x16x32_f16 v[36:39], v[144:147], v[188:191], v[36:39]
	v_mfma_f32_16x16x32_f16 v[32:35], v[154:157], v[188:191], v[32:35]
	v_mfma_f32_16x16x32_f16 v[20:23], v[144:147], v[210:213], v[20:23]
	v_mfma_f32_16x16x32_f16 v[16:19], v[154:157], v[210:213], v[16:19]
	v_mfma_f32_16x16x32_f16 v[4:7], v[144:147], v[218:221], v[4:7]
	v_mfma_f32_16x16x32_f16 v[0:3], v[154:157], v[218:221], v[0:3]
	v_mfma_f32_16x16x32_f16 v[52:55], v[148:151], v[180:183], v[52:55]
	v_mfma_f32_16x16x32_f16 v[48:51], v[162:165], v[180:183], v[48:51]
	v_mfma_f32_16x16x32_f16 v[36:39], v[148:151], v[192:195], v[36:39]
	v_mfma_f32_16x16x32_f16 v[32:35], v[162:165], v[192:195], v[32:35]
	v_mfma_f32_16x16x32_f16 v[20:23], v[148:151], v[214:217], v[20:23]
	v_mfma_f32_16x16x32_f16 v[16:19], v[162:165], v[214:217], v[16:19]
	v_mfma_f32_16x16x32_f16 v[4:7], v[148:151], v[222:225], v[4:7]
	v_mfma_f32_16x16x32_f16 v[0:3], v[162:165], v[222:225], v[0:3]
	s_barrier
	s_add_i32 s46, s46, 2
	s_add_u32 s2, s2, 0x100
	s_addc_u32 s3, s3, 0
	s_cmp_gt_u32 s46, 41
	s_mov_b64 s[16:17], s[18:19]
	s_cbranch_scc0 .LBB0_336
	s_and_b64 vcc, exec, s[12:13]
	s_cbranch_vccz .LBB0_339
	s_barrier

; #define PG8_STAGE(bufoff, gbase, voff) do { _Pragma("unroll") for (int _i = 0; _i < 2; ++_i) \
;         __builtin_amdgcn_global_load_lds((const unsigned*)((const char*)(gbase) + (voff)[_i]), (LAS unsigned*)(lds + (bufoff) + ldsw + _i * 8192), 16, 0, 0); } while (0)
; #define PG8_LDA(dst, b, h) do { _Pragma("unroll") for (int m = 0; m < 4; ++m) _Pragma("unroll") for (int k = 0; k < 2; ++k) dst[m][k] = *(const LAS h16x8*)(lds + PG8_SA(b, h) + aoff + m * 2048 + k * 1024); } while (0)
; #define PG8_LDB(dst, b, h) do { _Pragma("unroll") for (int n = 0; n < 2; ++n) _Pragma("unroll") for (int k = 0; k < 2; ++k) dst[n][k] = *(const LAS h16x8*)(lds + PG8_SB(b, h) + boff + n * 2048 + k * 1024); } while (0)
; #define PG8_MMA(ai, bj, At, Bt) do { __builtin_amdgcn_s_setprio(1); _Pragma("unroll") for (int m = 0; m < 4; ++m) _Pragma("unroll") for (int n = 0; n < 2; ++n) _Pragma("unroll") for (int k = 0; k < 2; ++k) \
;         acc[ai][bj][m][n] = __builtin_amdgcn_mfma_f32_16x16x32_f16(Bt[n][k], At[m][k], acc[ai][bj][m][n], 0, 0, 0); __builtin_amdgcn_s_setprio(0); } while (0)
; #define PG8_WAIT_V(n) asm volatile("s_waitcnt vmcnt(" #n ")" ::: "memory")
; #define PG8_WAIT_L(n) asm volatile("s_waitcnt lgkmcnt(" #n ")" ::: "memory")
; #define PG8_BAR __builtin_amdgcn_s_barrier()
; #define PG8_SCHED __builtin_amdgcn_sched_barrier(0)
; template <class Epi>
; __device__ __forceinline__ void gemm_phase(LAS unsigned char* lds, const Gemm g, const StaticOrder& S, const Epi& E, const int tid) {
;     ...
;             const bool last = (t == nt - 2);
;             const char* a1 = cA + (size_t)(t + 1) * kstep;
;             const char* a2 = last ? nA : cA + (size_t)(t + 2) * kstep; const char* b2 = last ? nB : cB + (size_t)(t + 2) * kstep;
;             const char* a3 = a2 + kstep; const char* b3 = b2 + kstep;
;             PG8_LDB(B0, 0, 0); PG8_LDB(B1, 0, 1); PG8_SCHED; PG8_LDA(At, 0, 0); PG8_STAGE(PG8_SA(1, 1), a1 + hstepA, voffA);
;             PG8_WAIT_V(8); PG8_WAIT_L(0); PG8_BAR; PG8_MMA(0, 0, At, B0); PG8_MMA(0, 1, At, B1); PG8_BAR; PG8_SCHED;
;             PG8_LDA(At, 0, 1); PG8_STAGE(PG8_SB(0, 0), b2, voffB); PG8_STAGE(PG8_SB(0, 1), b2 + hstepB, voffB); PG8_STAGE(PG8_SA(0, 0), a2, voffA);
;             PG8_WAIT_V(8); PG8_WAIT_L(0); PG8_BAR; PG8_MMA(1, 0, At, B0); PG8_MMA(1, 1, At, B1); PG8_BAR; PG8_SCHED;
.LBB0_373:
	s_add_u32 s20, s8, 0xfffc0080
	s_addc_u32 s21, s9, -1
	s_add_i32 s31, 0, 0x10000
	s_cmp_eq_u32 s41, 12
	s_cselect_b32 s23, s15, s21
	s_cselect_b32 s22, s39, s20
	s_cselect_b32 s21, s13, s3
	s_cselect_b32 s20, s40, s2
	s_add_i32 s44, 0, 0x14000
	v_add_u32_e32 v154, s31, v163
	v_add_u32_e32 v164, s44, v163
	ds_read_b128 v[140:143], v154
	ds_read_b128 v[144:147], v154 offset:1024
	ds_read_b128 v[148:151], v154 offset:2048
	ds_read_b128 v[154:157], v154 offset:3072
	ds_read_b128 v[170:173], v164
	ds_read_b128 v[174:177], v164 offset:1024
	ds_read_b128 v[180:183], v164 offset:2048
	ds_read_b128 v[184:187], v164 offset:3072
	v_lshl_add_u64 v[164:165], s[8:9], 0, v[136:137]
	s_add_i32 m0, s26, 0xc000
	ds_read_b128 v[188:191], v179
	ds_read_b128 v[192:195], v179 offset:1024
	ds_read_b128 v[210:213], v179 offset:2048
	ds_read_b128 v[214:217], v179 offset:3072
	ds_read_b128 v[218:221], v179 offset:4096
	ds_read_b128 v[222:225], v179 offset:5120
	ds_read_b128 v[226:229], v179 offset:6144
	ds_read_b128 v[230:233], v179 offset:7168
	global_load_lds_dwordx4 v[164:165], off
	v_lshl_add_u64 v[164:165], s[8:9], 0, v[138:139]
	s_add_i32 m0, s26, 0xe000
	s_nop 0
	global_load_lds_dwordx4 v[164:165], off
	s_waitcnt vmcnt(8)
	s_waitcnt lgkmcnt(0)
	s_barrier
	s_waitcnt lgkmcnt(0)
	v_mfma_f32_16x16x32_f16 v[124:127], v[140:143], v[188:191], v[124:127]
	v_mfma_f32_16x16x32_f16 v[120:123], v[148:151], v[188:191], v[120:123]
	v_mfma_f32_16x16x32_f16 v[112:115], v[140:143], v[210:213], v[112:115]
	v_mfma_f32_16x16x32_f16 v[104:107], v[148:151], v[210:213], v[104:107]
	v_mfma_f32_16x16x32_f16 v[96:99], v[140:143], v[218:221], v[96:99]
	v_mfma_f32_16x16x32_f16 v[88:91], v[148:151], v[218:221], v[88:91]
	v_mfma_f32_16x16x32_f16 v[80:83], v[140:143], v[226:229], v[80:83]
	v_mfma_f32_16x16x32_f16 v[72:75], v[148:151], v[226:229], v[72:75]
	v_mfma_f32_16x16x32_f16 v[124:127], v[144:147], v[192:195], v[124:127]
	v_mfma_f32_16x16x32_f16 v[120:123], v[154:157], v[192:195], v[120:123]
	v_mfma_f32_16x16x32_f16 v[112:115], v[144:147], v[214:217], v[112:115]
	v_mfma_f32_16x16x32_f16 v[104:107], v[154:157], v[214:217], v[104:107]
	v_mfma_f32_16x16x32_f16 v[96:99], v[144:147], v[222:225], v[96:99]
	v_mfma_f32_16x16x32_f16 v[88:91], v[154:157], v[222:225], v[88:91]
	v_mfma_f32_16x16x32_f16 v[80:83], v[144:147], v[230:233], v[80:83]
	v_mfma_f32_16x16x32_f16 v[72:75], v[154:157], v[230:233], v[72:75]
	v_mfma_f32_16x16x32_f16 v[116:119], v[170:173], v[188:191], v[116:119]
	v_mfma_f32_16x16x32_f16 v[108:111], v[180:183], v[188:191], v[108:111]
	v_mfma_f32_16x16x32_f16 v[100:103], v[170:173], v[210:213], v[100:103]
	v_mfma_f32_16x16x32_f16 v[92:95], v[180:183], v[210:213], v[92:95]
	v_mfma_f32_16x16x32_f16 v[84:87], v[170:173], v[218:221], v[84:87]
	v_mfma_f32_16x16x32_f16 v[76:79], v[180:183], v[218:221], v[76:79]
	v_mfma_f32_16x16x32_f16 v[68:71], v[170:173], v[226:229], v[68:71]
	v_mfma_f32_16x16x32_f16 v[64:67], v[180:183], v[226:229], v[64:67]
	v_mfma_f32_16x16x32_f16 v[116:119], v[174:177], v[192:195], v[116:119]
	v_mfma_f32_16x16x32_f16 v[108:111], v[184:187], v[192:195], v[108:111]
	v_mfma_f32_16x16x32_f16 v[100:103], v[174:177], v[214:217], v[100:103]
	v_mfma_f32_16x16x32_f16 v[92:95], v[184:187], v[214:217], v[92:95]
	v_mfma_f32_16x16x32_f16 v[84:87], v[174:177], v[222:225], v[84:87]
	v_mfma_f32_16x16x32_f16 v[76:79], v[184:187], v[222:225], v[76:79]
	v_mfma_f32_16x16x32_f16 v[68:71], v[174:177], v[230:233], v[68:71]
	v_mfma_f32_16x16x32_f16 v[64:67], v[184:187], v[230:233], v[64:67]
	s_barrier
	s_add_i32 s31, s31, s25
	v_lshl_add_u64 v[164:165], s[20:21], 0, v[152:153]
	s_mov_b32 m0, s31
	ds_read_b128 v[188:191], v179 offset:16384
	ds_read_b128 v[192:195], v179 offset:17408
	ds_read_b128 v[210:213], v179 offset:18432
	ds_read_b128 v[214:217], v179 offset:19456
	ds_read_b128 v[218:221], v179 offset:20480
	ds_read_b128 v[222:225], v179 offset:21504
	ds_read_b128 v[226:229], v179 offset:22528
	ds_read_b128 v[230:233], v179 offset:23552
	global_load_lds_dwordx4 v[164:165], off
	s_add_i32 m0, s31, 0x2000
	s_add_u32 s42, s20, 0x40000
	v_lshl_add_u64 v[166:167], s[20:21], 0, v[128:129]
	s_addc_u32 s43, s21, 0
	s_add_i32 s31, s44, s25
	global_load_lds_dwordx4 v[166:167], off
	v_lshl_add_u64 v[196:197], s[42:43], 0, v[152:153]
	s_mov_b32 m0, s31
	v_lshl_add_u64 v[204:205], s[22:23], 0, v[130:131]
	global_load_lds_dwordx4 v[196:197], off
	v_lshl_add_u64 v[196:197], s[42:43], 0, v[128:129]
	s_add_i32 m0, s31, 0x2000
	s_nop 0
	global_load_lds_dwordx4 v[196:197], off
	v_lshl_add_u64 v[196:197], s[22:23], 0, v[132:133]
	s_mov_b32 m0, s26
	s_nop 0
	global_load_lds_dwordx4 v[196:197], off
	s_mov_b32 m0, s27
	s_nop 0
	global_load_lds_dwordx4 v[204:205], off
	s_waitcnt vmcnt(8)
	s_waitcnt lgkmcnt(0)
	s_barrier
; #define PG8_STAGE(bufoff, gbase, voff) do { _Pragma("unroll") for (int _i = 0; _i < 2; ++_i) \
;         __builtin_amdgcn_global_load_lds((const unsigned*)((const char*)(gbase) + (voff)[_i]), (LAS unsigned*)(lds + (bufoff) + ldsw + _i * 8192), 16, 0, 0); } while (0)
; #define PG8_LDA(dst, b, h) do { _Pragma("unroll") for (int m = 0; m < 4; ++m) _Pragma("unroll") for (int k = 0; k < 2; ++k) dst[m][k] = *(const LAS h16x8*)(lds + PG8_SA(b, h) + aoff + m * 2048 + k * 1024); } while (0)
; #define PG8_LDB(dst, b, h) do { _Pragma("unroll") for (int n = 0; n < 2; ++n) _Pragma("unroll") for (int k = 0; k < 2; ++k) dst[n][k] = *(const LAS h16x8*)(lds + PG8_SB(b, h) + boff + n * 2048 + k * 1024); } while (0)
; #define PG8_MMA(ai, bj, At, Bt) do { __builtin_amdgcn_s_setprio(1); _Pragma("unroll") for (int m = 0; m < 4; ++m) _Pragma("unroll") for (int n = 0; n < 2; ++n) _Pragma("unroll") for (int k = 0; k < 2; ++k) \
;         acc[ai][bj][m][n] = __builtin_amdgcn_mfma_f32_16x16x32_f16(Bt[n][k], At[m][k], acc[ai][bj][m][n], 0, 0, 0); __builtin_amdgcn_s_setprio(0); } while (0)
; #define PG8_WAIT_V(n) asm volatile("s_waitcnt vmcnt(" #n ")" ::: "memory")
; #define PG8_WAIT_L(n) asm volatile("s_waitcnt lgkmcnt(" #n ")" ::: "memory")
; #define PG8_BAR __builtin_amdgcn_s_barrier()
; #define PG8_SCHED __builtin_amdgcn_sched_barrier(0)
; template <class Epi>
; __device__ __forceinline__ void gemm_phase(LAS unsigned char* lds, const Gemm g, const StaticOrder& S, const Epi& E, const int tid) {
;     ...
;             PG8_WAIT_V(8); PG8_WAIT_L(0); PG8_BAR; PG8_MMA(1, 0, At, B0); PG8_MMA(1, 1, At, B1); PG8_BAR; PG8_SCHED;
;             PG8_LDB(B0, 1, 0); PG8_LDB(B1, 1, 1); PG8_SCHED; PG8_LDA(At, 1, 0); PG8_STAGE(PG8_SA(0, 1), a2 + hstepA, voffA);
;             PG8_WAIT_V(8); PG8_WAIT_L(0); PG8_BAR; PG8_MMA(0, 0, At, B0); PG8_MMA(0, 1, At, B1); PG8_BAR; PG8_SCHED;
	s_waitcnt lgkmcnt(0)
	v_mfma_f32_16x16x32_f16 v[60:63], v[140:143], v[188:191], v[60:63]
	v_mfma_f32_16x16x32_f16 v[56:59], v[148:151], v[188:191], v[56:59]
	v_mfma_f32_16x16x32_f16 v[48:51], v[140:143], v[210:213], v[48:51]
	v_mfma_f32_16x16x32_f16 v[40:43], v[148:151], v[210:213], v[40:43]
	v_mfma_f32_16x16x32_f16 v[32:35], v[140:143], v[218:221], v[32:35]
	v_mfma_f32_16x16x32_f16 v[24:27], v[148:151], v[218:221], v[24:27]
	v_mfma_f32_16x16x32_f16 v[16:19], v[140:143], v[226:229], v[16:19]
	v_mfma_f32_16x16x32_f16 v[8:11], v[148:151], v[226:229], v[8:11]
	v_mfma_f32_16x16x32_f16 v[60:63], v[144:147], v[192:195], v[60:63]
	v_mfma_f32_16x16x32_f16 v[56:59], v[154:157], v[192:195], v[56:59]
	v_mfma_f32_16x16x32_f16 v[48:51], v[144:147], v[214:217], v[48:51]
	v_mfma_f32_16x16x32_f16 v[40:43], v[154:157], v[214:217], v[40:43]
	v_mfma_f32_16x16x32_f16 v[32:35], v[144:147], v[222:225], v[32:35]
	v_mfma_f32_16x16x32_f16 v[24:27], v[154:157], v[222:225], v[24:27]
	v_mfma_f32_16x16x32_f16 v[16:19], v[144:147], v[230:233], v[16:19]
	v_mfma_f32_16x16x32_f16 v[8:11], v[154:157], v[230:233], v[8:11]
	v_mfma_f32_16x16x32_f16 v[52:55], v[170:173], v[188:191], v[52:55]
	v_mfma_f32_16x16x32_f16 v[44:47], v[180:183], v[188:191], v[44:47]
	v_mfma_f32_16x16x32_f16 v[36:39], v[170:173], v[210:213], v[36:39]
	v_mfma_f32_16x16x32_f16 v[28:31], v[180:183], v[210:213], v[28:31]
	v_mfma_f32_16x16x32_f16 v[20:23], v[170:173], v[218:221], v[20:23]
	v_mfma_f32_16x16x32_f16 v[12:15], v[180:183], v[218:221], v[12:15]
	v_mfma_f32_16x16x32_f16 v[4:7], v[170:173], v[226:229], v[4:7]
	v_mfma_f32_16x16x32_f16 v[0:3], v[180:183], v[226:229], v[0:3]
	v_mfma_f32_16x16x32_f16 v[52:55], v[174:177], v[192:195], v[52:55]
	v_mfma_f32_16x16x32_f16 v[44:47], v[184:187], v[192:195], v[44:47]
	v_mfma_f32_16x16x32_f16 v[36:39], v[174:177], v[214:217], v[36:39]
	v_mfma_f32_16x16x32_f16 v[28:31], v[184:187], v[214:217], v[28:31]
	v_mfma_f32_16x16x32_f16 v[20:23], v[174:177], v[222:225], v[20:23]
	v_mfma_f32_16x16x32_f16 v[12:15], v[184:187], v[222:225], v[12:15]
	v_mfma_f32_16x16x32_f16 v[4:7], v[174:177], v[230:233], v[4:7]
	v_mfma_f32_16x16x32_f16 v[0:3], v[184:187], v[230:233], v[0:3]
	s_barrier
	s_add_i32 s31, 0, 0x18000
	s_add_i32 s42, 0, 0x1c000
	v_add_u32_e32 v154, s31, v163
	v_add_u32_e32 v184, s42, v163
	ds_read_b128 v[140:143], v154
	ds_read_b128 v[144:147], v154 offset:1024
	ds_read_b128 v[148:151], v154 offset:2048
	ds_read_b128 v[154:157], v154 offset:3072
	ds_read_b128 v[170:173], v184
	ds_read_b128 v[174:177], v184 offset:1024
	ds_read_b128 v[180:183], v184 offset:2048
	ds_read_b128 v[184:187], v184 offset:3072
	s_add_u32 s22, s22, 0x40000
	s_addc_u32 s23, s23, 0
	s_mov_b32 m0, s28
	v_lshl_add_u64 v[234:235], s[22:23], 0, v[132:133]
	ds_read_b128 v[188:191], v179 offset:32768
	ds_read_b128 v[192:195], v179 offset:33792
	ds_read_b128 v[210:213], v179 offset:34816
	ds_read_b128 v[214:217], v179 offset:35840
	ds_read_b128 v[218:221], v179 offset:36864
	ds_read_b128 v[222:225], v179 offset:37888
	ds_read_b128 v[226:229], v179 offset:38912
	ds_read_b128 v[230:233], v179 offset:39936
	global_load_lds_dwordx4 v[234:235], off
	v_lshl_add_u64 v[234:235], s[22:23], 0, v[130:131]
	s_mov_b32 m0, s29
	s_nop 0
	global_load_lds_dwordx4 v[234:235], off
	s_waitcnt vmcnt(8)
	s_waitcnt lgkmcnt(0)
	s_barrier
	s_waitcnt lgkmcnt(0)
	v_mfma_f32_16x16x32_f16 v[124:127], v[140:143], v[188:191], v[124:127]
	v_mfma_f32_16x16x32_f16 v[120:123], v[148:151], v[188:191], v[120:123]
	v_mfma_f32_16x16x32_f16 v[112:115], v[140:143], v[210:213], v[112:115]
	v_mfma_f32_16x16x32_f16 v[104:107], v[148:151], v[210:213], v[104:107]
	v_mfma_f32_16x16x32_f16 v[96:99], v[140:143], v[218:221], v[96:99]
	v_mfma_f32_16x16x32_f16 v[88:91], v[148:151], v[218:221], v[88:91]
	v_mfma_f32_16x16x32_f16 v[80:83], v[140:143], v[226:229], v[80:83]
	v_mfma_f32_16x16x32_f16 v[72:75], v[148:151], v[226:229], v[72:75]
	v_mfma_f32_16x16x32_f16 v[124:127], v[144:147], v[192:195], v[124:127]
	v_mfma_f32_16x16x32_f16 v[120:123], v[154:157], v[192:195], v[120:123]
	v_mfma_f32_16x16x32_f16 v[112:115], v[144:147], v[214:217], v[112:115]
	v_mfma_f32_16x16x32_f16 v[104:107], v[154:157], v[214:217], v[104:107]
	v_mfma_f32_16x16x32_f16 v[96:99], v[144:147], v[222:225], v[96:99]
	v_mfma_f32_16x16x32_f16 v[88:91], v[154:157], v[222:225], v[88:91]
	v_mfma_f32_16x16x32_f16 v[80:83], v[144:147], v[230:233], v[80:83]
	v_mfma_f32_16x16x32_f16 v[72:75], v[154:157], v[230:233], v[72:75]
	v_mfma_f32_16x16x32_f16 v[116:119], v[170:173], v[188:191], v[116:119]
	v_mfma_f32_16x16x32_f16 v[108:111], v[180:183], v[188:191], v[108:111]
	v_mfma_f32_16x16x32_f16 v[100:103], v[170:173], v[210:213], v[100:103]
	v_mfma_f32_16x16x32_f16 v[92:95], v[180:183], v[210:213], v[92:95]
	v_mfma_f32_16x16x32_f16 v[84:87], v[170:173], v[218:221], v[84:87]
	v_mfma_f32_16x16x32_f16 v[76:79], v[180:183], v[218:221], v[76:79]
	v_mfma_f32_16x16x32_f16 v[68:71], v[170:173], v[226:229], v[68:71]
	v_mfma_f32_16x16x32_f16 v[64:67], v[180:183], v[226:229], v[64:67]
	v_mfma_f32_16x16x32_f16 v[116:119], v[174:177], v[192:195], v[116:119]
	v_mfma_f32_16x16x32_f16 v[108:111], v[184:187], v[192:195], v[108:111]
	v_mfma_f32_16x16x32_f16 v[100:103], v[174:177], v[214:217], v[100:103]
	v_mfma_f32_16x16x32_f16 v[92:95], v[184:187], v[214:217], v[92:95]
	v_mfma_f32_16x16x32_f16 v[84:87], v[174:177], v[222:225], v[84:87]
	v_mfma_f32_16x16x32_f16 v[76:79], v[184:187], v[222:225], v[76:79]
	v_mfma_f32_16x16x32_f16 v[68:71], v[174:177], v[230:233], v[68:71]
	v_mfma_f32_16x16x32_f16 v[64:67], v[184:187], v[230:233], v[64:67]
	s_barrier
; #define PG8_STAGE(bufoff, gbase, voff) do { _Pragma("unroll") for (int _i = 0; _i < 2; ++_i) \
;         __builtin_amdgcn_global_load_lds((const unsigned*)((const char*)(gbase) + (voff)[_i]), (LAS unsigned*)(lds + (bufoff) + ldsw + _i * 8192), 16, 0, 0); } while (0)
; #define PG8_LDA(dst, b, h) do { _Pragma("unroll") for (int m = 0; m < 4; ++m) _Pragma("unroll") for (int k = 0; k < 2; ++k) dst[m][k] = *(const LAS h16x8*)(lds + PG8_SA(b, h) + aoff + m * 2048 + k * 1024); } while (0)
; #define PG8_MMA(ai, bj, At, Bt) do { __builtin_amdgcn_s_setprio(1); _Pragma("unroll") for (int m = 0; m < 4; ++m) _Pragma("unroll") for (int n = 0; n < 2; ++n) _Pragma("unroll") for (int k = 0; k < 2; ++k) \
;         acc[ai][bj][m][n] = __builtin_amdgcn_mfma_f32_16x16x32_f16(Bt[n][k], At[m][k], acc[ai][bj][m][n], 0, 0, 0); __builtin_amdgcn_s_setprio(0); } while (0)
; #define PG8_WAIT_V(n) asm volatile("s_waitcnt vmcnt(" #n ")" ::: "memory")
; #define PG8_WAIT_L(n) asm volatile("s_waitcnt lgkmcnt(" #n ")" ::: "memory")
; #define PG8_BAR __builtin_amdgcn_s_barrier()
; #define PG8_SCHED __builtin_amdgcn_sched_barrier(0)
; template <class Epi>
; __device__ __forceinline__ void gemm_phase(LAS unsigned char* lds, const Gemm g, const StaticOrder& S, const Epi& E, const int tid) {
;     ...
;             PG8_LDA(At, 1, 1); PG8_STAGE(PG8_SB(1, 0), b3, voffB); PG8_STAGE(PG8_SB(1, 1), b3 + hstepB, voffB); PG8_STAGE(PG8_SA(1, 0), a3, voffA);
;             PG8_WAIT_V(8); PG8_WAIT_L(0); PG8_BAR; PG8_MMA(1, 0, At, B0); PG8_MMA(1, 1, At, B1); PG8_BAR; PG8_SCHED;
;         }
;         if (wr == 0) PG8_BAR;
	s_add_i32 s22, s31, s25
	v_lshl_add_u64 v[164:165], v[164:165], 0, s[0:1]
	s_mov_b32 m0, s22
	ds_read_b128 v[188:191], v179 offset:49152
	ds_read_b128 v[192:195], v179 offset:50176
	ds_read_b128 v[210:213], v179 offset:51200
	ds_read_b128 v[214:217], v179 offset:52224
	ds_read_b128 v[218:221], v179 offset:53248
	ds_read_b128 v[222:225], v179 offset:54272
	ds_read_b128 v[226:229], v179 offset:55296
	ds_read_b128 v[230:233], v179 offset:56320
	global_load_lds_dwordx4 v[164:165], off
	s_add_i32 m0, s22, 0x2000
	s_add_u32 s20, s20, 0x40080
	v_lshl_add_u64 v[164:165], v[166:167], 0, s[0:1]
	s_addc_u32 s21, s21, 0
	s_add_i32 s22, s42, s25
	global_load_lds_dwordx4 v[164:165], off
	v_lshl_add_u64 v[164:165], s[20:21], 0, v[152:153]
	s_mov_b32 m0, s22
	s_nop 0
	global_load_lds_dwordx4 v[164:165], off
	v_lshl_add_u64 v[164:165], s[20:21], 0, v[128:129]
	s_add_i32 m0, s22, 0x2000
	s_nop 0
	global_load_lds_dwordx4 v[164:165], off
	v_lshl_add_u64 v[164:165], v[196:197], 0, s[0:1]
	s_mov_b32 m0, s34
	s_nop 0
	global_load_lds_dwordx4 v[164:165], off
	v_lshl_add_u64 v[164:165], v[204:205], 0, s[0:1]
	s_mov_b32 m0, s35
	s_nop 0
	global_load_lds_dwordx4 v[164:165], off
	s_waitcnt vmcnt(8)
	s_waitcnt lgkmcnt(0)
	s_barrier
	s_waitcnt lgkmcnt(0)
	v_mfma_f32_16x16x32_f16 v[60:63], v[140:143], v[188:191], v[60:63]
	v_mfma_f32_16x16x32_f16 v[56:59], v[148:151], v[188:191], v[56:59]
	v_mfma_f32_16x16x32_f16 v[48:51], v[140:143], v[210:213], v[48:51]
	v_mfma_f32_16x16x32_f16 v[40:43], v[148:151], v[210:213], v[40:43]
	v_mfma_f32_16x16x32_f16 v[32:35], v[140:143], v[218:221], v[32:35]
	v_mfma_f32_16x16x32_f16 v[24:27], v[148:151], v[218:221], v[24:27]
	v_mfma_f32_16x16x32_f16 v[16:19], v[140:143], v[226:229], v[16:19]
	v_mfma_f32_16x16x32_f16 v[8:11], v[148:151], v[226:229], v[8:11]
	v_mfma_f32_16x16x32_f16 v[60:63], v[144:147], v[192:195], v[60:63]
	v_mfma_f32_16x16x32_f16 v[56:59], v[154:157], v[192:195], v[56:59]
	v_mfma_f32_16x16x32_f16 v[48:51], v[144:147], v[214:217], v[48:51]
	v_mfma_f32_16x16x32_f16 v[40:43], v[154:157], v[214:217], v[40:43]
	v_mfma_f32_16x16x32_f16 v[32:35], v[144:147], v[222:225], v[32:35]
	v_mfma_f32_16x16x32_f16 v[24:27], v[154:157], v[222:225], v[24:27]
	v_mfma_f32_16x16x32_f16 v[16:19], v[144:147], v[230:233], v[16:19]
	v_mfma_f32_16x16x32_f16 v[8:11], v[154:157], v[230:233], v[8:11]
	v_mfma_f32_16x16x32_f16 v[52:55], v[170:173], v[188:191], v[52:55]
	v_mfma_f32_16x16x32_f16 v[44:47], v[180:183], v[188:191], v[44:47]
	v_mfma_f32_16x16x32_f16 v[36:39], v[170:173], v[210:213], v[36:39]
	v_mfma_f32_16x16x32_f16 v[28:31], v[180:183], v[210:213], v[28:31]
	v_mfma_f32_16x16x32_f16 v[20:23], v[170:173], v[218:221], v[20:23]
	v_mfma_f32_16x16x32_f16 v[12:15], v[180:183], v[218:221], v[12:15]
	v_mfma_f32_16x16x32_f16 v[4:7], v[170:173], v[226:229], v[4:7]
	v_mfma_f32_16x16x32_f16 v[0:3], v[180:183], v[226:229], v[0:3]
	v_mfma_f32_16x16x32_f16 v[52:55], v[174:177], v[192:195], v[52:55]
	v_mfma_f32_16x16x32_f16 v[44:47], v[184:187], v[192:195], v[44:47]
	v_mfma_f32_16x16x32_f16 v[36:39], v[174:177], v[214:217], v[36:39]
	v_mfma_f32_16x16x32_f16 v[28:31], v[184:187], v[214:217], v[28:31]
	v_mfma_f32_16x16x32_f16 v[20:23], v[174:177], v[222:225], v[20:23]
	v_mfma_f32_16x16x32_f16 v[12:15], v[184:187], v[222:225], v[12:15]
	v_mfma_f32_16x16x32_f16 v[4:7], v[174:177], v[230:233], v[4:7]
	v_mfma_f32_16x16x32_f16 v[0:3], v[184:187], v[230:233], v[0:3]
	s_barrier
	s_add_i32 s41, s41, 2
	s_add_u32 s8, s8, 0x100
	s_addc_u32 s9, s9, 0
	s_add_u32 s2, s2, 0x100
	s_addc_u32 s3, s3, 0
	s_cmp_gt_u32 s41, 13
	s_cbranch_scc0 .LBB0_373
	s_and_b64 vcc, exec, s[10:11]
	s_cbranch_vccz .LBB0_376
	s_barrier

; template <int R>
; __device__ __forceinline__ void scan_item(const Args& a, int layer, int q, int rowhalf, LAS unsigned char* lds, int tid, int lane, int wave) {
;     ...
;     if (wave >= 4) {
;         const int pw = wave - 4, j = lane, col = h * 64 + j;
;         const float* mu = a.in[I_MU] + l * 1920;
;         const float mu_r = mu[col], mu_k = mu[512 + col], mu_v = mu[1024 + col], mu_wl = mu[1536 + d * 64 + j], mu_al = mu[1536 + 128 + d * 64 + j];
;         const float k_k = a.in[I_KK][l * 512 + col], k_a = a.in[I_KA][l * 512 + col], r_k = a.in[I_RK][l * 512 + col];
;         const float w0 = a.in[I_W0][(l * 2 + d) * 512 + col], a0 = a.in[I_A0][(l * 2 + d) * 512 + col];
;         h16x8 bw[4][2], ba[4][2];
;         { const int n = lane & 15, kg = lane >> 4;
;           const float* wu = a.in[I_WUP] + ((l * 2 + d) * 64 + 8 * kg) * 512 + h * 64 + n; const float* au = a.in[I_AUP] + ((l * 2 + d) * 64 + 8 * kg) * 512 + h * 64 + n;
; #pragma unroll
;           for (int ks = 0; ks < 2; ++ks) {
; #pragma unroll
;               for (int e = 0; e < 8; ++e) {
;                   const float w_0 = wu[0], w_1 = wu[16], w_2 = wu[32], w_3 = wu[48], a_0 = au[0], a_1 = au[16], a_2 = au[32], a_3 = au[48];
;                   wu += 512; au += 512; asm volatile("" : "+v"(wu), "+v"(au));
;                   bw[0][ks][e] = (h16)w_0; bw[1][ks][e] = (h16)w_1; bw[2][ks][e] = (h16)w_2; bw[3][ks][e] = (h16)w_3;
;                   ba[0][ks][e] = (h16)a_0; ba[1][ks][e] = (h16)a_1; ba[2][ks][e] = (h16)a_2; ba[3][ks][e] = (h16)a_3; }
;               wu += 24 * 512; au += 24 * 512; asm volatile("" : "+v"(wu), "+v"(au)); } }
.LBB0_423:
	v_and_b32_e32 v171, 63, v190
	s_and_b64 vcc, exec, s[2:3]
	v_writelane_b32 v254, s10, 51
	s_cbranch_vccz .LBB0_446
	s_setprio 0
	v_readlane_b32 s4, v248, 16
	s_mul_i32 s2, s74, 0x1e00
	v_readlane_b32 s10, v248, 22
	v_or_b32_e32 v64, s76, v171
	v_readlane_b32 s11, v248, 23
	s_add_u32 s2, s10, s2
	v_readlane_b32 s5, v248, 17
	s_addc_u32 s3, s11, 0
	v_lshlrev_b32_e32 v152, 2, v64
	v_lshl_add_u64 v[0:1], s[2:3], 0, v[152:153]
	s_movk_i32 s5, 0x1000
	v_add_co_u32_e32 v0, vcc, s5, v0
	v_readlane_b32 s4, v249, 39
	s_nop 0
	v_addc_co_u32_e32 v1, vcc, 0, v1, vcc
	global_load_dword v97, v152, s[2:3]
	global_load_dword v100, v152, s[2:3] offset:2048
	global_load_dword v101, v[0:1], off
	v_or_b32_e32 v0, s4, v171
	v_lshlrev_b32_e32 v0, 2, v0
	v_mov_b32_e32 v1, v153
	v_lshl_add_u64 v[0:1], s[2:3], 0, v[0:1]
	v_add_co_u32_e32 v0, vcc, s5, v0
	s_lshl_b64 s[2:3], s[74:75], 11
	s_nop 0
	v_addc_co_u32_e32 v1, vcc, 0, v1, vcc
	v_readlane_b32 s52, v248, 32
	v_readlane_b32 s4, v253, 16
	global_load_dword v102, v[0:1], off offset:2048
	global_load_dword v103, v[0:1], off offset:2560
	v_or_b32_e32 v0, s2, v152
	v_mov_b32_e32 v1, s3
	v_readlane_b32 s54, v248, 34
	v_readlane_b32 s55, v248, 35
	s_lshl_b64 s[2:3], s[74:75], 1
	v_readlane_b32 s5, v253, 17
	v_readlane_b32 s56, v248, 36
	v_readlane_b32 s57, v248, 37
	v_readlane_b32 s58, v248, 38
	v_readlane_b32 s59, v248, 39
	v_lshl_add_u64 v[2:3], s[54:55], 0, v[0:1]
	s_or_b64 s[2:3], s[2:3], s[4:5]
	global_load_dword v104, v[2:3], off
	v_lshl_add_u64 v[2:3], s[56:57], 0, v[0:1]
	v_lshl_add_u64 v[0:1], s[58:59], 0, v[0:1]
	s_lshl_b64 s[4:5], s[2:3], 11
	v_readlane_b32 s12, v248, 24
	v_readlane_b32 s13, v248, 25
	v_readlane_b32 s16, v248, 28
	v_readlane_b32 s17, v248, 29
	global_load_dword v106, v[0:1], off
	v_or_b32_e32 v0, s4, v152
	v_mov_b32_e32 v1, s5
	global_load_dword v105, v[2:3], off
	v_lshl_add_u64 v[2:3], s[12:13], 0, v[0:1]
	v_lshl_add_u64 v[0:1], s[16:17], 0, v[0:1]
	v_lshrrev_b32_e32 v65, 4, v171
	s_lshl_b64 s[2:3], s[2:3], 17
	global_load_dword v108, v[0:1], off
	v_lshl_or_b32 v0, v65, 14, s2
	v_mov_b32_e32 v1, s3
	v_readlane_b32 s2, v249, 40
	v_readlane_b32 s3, v249, 41
	global_load_dword v107, v[2:3], off
	v_lshlrev_b32_e32 v4, 2, v190
	v_lshl_add_u64 v[2:3], s[2:3], 0, v[0:1]
	v_readlane_b32 s2, v249, 42
	v_readlane_b32 s3, v249, 43
	v_and_b32_e32 v152, 60, v4
	v_lshl_add_u64 v[2:3], v[2:3], 0, v[152:153]
	v_lshl_add_u64 v[0:1], s[2:3], 0, v[0:1]
	v_lshl_add_u64 v[0:1], v[0:1], 0, v[152:153]
	s_mov_b64 s[2:3], 0x800
	global_load_dword v4, v[2:3], off
	global_load_dword v8, v[2:3], off offset:64
	global_load_dword v12, v[2:3], off offset:128
	global_load_dword v16, v[2:3], off offset:192
	global_load_dword v20, v[0:1], off
	global_load_dword v24, v[0:1], off offset:64
	global_load_dword v28, v[0:1], off offset:128
	global_load_dword v36, v[0:1], off offset:192
	v_lshl_add_u64 v[2:3], v[2:3], 0, s[2:3]
	v_lshl_add_u64 v[0:1], v[0:1], 0, s[2:3]
	flat_load_dword v5, v[2:3]
	flat_load_dword v9, v[2:3] offset:64
	flat_load_dword v13, v[2:3] offset:128
	flat_load_dword v17, v[2:3] offset:192
	flat_load_dword v21, v[0:1]
	flat_load_dword v25, v[0:1] offset:64
	flat_load_dword v29, v[0:1] offset:128
	flat_load_dword v37, v[0:1] offset:192
	v_lshl_add_u64 v[2:3], v[2:3], 0, s[2:3]
	v_lshl_add_u64 v[0:1], v[0:1], 0, s[2:3]
	flat_load_dword v6, v[2:3]
	flat_load_dword v10, v[2:3] offset:64
	flat_load_dword v14, v[2:3] offset:128
	flat_load_dword v18, v[2:3] offset:192
	flat_load_dword v22, v[0:1]
	flat_load_dword v26, v[0:1] offset:64
	flat_load_dword v30, v[0:1] offset:128
	flat_load_dword v38, v[0:1] offset:192
	v_lshl_add_u64 v[2:3], v[2:3], 0, s[2:3]
	v_lshl_add_u64 v[0:1], v[0:1], 0, s[2:3]
	flat_load_dword v7, v[2:3]
	flat_load_dword v11, v[2:3] offset:64
	flat_load_dword v15, v[2:3] offset:128
	flat_load_dword v19, v[2:3] offset:192
	flat_load_dword v23, v[0:1]
	flat_load_dword v27, v[0:1] offset:64
	flat_load_dword v31, v[0:1] offset:128
	flat_load_dword v39, v[0:1] offset:192
	v_lshl_add_u64 v[2:3], v[2:3], 0, s[2:3]
	v_lshl_add_u64 v[0:1], v[0:1], 0, s[2:3]
	flat_load_dword v40, v[2:3]
	flat_load_dword v41, v[2:3] offset:64
	flat_load_dword v42, v[2:3] offset:128
	flat_load_dword v43, v[2:3] offset:192
	flat_load_dword v44, v[0:1]
	flat_load_dword v45, v[0:1] offset:64
	flat_load_dword v46, v[0:1] offset:128
	flat_load_dword v47, v[0:1] offset:192
	v_lshl_add_u64 v[2:3], v[2:3], 0, s[2:3]
	v_lshl_add_u64 v[0:1], v[0:1], 0, s[2:3]
	flat_load_dword v48, v[2:3]
	flat_load_dword v49, v[2:3] offset:64
	flat_load_dword v50, v[2:3] offset:128
	flat_load_dword v51, v[2:3] offset:192
	flat_load_dword v52, v[0:1]
	flat_load_dword v53, v[0:1] offset:64
	flat_load_dword v54, v[0:1] offset:128
	flat_load_dword v55, v[0:1] offset:192
	v_lshl_add_u64 v[2:3], v[2:3], 0, s[2:3]
	v_lshl_add_u64 v[0:1], v[0:1], 0, s[2:3]
	flat_load_dword v56, v[2:3]
	flat_load_dword v57, v[2:3] offset:64
	flat_load_dword v58, v[2:3] offset:128
	flat_load_dword v59, v[2:3] offset:192
	flat_load_dword v60, v[0:1]
	flat_load_dword v61, v[0:1] offset:64
	flat_load_dword v62, v[0:1] offset:128
	flat_load_dword v63, v[0:1] offset:192
	v_lshl_add_u64 v[2:3], v[2:3], 0, s[2:3]
	v_lshl_add_u64 v[0:1], v[0:1], 0, s[2:3]
	flat_load_dword v66, v[2:3]
	flat_load_dword v67, v[2:3] offset:64
	flat_load_dword v68, v[2:3] offset:128
	flat_load_dword v69, v[2:3] offset:192
	flat_load_dword v70, v[0:1]
	flat_load_dword v71, v[0:1] offset:64
	flat_load_dword v72, v[0:1] offset:128
	flat_load_dword v73, v[0:1] offset:192
	v_lshl_add_u64 v[32:33], v[2:3], 0, s[2:3]
	v_lshl_add_u64 v[34:35], v[0:1], 0, s[2:3]
	s_mov_b64 s[4:5], 0xc000
	v_lshl_add_u64 v[32:33], v[32:33], 0, s[4:5]
	v_lshl_add_u64 v[34:35], v[34:35], 0, s[4:5]
	v_readlane_b32 s35, v254, 48
	s_add_i32 s29, s35, -4
	v_readlane_b32 s8, v248, 20
	v_readlane_b32 s6, v248, 18
	v_readlane_b32 s7, v248, 19
	v_readlane_b32 s31, v253, 52
	v_readlane_b32 s9, v248, 21
	v_readlane_b32 s18, v248, 30
	v_readlane_b32 s19, v248, 31
	v_readlane_b32 s18, v249, 33
	v_readlane_b32 s19, v249, 34
	v_readlane_b32 s20, v249, 35
	v_readlane_b32 s22, v249, 37
	v_readlane_b32 s36, v253, 12
	v_readlane_b32 s21, v249, 36
	v_readlane_b32 s23, v249, 38
	v_readlane_b32 s37, v253, 13
	v_readlane_b32 s14, v248, 26
	v_readlane_b32 s15, v248, 27
	v_lshlrev_b32_e32 v65, 10, v65
	s_mov_b32 s27, 0
	s_mov_b32 s28, 1
	v_mov_b32_e32 v163, 0xfff
	v_cmp_eq_u32_e64 s[24:25], 0, v171
	v_lshlrev_b32_e32 v240, 1, v64
	v_readlane_b32 s53, v248, 33
	v_readlane_b32 s60, v248, 40
	v_readlane_b32 s61, v248, 41
	v_readlane_b32 s62, v248, 42
	v_readlane_b32 s63, v248, 43
	v_readlane_b32 s64, v248, 44
	v_readlane_b32 s65, v248, 45
	v_readlane_b32 s66, v248, 46
	v_readlane_b32 s67, v248, 47
	s_waitcnt vmcnt(0) lgkmcnt(0)
; #define LAS __attribute__((address_space(3)))
; template <int R>
; __device__ __forceinline__ void scan_item(const Args& a, int layer, int q, int rowhalf, LAS unsigned char* lds, int tid, int lane, int wave) {
;     ...
;         { const int n = lane & 15, kg = lane >> 4;
;           const float* wu = a.in[I_WUP] + ((l * 2 + d) * 64 + 8 * kg) * 512 + h * 64 + n; const float* au = a.in[I_AUP] + ((l * 2 + d) * 64 + 8 * kg) * 512 + h * 64 + n;
; #pragma unroll
;           for (int ks = 0; ks < 2; ++ks) {
; #pragma unroll
;               for (int e = 0; e < 8; ++e) {
;                   const float w_0 = wu[0], w_1 = wu[16], w_2 = wu[32], w_3 = wu[48], a_0 = au[0], a_1 = au[16], a_2 = au[32], a_3 = au[48];
;                   wu += 512; au += 512; asm volatile("" : "+v"(wu), "+v"(au));
;                   bw[0][ks][e] = (h16)w_0; bw[1][ks][e] = (h16)w_1; bw[2][ks][e] = (h16)w_2; bw[3][ks][e] = (h16)w_3;
;                   ba[0][ks][e] = (h16)a_0; ba[1][ks][e] = (h16)a_1; ba[2][ks][e] = (h16)a_2; ba[3][ks][e] = (h16)a_3; }
;               wu += 24 * 512; au += 24 * 512; asm volatile("" : "+v"(wu), "+v"(au)); } }
;         LAS float* zl = (LAS float*)(lds + SC_ZOFF + pw * 4096);
;         LAS unsigned char* xsb = lds + SC_XOFF + pw * 2048;
;         ScanWin cur; ScanWinRaw nxt;
	v_cvt_pk_f16_f32 v0, v4, v5
	v_cvt_pk_f16_f32 v4, v8, v9
	v_cvt_pk_f16_f32 v8, v12, v13
	v_cvt_pk_f16_f32 v12, v16, v17
	v_cvt_pk_f16_f32 v16, v20, v21
	v_cvt_pk_f16_f32 v20, v24, v25
	v_cvt_pk_f16_f32 v24, v28, v29
	v_cvt_pk_f16_f32 v28, v36, v37
	v_cvt_pk_f16_f32 v1, v6, v7
	v_cvt_pk_f16_f32 v5, v10, v11
	v_cvt_pk_f16_f32 v9, v14, v15
	v_cvt_pk_f16_f32 v13, v18, v19
	v_cvt_pk_f16_f32 v17, v22, v23
	v_cvt_pk_f16_f32 v21, v26, v27
	v_cvt_pk_f16_f32 v25, v30, v31
	v_cvt_pk_f16_f32 v29, v38, v39
	v_cvt_pk_f16_f32 v2, v40, v48
	v_cvt_pk_f16_f32 v6, v41, v49
	v_cvt_pk_f16_f32 v10, v42, v50
	v_cvt_pk_f16_f32 v14, v43, v51
	v_cvt_pk_f16_f32 v18, v44, v52
	v_cvt_pk_f16_f32 v22, v45, v53
	v_cvt_pk_f16_f32 v26, v46, v54
	v_cvt_pk_f16_f32 v30, v47, v55
	v_cvt_pk_f16_f32 v3, v56, v66
	v_cvt_pk_f16_f32 v7, v57, v67
	v_cvt_pk_f16_f32 v11, v58, v68
	v_cvt_pk_f16_f32 v15, v59, v69
	v_cvt_pk_f16_f32 v19, v60, v70
	flat_load_dword v36, v[32:33]
	flat_load_dword v40, v[32:33] offset:64
	flat_load_dword v44, v[32:33] offset:128
	flat_load_dword v48, v[32:33] offset:192
	flat_load_dword v52, v[34:35]
	flat_load_dword v56, v[34:35] offset:64
	flat_load_dword v60, v[34:35] offset:128
	flat_load_dword v70, v[34:35] offset:192
	v_lshl_add_u64 v[32:33], v[32:33], 0, s[2:3]
	v_lshl_add_u64 v[34:35], v[34:35], 0, s[2:3]
	v_cvt_pk_f16_f32 v23, v61, v71
	flat_load_dword v37, v[32:33]
	flat_load_dword v41, v[32:33] offset:64
	flat_load_dword v45, v[32:33] offset:128
	flat_load_dword v49, v[32:33] offset:192
	flat_load_dword v53, v[34:35]
	flat_load_dword v57, v[34:35] offset:64
	flat_load_dword v61, v[34:35] offset:128
	flat_load_dword v71, v[34:35] offset:192
	v_lshl_add_u64 v[32:33], v[32:33], 0, s[2:3]
	v_lshl_add_u64 v[34:35], v[34:35], 0, s[2:3]
	v_cvt_pk_f16_f32 v27, v62, v72
	flat_load_dword v38, v[32:33]
	flat_load_dword v42, v[32:33] offset:64
	flat_load_dword v46, v[32:33] offset:128
	flat_load_dword v50, v[32:33] offset:192
	flat_load_dword v54, v[34:35]
	flat_load_dword v58, v[34:35] offset:64
	flat_load_dword v62, v[34:35] offset:128
	flat_load_dword v72, v[34:35] offset:192
	v_lshl_add_u64 v[32:33], v[32:33], 0, s[2:3]
	v_lshl_add_u64 v[34:35], v[34:35], 0, s[2:3]
	v_cvt_pk_f16_f32 v31, v63, v73
	flat_load_dword v39, v[32:33]
	flat_load_dword v43, v[32:33] offset:64
	flat_load_dword v47, v[32:33] offset:128
	flat_load_dword v51, v[32:33] offset:192
	flat_load_dword v55, v[34:35]
	flat_load_dword v59, v[34:35] offset:64
	flat_load_dword v63, v[34:35] offset:128
	flat_load_dword v73, v[34:35] offset:192
	v_lshl_add_u64 v[32:33], v[32:33], 0, s[2:3]
	v_lshl_add_u64 v[34:35], v[34:35], 0, s[2:3]
	flat_load_dword v74, v[32:33]
	flat_load_dword v75, v[32:33] offset:64
	flat_load_dword v76, v[32:33] offset:128
	flat_load_dword v77, v[32:33] offset:192
	flat_load_dword v78, v[34:35]
	flat_load_dword v79, v[34:35] offset:64
	flat_load_dword v80, v[34:35] offset:128
	flat_load_dword v81, v[34:35] offset:192
	v_lshl_add_u64 v[32:33], v[32:33], 0, s[2:3]
	v_lshl_add_u64 v[34:35], v[34:35], 0, s[2:3]
	flat_load_dword v82, v[32:33]
	flat_load_dword v83, v[32:33] offset:64
	flat_load_dword v84, v[32:33] offset:128
	flat_load_dword v85, v[32:33] offset:192
	flat_load_dword v86, v[34:35]
	flat_load_dword v87, v[34:35] offset:64
	flat_load_dword v88, v[34:35] offset:128
	flat_load_dword v89, v[34:35] offset:192
	v_lshl_add_u64 v[32:33], v[32:33], 0, s[2:3]
	v_lshl_add_u64 v[34:35], v[34:35], 0, s[2:3]
	flat_load_dword v90, v[32:33]
	flat_load_dword v91, v[32:33] offset:64
	flat_load_dword v92, v[32:33] offset:128
	flat_load_dword v93, v[32:33] offset:192
	flat_load_dword v94, v[34:35]
	flat_load_dword v95, v[34:35] offset:64
	flat_load_dword v96, v[34:35] offset:128
	flat_load_dword v98, v[34:35] offset:192
	v_lshl_add_u64 v[32:33], v[32:33], 0, s[2:3]
	v_lshl_add_u64 v[34:35], v[34:35], 0, s[2:3]
	flat_load_dword v99, v[32:33]
	flat_load_dword v109, v[32:33] offset:64
	flat_load_dword v110, v[32:33] offset:128
	flat_load_dword v111, v[32:33] offset:192
	flat_load_dword v112, v[34:35]
	flat_load_dword v113, v[34:35] offset:64
	flat_load_dword v114, v[34:35] offset:128
	flat_load_dword v115, v[34:35] offset:192
	v_lshl_add_u64 v[66:67], v[32:33], 0, s[2:3]
	v_lshl_add_u64 v[68:69], v[34:35], 0, s[2:3]
	s_lshl_b32 s2, s29, 3
	v_lshl_add_u64 v[66:67], v[66:67], 0, s[4:5]
	v_lshl_add_u64 v[68:69], v[68:69], 0, s[4:5]
	s_lshl_b32 s4, s29, 12
	s_lshl_b32 s3, s29, 11
	s_add_i32 s5, s2, -1
	s_sub_i32 s8, 0x1000, s2
	s_and_b64 s[6:7], s[78:79], exec
	s_cselect_b32 s7, s5, s8
	s_mulk_i32 s29, 0x3000
	s_waitcnt vmcnt(0) lgkmcnt(0)
; template <int R>
; __device__ __forceinline__ void scan_item(const Args& a, int layer, int q, int rowhalf, LAS unsigned char* lds, int tid, int lane, int wave) {
;     ...
;         SCAN_LOAD_RAW(0); SCAN_UNPACK(0);
	v_cvt_pk_f16_f32 v32, v36, v37
	v_cvt_pk_f16_f32 v36, v40, v41
	v_cvt_pk_f16_f32 v40, v44, v45
	v_cvt_pk_f16_f32 v44, v48, v49
	v_cvt_pk_f16_f32 v48, v52, v53
	v_cvt_pk_f16_f32 v52, v56, v57
	v_cvt_pk_f16_f32 v56, v60, v61
	v_cvt_pk_f16_f32 v60, v70, v71
	v_cvt_pk_f16_f32 v33, v38, v39
	v_cvt_pk_f16_f32 v37, v42, v43
	v_cvt_pk_f16_f32 v41, v46, v47
	v_cvt_pk_f16_f32 v45, v50, v51
	v_cvt_pk_f16_f32 v49, v54, v55
	v_cvt_pk_f16_f32 v53, v58, v59
	v_cvt_pk_f16_f32 v57, v62, v63
	v_cvt_pk_f16_f32 v61, v72, v73
	v_mov_b32_e32 v73, 0xfff
	v_med3_i32 v66, s7, 0, v73
	v_lshlrev_b32_e32 v72, 1, v64
	v_readfirstlane_b32 s5, v66
	s_or_b32 s92, s5, s31
	s_lshl_b64 s[8:9], s[92:93], 10
	v_or_b32_e32 v66, s8, v72
	v_mov_b32_e32 v67, s9
	s_mul_i32 s6, s92, 0x300
	v_lshl_add_u64 v[68:69], s[18:19], 0, v[66:67]
	s_mul_hi_u32 s5, s92, 0x300
	s_add_u32 s8, s36, s6
	v_cvt_pk_f16_f32 v39, v91, v109
	global_load_ushort v109, v[68:69], off
	v_lshl_add_u64 v[68:69], s[20:21], 0, v[66:67]
	v_lshl_add_u64 v[66:67], s[22:23], 0, v[66:67]
	s_addc_u32 s9, s37, s5
	s_or_b32 s34, s2, 1
	v_cvt_pk_f16_f32 v43, v92, v110
	v_cvt_pk_f16_f32 v47, v93, v111
	global_load_ushort v110, v[68:69], off
	global_load_ushort v111, v[66:67], off
	v_lshlrev_b32_e32 v66, 1, v171
	s_sub_i32 s5, 0x1000, s34
	v_cvt_pk_f16_f32 v51, v94, v112
	v_cvt_pk_f16_f32 v55, v95, v113
	global_load_ushort v112, v66, s[8:9]
	global_load_ushort v113, v66, s[8:9] offset:256
	s_and_b64 s[8:9], s[78:79], exec
	s_cselect_b32 s6, s2, s5
	v_med3_i32 v68, s6, 0, v73
	v_cvt_pk_f16_f32 v59, v96, v114
	v_readfirstlane_b32 s5, v68
	s_or_b32 s92, s5, s31
	s_lshl_b64 s[8:9], s[92:93], 10
	v_or_b32_e32 v68, s8, v72
	s_mul_i32 s8, s92, 0x300
	v_mov_b32_e32 v69, s9
	s_mul_hi_u32 s5, s92, 0x300
	s_add_u32 s8, s36, s8
	v_lshl_add_u64 v[70:71], s[18:19], 0, v[68:69]
	s_addc_u32 s9, s37, s5
	s_or_b32 s10, s2, 2
	global_load_ushort v114, v[70:71], off
	v_lshl_add_u64 v[70:71], s[20:21], 0, v[68:69]
	v_lshl_add_u64 v[68:69], s[22:23], 0, v[68:69]
	s_sub_i32 s5, 0x1000, s10
	v_cvt_pk_f16_f32 v63, v98, v115
	global_load_ushort v115, v[70:71], off
	global_load_ushort v116, v[68:69], off
	global_load_ushort v117, v66, s[8:9]
	global_load_ushort v118, v66, s[8:9] offset:256
	s_and_b64 s[8:9], s[78:79], exec
	s_cselect_b32 s5, s34, s5
	v_med3_i32 v68, s5, 0, v73
	v_mov_b32_e32 v67, v153
	v_readfirstlane_b32 s8, v68
	s_or_b32 s92, s8, s31
	s_lshl_b64 s[8:9], s[92:93], 10
	v_or_b32_e32 v68, s8, v72
	s_mul_i32 s8, s92, 0x300
	v_mov_b32_e32 v69, s9
	s_mul_hi_u32 s9, s92, 0x300
	s_add_u32 s8, s36, s8
	v_lshl_add_u64 v[70:71], s[18:19], 0, v[68:69]
	s_addc_u32 s9, s37, s9
	s_or_b32 s12, s2, 3
	global_load_ushort v119, v[70:71], off
	v_lshl_add_u64 v[70:71], s[20:21], 0, v[68:69]
	v_lshl_add_u64 v[68:69], s[22:23], 0, v[68:69]
	s_sub_i32 s11, 0x1000, s12
	global_load_ushort v120, v[70:71], off
	global_load_ushort v121, v[68:69], off
	global_load_ushort v122, v66, s[8:9]
	global_load_ushort v123, v66, s[8:9] offset:256
	s_and_b64 s[8:9], s[78:79], exec
	s_cselect_b32 s9, s10, s11
	v_med3_i32 v68, s9, 0, v73
	v_cvt_pk_f16_f32 v35, v90, v99
	v_readfirstlane_b32 s8, v68
	s_or_b32 s92, s8, s31
	s_lshl_b64 s[10:11], s[92:93], 10
	v_or_b32_e32 v68, s10, v72
	s_mul_i32 s10, s92, 0x300
	v_mov_b32_e32 v69, s11
	s_mul_hi_u32 s8, s92, 0x300
	s_add_u32 s10, s36, s10
	v_lshl_add_u64 v[70:71], s[18:19], 0, v[68:69]
	s_addc_u32 s11, s37, s8
	s_or_b32 s13, s2, 4
	global_load_ushort v124, v[70:71], off
	v_lshl_add_u64 v[70:71], s[20:21], 0, v[68:69]
	v_lshl_add_u64 v[68:69], s[22:23], 0, v[68:69]
	s_sub_i32 s8, 0x1000, s13
	global_load_ushort v125, v[70:71], off
	global_load_ushort v126, v[68:69], off
	global_load_ushort v127, v66, s[10:11]
	global_load_ushort v128, v66, s[10:11] offset:256
	s_and_b64 s[10:11], s[78:79], exec
	s_cselect_b32 s8, s12, s8
	v_med3_i32 v68, s8, 0, v73
	v_lshl_add_u64 v[98:99], s[36:37], 0, v[66:67]
	v_readfirstlane_b32 s10, v68
	s_or_b32 s92, s10, s31
	s_lshl_b64 s[10:11], s[92:93], 10
	v_or_b32_e32 v68, s10, v72
	s_mul_i32 s10, s92, 0x300
	v_mov_b32_e32 v69, s11
	s_mul_hi_u32 s11, s92, 0x300
	s_add_u32 s10, s36, s10
	v_lshl_add_u64 v[70:71], s[18:19], 0, v[68:69]
	s_addc_u32 s11, s37, s11
	s_or_b32 s14, s2, 5
	global_load_ushort v129, v[70:71], off
	v_lshl_add_u64 v[70:71], s[20:21], 0, v[68:69]
	v_lshl_add_u64 v[68:69], s[22:23], 0, v[68:69]
	s_sub_i32 s12, 0x1000, s14
	global_load_ushort v130, v[70:71], off
	global_load_ushort v131, v[68:69], off
	global_load_ushort v132, v66, s[10:11]
	global_load_ushort v133, v66, s[10:11] offset:256
	s_and_b64 s[10:11], s[78:79], exec
	s_cselect_b32 s10, s13, s12
	v_med3_i32 v68, s10, 0, v73
	v_cvt_pk_f16_f32 v34, v74, v82
	v_readfirstlane_b32 s11, v68
	s_or_b32 s92, s11, s31
	s_lshl_b64 s[12:13], s[92:93], 10
	v_or_b32_e32 v68, s12, v72
	s_mul_i32 s12, s92, 0x300
	v_mov_b32_e32 v69, s13
	s_mul_hi_u32 s11, s92, 0x300
	s_add_u32 s12, s36, s12
	v_lshl_add_u64 v[70:71], s[18:19], 0, v[68:69]
	s_addc_u32 s13, s37, s11
	s_or_b32 s11, s2, 6
	global_load_ushort v134, v[70:71], off
	v_lshl_add_u64 v[70:71], s[20:21], 0, v[68:69]
	v_lshl_add_u64 v[68:69], s[22:23], 0, v[68:69]
	s_sub_i32 s15, 0x1000, s11
	global_load_ushort v136, v[70:71], off
	global_load_ushort v139, v[68:69], off
	global_load_ushort v140, v66, s[12:13]
	global_load_ushort v142, v66, s[12:13] offset:256
	s_and_b64 s[12:13], s[78:79], exec
	s_cselect_b32 s12, s14, s15
	v_med3_i32 v68, s12, 0, v73
	v_cvt_pk_f16_f32 v38, v75, v83
	v_readfirstlane_b32 s13, v68
	s_or_b32 s92, s13, s31
	s_lshl_b64 s[14:15], s[92:93], 10
	v_or_b32_e32 v68, s14, v72
	s_mul_i32 s14, s92, 0x300
	v_mov_b32_e32 v69, s15
	s_mul_hi_u32 s13, s92, 0x300
	s_add_u32 s14, s36, s14
	v_lshl_add_u64 v[70:71], s[18:19], 0, v[68:69]
	s_addc_u32 s15, s37, s13
	s_or_b32 s13, s2, 7
	global_load_ushort v147, v[70:71], off
	v_lshl_add_u64 v[70:71], s[20:21], 0, v[68:69]
	v_lshl_add_u64 v[68:69], s[22:23], 0, v[68:69]
	s_sub_i32 s16, 0x1000, s13
	global_load_ushort v150, v[70:71], off
	global_load_ushort v151, v[68:69], off
	global_load_ushort v172, v66, s[14:15]
	global_load_ushort v174, v66, s[14:15] offset:256
	s_and_b64 s[14:15], s[78:79], exec
	s_cselect_b32 s11, s11, s16
	v_med3_i32 v68, s11, 0, v73
	v_cvt_pk_f16_f32 v42, v76, v84
	v_readfirstlane_b32 s14, v68
	s_or_b32 s92, s14, s31
	s_lshl_b64 s[14:15], s[92:93], 10
	v_or_b32_e32 v68, s14, v72
	v_mov_b32_e32 v69, s15
	s_mul_i32 s14, s92, 0x300
	v_lshl_add_u64 v[70:71], s[18:19], 0, v[68:69]
	s_mul_hi_u32 s15, s92, 0x300
	s_add_u32 s14, s36, s14
	global_load_ushort v178, v[70:71], off
	v_lshl_add_u64 v[70:71], s[20:21], 0, v[68:69]
	v_lshl_add_u64 v[68:69], s[22:23], 0, v[68:69]
	s_addc_u32 s15, s37, s15
	s_add_i32 s16, s2, 8
	s_sub_i32 s17, 0xff8, s2
	global_load_ushort v180, v[70:71], off
	global_load_ushort v185, v[68:69], off
	global_load_ushort v188, v66, s[14:15]
	global_load_ushort v189, v66, s[14:15] offset:256
	s_and_b64 s[14:15], s[78:79], exec
	s_cselect_b32 s13, s13, s17
	v_med3_i32 v68, s13, 0, v73
	v_cvt_pk_f16_f32 v46, v77, v85
	v_readfirstlane_b32 s14, v68
	s_or_b32 s92, s14, s31
	s_lshl_b64 s[14:15], s[92:93], 10
	v_or_b32_e32 v68, s14, v72
	v_mov_b32_e32 v69, s15
	s_mul_i32 s14, s92, 0x300
	v_lshl_add_u64 v[70:71], s[18:19], 0, v[68:69]
	s_mul_hi_u32 s15, s92, 0x300
	s_add_u32 s14, s36, s14
	global_load_ushort v194, v[70:71], off
	v_lshl_add_u64 v[70:71], s[20:21], 0, v[68:69]
	v_lshl_add_u64 v[68:69], s[22:23], 0, v[68:69]
	s_addc_u32 s15, s37, s15
	s_sub_i32 s17, 0xff7, s2
	global_load_ushort v195, v[70:71], off
	global_load_ushort v211, v[68:69], off
	global_load_ushort v214, v66, s[14:15]
	global_load_ushort v215, v66, s[14:15] offset:256
	s_and_b64 s[14:15], s[78:79], exec
	s_cselect_b32 s14, s16, s17
	v_med3_i32 v68, s14, 0, v73
	v_cvt_pk_f16_f32 v50, v78, v86
	v_readfirstlane_b32 s15, v68
	s_or_b32 s92, s15, s31
	s_lshl_b64 s[16:17], s[92:93], 10
	v_or_b32_e32 v68, s16, v72
	v_mov_b32_e32 v69, s17
	v_lshl_add_u64 v[70:71], s[18:19], 0, v[68:69]
	global_load_ushort v220, v[70:71], off
	v_lshl_add_u64 v[70:71], s[20:21], 0, v[68:69]
	v_lshl_add_u64 v[68:69], s[22:23], 0, v[68:69]
	global_load_ushort v223, v[70:71], off
	global_load_ushort v233, v[68:69], off
	s_mul_i32 s16, s92, 0x300
	s_mul_hi_u32 s15, s92, 0x300
	s_add_u32 s16, s36, s16
	s_addc_u32 s17, s37, s15
	global_load_ushort v237, v66, s[16:17]
	global_load_ushort v238, v66, s[16:17] offset:256
	s_add_i32 s4, s4, 0
	s_waitcnt vmcnt(49)
	v_cvt_f32_f16_e32 v68, v109
	s_waitcnt vmcnt(48)
	v_cvt_f32_f16_e32 v69, v110
	s_add_i32 s4, s4, 0x1e000
	s_cmpk_lt_u32 s7, 0x1000
	s_cselect_b64 vcc, -1, 0
	v_cndmask_b32_e32 v135, 0, v69, vcc
	v_cndmask_b32_e32 v137, 0, v68, vcc
	s_waitcnt vmcnt(46)
	v_cvt_f32_f16_e32 v68, v112
	s_waitcnt vmcnt(45)
	v_cvt_f32_f16_e32 v69, v113
	v_cvt_f32_f16_e32 v70, v111
	s_cmpk_lt_u32 s6, 0x1000
	v_cndmask_b32_e32 v141, 0, v68, vcc
	v_cndmask_b32_e32 v143, 0, v69, vcc
	s_waitcnt vmcnt(44)
	v_cvt_f32_f16_e32 v68, v114
	s_waitcnt vmcnt(43)
	v_cvt_f32_f16_e32 v69, v115
	v_cndmask_b32_e32 v138, 0, v70, vcc
	s_cselect_b64 vcc, -1, 0
	v_cndmask_b32_e32 v145, 0, v68, vcc
	v_cndmask_b32_e32 v144, 0, v69, vcc
	s_waitcnt vmcnt(41)
	v_cvt_f32_f16_e32 v68, v117
	s_waitcnt vmcnt(40)
	v_cvt_f32_f16_e32 v69, v118
	v_cvt_f32_f16_e32 v70, v116
	s_cmpk_lt_u32 s5, 0x1000
	v_cndmask_b32_e32 v148, 0, v68, vcc
	v_cndmask_b32_e32 v149, 0, v69, vcc
	s_waitcnt vmcnt(39)
	v_cvt_f32_f16_e32 v68, v119
	s_waitcnt vmcnt(38)
	v_cvt_f32_f16_e32 v69, v120
	v_cndmask_b32_e32 v146, 0, v70, vcc
	s_cselect_b64 vcc, -1, 0
	v_cndmask_b32_e32 v173, 0, v68, vcc
	v_cndmask_b32_e32 v170, 0, v69, vcc
	s_waitcnt vmcnt(36)
	v_cvt_f32_f16_e32 v68, v122
	s_waitcnt vmcnt(35)
	v_cvt_f32_f16_e32 v69, v123
	v_cvt_f32_f16_e32 v70, v121
	s_cmpk_lt_u32 s9, 0x1000
	v_cndmask_b32_e32 v176, 0, v68, vcc
	v_cndmask_b32_e32 v177, 0, v69, vcc
	s_waitcnt vmcnt(34)
	v_cvt_f32_f16_e32 v68, v124
	s_waitcnt vmcnt(33)
	v_cvt_f32_f16_e32 v69, v125
	v_cndmask_b32_e32 v175, 0, v70, vcc
	s_cselect_b64 vcc, -1, 0
	v_cndmask_b32_e32 v181, 0, v68, vcc
	v_cndmask_b32_e32 v179, 0, v69, vcc
	s_waitcnt vmcnt(31)
; template <int R>
; __device__ __forceinline__ void scan_item(const Args& a, int layer, int q, int rowhalf, LAS unsigned char* lds, int tid, int lane, int wave) {
;     ...
;         SCAN_LOAD_RAW(0); SCAN_UNPACK(0);
;         for (int c = -1; c < nch; ++c) {
;             if (c >= 1) scan_flush<R>(lds, c - 1, pw, lane, d, T, tok0, h, rowbase, Yf, Yb);
;             if (c + 1 < nch) {
;                 const int cp = c + 1; LAS float* op = (LAS float*)(lds + (cp & 1) * SC_OPB);
;                 if (c + 2 < nch) SCAN_LOAD_RAW(c + 2);
;                 float bsv = 0.f;
; #pragma unroll
;                 for (int s8 = 0; s8 < 8; ++s8) {
;                     const float wl = mix3f(cur.wl[s8], cur.wl[s8 + 1], cur.wl[s8 + 2], mu_wl);
;                     const float al = mix3f(cur.al[s8], cur.al[s8 + 1], cur.al[s8 + 2], mu_al);
;                     const float e2 = __expf(2.0f * wl); const float th = 1.0f - 2.0f * __builtin_amdgcn_rcpf(e2 + 1.0f);
;                     LAS h16* xs = (LAS h16*)(xsb + s8 * 256);
;                     xs[j] = (h16)th; xs[64 + j] = (h16)al;
;                 }
;                 {
;                     const LAS unsigned char* xr = xsb + (lane & 7) * 256 + (lane >> 4) * 16;
;                     const h16x8 xw0 = *(const LAS h16x8a*)(xr), xw1 = *(const LAS h16x8a*)(xr + 64), xa0 = *(const LAS h16x8a*)(xr + 128), xa1 = *(const LAS h16x8a*)(xr + 192);
;                     f32x4 accw[4], acca[4];
; #pragma unroll
;                     for (int nt = 0; nt < 4; ++nt) {
;                         accw[nt] = __builtin_amdgcn_mfma_f32_16x16x32_f16(xw0, bw[nt][0], (f32x4){0.f, 0.f, 0.f, 0.f}, 0, 0, 0);
;                         accw[nt] = __builtin_amdgcn_mfma_f32_16x16x32_f16(xw1, bw[nt][1], accw[nt], 0, 0, 0);
;                         acca[nt] = __builtin_amdgcn_mfma_f32_16x16x32_f16(xa0, ba[nt][0], (f32x4){0.f, 0.f, 0.f, 0.f}, 0, 0, 0);
;                         acca[nt] = __builtin_amdgcn_mfma_f32_16x16x32_f16(xa1, ba[nt][1], acca[nt], 0, 0, 0); }
;                     if (lane < 32) {
;                         LAS float* zw = zl + (4 * (lane >> 4)) * 64 + (lane & 15);
; #pragma unroll
;                         for (int nt = 0; nt < 4; ++nt)
; #pragma unroll
;                             for (int r = 0; r < 4; ++r) { zw[r * 64 + 16 * nt] = accw[nt][r]; zw[512 + r * 64 + 16 * nt] = acca[nt][r]; }
;                     }
;                 }
	v_cvt_f32_f16_e32 v68, v127
	s_waitcnt vmcnt(30)
	v_cvt_f32_f16_e32 v69, v128
	v_cvt_f32_f16_e32 v70, v126
	s_cmpk_lt_u32 s8, 0x1000
	v_cndmask_b32_e32 v183, 0, v68, vcc
	v_cndmask_b32_e32 v184, 0, v69, vcc
	s_waitcnt vmcnt(29)
	v_cvt_f32_f16_e32 v68, v129
	s_waitcnt vmcnt(28)
	v_cvt_f32_f16_e32 v69, v130
	v_cndmask_b32_e32 v182, 0, v70, vcc
	s_cselect_b64 vcc, -1, 0
	v_cndmask_b32_e32 v187, 0, v68, vcc
	v_cndmask_b32_e32 v186, 0, v69, vcc
	s_waitcnt vmcnt(26)
	v_cvt_f32_f16_e32 v68, v132
	s_waitcnt vmcnt(25)
	v_cvt_f32_f16_e32 v69, v133
	v_cvt_f32_f16_e32 v70, v131
	s_cmpk_lt_u32 s10, 0x1000
	v_cndmask_b32_e32 v192, 0, v68, vcc
	v_cndmask_b32_e32 v193, 0, v69, vcc
	s_waitcnt vmcnt(24)
	v_cvt_f32_f16_e32 v68, v134
	s_waitcnt vmcnt(23)
	v_cvt_f32_f16_e32 v69, v136
	v_cndmask_b32_e32 v191, 0, v70, vcc
	s_cselect_b64 vcc, -1, 0
	v_cndmask_b32_e32 v197, 0, v68, vcc
	v_cndmask_b32_e32 v196, 0, v69, vcc
	s_waitcnt vmcnt(21)
	v_cvt_f32_f16_e32 v68, v140
	s_waitcnt vmcnt(20)
	v_cvt_f32_f16_e32 v69, v142
	v_cvt_f32_f16_e32 v70, v139
	s_cmpk_lt_u32 s12, 0x1000
	v_cndmask_b32_e32 v212, 0, v68, vcc
	v_cndmask_b32_e32 v213, 0, v69, vcc
	s_waitcnt vmcnt(19)
	v_cvt_f32_f16_e32 v68, v147
	s_waitcnt vmcnt(18)
	v_cvt_f32_f16_e32 v69, v150
	v_cndmask_b32_e32 v198, 0, v70, vcc
	s_cselect_b64 vcc, -1, 0
	v_cndmask_b32_e32 v217, 0, v68, vcc
	v_cndmask_b32_e32 v216, 0, v69, vcc
	s_waitcnt vmcnt(16)
	v_cvt_f32_f16_e32 v68, v172
	s_waitcnt vmcnt(15)
	v_cvt_f32_f16_e32 v69, v174
	v_cvt_f32_f16_e32 v70, v151
	s_cmpk_lt_u32 s11, 0x1000
	v_cndmask_b32_e32 v221, 0, v68, vcc
	v_cndmask_b32_e32 v222, 0, v69, vcc
	s_waitcnt vmcnt(14)
	v_cvt_f32_f16_e32 v68, v178
	s_waitcnt vmcnt(13)
	v_cvt_f32_f16_e32 v69, v180
	v_cndmask_b32_e32 v218, 0, v70, vcc
	s_cselect_b64 vcc, -1, 0
	v_cndmask_b32_e32 v227, 0, v68, vcc
	v_cndmask_b32_e32 v226, 0, v69, vcc
	s_waitcnt vmcnt(11)
	v_cvt_f32_f16_e32 v68, v188
	s_waitcnt vmcnt(10)
	v_cvt_f32_f16_e32 v69, v189
	v_cvt_f32_f16_e32 v70, v185
	s_cmpk_lt_u32 s13, 0x1000
	v_cndmask_b32_e32 v232, 0, v68, vcc
	v_cndmask_b32_e32 v235, 0, v69, vcc
	s_waitcnt vmcnt(9)
	v_cvt_f32_f16_e32 v68, v194
	s_waitcnt vmcnt(8)
	v_cvt_f32_f16_e32 v69, v195
	v_cndmask_b32_e32 v230, 0, v70, vcc
	s_waitcnt vmcnt(7)
	v_cvt_f32_f16_e32 v70, v211
	s_cselect_b64 vcc, -1, 0
	v_cndmask_b32_e32 v243, 0, v69, vcc
	v_cndmask_b32_e32 v244, 0, v68, vcc
	s_waitcnt vmcnt(6)
	v_cvt_f32_f16_e32 v68, v214
	s_waitcnt vmcnt(5)
	v_cvt_f32_f16_e32 v69, v215
	v_cndmask_b32_e32 v245, 0, v70, vcc
	s_waitcnt vmcnt(2)
	v_cvt_f32_f16_e32 v70, v233
	s_cmpk_lt_u32 s14, 0x1000
	v_cndmask_b32_e32 v205, 0, v68, vcc
	v_cndmask_b32_e32 v206, 0, v69, vcc
	s_cselect_b64 vcc, -1, 0
	v_cvt_f32_f16_e32 v68, v220
	v_cvt_f32_f16_e32 v69, v223
	v_cndmask_b32_e32 v246, 0, v70, vcc
	v_lshrrev_b32_e32 v70, 3, v171
	v_lshlrev_b32_e32 v71, 3, v171
	v_or_b32_e32 v219, s2, v70
	v_and_b32_e32 v96, 56, v71
	v_lshlrev_b32_e32 v225, 8, v219
	s_add_i32 s2, 0, 0x18000
	v_lshlrev_b32_e32 v71, 2, v96
	v_cndmask_b32_e32 v204, 0, v69, vcc
	v_cndmask_b32_e32 v210, 0, v68, vcc
	s_waitcnt vmcnt(1)
	v_cvt_f32_f16_e32 v68, v237
	s_waitcnt vmcnt(0)
	v_cvt_f32_f16_e32 v69, v238
	s_add_i32 s3, s3, 0
	v_add3_u32 v228, s2, v225, v71
	v_lshlrev_b32_e32 v71, 8, v171
	s_add_i32 s3, s3, 0x1c000
	v_and_b32_e32 v71, 0x700, v71
	v_add_u32_e32 v229, s3, v66
	v_add_u32_e32 v71, s3, v71
	v_readlane_b32 s3, v253, 53
	s_lshl_b32 s2, s35, 3
	v_cndmask_b32_e32 v247, 0, v68, vcc
	v_sub_u32_e32 v66, s3, v70
	v_cndmask_b32_e32 v162, 0, v69, vcc
	v_add_u32_e32 v68, s4, v152
	v_lshlrev_b32_e32 v69, 2, v171
	v_and_b32_e32 v72, 48, v190
	v_subrev_u32_e32 v236, s2, v66
	v_add_u32_e32 v66, s2, v171
	v_cvt_pk_f16_f32 v54, v79, v87
	v_cvt_pk_f16_f32 v58, v80, v88
	v_cvt_pk_f16_f32 v62, v81, v89
	v_add_u32_e32 v224, 0, v69
	v_cmp_gt_u32_e64 s[6:7], 32, v171
	v_add_u32_e32 v231, s4, v69
	v_cmp_gt_u32_e64 s[8:9], 8, v171
	s_mulk_i32 s34, 0x600
	v_cmp_eq_u32_e64 s[10:11], 7, v171
	v_cmp_eq_u32_e64 s[12:13], 6, v171
	v_cmp_eq_u32_e64 s[14:15], 5, v171
	v_cmp_eq_u32_e64 s[16:17], 4, v171
	v_cmp_eq_u32_e64 s[18:19], 3, v171
	v_cmp_eq_u32_e64 s[20:21], 2, v171
	v_cmp_eq_u32_e64 s[22:23], 1, v171
	v_add_u32_e32 v234, s31, v70
	s_add_i32 s35, s2, 8
	s_sub_i32 s36, 0, s2
	v_sub_u32_e32 v239, 0x101f, v66
	s_movk_i32 s37, 0xc000
	v_add_u32_e32 v241, v71, v72
	v_add_u32_e32 v242, v68, v65
	s_branch .LBB0_426

; #define LAS __attribute__((address_space(3)))
; template <int R>
; __device__ __forceinline__ void scan_flush(LAS unsigned char* lds, int cf, int pw, int lane, int d, int T, int tok0, int h, int rowbase, h16* Yf, h16* Yb) {
;     const LAS float* yb = (const LAS float*)(lds + SC_YOFF + (cf & 1) * SC_YB);
;     const int s = pw * 8 + (lane >> 3); const int g = cf * SC_CH + s; const int t = d ? (T - 1 - g) : g;
;     if (R == 4) {
;         const int r8 = (lane & 7) * 8;
;         const f32x4 y0 = *(const LAS f32x4*)(yb + s * 64 + r8), y1 = *(const LAS f32x4*)(yb + s * 64 + r8 + 4);
;         u32x4 w4; w4.x = pk2h(y0.x, y0.y); w4.y = pk2h(y0.z, y0.w); w4.z = pk2h(y1.x, y1.y); w4.w = pk2h(y1.z, y1.w);
;         if (d == 0) *(u32x4*)(Yf + (size_t)(tok0 + t) * 1024 + 512 + h * 64 + r8) = w4; else *(u32x4*)(Yb + (size_t)(tok0 + t) * 512 + h * 64 + r8) = w4;
; template <int R>
; __device__ __forceinline__ void scan_item(const Args& a, int layer, int q, int rowhalf, LAS unsigned char* lds, int tid, int lane, int wave) {
;     ...
;         scan_flush<R>(lds, nch - 1, pw, lane, d, T, tok0, h, rowbase, Yf, Yb);
.LBB0_441:
	s_setprio 1
	s_add_i32 s2, 0, 0x1a000
	v_lshlrev_b32_e32 v0, 2, v96
	v_add3_u32 v0, s2, v225, v0
	ds_read_b128 v[4:7], v0
	ds_read_b128 v[0:3], v0 offset:16
	s_mov_b64 s[2:3], -1
	s_and_b64 vcc, exec, s[84:85]
	s_cbranch_vccz .LBB0_443
	v_readlane_b32 s2, v249, 48
	s_nop 1
	v_sub_u32_e32 v8, s2, v219
	v_ashrrev_i32_e32 v9, 31, v8
	v_readlane_b32 s2, v253, 24
	v_lshlrev_b64 v[8:9], 10, v[8:9]
	v_readlane_b32 s3, v253, 25
	s_nop 1
	v_lshl_add_u64 v[8:9], s[2:3], 0, v[8:9]
	s_mov_b64 s[2:3], 0

; template <int R>
; __device__ __forceinline__ void scan_item(const Args& a, int layer, int q, int rowhalf, LAS unsigned char* lds, int tid, int lane, int wave) {
;     ...
;     if (wave >= 4) {
;         const int pw = wave - 4, j = lane, col = h * 64 + j;
;         const float* mu = a.in[I_MU] + l * 1920;
;         const float mu_r = mu[col], mu_k = mu[512 + col], mu_v = mu[1024 + col], mu_wl = mu[1536 + d * 64 + j], mu_al = mu[1536 + 128 + d * 64 + j];
;         const float k_k = a.in[I_KK][l * 512 + col], k_a = a.in[I_KA][l * 512 + col], r_k = a.in[I_RK][l * 512 + col];
;         const float w0 = a.in[I_W0][(l * 2 + d) * 512 + col], a0 = a.in[I_A0][(l * 2 + d) * 512 + col];
;         h16x8 bw[4][2], ba[4][2];
;         { const int n = lane & 15, kg = lane >> 4;
;           const float* wu = a.in[I_WUP] + ((l * 2 + d) * 64 + 8 * kg) * 512 + h * 64 + n; const float* au = a.in[I_AUP] + ((l * 2 + d) * 64 + 8 * kg) * 512 + h * 64 + n;
; #pragma unroll
;           for (int ks = 0; ks < 2; ++ks) {
; #pragma unroll
;               for (int e = 0; e < 8; ++e) {
;                   const float w_0 = wu[0], w_1 = wu[16], w_2 = wu[32], w_3 = wu[48], a_0 = au[0], a_1 = au[16], a_2 = au[32], a_3 = au[48];
;                   wu += 512; au += 512; asm volatile("" : "+v"(wu), "+v"(au));
;                   bw[0][ks][e] = (h16)w_0; bw[1][ks][e] = (h16)w_1; bw[2][ks][e] = (h16)w_2; bw[3][ks][e] = (h16)w_3;
;                   ba[0][ks][e] = (h16)a_0; ba[1][ks][e] = (h16)a_1; ba[2][ks][e] = (h16)a_2; ba[3][ks][e] = (h16)a_3; }
;               wu += 24 * 512; au += 24 * 512; asm volatile("" : "+v"(wu), "+v"(au)); } }
.LBB0_481:
	s_and_b64 vcc, exec, s[2:3]
	s_cbranch_vccz .LBB0_505
	s_setprio 0
	v_readlane_b32 s2, v249, 58
	v_readlane_b32 s4, v248, 16
	v_readlane_b32 s10, v248, 22
	v_or_b32_e32 v64, s2, v171
	s_mul_i32 s2, s74, 0x1e00
	v_readlane_b32 s11, v248, 23
	s_add_u32 s2, s10, s2
	v_readlane_b32 s5, v248, 17
	s_addc_u32 s3, s11, 0
	v_lshlrev_b32_e32 v152, 2, v64
	v_lshl_add_u64 v[0:1], s[2:3], 0, v[152:153]
	s_movk_i32 s5, 0x1000
	v_add_co_u32_e32 v0, vcc, s5, v0
	v_readlane_b32 s4, v249, 59
	s_nop 0
	v_addc_co_u32_e32 v1, vcc, 0, v1, vcc
	global_load_dword v97, v152, s[2:3]
	global_load_dword v100, v152, s[2:3] offset:2048
	global_load_dword v101, v[0:1], off
	v_or_b32_e32 v0, s4, v171
	v_lshlrev_b32_e32 v0, 2, v0
	v_mov_b32_e32 v1, v153
	v_lshl_add_u64 v[0:1], s[2:3], 0, v[0:1]
	v_add_co_u32_e32 v0, vcc, s5, v0
	s_lshl_b64 s[2:3], s[74:75], 11
	s_nop 0
	v_addc_co_u32_e32 v1, vcc, 0, v1, vcc
	v_readlane_b32 s52, v248, 32
	v_readlane_b32 s4, v253, 18
	global_load_dword v102, v[0:1], off offset:2048
	global_load_dword v103, v[0:1], off offset:2560
	v_or_b32_e32 v0, s2, v152
	v_mov_b32_e32 v1, s3
	v_readlane_b32 s54, v248, 34
	v_readlane_b32 s55, v248, 35
	s_lshl_b64 s[2:3], s[74:75], 1
	v_readlane_b32 s5, v253, 19
	v_readlane_b32 s56, v248, 36
	v_readlane_b32 s57, v248, 37
	v_readlane_b32 s58, v248, 38
	v_readlane_b32 s59, v248, 39
	v_lshl_add_u64 v[2:3], s[54:55], 0, v[0:1]
	s_or_b64 s[2:3], s[2:3], s[4:5]
	global_load_dword v104, v[2:3], off
	v_lshl_add_u64 v[2:3], s[56:57], 0, v[0:1]
	v_lshl_add_u64 v[0:1], s[58:59], 0, v[0:1]
	s_lshl_b64 s[4:5], s[2:3], 11
	v_readlane_b32 s12, v248, 24
	v_readlane_b32 s13, v248, 25
	v_readlane_b32 s16, v248, 28
	v_readlane_b32 s17, v248, 29
	global_load_dword v106, v[0:1], off
	v_or_b32_e32 v0, s4, v152
	v_mov_b32_e32 v1, s5
	global_load_dword v105, v[2:3], off
	v_lshl_add_u64 v[2:3], s[12:13], 0, v[0:1]
	v_lshl_add_u64 v[0:1], s[16:17], 0, v[0:1]
	v_lshrrev_b32_e32 v65, 4, v171
	s_lshl_b64 s[2:3], s[2:3], 17
	global_load_dword v108, v[0:1], off
	v_lshl_or_b32 v0, v65, 14, s2
	v_mov_b32_e32 v1, s3
	v_readlane_b32 s2, v249, 60
	v_readlane_b32 s3, v249, 61
	global_load_dword v107, v[2:3], off
	v_lshlrev_b32_e32 v4, 2, v190
	v_lshl_add_u64 v[2:3], s[2:3], 0, v[0:1]
	v_readlane_b32 s2, v249, 62
	v_readlane_b32 s3, v249, 63
	v_and_b32_e32 v152, 60, v4
	v_lshl_add_u64 v[2:3], v[2:3], 0, v[152:153]
	v_lshl_add_u64 v[0:1], s[2:3], 0, v[0:1]
	v_lshl_add_u64 v[0:1], v[0:1], 0, v[152:153]
	s_mov_b64 s[2:3], 0x800
	global_load_dword v4, v[2:3], off
	global_load_dword v8, v[2:3], off offset:64
	global_load_dword v12, v[2:3], off offset:128
	global_load_dword v16, v[2:3], off offset:192
	global_load_dword v20, v[0:1], off
	global_load_dword v24, v[0:1], off offset:64
	global_load_dword v28, v[0:1], off offset:128
	global_load_dword v36, v[0:1], off offset:192
	v_lshl_add_u64 v[2:3], v[2:3], 0, s[2:3]
	v_lshl_add_u64 v[0:1], v[0:1], 0, s[2:3]
	flat_load_dword v5, v[2:3]
	flat_load_dword v9, v[2:3] offset:64
	flat_load_dword v13, v[2:3] offset:128
	flat_load_dword v17, v[2:3] offset:192
	flat_load_dword v21, v[0:1]
	flat_load_dword v25, v[0:1] offset:64
	flat_load_dword v29, v[0:1] offset:128
	flat_load_dword v37, v[0:1] offset:192
	v_lshl_add_u64 v[2:3], v[2:3], 0, s[2:3]
	v_lshl_add_u64 v[0:1], v[0:1], 0, s[2:3]
	flat_load_dword v6, v[2:3]
	flat_load_dword v10, v[2:3] offset:64
	flat_load_dword v14, v[2:3] offset:128
	flat_load_dword v18, v[2:3] offset:192
	flat_load_dword v22, v[0:1]
	flat_load_dword v26, v[0:1] offset:64
	flat_load_dword v30, v[0:1] offset:128
	flat_load_dword v38, v[0:1] offset:192
	v_lshl_add_u64 v[2:3], v[2:3], 0, s[2:3]
	v_lshl_add_u64 v[0:1], v[0:1], 0, s[2:3]
	flat_load_dword v7, v[2:3]
	flat_load_dword v11, v[2:3] offset:64
	flat_load_dword v15, v[2:3] offset:128
	flat_load_dword v19, v[2:3] offset:192
	flat_load_dword v23, v[0:1]
	flat_load_dword v27, v[0:1] offset:64
	flat_load_dword v31, v[0:1] offset:128
	flat_load_dword v39, v[0:1] offset:192
	v_lshl_add_u64 v[2:3], v[2:3], 0, s[2:3]
	v_lshl_add_u64 v[0:1], v[0:1], 0, s[2:3]
	flat_load_dword v40, v[2:3]
	flat_load_dword v41, v[2:3] offset:64
	flat_load_dword v42, v[2:3] offset:128
	flat_load_dword v43, v[2:3] offset:192
	flat_load_dword v44, v[0:1]
	flat_load_dword v45, v[0:1] offset:64
	flat_load_dword v46, v[0:1] offset:128
	flat_load_dword v47, v[0:1] offset:192
	v_lshl_add_u64 v[2:3], v[2:3], 0, s[2:3]
	v_lshl_add_u64 v[0:1], v[0:1], 0, s[2:3]
	flat_load_dword v48, v[2:3]
	flat_load_dword v49, v[2:3] offset:64
	flat_load_dword v50, v[2:3] offset:128
	flat_load_dword v51, v[2:3] offset:192
	flat_load_dword v52, v[0:1]
	flat_load_dword v53, v[0:1] offset:64
	flat_load_dword v54, v[0:1] offset:128
	flat_load_dword v55, v[0:1] offset:192
	v_lshl_add_u64 v[2:3], v[2:3], 0, s[2:3]
	v_lshl_add_u64 v[0:1], v[0:1], 0, s[2:3]
	flat_load_dword v56, v[2:3]
	flat_load_dword v57, v[2:3] offset:64
	flat_load_dword v58, v[2:3] offset:128
	flat_load_dword v59, v[2:3] offset:192
	flat_load_dword v60, v[0:1]
	flat_load_dword v61, v[0:1] offset:64
	flat_load_dword v62, v[0:1] offset:128
	flat_load_dword v63, v[0:1] offset:192
	v_lshl_add_u64 v[2:3], v[2:3], 0, s[2:3]
	v_lshl_add_u64 v[0:1], v[0:1], 0, s[2:3]
	flat_load_dword v66, v[2:3]
	flat_load_dword v67, v[2:3] offset:64
	flat_load_dword v68, v[2:3] offset:128
	flat_load_dword v69, v[2:3] offset:192
	flat_load_dword v70, v[0:1]
	flat_load_dword v71, v[0:1] offset:64
	flat_load_dword v72, v[0:1] offset:128
	flat_load_dword v73, v[0:1] offset:192
	v_lshl_add_u64 v[32:33], v[2:3], 0, s[2:3]
	v_lshl_add_u64 v[34:35], v[0:1], 0, s[2:3]
	s_mov_b64 s[4:5], 0xc000
	v_lshl_add_u64 v[32:33], v[32:33], 0, s[4:5]
	v_lshl_add_u64 v[34:35], v[34:35], 0, s[4:5]
	v_readlane_b32 s37, v254, 48
	s_add_i32 s26, s37, -4
	v_readlane_b32 s21, v250, 49
	v_readlane_b32 s22, v250, 0
	v_readlane_b32 s6, v248, 18
	v_readlane_b32 s7, v248, 19
	v_readlane_b32 s23, v250, 1
	v_readlane_b32 s31, v250, 45
	v_readlane_b32 s8, v248, 20
	v_readlane_b32 s25, v253, 54
	v_readlane_b32 s9, v248, 21
	v_readlane_b32 s28, v250, 35
	v_readlane_b32 s29, v250, 36
	v_readlane_b32 s34, v250, 37
	v_readlane_b32 s38, v250, 41
	v_readlane_b32 s44, v253, 14
	v_readlane_b32 s35, v250, 38
	v_readlane_b32 s39, v250, 42
	v_readlane_b32 s45, v253, 15
	v_readlane_b32 s14, v248, 26
	v_readlane_b32 s15, v248, 27
	v_readlane_b32 s18, v248, 30
	v_readlane_b32 s19, v248, 31
	v_lshlrev_b32_e32 v65, 10, v65
	s_mov_b32 s24, -1
	v_add_u32_e32 v228, s25, v91
	v_lshlrev_b32_e32 v232, 1, v64
	v_readlane_b32 s53, v248, 33
	v_readlane_b32 s60, v248, 40
	v_readlane_b32 s61, v248, 41
	v_readlane_b32 s62, v248, 42
	v_readlane_b32 s63, v248, 43
	v_readlane_b32 s64, v248, 44
	v_readlane_b32 s65, v248, 45
	v_readlane_b32 s66, v248, 46
	v_readlane_b32 s67, v248, 47
	s_waitcnt vmcnt(0) lgkmcnt(0)
; #define LAS __attribute__((address_space(3)))
; template <int R>
; __device__ __forceinline__ void scan_item(const Args& a, int layer, int q, int rowhalf, LAS unsigned char* lds, int tid, int lane, int wave) {
;     ...
;         { const int n = lane & 15, kg = lane >> 4;
;           const float* wu = a.in[I_WUP] + ((l * 2 + d) * 64 + 8 * kg) * 512 + h * 64 + n; const float* au = a.in[I_AUP] + ((l * 2 + d) * 64 + 8 * kg) * 512 + h * 64 + n;
; #pragma unroll
;           for (int ks = 0; ks < 2; ++ks) {
; #pragma unroll
;               for (int e = 0; e < 8; ++e) {
;                   const float w_0 = wu[0], w_1 = wu[16], w_2 = wu[32], w_3 = wu[48], a_0 = au[0], a_1 = au[16], a_2 = au[32], a_3 = au[48];
;                   wu += 512; au += 512; asm volatile("" : "+v"(wu), "+v"(au));
;                   bw[0][ks][e] = (h16)w_0; bw[1][ks][e] = (h16)w_1; bw[2][ks][e] = (h16)w_2; bw[3][ks][e] = (h16)w_3;
;                   ba[0][ks][e] = (h16)a_0; ba[1][ks][e] = (h16)a_1; ba[2][ks][e] = (h16)a_2; ba[3][ks][e] = (h16)a_3; }
;               wu += 24 * 512; au += 24 * 512; asm volatile("" : "+v"(wu), "+v"(au)); } }
;         LAS float* zl = (LAS float*)(lds + SC_ZOFF + pw * 4096);
;         LAS unsigned char* xsb = lds + SC_XOFF + pw * 2048;
;         ScanWin cur; ScanWinRaw nxt;
	v_cvt_pk_f16_f32 v0, v4, v5
	v_cvt_pk_f16_f32 v4, v8, v9
	v_cvt_pk_f16_f32 v8, v12, v13
	v_cvt_pk_f16_f32 v12, v16, v17
	v_cvt_pk_f16_f32 v16, v20, v21
	v_cvt_pk_f16_f32 v20, v24, v25
	v_cvt_pk_f16_f32 v24, v28, v29
	v_cvt_pk_f16_f32 v28, v36, v37
	v_cvt_pk_f16_f32 v1, v6, v7
	v_cvt_pk_f16_f32 v5, v10, v11
	v_cvt_pk_f16_f32 v9, v14, v15
	v_cvt_pk_f16_f32 v13, v18, v19
	v_cvt_pk_f16_f32 v17, v22, v23
	v_cvt_pk_f16_f32 v21, v26, v27
	v_cvt_pk_f16_f32 v25, v30, v31
	v_cvt_pk_f16_f32 v29, v38, v39
	v_cvt_pk_f16_f32 v2, v40, v48
	v_cvt_pk_f16_f32 v6, v41, v49
	v_cvt_pk_f16_f32 v10, v42, v50
	v_cvt_pk_f16_f32 v14, v43, v51
	v_cvt_pk_f16_f32 v18, v44, v52
	v_cvt_pk_f16_f32 v22, v45, v53
	v_cvt_pk_f16_f32 v26, v46, v54
	v_cvt_pk_f16_f32 v30, v47, v55
	v_cvt_pk_f16_f32 v3, v56, v66
	v_cvt_pk_f16_f32 v7, v57, v67
	v_cvt_pk_f16_f32 v11, v58, v68
	v_cvt_pk_f16_f32 v15, v59, v69
	v_cvt_pk_f16_f32 v19, v60, v70
	flat_load_dword v36, v[32:33]
	flat_load_dword v40, v[32:33] offset:64
	flat_load_dword v44, v[32:33] offset:128
	flat_load_dword v48, v[32:33] offset:192
	flat_load_dword v52, v[34:35]
	flat_load_dword v56, v[34:35] offset:64
	flat_load_dword v60, v[34:35] offset:128
	flat_load_dword v70, v[34:35] offset:192
	v_lshl_add_u64 v[32:33], v[32:33], 0, s[2:3]
	v_lshl_add_u64 v[34:35], v[34:35], 0, s[2:3]
	v_cvt_pk_f16_f32 v23, v61, v71
	flat_load_dword v37, v[32:33]
	flat_load_dword v41, v[32:33] offset:64
	flat_load_dword v45, v[32:33] offset:128
	flat_load_dword v49, v[32:33] offset:192
	flat_load_dword v53, v[34:35]
	flat_load_dword v57, v[34:35] offset:64
	flat_load_dword v61, v[34:35] offset:128
	flat_load_dword v71, v[34:35] offset:192
	v_lshl_add_u64 v[32:33], v[32:33], 0, s[2:3]
	v_lshl_add_u64 v[34:35], v[34:35], 0, s[2:3]
	v_cvt_pk_f16_f32 v27, v62, v72
	flat_load_dword v38, v[32:33]
	flat_load_dword v42, v[32:33] offset:64
	flat_load_dword v46, v[32:33] offset:128
	flat_load_dword v50, v[32:33] offset:192
	flat_load_dword v54, v[34:35]
	flat_load_dword v58, v[34:35] offset:64
	flat_load_dword v62, v[34:35] offset:128
	flat_load_dword v72, v[34:35] offset:192
	v_lshl_add_u64 v[32:33], v[32:33], 0, s[2:3]
	v_lshl_add_u64 v[34:35], v[34:35], 0, s[2:3]
	v_cvt_pk_f16_f32 v31, v63, v73
	flat_load_dword v39, v[32:33]
	flat_load_dword v43, v[32:33] offset:64
	flat_load_dword v47, v[32:33] offset:128
	flat_load_dword v51, v[32:33] offset:192
	flat_load_dword v55, v[34:35]
	flat_load_dword v59, v[34:35] offset:64
	flat_load_dword v63, v[34:35] offset:128
	flat_load_dword v73, v[34:35] offset:192
	v_lshl_add_u64 v[32:33], v[32:33], 0, s[2:3]
	v_lshl_add_u64 v[34:35], v[34:35], 0, s[2:3]
	flat_load_dword v74, v[32:33]
	flat_load_dword v75, v[32:33] offset:64
	flat_load_dword v76, v[32:33] offset:128
	flat_load_dword v77, v[32:33] offset:192
	flat_load_dword v78, v[34:35]
	flat_load_dword v79, v[34:35] offset:64
	flat_load_dword v80, v[34:35] offset:128
	flat_load_dword v81, v[34:35] offset:192
	v_lshl_add_u64 v[32:33], v[32:33], 0, s[2:3]
	v_lshl_add_u64 v[34:35], v[34:35], 0, s[2:3]
	flat_load_dword v82, v[32:33]
	flat_load_dword v83, v[32:33] offset:64
	flat_load_dword v84, v[32:33] offset:128
	flat_load_dword v85, v[32:33] offset:192
	flat_load_dword v86, v[34:35]
	flat_load_dword v87, v[34:35] offset:64
	flat_load_dword v88, v[34:35] offset:128
	flat_load_dword v89, v[34:35] offset:192
	v_lshl_add_u64 v[32:33], v[32:33], 0, s[2:3]
	v_lshl_add_u64 v[34:35], v[34:35], 0, s[2:3]
	flat_load_dword v90, v[32:33]
	flat_load_dword v92, v[32:33] offset:64
	flat_load_dword v93, v[32:33] offset:128
	flat_load_dword v94, v[32:33] offset:192
	flat_load_dword v95, v[34:35]
	flat_load_dword v96, v[34:35] offset:64
	flat_load_dword v98, v[34:35] offset:128
	flat_load_dword v99, v[34:35] offset:192
	v_lshl_add_u64 v[32:33], v[32:33], 0, s[2:3]
	v_lshl_add_u64 v[34:35], v[34:35], 0, s[2:3]
	flat_load_dword v109, v[32:33]
	flat_load_dword v110, v[32:33] offset:64
	flat_load_dword v111, v[32:33] offset:128
	flat_load_dword v112, v[32:33] offset:192
	flat_load_dword v113, v[34:35]
	flat_load_dword v114, v[34:35] offset:64
	flat_load_dword v115, v[34:35] offset:128
	flat_load_dword v116, v[34:35] offset:192
	v_lshl_add_u64 v[66:67], v[32:33], 0, s[2:3]
	v_lshl_add_u64 v[68:69], v[34:35], 0, s[2:3]
	s_lshl_b32 s2, s26, 3
	v_lshl_add_u64 v[66:67], v[66:67], 0, s[4:5]
	v_lshl_add_u64 v[68:69], v[68:69], 0, s[4:5]
	s_lshl_b32 s4, s26, 12
	s_lshl_b32 s3, s26, 11
	s_add_i32 s5, s2, -1
	s_sub_i32 s11, s21, s2
	s_and_b64 s[6:7], s[22:23], exec
	s_cselect_b32 s6, s5, s11
	s_min_u32 s5, s6, s31
	s_cmp_gt_i32 s6, -1
	s_cselect_b32 s5, s5, 0
	s_add_i32 s8, s5, s25
	s_ashr_i32 s9, s8, 31
	s_lshl_b64 s[12:13], s[8:9], 10
	v_mov_b32_e32 v67, s13
	s_mul_i32 s7, s8, 0x300
	s_mul_hi_i32 s5, s8, 0x300
	s_add_u32 s8, s44, s7
	s_addc_u32 s9, s45, s5
	s_or_b32 s27, s2, 1
	s_sub_i32 s5, s21, s27
	v_or_b32_e32 v221, s2, v91
	v_lshlrev_b32_e32 v219, 7, v221
	s_mulk_i32 s26, 0x3000
	s_waitcnt vmcnt(0) lgkmcnt(0)
	v_cvt_pk_f16_f32 v32, v36, v37
	v_cvt_pk_f16_f32 v36, v40, v41
	v_cvt_pk_f16_f32 v40, v44, v45
	v_cvt_pk_f16_f32 v44, v48, v49
	v_cvt_pk_f16_f32 v48, v52, v53
	v_cvt_pk_f16_f32 v52, v56, v57
	v_cvt_pk_f16_f32 v56, v60, v61
	v_cvt_pk_f16_f32 v60, v70, v71
	v_cvt_pk_f16_f32 v33, v38, v39
	v_cvt_pk_f16_f32 v37, v42, v43
	v_cvt_pk_f16_f32 v41, v46, v47
	v_cvt_pk_f16_f32 v45, v50, v51
	v_cvt_pk_f16_f32 v49, v54, v55
	v_cvt_pk_f16_f32 v53, v58, v59
	v_cvt_pk_f16_f32 v57, v62, v63
	v_cvt_pk_f16_f32 v61, v72, v73
	v_lshlrev_b32_e32 v72, 1, v64
	v_or_b32_e32 v66, s12, v72
	v_lshl_add_u64 v[68:69], s[28:29], 0, v[66:67]
	v_cvt_pk_f16_f32 v34, v74, v82
	v_cvt_pk_f16_f32 v38, v75, v83
	v_cvt_pk_f16_f32 v42, v76, v84
	v_cvt_pk_f16_f32 v46, v77, v85
	v_cvt_pk_f16_f32 v50, v78, v86
	v_cvt_pk_f16_f32 v35, v90, v109
	global_load_ushort v109, v[68:69], off
	v_lshl_add_u64 v[68:69], s[34:35], 0, v[66:67]
	v_lshl_add_u64 v[66:67], s[38:39], 0, v[66:67]
	v_cvt_pk_f16_f32 v39, v92, v110
	v_cvt_pk_f16_f32 v43, v93, v111
	global_load_ushort v110, v[68:69], off
	global_load_ushort v111, v[66:67], off
	v_lshlrev_b32_e32 v66, 1, v171
	v_cvt_pk_f16_f32 v47, v94, v112
	v_cvt_pk_f16_f32 v51, v95, v113
	global_load_ushort v112, v66, s[8:9]
	global_load_ushort v113, v66, s[8:9] offset:256
	s_and_b64 s[8:9], s[22:23], exec
	s_cselect_b32 s5, s2, s5
	s_min_i32 s7, s5, s31
	s_cmp_gt_i32 s5, -1
	s_cselect_b32 s7, s7, 0
	s_add_i32 s8, s7, s25
	s_ashr_i32 s9, s8, 31
	s_lshl_b64 s[12:13], s[8:9], 10
	s_mul_hi_i32 s7, s8, 0x300
	s_mulk_i32 s8, 0x300
	v_or_b32_e32 v68, s12, v72
	v_mov_b32_e32 v69, s13
	s_add_u32 s8, s44, s8
	v_lshl_add_u64 v[70:71], s[28:29], 0, v[68:69]
	s_addc_u32 s9, s45, s7
	s_or_b32 s10, s2, 2
	v_cvt_pk_f16_f32 v55, v96, v114
	global_load_ushort v114, v[70:71], off
	v_lshl_add_u64 v[70:71], s[34:35], 0, v[68:69]
	v_lshl_add_u64 v[68:69], s[38:39], 0, v[68:69]
	s_sub_i32 s7, s21, s10
	v_cvt_pk_f16_f32 v59, v98, v115
	v_cvt_pk_f16_f32 v63, v99, v116
	global_load_ushort v115, v[70:71], off
	global_load_ushort v116, v[68:69], off
	global_load_ushort v117, v66, s[8:9]
	global_load_ushort v118, v66, s[8:9] offset:256
	s_and_b64 s[8:9], s[22:23], exec
	s_cselect_b32 s7, s27, s7
	s_min_i32 s8, s7, s31
	s_cmp_gt_i32 s7, -1
	s_cselect_b32 s8, s8, 0
	s_add_i32 s8, s8, s25
	s_ashr_i32 s9, s8, 31
	s_lshl_b64 s[12:13], s[8:9], 10
	s_mul_hi_i32 s9, s8, 0x300
	s_mulk_i32 s8, 0x300
	v_or_b32_e32 v68, s12, v72
	v_mov_b32_e32 v69, s13
	s_add_u32 s8, s44, s8
	v_lshl_add_u64 v[70:71], s[28:29], 0, v[68:69]
	s_addc_u32 s9, s45, s9
	s_or_b32 s16, s2, 3
	global_load_ushort v119, v[70:71], off
	v_lshl_add_u64 v[70:71], s[34:35], 0, v[68:69]
	v_lshl_add_u64 v[68:69], s[38:39], 0, v[68:69]
	s_sub_i32 s12, s21, s16
	global_load_ushort v120, v[70:71], off
	global_load_ushort v121, v[68:69], off
	global_load_ushort v122, v66, s[8:9]
	global_load_ushort v123, v66, s[8:9] offset:256
	s_and_b64 s[8:9], s[22:23], exec
	s_cselect_b32 s8, s10, s12
	s_min_i32 s9, s8, s31
	s_cmp_gt_i32 s8, -1
	s_cselect_b32 s9, s9, 0
	s_add_i32 s12, s9, s25
	s_ashr_i32 s13, s12, 31
	s_lshl_b64 s[14:15], s[12:13], 10
	s_mul_i32 s10, s12, 0x300
	v_or_b32_e32 v68, s14, v72
	v_mov_b32_e32 v69, s15
	s_mul_hi_i32 s9, s12, 0x300
	s_add_u32 s12, s44, s10
	v_lshl_add_u64 v[70:71], s[28:29], 0, v[68:69]
	s_addc_u32 s13, s45, s9
	s_or_b32 s10, s2, 4
	global_load_ushort v124, v[70:71], off
	v_lshl_add_u64 v[70:71], s[34:35], 0, v[68:69]
	v_lshl_add_u64 v[68:69], s[38:39], 0, v[68:69]
	s_sub_i32 s9, s21, s10
	global_load_ushort v125, v[70:71], off
	global_load_ushort v126, v[68:69], off
	global_load_ushort v127, v66, s[12:13]
	global_load_ushort v128, v66, s[12:13] offset:256
	s_and_b64 s[12:13], s[22:23], exec
	s_cselect_b32 s9, s16, s9
	s_min_i32 s12, s9, s31
	s_cmp_gt_i32 s9, -1
	s_cselect_b32 s12, s12, 0
	s_add_i32 s12, s12, s25
	s_ashr_i32 s13, s12, 31
	s_lshl_b64 s[14:15], s[12:13], 10
	s_mul_hi_i32 s13, s12, 0x300
	s_mulk_i32 s12, 0x300
	v_or_b32_e32 v68, s14, v72
	v_mov_b32_e32 v69, s15
	s_add_u32 s12, s44, s12
	v_lshl_add_u64 v[70:71], s[28:29], 0, v[68:69]
	s_addc_u32 s13, s45, s13
	s_or_b32 s16, s2, 5
	global_load_ushort v129, v[70:71], off
	v_lshl_add_u64 v[70:71], s[34:35], 0, v[68:69]
	v_lshl_add_u64 v[68:69], s[38:39], 0, v[68:69]
	s_sub_i32 s14, s21, s16
	global_load_ushort v130, v[70:71], off
	global_load_ushort v131, v[68:69], off
	global_load_ushort v132, v66, s[12:13]
	global_load_ushort v133, v66, s[12:13] offset:256
	s_and_b64 s[12:13], s[22:23], exec
	s_cselect_b32 s10, s10, s14
	s_min_i32 s12, s10, s31
	s_cmp_gt_i32 s10, -1
	s_cselect_b32 s12, s12, 0
	s_add_i32 s12, s12, s25
	s_ashr_i32 s13, s12, 31
	s_lshl_b64 s[14:15], s[12:13], 10
	s_mul_hi_i32 s13, s12, 0x300
	s_mulk_i32 s12, 0x300
	v_or_b32_e32 v68, s14, v72
	v_mov_b32_e32 v69, s15
	s_add_u32 s12, s44, s12
	v_lshl_add_u64 v[70:71], s[28:29], 0, v[68:69]
	s_addc_u32 s13, s45, s13
	s_or_b32 s18, s2, 6
	global_load_ushort v135, v[70:71], off
	v_lshl_add_u64 v[70:71], s[34:35], 0, v[68:69]
	v_lshl_add_u64 v[68:69], s[38:39], 0, v[68:69]
	s_sub_i32 s14, s21, s18
	global_load_ushort v138, v[70:71], off
	global_load_ushort v139, v[68:69], off
	global_load_ushort v142, v66, s[12:13]
	global_load_ushort v143, v66, s[12:13] offset:256
	s_and_b64 s[12:13], s[22:23], exec
	s_cselect_b32 s12, s16, s14
	s_min_i32 s13, s12, s31
	s_cmp_gt_i32 s12, -1
	s_cselect_b32 s13, s13, 0
	s_add_i32 s14, s13, s25
	s_ashr_i32 s15, s14, 31
	s_lshl_b64 s[16:17], s[14:15], 10
	s_mul_hi_i32 s13, s14, 0x300
	s_mulk_i32 s14, 0x300
	v_or_b32_e32 v68, s16, v72
	v_mov_b32_e32 v69, s17
	s_add_u32 s14, s44, s14
	v_lshl_add_u64 v[70:71], s[28:29], 0, v[68:69]
	s_addc_u32 s15, s45, s13
	s_or_b32 s19, s2, 7
	global_load_ushort v147, v[70:71], off
	v_lshl_add_u64 v[70:71], s[34:35], 0, v[68:69]
	v_lshl_add_u64 v[68:69], s[38:39], 0, v[68:69]
	s_sub_i32 s13, s21, s19
	global_load_ushort v150, v[70:71], off
	global_load_ushort v151, v[68:69], off
	global_load_ushort v174, v66, s[14:15]
	global_load_ushort v175, v66, s[14:15] offset:256
	s_and_b64 s[14:15], s[22:23], exec
	s_cselect_b32 s13, s18, s13
	s_min_i32 s14, s13, s31
	s_cmp_gt_i32 s13, -1
	s_cselect_b32 s14, s14, 0
	s_add_i32 s14, s14, s25
	s_ashr_i32 s15, s14, 31
	s_lshl_b64 s[16:17], s[14:15], 10
	s_mul_hi_i32 s15, s14, 0x300
	s_mulk_i32 s14, 0x300
	v_or_b32_e32 v68, s16, v72
	v_mov_b32_e32 v69, s17
	s_add_u32 s14, s44, s14
	v_lshl_add_u64 v[70:71], s[28:29], 0, v[68:69]
	s_addc_u32 s15, s45, s15
	s_add_i32 s20, s2, 8
	global_load_ushort v178, v[70:71], off
	v_lshl_add_u64 v[70:71], s[34:35], 0, v[68:69]
	v_lshl_add_u64 v[68:69], s[38:39], 0, v[68:69]
	s_sub_i32 s16, s21, s20
	global_load_ushort v181, v[70:71], off
	global_load_ushort v185, v[68:69], off
	global_load_ushort v187, v66, s[14:15]
	global_load_ushort v188, v66, s[14:15] offset:256
	s_and_b64 s[14:15], s[22:23], exec
	s_cselect_b32 s14, s19, s16
	s_min_i32 s15, s14, s31
	s_cmp_gt_i32 s14, -1
	s_cselect_b32 s15, s15, 0
	s_add_i32 s16, s15, s25
	s_ashr_i32 s17, s16, 31
	s_lshl_b64 s[18:19], s[16:17], 10
	v_or_b32_e32 v68, s18, v72
	v_mov_b32_e32 v69, s19
	s_mul_hi_i32 s15, s16, 0x300
	s_mulk_i32 s16, 0x300
	v_lshl_add_u64 v[70:71], s[28:29], 0, v[68:69]
	s_add_u32 s16, s44, s16
	global_load_ushort v194, v[70:71], off
	v_lshl_add_u64 v[70:71], s[34:35], 0, v[68:69]
	v_lshl_add_u64 v[68:69], s[38:39], 0, v[68:69]
	s_addc_u32 s17, s45, s15
	s_add_i32 s11, s11, -9
	global_load_ushort v195, v[70:71], off
	global_load_ushort v197, v[68:69], off
	global_load_ushort v214, v66, s[16:17]
	global_load_ushort v215, v66, s[16:17] offset:256
	s_and_b64 s[16:17], s[22:23], exec
	s_cselect_b32 s11, s20, s11
	s_min_i32 s15, s11, s31
	s_cmp_gt_i32 s11, -1
	s_cselect_b32 s15, s15, 0
	s_add_i32 s16, s15, s25
	s_ashr_i32 s17, s16, 31
	s_lshl_b64 s[18:19], s[16:17], 10
	v_or_b32_e32 v68, s18, v72
	v_mov_b32_e32 v69, s19
	v_lshl_add_u64 v[70:71], s[28:29], 0, v[68:69]
	global_load_ushort v220, v[70:71], off
	v_lshl_add_u64 v[70:71], s[34:35], 0, v[68:69]
	global_load_ushort v227, v[70:71], off
	s_mul_hi_i32 s15, s16, 0x300
	s_mulk_i32 s16, 0x300
	s_add_u32 s16, s44, s16
	v_lshl_add_u64 v[68:69], s[38:39], 0, v[68:69]
	s_addc_u32 s17, s45, s15
	global_load_ushort v237, v[68:69], off
	global_load_ushort v239, v66, s[16:17]
	global_load_ushort v241, v66, s[16:17] offset:256
	s_add_i32 s4, s4, 0
	s_waitcnt vmcnt(48)
	v_cvt_f32_f16_e32 v69, v110
	s_add_i32 s4, s4, 0x1e000
	s_cmp_lt_u32 s6, s21
	s_cselect_b64 vcc, -1, 0
	v_cvt_f32_f16_e32 v68, v109
	v_cndmask_b32_e32 v134, 0, v69, vcc
	s_waitcnt vmcnt(45)
	v_cvt_f32_f16_e32 v69, v113
	v_cvt_f32_f16_e32 v70, v111
	v_cndmask_b32_e32 v136, 0, v68, vcc
	v_cvt_f32_f16_e32 v68, v112
	v_cndmask_b32_e32 v141, 0, v69, vcc
	s_waitcnt vmcnt(43)
	v_cvt_f32_f16_e32 v69, v115
	s_cmp_lt_u32 s5, s21
	v_cndmask_b32_e32 v137, 0, v70, vcc
	v_cndmask_b32_e32 v140, 0, v68, vcc
	s_cselect_b64 vcc, -1, 0
	v_cvt_f32_f16_e32 v68, v114
	v_cndmask_b32_e32 v144, 0, v69, vcc
	s_waitcnt vmcnt(40)
	v_cvt_f32_f16_e32 v69, v118
	v_cvt_f32_f16_e32 v70, v116
	v_cndmask_b32_e32 v145, 0, v68, vcc
	v_cvt_f32_f16_e32 v68, v117
	v_cndmask_b32_e32 v149, 0, v69, vcc
	s_waitcnt vmcnt(38)
	v_cvt_f32_f16_e32 v69, v120
	s_cmp_lt_u32 s7, s21
	v_cndmask_b32_e32 v146, 0, v70, vcc
	v_cndmask_b32_e32 v148, 0, v68, vcc
	s_cselect_b64 vcc, -1, 0
	v_cvt_f32_f16_e32 v68, v119
	v_cndmask_b32_e32 v170, 0, v69, vcc
	s_waitcnt vmcnt(35)
	v_cvt_f32_f16_e32 v69, v123
	v_cvt_f32_f16_e32 v70, v121
	v_cndmask_b32_e32 v172, 0, v68, vcc
	v_cvt_f32_f16_e32 v68, v122
	v_cndmask_b32_e32 v177, 0, v69, vcc
	s_waitcnt vmcnt(33)
	v_cvt_f32_f16_e32 v69, v125
	s_cmp_lt_u32 s8, s21
	v_cndmask_b32_e32 v173, 0, v70, vcc
	v_cndmask_b32_e32 v176, 0, v68, vcc
	s_cselect_b64 vcc, -1, 0
	v_cvt_f32_f16_e32 v68, v124
	v_cndmask_b32_e32 v179, 0, v69, vcc
	s_waitcnt vmcnt(30)
; template <int R>
; __device__ __forceinline__ void scan_item(const Args& a, int layer, int q, int rowhalf, LAS unsigned char* lds, int tid, int lane, int wave) {
;     ...
;         SCAN_LOAD_RAW(0); SCAN_UNPACK(0);
;         for (int c = -1; c < nch; ++c) {
;             if (c >= 1) scan_flush<R>(lds, c - 1, pw, lane, d, T, tok0, h, rowbase, Yf, Yb);
;             if (c + 1 < nch) {
;                 const int cp = c + 1; LAS float* op = (LAS float*)(lds + (cp & 1) * SC_OPB);
;                 if (c + 2 < nch) SCAN_LOAD_RAW(c + 2);
;                 float bsv = 0.f;
; #pragma unroll
;                 for (int s8 = 0; s8 < 8; ++s8) {
;                     const float wl = mix3f(cur.wl[s8], cur.wl[s8 + 1], cur.wl[s8 + 2], mu_wl);
;                     const float al = mix3f(cur.al[s8], cur.al[s8 + 1], cur.al[s8 + 2], mu_al);
;                     const float e2 = __expf(2.0f * wl); const float th = 1.0f - 2.0f * __builtin_amdgcn_rcpf(e2 + 1.0f);
;                     LAS h16* xs = (LAS h16*)(xsb + s8 * 256);
;                     xs[j] = (h16)th; xs[64 + j] = (h16)al;
;                 }
;                 {
;                     const LAS unsigned char* xr = xsb + (lane & 7) * 256 + (lane >> 4) * 16;
;                     const h16x8 xw0 = *(const LAS h16x8a*)(xr), xw1 = *(const LAS h16x8a*)(xr + 64), xa0 = *(const LAS h16x8a*)(xr + 128), xa1 = *(const LAS h16x8a*)(xr + 192);
;                     f32x4 accw[4], acca[4];
; #pragma unroll
;                     for (int nt = 0; nt < 4; ++nt) {
;                         accw[nt] = __builtin_amdgcn_mfma_f32_16x16x32_f16(xw0, bw[nt][0], (f32x4){0.f, 0.f, 0.f, 0.f}, 0, 0, 0);
;                         accw[nt] = __builtin_amdgcn_mfma_f32_16x16x32_f16(xw1, bw[nt][1], accw[nt], 0, 0, 0);
;                         acca[nt] = __builtin_amdgcn_mfma_f32_16x16x32_f16(xa0, ba[nt][0], (f32x4){0.f, 0.f, 0.f, 0.f}, 0, 0, 0);
;                         acca[nt] = __builtin_amdgcn_mfma_f32_16x16x32_f16(xa1, ba[nt][1], acca[nt], 0, 0, 0); }
;                     if (lane < 32) {
;                         LAS float* zw = zl + (4 * (lane >> 4)) * 64 + (lane & 15);
; #pragma unroll
;                         for (int nt = 0; nt < 4; ++nt)
; #pragma unroll
;                             for (int r = 0; r < 4; ++r) { zw[r * 64 + 16 * nt] = accw[nt][r]; zw[512 + r * 64 + 16 * nt] = acca[nt][r]; }
;                     }
;                 }
	v_cvt_f32_f16_e32 v69, v128
	v_cvt_f32_f16_e32 v70, v126
	v_cndmask_b32_e32 v180, 0, v68, vcc
	v_cvt_f32_f16_e32 v68, v127
	v_cndmask_b32_e32 v184, 0, v69, vcc
	s_waitcnt vmcnt(28)
	v_cvt_f32_f16_e32 v69, v130
	s_cmp_lt_u32 s9, s21
	v_cndmask_b32_e32 v182, 0, v70, vcc
	v_cndmask_b32_e32 v183, 0, v68, vcc
	s_cselect_b64 vcc, -1, 0
	v_cvt_f32_f16_e32 v68, v129
	v_cndmask_b32_e32 v186, 0, v69, vcc
	s_waitcnt vmcnt(25)
	v_cvt_f32_f16_e32 v69, v133
	v_cvt_f32_f16_e32 v70, v131
	v_cndmask_b32_e32 v189, 0, v68, vcc
	v_cvt_f32_f16_e32 v68, v132
	v_cndmask_b32_e32 v193, 0, v69, vcc
	s_waitcnt vmcnt(23)
	v_cvt_f32_f16_e32 v69, v138
	s_cmp_lt_u32 s10, s21
	v_cndmask_b32_e32 v191, 0, v70, vcc
	v_cndmask_b32_e32 v192, 0, v68, vcc
	s_cselect_b64 vcc, -1, 0
	v_cvt_f32_f16_e32 v68, v135
	v_cndmask_b32_e32 v196, 0, v69, vcc
	s_waitcnt vmcnt(20)
	v_cvt_f32_f16_e32 v69, v143
	v_cvt_f32_f16_e32 v70, v139
	v_cndmask_b32_e32 v198, 0, v68, vcc
	v_cvt_f32_f16_e32 v68, v142
	v_cndmask_b32_e32 v213, 0, v69, vcc
	s_waitcnt vmcnt(18)
	v_cvt_f32_f16_e32 v69, v150
	s_cmp_lt_u32 s12, s21
	v_cndmask_b32_e32 v211, 0, v70, vcc
	v_cndmask_b32_e32 v212, 0, v68, vcc
	s_cselect_b64 vcc, -1, 0
	v_cvt_f32_f16_e32 v68, v147
	v_cndmask_b32_e32 v216, 0, v69, vcc
	s_waitcnt vmcnt(15)
	v_cvt_f32_f16_e32 v69, v175
	v_cvt_f32_f16_e32 v70, v151
	v_cndmask_b32_e32 v217, 0, v68, vcc
	v_cvt_f32_f16_e32 v68, v174
	v_cndmask_b32_e32 v225, 0, v69, vcc
	s_waitcnt vmcnt(13)
	v_cvt_f32_f16_e32 v69, v181
	s_cmp_lt_u32 s13, s21
	v_cndmask_b32_e32 v218, 0, v70, vcc
	v_cndmask_b32_e32 v223, 0, v68, vcc
	s_cselect_b64 vcc, -1, 0
	v_cvt_f32_f16_e32 v68, v178
	v_cndmask_b32_e32 v230, 0, v69, vcc
	s_waitcnt vmcnt(10)
	v_cvt_f32_f16_e32 v69, v188
	v_cvt_f32_f16_e32 v70, v185
	v_cndmask_b32_e32 v235, 0, v68, vcc
	v_cvt_f32_f16_e32 v68, v187
	v_cndmask_b32_e32 v240, 0, v69, vcc
	s_waitcnt vmcnt(8)
	v_cvt_f32_f16_e32 v69, v195
	s_cmp_lt_u32 s14, s21
	v_cndmask_b32_e32 v236, 0, v70, vcc
	v_cndmask_b32_e32 v238, 0, v68, vcc
	s_cselect_b64 vcc, -1, 0
	v_cvt_f32_f16_e32 v68, v194
	v_cndmask_b32_e32 v242, 0, v69, vcc
	s_waitcnt vmcnt(5)
	v_cvt_f32_f16_e32 v69, v215
	v_cvt_f32_f16_e32 v70, v197
	v_cndmask_b32_e32 v243, 0, v68, vcc
	v_cvt_f32_f16_e32 v68, v214
	v_cndmask_b32_e32 v246, 0, v69, vcc
	s_waitcnt vmcnt(3)
	v_cvt_f32_f16_e32 v69, v227
	s_cmp_lt_u32 s11, s21
	v_cndmask_b32_e32 v244, 0, v70, vcc
	v_cndmask_b32_e32 v245, 0, v68, vcc
	s_cselect_b64 vcc, -1, 0
	v_cndmask_b32_e32 v247, 0, v69, vcc
	s_waitcnt vmcnt(0)
	v_cvt_f32_f16_e32 v69, v241
	v_cvt_f32_f16_e32 v70, v237
	v_cvt_f32_f16_e32 v68, v220
	s_add_i32 s2, 0, 0x18000
	v_cndmask_b32_e32 v204, 0, v69, vcc
	v_lshlrev_b32_e32 v69, 2, v171
	v_and_b32_e32 v96, 28, v69
	v_cndmask_b32_e32 v206, 0, v70, vcc
	v_lshlrev_b32_e32 v70, 2, v96
	v_cndmask_b32_e32 v205, 0, v68, vcc
	v_cvt_f32_f16_e32 v68, v239
	s_add_i32 s3, s3, 0
	v_add3_u32 v224, s2, v219, v70
	v_lshlrev_b32_e32 v70, 8, v171
	s_add_i32 s3, s3, 0x1c000
	v_and_b32_e32 v70, 0x700, v70
	v_mov_b32_e32 v67, v153
	v_add_u32_e32 v226, s3, v66
	v_add_u32_e32 v70, s3, v70
	v_readlane_b32 s3, v253, 55
	v_lshl_add_u64 v[98:99], s[44:45], 0, v[66:67]
	s_lshl_b32 s2, s37, 3
	v_sub_u32_e32 v66, s3, v91
	v_cndmask_b32_e32 v210, 0, v68, vcc
	v_add_u32_e32 v68, s4, v152
	v_and_b32_e32 v71, 48, v190
	v_cmp_gt_u32_e32 vcc, 8, v171
	v_subrev_u32_e32 v229, s2, v66
	v_add_u32_e32 v66, s2, v171
	v_cvt_pk_f16_f32 v54, v79, v87
	v_cvt_pk_f16_f32 v58, v80, v88
	v_cvt_pk_f16_f32 v62, v81, v89
	v_add_u32_e32 v222, 0, v69
	v_cmp_gt_u32_e64 s[6:7], 32, v171
	v_add_u32_e32 v190, s4, v69
	s_and_b64 s[4:5], s[78:79], vcc
	s_mulk_i32 s27, 0x600
	v_cmp_eq_u32_e64 s[8:9], 7, v171
	v_cmp_eq_u32_e64 s[10:11], 6, v171
	v_cmp_eq_u32_e64 s[12:13], 5, v171
	v_cmp_eq_u32_e64 s[14:15], 4, v171
	v_cmp_eq_u32_e64 s[16:17], 3, v171
	v_cmp_eq_u32_e64 s[18:19], 2, v171
	v_cmp_eq_u32_e64 s[20:21], 1, v171
	v_cmp_eq_u32_e64 s[22:23], 0, v171
	s_add_i32 s28, s2, 8
	s_sub_i32 s29, 0, s2
	v_sub_u32_e32 v231, 31, v66
	s_movk_i32 s34, 0xc000
	v_add_u32_e32 v233, v70, v71
	v_add_u32_e32 v234, v68, v65
	s_branch .LBB0_485

; #define LAS __attribute__((address_space(3)))
; template <int R>
; __device__ __forceinline__ void scan_flush(LAS unsigned char* lds, int cf, int pw, int lane, int d, int T, int tok0, int h, int rowbase, h16* Yf, h16* Yb) {
;     ...
;         const int r4 = (lane & 7) * 4;
;         const f32x4 y0 = *(const LAS f32x4*)(yb + s * 32 + r4);
;         u32x2 w2; w2.x = pk2h(y0.x, y0.y); w2.y = pk2h(y0.z, y0.w);
;         if (d == 0) *(u32x2*)(Yf + (size_t)(tok0 + t) * 1024 + 512 + h * 64 + rowbase + r4) = w2; else *(u32x2*)(Yb + (size_t)(tok0 + t) * 512 + h * 64 + rowbase + r4) = w2;
; template <int R>
; __device__ __forceinline__ void scan_item(const Args& a, int layer, int q, int rowhalf, LAS unsigned char* lds, int tid, int lane, int wave) {
;     ...
;         scan_flush<R>(lds, nch - 1, pw, lane, d, T, tok0, h, rowbase, Yf, Yb);
.LBB0_500:
	s_setprio 1
	v_readlane_b32 s2, v250, 50
	v_lshlrev_b32_e32 v0, 2, v96
	v_readlane_b32 s4, v250, 2
	v_add_u32_e32 v6, s2, v221
	s_add_i32 s2, 0, 0x1a000
	v_add3_u32 v0, s2, v219, v0
	ds_read_b128 v[0:3], v0
	v_readlane_b32 s5, v250, 3
	s_mov_b64 s[2:3], -1
	s_and_b64 vcc, exec, s[4:5]
	s_cbranch_vccz .LBB0_502
	v_readlane_b32 s2, v250, 46
	s_nop 1
	v_xad_u32 v4, v6, -1, s2
	v_ashrrev_i32_e32 v5, 31, v4
	v_readlane_b32 s2, v250, 39
	v_lshlrev_b64 v[4:5], 10, v[4:5]
	v_readlane_b32 s3, v250, 40
	s_nop 1
	v_lshl_add_u64 v[4:5], s[2:3], 0, v[4:5]
	s_mov_b64 s[2:3], 0

; #define PG8_STAGE(bufoff, gbase, voff) do { _Pragma("unroll") for (int _i = 0; _i < 2; ++_i) \
;         __builtin_amdgcn_global_load_lds((const unsigned*)((const char*)(gbase) + (voff)[_i]), (LAS unsigned*)(lds + (bufoff) + ldsw + _i * 8192), 16, 0, 0); } while (0)
; #define PG8_LDA(dst, b, h) do { _Pragma("unroll") for (int m = 0; m < 4; ++m) _Pragma("unroll") for (int k = 0; k < 2; ++k) dst[m][k] = *(const LAS h16x8*)(lds + PG8_SA(b, h) + aoff + m * 2048 + k * 1024); } while (0)
; #define PG8_LDB(dst, b, h) do { _Pragma("unroll") for (int n = 0; n < 2; ++n) _Pragma("unroll") for (int k = 0; k < 2; ++k) dst[n][k] = *(const LAS h16x8*)(lds + PG8_SB(b, h) + boff + n * 2048 + k * 1024); } while (0)
; #define PG8_MMA(ai, bj, At, Bt) do { __builtin_amdgcn_s_setprio(1); _Pragma("unroll") for (int m = 0; m < 4; ++m) _Pragma("unroll") for (int n = 0; n < 2; ++n) _Pragma("unroll") for (int k = 0; k < 2; ++k) \
;         acc[ai][bj][m][n] = __builtin_amdgcn_mfma_f32_16x16x32_f16(Bt[n][k], At[m][k], acc[ai][bj][m][n], 0, 0, 0); __builtin_amdgcn_s_setprio(0); } while (0)
; #define PG8_WAIT_V(n) asm volatile("s_waitcnt vmcnt(" #n ")" ::: "memory")
; #define PG8_WAIT_L(n) asm volatile("s_waitcnt lgkmcnt(" #n ")" ::: "memory")
; #define PG8_BAR __builtin_amdgcn_s_barrier()
; #define PG8_SCHED __builtin_amdgcn_sched_barrier(0)
; template <class Epi>
; __device__ __forceinline__ void gemm_phase(LAS unsigned char* lds, const Gemm g, const StaticOrder& S, const Epi& E, const int tid) {
;     ...
;             const bool last = (t == nt - 2);
;             const char* a1 = cA + (size_t)(t + 1) * kstep;
;             const char* a2 = last ? nA : cA + (size_t)(t + 2) * kstep; const char* b2 = last ? nB : cB + (size_t)(t + 2) * kstep;
;             const char* a3 = a2 + kstep; const char* b3 = b2 + kstep;
;             PG8_LDB(B0, 0, 0); PG8_LDB(B1, 0, 1); PG8_SCHED; PG8_LDA(At, 0, 0); PG8_STAGE(PG8_SA(1, 1), a1 + hstepA, voffA);
;             PG8_WAIT_V(8); PG8_WAIT_L(0); PG8_BAR; PG8_MMA(0, 0, At, B0); PG8_MMA(0, 1, At, B1); PG8_BAR; PG8_SCHED;
;             PG8_LDA(At, 0, 1); PG8_STAGE(PG8_SB(0, 0), b2, voffB); PG8_STAGE(PG8_SB(0, 1), b2 + hstepB, voffB); PG8_STAGE(PG8_SA(0, 0), a2, voffA);
;             PG8_WAIT_V(8); PG8_WAIT_L(0); PG8_BAR; PG8_MMA(1, 0, At, B0); PG8_MMA(1, 1, At, B1); PG8_BAR; PG8_SCHED;
.LBB0_579:
	s_add_u32 s22, s20, 0xfffc0080
	s_addc_u32 s23, s21, -1
	s_add_i32 s31, 0, 0x10000
	s_cmp_eq_u32 s44, 12
	s_cselect_b32 s25, s15, s23
	s_cselect_b32 s24, s42, s22
	s_cselect_b32 s23, s13, s3
	s_cselect_b32 s22, s43, s2
	s_add_i32 s45, 0, 0x14000
	v_add_u32_e32 v140, s31, v189
	v_add_u32_e32 v162, s45, v189
	ds_read_b128 v[128:131], v140
	ds_read_b128 v[132:135], v140 offset:1024
	ds_read_b128 v[136:139], v140 offset:2048
	ds_read_b128 v[140:143], v140 offset:3072
	ds_read_b128 v[144:147], v162
	ds_read_b128 v[148:151], v162 offset:1024
	ds_read_b128 v[154:157], v162 offset:2048
	ds_read_b128 v[162:165], v162 offset:3072
	v_lshl_add_u64 v[166:167], s[20:21], 0, v[172:173]
	s_add_i32 m0, s28, 0xc000
	ds_read_b128 v[176:179], v191
	ds_read_b128 v[180:183], v191 offset:1024
	ds_read_b128 v[184:187], v191 offset:2048
	ds_read_b128 v[192:195], v191 offset:3072
	ds_read_b128 v[210:213], v191 offset:4096
	ds_read_b128 v[214:217], v191 offset:5120
	ds_read_b128 v[218:221], v191 offset:6144
	ds_read_b128 v[222:225], v191 offset:7168
	global_load_lds_dwordx4 v[166:167], off
	v_lshl_add_u64 v[166:167], s[20:21], 0, v[174:175]
	s_add_i32 m0, s28, 0xe000
	s_nop 0
	global_load_lds_dwordx4 v[166:167], off
	s_waitcnt vmcnt(8)
	s_waitcnt lgkmcnt(0)
	s_barrier
	s_waitcnt lgkmcnt(0)
	v_mfma_f32_16x16x32_f16 v[124:127], v[128:131], v[176:179], v[124:127]
	v_mfma_f32_16x16x32_f16 v[120:123], v[136:139], v[176:179], v[120:123]
	v_mfma_f32_16x16x32_f16 v[108:111], v[128:131], v[184:187], v[108:111]
	v_mfma_f32_16x16x32_f16 v[104:107], v[136:139], v[184:187], v[104:107]
	v_mfma_f32_16x16x32_f16 v[92:95], v[128:131], v[210:213], v[92:95]
	v_mfma_f32_16x16x32_f16 v[88:91], v[136:139], v[210:213], v[88:91]
	v_mfma_f32_16x16x32_f16 v[76:79], v[128:131], v[218:221], v[76:79]
	v_mfma_f32_16x16x32_f16 v[72:75], v[136:139], v[218:221], v[72:75]
	v_mfma_f32_16x16x32_f16 v[124:127], v[132:135], v[180:183], v[124:127]
	v_mfma_f32_16x16x32_f16 v[120:123], v[140:143], v[180:183], v[120:123]
	v_mfma_f32_16x16x32_f16 v[108:111], v[132:135], v[192:195], v[108:111]
	v_mfma_f32_16x16x32_f16 v[104:107], v[140:143], v[192:195], v[104:107]
	v_mfma_f32_16x16x32_f16 v[92:95], v[132:135], v[214:217], v[92:95]
	v_mfma_f32_16x16x32_f16 v[88:91], v[140:143], v[214:217], v[88:91]
	v_mfma_f32_16x16x32_f16 v[76:79], v[132:135], v[222:225], v[76:79]
	v_mfma_f32_16x16x32_f16 v[72:75], v[140:143], v[222:225], v[72:75]
	v_mfma_f32_16x16x32_f16 v[116:119], v[144:147], v[176:179], v[116:119]
	v_mfma_f32_16x16x32_f16 v[112:115], v[154:157], v[176:179], v[112:115]
	v_mfma_f32_16x16x32_f16 v[100:103], v[144:147], v[184:187], v[100:103]
	v_mfma_f32_16x16x32_f16 v[96:99], v[154:157], v[184:187], v[96:99]
	v_mfma_f32_16x16x32_f16 v[84:87], v[144:147], v[210:213], v[84:87]
	v_mfma_f32_16x16x32_f16 v[80:83], v[154:157], v[210:213], v[80:83]
	v_mfma_f32_16x16x32_f16 v[68:71], v[144:147], v[218:221], v[68:71]
	v_mfma_f32_16x16x32_f16 v[64:67], v[154:157], v[218:221], v[64:67]
	v_mfma_f32_16x16x32_f16 v[116:119], v[148:151], v[180:183], v[116:119]
	v_mfma_f32_16x16x32_f16 v[112:115], v[162:165], v[180:183], v[112:115]
	v_mfma_f32_16x16x32_f16 v[100:103], v[148:151], v[192:195], v[100:103]
	v_mfma_f32_16x16x32_f16 v[96:99], v[162:165], v[192:195], v[96:99]
	v_mfma_f32_16x16x32_f16 v[84:87], v[148:151], v[214:217], v[84:87]
	v_mfma_f32_16x16x32_f16 v[80:83], v[162:165], v[214:217], v[80:83]
	v_mfma_f32_16x16x32_f16 v[68:71], v[148:151], v[222:225], v[68:71]
	v_mfma_f32_16x16x32_f16 v[64:67], v[162:165], v[222:225], v[64:67]
	s_barrier
	s_add_i32 s31, s31, s27
	v_lshl_add_u64 v[166:167], s[22:23], 0, v[152:153]
	s_mov_b32 m0, s31
	ds_read_b128 v[176:179], v191 offset:16384
	ds_read_b128 v[180:183], v191 offset:17408
	ds_read_b128 v[184:187], v191 offset:18432
	ds_read_b128 v[192:195], v191 offset:19456
	ds_read_b128 v[210:213], v191 offset:20480
	ds_read_b128 v[214:217], v191 offset:21504
	ds_read_b128 v[218:221], v191 offset:22528
	ds_read_b128 v[222:225], v191 offset:23552
	global_load_lds_dwordx4 v[166:167], off
	s_add_i32 m0, s31, 0x2000
	s_add_u32 s46, s22, 0x40000
	v_lshl_add_u64 v[196:197], s[22:23], 0, v[170:171]
	s_addc_u32 s47, s23, 0
	s_add_i32 s31, s45, s27
	global_load_lds_dwordx4 v[196:197], off
	v_lshl_add_u64 v[204:205], s[46:47], 0, v[152:153]
	s_mov_b32 m0, s31
	v_lshl_add_u64 v[226:227], s[24:25], 0, v[170:171]
	global_load_lds_dwordx4 v[204:205], off
	v_lshl_add_u64 v[204:205], s[46:47], 0, v[170:171]
	s_add_i32 m0, s31, 0x2000
	s_nop 0
	global_load_lds_dwordx4 v[204:205], off
	v_lshl_add_u64 v[204:205], s[24:25], 0, v[152:153]
	s_mov_b32 m0, s28
	s_nop 0
	global_load_lds_dwordx4 v[204:205], off
	s_mov_b32 m0, s29
	s_nop 0
	global_load_lds_dwordx4 v[226:227], off
	s_waitcnt vmcnt(8)
	s_waitcnt lgkmcnt(0)
	s_barrier
; #define PG8_STAGE(bufoff, gbase, voff) do { _Pragma("unroll") for (int _i = 0; _i < 2; ++_i) \
;         __builtin_amdgcn_global_load_lds((const unsigned*)((const char*)(gbase) + (voff)[_i]), (LAS unsigned*)(lds + (bufoff) + ldsw + _i * 8192), 16, 0, 0); } while (0)
; #define PG8_LDA(dst, b, h) do { _Pragma("unroll") for (int m = 0; m < 4; ++m) _Pragma("unroll") for (int k = 0; k < 2; ++k) dst[m][k] = *(const LAS h16x8*)(lds + PG8_SA(b, h) + aoff + m * 2048 + k * 1024); } while (0)
; #define PG8_LDB(dst, b, h) do { _Pragma("unroll") for (int n = 0; n < 2; ++n) _Pragma("unroll") for (int k = 0; k < 2; ++k) dst[n][k] = *(const LAS h16x8*)(lds + PG8_SB(b, h) + boff + n * 2048 + k * 1024); } while (0)
; #define PG8_MMA(ai, bj, At, Bt) do { __builtin_amdgcn_s_setprio(1); _Pragma("unroll") for (int m = 0; m < 4; ++m) _Pragma("unroll") for (int n = 0; n < 2; ++n) _Pragma("unroll") for (int k = 0; k < 2; ++k) \
;         acc[ai][bj][m][n] = __builtin_amdgcn_mfma_f32_16x16x32_f16(Bt[n][k], At[m][k], acc[ai][bj][m][n], 0, 0, 0); __builtin_amdgcn_s_setprio(0); } while (0)
; #define PG8_WAIT_V(n) asm volatile("s_waitcnt vmcnt(" #n ")" ::: "memory")
; #define PG8_WAIT_L(n) asm volatile("s_waitcnt lgkmcnt(" #n ")" ::: "memory")
; #define PG8_BAR __builtin_amdgcn_s_barrier()
; #define PG8_SCHED __builtin_amdgcn_sched_barrier(0)
; template <class Epi>
; __device__ __forceinline__ void gemm_phase(LAS unsigned char* lds, const Gemm g, const StaticOrder& S, const Epi& E, const int tid) {
;     ...
;             PG8_WAIT_V(8); PG8_WAIT_L(0); PG8_BAR; PG8_MMA(1, 0, At, B0); PG8_MMA(1, 1, At, B1); PG8_BAR; PG8_SCHED;
;             PG8_LDB(B0, 1, 0); PG8_LDB(B1, 1, 1); PG8_SCHED; PG8_LDA(At, 1, 0); PG8_STAGE(PG8_SA(0, 1), a2 + hstepA, voffA);
;             PG8_WAIT_V(8); PG8_WAIT_L(0); PG8_BAR; PG8_MMA(0, 0, At, B0); PG8_MMA(0, 1, At, B1); PG8_BAR; PG8_SCHED;
	s_waitcnt lgkmcnt(0)
	v_mfma_f32_16x16x32_f16 v[60:63], v[128:131], v[176:179], v[60:63]
	v_mfma_f32_16x16x32_f16 v[56:59], v[136:139], v[176:179], v[56:59]
	v_mfma_f32_16x16x32_f16 v[44:47], v[128:131], v[184:187], v[44:47]
	v_mfma_f32_16x16x32_f16 v[40:43], v[136:139], v[184:187], v[40:43]
	v_mfma_f32_16x16x32_f16 v[28:31], v[128:131], v[210:213], v[28:31]
	v_mfma_f32_16x16x32_f16 v[24:27], v[136:139], v[210:213], v[24:27]
	v_mfma_f32_16x16x32_f16 v[12:15], v[128:131], v[218:221], v[12:15]
	v_mfma_f32_16x16x32_f16 v[8:11], v[136:139], v[218:221], v[8:11]
	v_mfma_f32_16x16x32_f16 v[60:63], v[132:135], v[180:183], v[60:63]
	v_mfma_f32_16x16x32_f16 v[56:59], v[140:143], v[180:183], v[56:59]
	v_mfma_f32_16x16x32_f16 v[44:47], v[132:135], v[192:195], v[44:47]
	v_mfma_f32_16x16x32_f16 v[40:43], v[140:143], v[192:195], v[40:43]
	v_mfma_f32_16x16x32_f16 v[28:31], v[132:135], v[214:217], v[28:31]
	v_mfma_f32_16x16x32_f16 v[24:27], v[140:143], v[214:217], v[24:27]
	v_mfma_f32_16x16x32_f16 v[12:15], v[132:135], v[222:225], v[12:15]
	v_mfma_f32_16x16x32_f16 v[8:11], v[140:143], v[222:225], v[8:11]
	v_mfma_f32_16x16x32_f16 v[52:55], v[144:147], v[176:179], v[52:55]
	v_mfma_f32_16x16x32_f16 v[48:51], v[154:157], v[176:179], v[48:51]
	v_mfma_f32_16x16x32_f16 v[36:39], v[144:147], v[184:187], v[36:39]
	v_mfma_f32_16x16x32_f16 v[32:35], v[154:157], v[184:187], v[32:35]
	v_mfma_f32_16x16x32_f16 v[20:23], v[144:147], v[210:213], v[20:23]
	v_mfma_f32_16x16x32_f16 v[16:19], v[154:157], v[210:213], v[16:19]
	v_mfma_f32_16x16x32_f16 v[4:7], v[144:147], v[218:221], v[4:7]
	v_mfma_f32_16x16x32_f16 v[0:3], v[154:157], v[218:221], v[0:3]
	v_mfma_f32_16x16x32_f16 v[52:55], v[148:151], v[180:183], v[52:55]
	v_mfma_f32_16x16x32_f16 v[48:51], v[162:165], v[180:183], v[48:51]
	v_mfma_f32_16x16x32_f16 v[36:39], v[148:151], v[192:195], v[36:39]
	v_mfma_f32_16x16x32_f16 v[32:35], v[162:165], v[192:195], v[32:35]
	v_mfma_f32_16x16x32_f16 v[20:23], v[148:151], v[214:217], v[20:23]
	v_mfma_f32_16x16x32_f16 v[16:19], v[162:165], v[214:217], v[16:19]
	v_mfma_f32_16x16x32_f16 v[4:7], v[148:151], v[222:225], v[4:7]
	v_mfma_f32_16x16x32_f16 v[0:3], v[162:165], v[222:225], v[0:3]
	s_barrier
	s_add_i32 s31, 0, 0x18000
	s_add_i32 s45, 0, 0x1c000
	v_add_u32_e32 v140, s31, v189
	v_add_u32_e32 v162, s45, v189
	ds_read_b128 v[128:131], v140
	ds_read_b128 v[132:135], v140 offset:1024
	ds_read_b128 v[136:139], v140 offset:2048
	ds_read_b128 v[140:143], v140 offset:3072
	ds_read_b128 v[144:147], v162
	ds_read_b128 v[148:151], v162 offset:1024
	ds_read_b128 v[154:157], v162 offset:2048
	ds_read_b128 v[162:165], v162 offset:3072
	s_add_u32 s24, s24, 0x40000
	s_addc_u32 s25, s25, 0
	s_mov_b32 m0, s34
	v_lshl_add_u64 v[228:229], s[24:25], 0, v[152:153]
	ds_read_b128 v[176:179], v191 offset:32768
	ds_read_b128 v[180:183], v191 offset:33792
	ds_read_b128 v[184:187], v191 offset:34816
	ds_read_b128 v[192:195], v191 offset:35840
	ds_read_b128 v[210:213], v191 offset:36864
	ds_read_b128 v[214:217], v191 offset:37888
	ds_read_b128 v[218:221], v191 offset:38912
	ds_read_b128 v[222:225], v191 offset:39936
	global_load_lds_dwordx4 v[228:229], off
	v_lshl_add_u64 v[228:229], s[24:25], 0, v[170:171]
	s_mov_b32 m0, s35
	s_nop 0
	global_load_lds_dwordx4 v[228:229], off
	s_waitcnt vmcnt(8)
	s_waitcnt lgkmcnt(0)
	s_barrier
	s_waitcnt lgkmcnt(0)
	v_mfma_f32_16x16x32_f16 v[124:127], v[128:131], v[176:179], v[124:127]
	v_mfma_f32_16x16x32_f16 v[120:123], v[136:139], v[176:179], v[120:123]
	v_mfma_f32_16x16x32_f16 v[108:111], v[128:131], v[184:187], v[108:111]
	v_mfma_f32_16x16x32_f16 v[104:107], v[136:139], v[184:187], v[104:107]
	v_mfma_f32_16x16x32_f16 v[92:95], v[128:131], v[210:213], v[92:95]
	v_mfma_f32_16x16x32_f16 v[88:91], v[136:139], v[210:213], v[88:91]
	v_mfma_f32_16x16x32_f16 v[76:79], v[128:131], v[218:221], v[76:79]
	v_mfma_f32_16x16x32_f16 v[72:75], v[136:139], v[218:221], v[72:75]
	v_mfma_f32_16x16x32_f16 v[124:127], v[132:135], v[180:183], v[124:127]
	v_mfma_f32_16x16x32_f16 v[120:123], v[140:143], v[180:183], v[120:123]
	v_mfma_f32_16x16x32_f16 v[108:111], v[132:135], v[192:195], v[108:111]
	v_mfma_f32_16x16x32_f16 v[104:107], v[140:143], v[192:195], v[104:107]
	v_mfma_f32_16x16x32_f16 v[92:95], v[132:135], v[214:217], v[92:95]
	v_mfma_f32_16x16x32_f16 v[88:91], v[140:143], v[214:217], v[88:91]
	v_mfma_f32_16x16x32_f16 v[76:79], v[132:135], v[222:225], v[76:79]
	v_mfma_f32_16x16x32_f16 v[72:75], v[140:143], v[222:225], v[72:75]
	v_mfma_f32_16x16x32_f16 v[116:119], v[144:147], v[176:179], v[116:119]
	v_mfma_f32_16x16x32_f16 v[112:115], v[154:157], v[176:179], v[112:115]
	v_mfma_f32_16x16x32_f16 v[100:103], v[144:147], v[184:187], v[100:103]
	v_mfma_f32_16x16x32_f16 v[96:99], v[154:157], v[184:187], v[96:99]
	v_mfma_f32_16x16x32_f16 v[84:87], v[144:147], v[210:213], v[84:87]
	v_mfma_f32_16x16x32_f16 v[80:83], v[154:157], v[210:213], v[80:83]
	v_mfma_f32_16x16x32_f16 v[68:71], v[144:147], v[218:221], v[68:71]
	v_mfma_f32_16x16x32_f16 v[64:67], v[154:157], v[218:221], v[64:67]
	v_mfma_f32_16x16x32_f16 v[116:119], v[148:151], v[180:183], v[116:119]
	v_mfma_f32_16x16x32_f16 v[112:115], v[162:165], v[180:183], v[112:115]
	v_mfma_f32_16x16x32_f16 v[100:103], v[148:151], v[192:195], v[100:103]
	v_mfma_f32_16x16x32_f16 v[96:99], v[162:165], v[192:195], v[96:99]
	v_mfma_f32_16x16x32_f16 v[84:87], v[148:151], v[214:217], v[84:87]
	v_mfma_f32_16x16x32_f16 v[80:83], v[162:165], v[214:217], v[80:83]
	v_mfma_f32_16x16x32_f16 v[68:71], v[148:151], v[222:225], v[68:71]
	v_mfma_f32_16x16x32_f16 v[64:67], v[162:165], v[222:225], v[64:67]
	s_barrier
; #define PG8_STAGE(bufoff, gbase, voff) do { _Pragma("unroll") for (int _i = 0; _i < 2; ++_i) \
;         __builtin_amdgcn_global_load_lds((const unsigned*)((const char*)(gbase) + (voff)[_i]), (LAS unsigned*)(lds + (bufoff) + ldsw + _i * 8192), 16, 0, 0); } while (0)
; #define PG8_LDA(dst, b, h) do { _Pragma("unroll") for (int m = 0; m < 4; ++m) _Pragma("unroll") for (int k = 0; k < 2; ++k) dst[m][k] = *(const LAS h16x8*)(lds + PG8_SA(b, h) + aoff + m * 2048 + k * 1024); } while (0)
; #define PG8_LDB(dst, b, h) do { _Pragma("unroll") for (int n = 0; n < 2; ++n) _Pragma("unroll") for (int k = 0; k < 2; ++k) dst[n][k] = *(const LAS h16x8*)(lds + PG8_SB(b, h) + boff + n * 2048 + k * 1024); } while (0)
; #define PG8_MMA(ai, bj, At, Bt) do { __builtin_amdgcn_s_setprio(1); _Pragma("unroll") for (int m = 0; m < 4; ++m) _Pragma("unroll") for (int n = 0; n < 2; ++n) _Pragma("unroll") for (int k = 0; k < 2; ++k) \
;         acc[ai][bj][m][n] = __builtin_amdgcn_mfma_f32_16x16x32_f16(Bt[n][k], At[m][k], acc[ai][bj][m][n], 0, 0, 0); __builtin_amdgcn_s_setprio(0); } while (0)
; #define PG8_WAIT_V(n) asm volatile("s_waitcnt vmcnt(" #n ")" ::: "memory")
; #define PG8_WAIT_L(n) asm volatile("s_waitcnt lgkmcnt(" #n ")" ::: "memory")
; #define PG8_BAR __builtin_amdgcn_s_barrier()
; #define PG8_SCHED __builtin_amdgcn_sched_barrier(0)
; template <class Epi>
; __device__ __forceinline__ void gemm_phase(LAS unsigned char* lds, const Gemm g, const StaticOrder& S, const Epi& E, const int tid) {
;     ...
;             PG8_WAIT_V(8); PG8_WAIT_L(0); PG8_BAR; PG8_MMA(1, 0, At, B0); PG8_MMA(1, 1, At, B1); PG8_BAR; PG8_SCHED;
;             PG8_LDB(B0, 1, 0); PG8_LDB(B1, 1, 1); PG8_SCHED; PG8_LDA(At, 1, 0); PG8_STAGE(PG8_SA(0, 1), a2 + hstepA, voffA);
;             PG8_WAIT_V(8); PG8_WAIT_L(0); PG8_BAR; PG8_MMA(0, 0, At, B0); PG8_MMA(0, 1, At, B1); PG8_BAR; PG8_SCHED;
;             PG8_LDA(At, 1, 1); PG8_STAGE(PG8_SB(1, 0), b3, voffB); PG8_STAGE(PG8_SB(1, 1), b3 + hstepB, voffB); PG8_STAGE(PG8_SA(1, 0), a3, voffA);
;             PG8_WAIT_V(8); PG8_WAIT_L(0); PG8_BAR; PG8_MMA(1, 0, At, B0); PG8_MMA(1, 1, At, B1); PG8_BAR; PG8_SCHED;
;         }
;         if (wr == 0) PG8_BAR;
	s_add_i32 s24, s31, s27
	v_lshl_add_u64 v[166:167], v[166:167], 0, s[0:1]
	s_mov_b32 m0, s24
	ds_read_b128 v[176:179], v191 offset:49152
	ds_read_b128 v[180:183], v191 offset:50176
	ds_read_b128 v[184:187], v191 offset:51200
	ds_read_b128 v[192:195], v191 offset:52224
	ds_read_b128 v[210:213], v191 offset:53248
	ds_read_b128 v[214:217], v191 offset:54272
	ds_read_b128 v[218:221], v191 offset:55296
	ds_read_b128 v[222:225], v191 offset:56320
	global_load_lds_dwordx4 v[166:167], off
	s_add_i32 m0, s24, 0x2000
	s_add_u32 s22, s22, 0x40080
	v_lshl_add_u64 v[166:167], v[196:197], 0, s[0:1]
	s_addc_u32 s23, s23, 0
	s_add_i32 s24, s45, s27
	global_load_lds_dwordx4 v[166:167], off
	v_lshl_add_u64 v[166:167], s[22:23], 0, v[152:153]
	s_mov_b32 m0, s24
	s_nop 0
	global_load_lds_dwordx4 v[166:167], off
	v_lshl_add_u64 v[166:167], s[22:23], 0, v[170:171]
	s_add_i32 m0, s24, 0x2000
	s_nop 0
	global_load_lds_dwordx4 v[166:167], off
	v_lshl_add_u64 v[166:167], v[204:205], 0, s[0:1]
	s_mov_b32 m0, s36
	s_nop 0
	global_load_lds_dwordx4 v[166:167], off
	v_lshl_add_u64 v[166:167], v[226:227], 0, s[0:1]
	s_mov_b32 m0, s37
	s_nop 0
	global_load_lds_dwordx4 v[166:167], off
	s_waitcnt vmcnt(8)
	s_waitcnt lgkmcnt(0)
	s_barrier
	s_waitcnt lgkmcnt(0)
	v_mfma_f32_16x16x32_f16 v[60:63], v[128:131], v[176:179], v[60:63]
	v_mfma_f32_16x16x32_f16 v[56:59], v[136:139], v[176:179], v[56:59]
	v_mfma_f32_16x16x32_f16 v[44:47], v[128:131], v[184:187], v[44:47]
	v_mfma_f32_16x16x32_f16 v[40:43], v[136:139], v[184:187], v[40:43]
	v_mfma_f32_16x16x32_f16 v[28:31], v[128:131], v[210:213], v[28:31]
	v_mfma_f32_16x16x32_f16 v[24:27], v[136:139], v[210:213], v[24:27]
	v_mfma_f32_16x16x32_f16 v[12:15], v[128:131], v[218:221], v[12:15]
	v_mfma_f32_16x16x32_f16 v[8:11], v[136:139], v[218:221], v[8:11]
	v_mfma_f32_16x16x32_f16 v[60:63], v[132:135], v[180:183], v[60:63]
	v_mfma_f32_16x16x32_f16 v[56:59], v[140:143], v[180:183], v[56:59]
	v_mfma_f32_16x16x32_f16 v[44:47], v[132:135], v[192:195], v[44:47]
	v_mfma_f32_16x16x32_f16 v[40:43], v[140:143], v[192:195], v[40:43]
	v_mfma_f32_16x16x32_f16 v[28:31], v[132:135], v[214:217], v[28:31]
	v_mfma_f32_16x16x32_f16 v[24:27], v[140:143], v[214:217], v[24:27]
	v_mfma_f32_16x16x32_f16 v[12:15], v[132:135], v[222:225], v[12:15]
	v_mfma_f32_16x16x32_f16 v[8:11], v[140:143], v[222:225], v[8:11]
	v_mfma_f32_16x16x32_f16 v[52:55], v[144:147], v[176:179], v[52:55]
	v_mfma_f32_16x16x32_f16 v[48:51], v[154:157], v[176:179], v[48:51]
	v_mfma_f32_16x16x32_f16 v[36:39], v[144:147], v[184:187], v[36:39]
	v_mfma_f32_16x16x32_f16 v[32:35], v[154:157], v[184:187], v[32:35]
	v_mfma_f32_16x16x32_f16 v[20:23], v[144:147], v[210:213], v[20:23]
	v_mfma_f32_16x16x32_f16 v[16:19], v[154:157], v[210:213], v[16:19]
	v_mfma_f32_16x16x32_f16 v[4:7], v[144:147], v[218:221], v[4:7]
	v_mfma_f32_16x16x32_f16 v[0:3], v[154:157], v[218:221], v[0:3]
	v_mfma_f32_16x16x32_f16 v[52:55], v[148:151], v[180:183], v[52:55]
	v_mfma_f32_16x16x32_f16 v[48:51], v[162:165], v[180:183], v[48:51]
	v_mfma_f32_16x16x32_f16 v[36:39], v[148:151], v[192:195], v[36:39]
	v_mfma_f32_16x16x32_f16 v[32:35], v[162:165], v[192:195], v[32:35]
	v_mfma_f32_16x16x32_f16 v[20:23], v[148:151], v[214:217], v[20:23]
	v_mfma_f32_16x16x32_f16 v[16:19], v[162:165], v[214:217], v[16:19]
	v_mfma_f32_16x16x32_f16 v[4:7], v[148:151], v[222:225], v[4:7]
	v_mfma_f32_16x16x32_f16 v[0:3], v[162:165], v[222:225], v[0:3]
	s_barrier
	s_add_i32 s44, s44, 2
	s_add_u32 s20, s20, 0x100
	s_addc_u32 s21, s21, 0
	s_add_u32 s2, s2, 0x100
	s_addc_u32 s3, s3, 0
	s_cmp_gt_u32 s44, 13
	s_cbranch_scc0 .LBB0_579
	s_and_b64 vcc, exec, s[10:11]
	s_cbranch_vccz .LBB0_582
	s_barrier

; #define PG8_STAGE(bufoff, gbase, voff) do { _Pragma("unroll") for (int _i = 0; _i < 2; ++_i) \
;         __builtin_amdgcn_global_load_lds((const unsigned*)((const char*)(gbase) + (voff)[_i]), (LAS unsigned*)(lds + (bufoff) + ldsw + _i * 8192), 16, 0, 0); } while (0)
; #define PG8_LDA(dst, b, h) do { _Pragma("unroll") for (int m = 0; m < 4; ++m) _Pragma("unroll") for (int k = 0; k < 2; ++k) dst[m][k] = *(const LAS h16x8*)(lds + PG8_SA(b, h) + aoff + m * 2048 + k * 1024); } while (0)
; #define PG8_LDB(dst, b, h) do { _Pragma("unroll") for (int n = 0; n < 2; ++n) _Pragma("unroll") for (int k = 0; k < 2; ++k) dst[n][k] = *(const LAS h16x8*)(lds + PG8_SB(b, h) + boff + n * 2048 + k * 1024); } while (0)
; #define PG8_MMA(ai, bj, At, Bt) do { __builtin_amdgcn_s_setprio(1); _Pragma("unroll") for (int m = 0; m < 4; ++m) _Pragma("unroll") for (int n = 0; n < 2; ++n) _Pragma("unroll") for (int k = 0; k < 2; ++k) \
;         acc[ai][bj][m][n] = __builtin_amdgcn_mfma_f32_16x16x32_f16(Bt[n][k], At[m][k], acc[ai][bj][m][n], 0, 0, 0); __builtin_amdgcn_s_setprio(0); } while (0)
; #define PG8_WAIT_V(n) asm volatile("s_waitcnt vmcnt(" #n ")" ::: "memory")
; #define PG8_BAR __builtin_amdgcn_s_barrier()
; template <class Epi>
; __device__ __forceinline__ void gemm_phase(LAS unsigned char* lds, const Gemm g, const StaticOrder& S, const Epi& E, const int tid) {
;     ...
;         const char* nA = has_next ? (const char*)g.A + (size_t)nxt.pm * tstepA : cA; const char* nB = has_next ? (const char*)g.Bt + (size_t)nxt.pn * tstepB : cB;
;         for (int t = 0; t < nt; t += 2) {
;             const bool last = (t == nt - 2);
;             const char* a1 = cA + (size_t)(t + 1) * kstep;
;             const char* a2 = last ? nA : cA + (size_t)(t + 2) * kstep; const char* b2 = last ? nB : cB + (size_t)(t + 2) * kstep;
;             const char* a3 = a2 + kstep; const char* b3 = b2 + kstep;
;             PG8_LDB(B0, 0, 0); PG8_LDB(B1, 0, 1); PG8_SCHED; PG8_LDA(At, 0, 0); PG8_STAGE(PG8_SA(1, 1), a1 + hstepA, voffA);
;             PG8_WAIT_V(8); PG8_WAIT_L(0); PG8_BAR; PG8_MMA(0, 0, At, B0); PG8_MMA(0, 1, At, B1); PG8_BAR; PG8_SCHED;
;             PG8_LDA(At, 0, 1); PG8_STAGE(PG8_SB(0, 0), b2, voffB); PG8_STAGE(PG8_SB(0, 1), b2 + hstepB, voffB); PG8_STAGE(PG8_SA(0, 0), a2, voffA);
;             PG8_WAIT_V(8); PG8_WAIT_L(0); PG8_BAR; PG8_MMA(1, 0, At, B0); PG8_MMA(1, 1, At, B1); PG8_BAR; PG8_SCHED;
.LBB0_616:
	s_add_u32 s20, s18, 0xfffc0080
	s_addc_u32 s21, s19, -1
	s_add_i32 s31, 0, 0x10000
	s_cmp_eq_u32 s41, 12
	s_cselect_b32 s23, s13, s21
	s_cselect_b32 s22, s39, s20
	s_cselect_b32 s21, s11, s3
	s_cselect_b32 s20, s40, s2
	s_add_i32 s44, 0, 0x14000
	v_add_u32_e32 v140, s31, v195
	v_add_u32_e32 v166, s44, v195
	ds_read_b128 v[128:131], v140
	ds_read_b128 v[132:135], v140 offset:1024
	ds_read_b128 v[136:139], v140 offset:2048
	ds_read_b128 v[140:143], v140 offset:3072
	ds_read_b128 v[154:157], v166
	ds_read_b128 v[162:165], v166 offset:1024
	ds_read_b128 v[174:177], v166 offset:2048
	ds_read_b128 v[178:181], v166 offset:3072
	v_lshl_add_u64 v[166:167], s[18:19], 0, v[170:171]
	s_add_i32 m0, s25, 0xc000
	ds_read_b128 v[182:185], v211
	ds_read_b128 v[190:193], v211 offset:1024
	ds_read_b128 v[212:215], v211 offset:2048
	ds_read_b128 v[216:219], v211 offset:3072
	ds_read_b128 v[220:223], v211 offset:4096
	ds_read_b128 v[224:227], v211 offset:5120
	ds_read_b128 v[228:231], v211 offset:6144
	ds_read_b128 v[232:235], v211 offset:7168
	global_load_lds_dwordx4 v[166:167], off
	v_lshl_add_u64 v[166:167], s[18:19], 0, v[172:173]
	s_add_i32 m0, s25, 0xe000
	s_nop 0
	global_load_lds_dwordx4 v[166:167], off
	s_waitcnt vmcnt(8)
	s_waitcnt lgkmcnt(0)
	s_barrier
	s_waitcnt lgkmcnt(0)
	v_mfma_f32_16x16x32_f16 v[124:127], v[128:131], v[182:185], v[124:127]
	v_mfma_f32_16x16x32_f16 v[116:119], v[136:139], v[182:185], v[116:119]
	v_mfma_f32_16x16x32_f16 v[108:111], v[128:131], v[212:215], v[108:111]
	v_mfma_f32_16x16x32_f16 v[100:103], v[136:139], v[212:215], v[100:103]
	v_mfma_f32_16x16x32_f16 v[92:95], v[128:131], v[220:223], v[92:95]
	v_mfma_f32_16x16x32_f16 v[84:87], v[136:139], v[220:223], v[84:87]
	v_mfma_f32_16x16x32_f16 v[76:79], v[128:131], v[228:231], v[76:79]
	v_mfma_f32_16x16x32_f16 v[68:71], v[136:139], v[228:231], v[68:71]
	v_mfma_f32_16x16x32_f16 v[124:127], v[132:135], v[190:193], v[124:127]
	v_mfma_f32_16x16x32_f16 v[116:119], v[140:143], v[190:193], v[116:119]
	v_mfma_f32_16x16x32_f16 v[108:111], v[132:135], v[216:219], v[108:111]
	v_mfma_f32_16x16x32_f16 v[100:103], v[140:143], v[216:219], v[100:103]
	v_mfma_f32_16x16x32_f16 v[92:95], v[132:135], v[224:227], v[92:95]
	v_mfma_f32_16x16x32_f16 v[84:87], v[140:143], v[224:227], v[84:87]
	v_mfma_f32_16x16x32_f16 v[76:79], v[132:135], v[232:235], v[76:79]
	v_mfma_f32_16x16x32_f16 v[68:71], v[140:143], v[232:235], v[68:71]
	v_mfma_f32_16x16x32_f16 v[120:123], v[154:157], v[182:185], v[120:123]
	v_mfma_f32_16x16x32_f16 v[112:115], v[174:177], v[182:185], v[112:115]
	v_mfma_f32_16x16x32_f16 v[104:107], v[154:157], v[212:215], v[104:107]
	v_mfma_f32_16x16x32_f16 v[96:99], v[174:177], v[212:215], v[96:99]
	v_mfma_f32_16x16x32_f16 v[88:91], v[154:157], v[220:223], v[88:91]
	v_mfma_f32_16x16x32_f16 v[80:83], v[174:177], v[220:223], v[80:83]
	v_mfma_f32_16x16x32_f16 v[72:75], v[154:157], v[228:231], v[72:75]
	v_mfma_f32_16x16x32_f16 v[64:67], v[174:177], v[228:231], v[64:67]
	v_mfma_f32_16x16x32_f16 v[120:123], v[162:165], v[190:193], v[120:123]
	v_mfma_f32_16x16x32_f16 v[112:115], v[178:181], v[190:193], v[112:115]
	v_mfma_f32_16x16x32_f16 v[104:107], v[162:165], v[216:219], v[104:107]
	v_mfma_f32_16x16x32_f16 v[96:99], v[178:181], v[216:219], v[96:99]
	v_mfma_f32_16x16x32_f16 v[88:91], v[162:165], v[224:227], v[88:91]
	v_mfma_f32_16x16x32_f16 v[80:83], v[178:181], v[224:227], v[80:83]
	v_mfma_f32_16x16x32_f16 v[72:75], v[162:165], v[232:235], v[72:75]
	v_mfma_f32_16x16x32_f16 v[64:67], v[178:181], v[232:235], v[64:67]
	s_barrier
	s_add_i32 s31, s31, s24
	v_lshl_add_u64 v[166:167], s[20:21], 0, v[152:153]
	s_mov_b32 m0, s31
	ds_read_b128 v[182:185], v211 offset:16384
	ds_read_b128 v[190:193], v211 offset:17408
	ds_read_b128 v[212:215], v211 offset:18432
	ds_read_b128 v[216:219], v211 offset:19456
	ds_read_b128 v[220:223], v211 offset:20480
	ds_read_b128 v[224:227], v211 offset:21504
	ds_read_b128 v[228:231], v211 offset:22528
	ds_read_b128 v[232:235], v211 offset:23552
	global_load_lds_dwordx4 v[166:167], off
	s_add_i32 m0, s31, 0x2000
	s_add_u32 s42, s20, 0x40000
	v_lshl_add_u64 v[186:187], s[20:21], 0, v[144:145]
	s_addc_u32 s43, s21, 0
	s_add_i32 s31, s44, s24
	global_load_lds_dwordx4 v[186:187], off
	v_lshl_add_u64 v[204:205], s[42:43], 0, v[152:153]
	s_mov_b32 m0, s31
	v_lshl_add_u64 v[236:237], s[22:23], 0, v[146:147]
	global_load_lds_dwordx4 v[204:205], off
	v_lshl_add_u64 v[204:205], s[42:43], 0, v[144:145]
	s_add_i32 m0, s31, 0x2000
	s_nop 0
	global_load_lds_dwordx4 v[204:205], off
	v_lshl_add_u64 v[204:205], s[22:23], 0, v[148:149]
	s_mov_b32 m0, s25
	s_nop 0
	global_load_lds_dwordx4 v[204:205], off
	s_mov_b32 m0, s26
	s_nop 0
	global_load_lds_dwordx4 v[236:237], off
	s_waitcnt vmcnt(8)
	s_waitcnt lgkmcnt(0)
	s_barrier
; #define PG8_STAGE(bufoff, gbase, voff) do { _Pragma("unroll") for (int _i = 0; _i < 2; ++_i) \
;         __builtin_amdgcn_global_load_lds((const unsigned*)((const char*)(gbase) + (voff)[_i]), (LAS unsigned*)(lds + (bufoff) + ldsw + _i * 8192), 16, 0, 0); } while (0)
; #define PG8_LDA(dst, b, h) do { _Pragma("unroll") for (int m = 0; m < 4; ++m) _Pragma("unroll") for (int k = 0; k < 2; ++k) dst[m][k] = *(const LAS h16x8*)(lds + PG8_SA(b, h) + aoff + m * 2048 + k * 1024); } while (0)
; #define PG8_LDB(dst, b, h) do { _Pragma("unroll") for (int n = 0; n < 2; ++n) _Pragma("unroll") for (int k = 0; k < 2; ++k) dst[n][k] = *(const LAS h16x8*)(lds + PG8_SB(b, h) + boff + n * 2048 + k * 1024); } while (0)
; #define PG8_MMA(ai, bj, At, Bt) do { __builtin_amdgcn_s_setprio(1); _Pragma("unroll") for (int m = 0; m < 4; ++m) _Pragma("unroll") for (int n = 0; n < 2; ++n) _Pragma("unroll") for (int k = 0; k < 2; ++k) \
;         acc[ai][bj][m][n] = __builtin_amdgcn_mfma_f32_16x16x32_f16(Bt[n][k], At[m][k], acc[ai][bj][m][n], 0, 0, 0); __builtin_amdgcn_s_setprio(0); } while (0)
; #define PG8_WAIT_V(n) asm volatile("s_waitcnt vmcnt(" #n ")" ::: "memory")
; #define PG8_WAIT_L(n) asm volatile("s_waitcnt lgkmcnt(" #n ")" ::: "memory")
; #define PG8_BAR __builtin_amdgcn_s_barrier()
; #define PG8_SCHED __builtin_amdgcn_sched_barrier(0)
; template <class Epi>
; __device__ __forceinline__ void gemm_phase(LAS unsigned char* lds, const Gemm g, const StaticOrder& S, const Epi& E, const int tid) {
;     ...
;             PG8_WAIT_V(8); PG8_WAIT_L(0); PG8_BAR; PG8_MMA(1, 0, At, B0); PG8_MMA(1, 1, At, B1); PG8_BAR; PG8_SCHED;
;             PG8_LDB(B0, 1, 0); PG8_LDB(B1, 1, 1); PG8_SCHED; PG8_LDA(At, 1, 0); PG8_STAGE(PG8_SA(0, 1), a2 + hstepA, voffA);
;             PG8_WAIT_V(8); PG8_WAIT_L(0); PG8_BAR; PG8_MMA(0, 0, At, B0); PG8_MMA(0, 1, At, B1); PG8_BAR; PG8_SCHED;
;             PG8_LDA(At, 1, 1); PG8_STAGE(PG8_SB(1, 0), b3, voffB); PG8_STAGE(PG8_SB(1, 1), b3 + hstepB, voffB); PG8_STAGE(PG8_SA(1, 0), a3, voffA);
	s_waitcnt lgkmcnt(0)
	v_mfma_f32_16x16x32_f16 v[60:63], v[128:131], v[182:185], v[60:63]
	v_mfma_f32_16x16x32_f16 v[52:55], v[136:139], v[182:185], v[52:55]
	v_mfma_f32_16x16x32_f16 v[44:47], v[128:131], v[212:215], v[44:47]
	v_mfma_f32_16x16x32_f16 v[36:39], v[136:139], v[212:215], v[36:39]
	v_mfma_f32_16x16x32_f16 v[28:31], v[128:131], v[220:223], v[28:31]
	v_mfma_f32_16x16x32_f16 v[20:23], v[136:139], v[220:223], v[20:23]
	v_mfma_f32_16x16x32_f16 v[12:15], v[128:131], v[228:231], v[12:15]
	v_mfma_f32_16x16x32_f16 v[4:7], v[136:139], v[228:231], v[4:7]
	v_mfma_f32_16x16x32_f16 v[60:63], v[132:135], v[190:193], v[60:63]
	v_mfma_f32_16x16x32_f16 v[52:55], v[140:143], v[190:193], v[52:55]
	v_mfma_f32_16x16x32_f16 v[44:47], v[132:135], v[216:219], v[44:47]
	v_mfma_f32_16x16x32_f16 v[36:39], v[140:143], v[216:219], v[36:39]
	v_mfma_f32_16x16x32_f16 v[28:31], v[132:135], v[224:227], v[28:31]
	v_mfma_f32_16x16x32_f16 v[20:23], v[140:143], v[224:227], v[20:23]
	v_mfma_f32_16x16x32_f16 v[12:15], v[132:135], v[232:235], v[12:15]
	v_mfma_f32_16x16x32_f16 v[4:7], v[140:143], v[232:235], v[4:7]
	v_mfma_f32_16x16x32_f16 v[56:59], v[154:157], v[182:185], v[56:59]
	v_mfma_f32_16x16x32_f16 v[48:51], v[174:177], v[182:185], v[48:51]
	v_mfma_f32_16x16x32_f16 v[40:43], v[154:157], v[212:215], v[40:43]
	v_mfma_f32_16x16x32_f16 v[32:35], v[174:177], v[212:215], v[32:35]
	v_mfma_f32_16x16x32_f16 v[24:27], v[154:157], v[220:223], v[24:27]
	v_mfma_f32_16x16x32_f16 v[16:19], v[174:177], v[220:223], v[16:19]
	v_mfma_f32_16x16x32_f16 v[8:11], v[154:157], v[228:231], v[8:11]
	v_mfma_f32_16x16x32_f16 v[0:3], v[174:177], v[228:231], v[0:3]
	v_mfma_f32_16x16x32_f16 v[56:59], v[162:165], v[190:193], v[56:59]
	v_mfma_f32_16x16x32_f16 v[48:51], v[178:181], v[190:193], v[48:51]
	v_mfma_f32_16x16x32_f16 v[40:43], v[162:165], v[216:219], v[40:43]
	v_mfma_f32_16x16x32_f16 v[32:35], v[178:181], v[216:219], v[32:35]
	v_mfma_f32_16x16x32_f16 v[24:27], v[162:165], v[224:227], v[24:27]
	v_mfma_f32_16x16x32_f16 v[16:19], v[178:181], v[224:227], v[16:19]
	v_mfma_f32_16x16x32_f16 v[8:11], v[162:165], v[232:235], v[8:11]
	v_mfma_f32_16x16x32_f16 v[0:3], v[178:181], v[232:235], v[0:3]
	s_barrier
	s_add_i32 s31, 0, 0x18000
	s_add_i32 s42, 0, 0x1c000
	v_add_u32_e32 v140, s31, v195
	v_add_u32_e32 v178, s42, v195
	ds_read_b128 v[128:131], v140
	ds_read_b128 v[132:135], v140 offset:1024
	ds_read_b128 v[136:139], v140 offset:2048
	ds_read_b128 v[140:143], v140 offset:3072
	ds_read_b128 v[154:157], v178
	ds_read_b128 v[162:165], v178 offset:1024
	ds_read_b128 v[174:177], v178 offset:2048
	ds_read_b128 v[178:181], v178 offset:3072
	s_add_u32 s22, s22, 0x40000
	s_addc_u32 s23, s23, 0
	s_mov_b32 m0, s27
	v_lshl_add_u64 v[238:239], s[22:23], 0, v[148:149]
	ds_read_b128 v[182:185], v211 offset:32768
	ds_read_b128 v[190:193], v211 offset:33792
	ds_read_b128 v[212:215], v211 offset:34816
	ds_read_b128 v[216:219], v211 offset:35840
	ds_read_b128 v[220:223], v211 offset:36864
	ds_read_b128 v[224:227], v211 offset:37888
	ds_read_b128 v[228:231], v211 offset:38912
	ds_read_b128 v[232:235], v211 offset:39936
	global_load_lds_dwordx4 v[238:239], off
	v_lshl_add_u64 v[238:239], s[22:23], 0, v[146:147]
	s_mov_b32 m0, s28
	s_nop 0
	global_load_lds_dwordx4 v[238:239], off
	s_waitcnt vmcnt(8)
	s_waitcnt lgkmcnt(0)
	s_barrier
	s_waitcnt lgkmcnt(0)
	v_mfma_f32_16x16x32_f16 v[124:127], v[128:131], v[182:185], v[124:127]
	v_mfma_f32_16x16x32_f16 v[116:119], v[136:139], v[182:185], v[116:119]
	v_mfma_f32_16x16x32_f16 v[108:111], v[128:131], v[212:215], v[108:111]
	v_mfma_f32_16x16x32_f16 v[100:103], v[136:139], v[212:215], v[100:103]
	v_mfma_f32_16x16x32_f16 v[92:95], v[128:131], v[220:223], v[92:95]
	v_mfma_f32_16x16x32_f16 v[84:87], v[136:139], v[220:223], v[84:87]
	v_mfma_f32_16x16x32_f16 v[76:79], v[128:131], v[228:231], v[76:79]
	v_mfma_f32_16x16x32_f16 v[68:71], v[136:139], v[228:231], v[68:71]
	v_mfma_f32_16x16x32_f16 v[124:127], v[132:135], v[190:193], v[124:127]
	v_mfma_f32_16x16x32_f16 v[116:119], v[140:143], v[190:193], v[116:119]
	v_mfma_f32_16x16x32_f16 v[108:111], v[132:135], v[216:219], v[108:111]
	v_mfma_f32_16x16x32_f16 v[100:103], v[140:143], v[216:219], v[100:103]
	v_mfma_f32_16x16x32_f16 v[92:95], v[132:135], v[224:227], v[92:95]
	v_mfma_f32_16x16x32_f16 v[84:87], v[140:143], v[224:227], v[84:87]
	v_mfma_f32_16x16x32_f16 v[76:79], v[132:135], v[232:235], v[76:79]
	v_mfma_f32_16x16x32_f16 v[68:71], v[140:143], v[232:235], v[68:71]
	v_mfma_f32_16x16x32_f16 v[120:123], v[154:157], v[182:185], v[120:123]
	v_mfma_f32_16x16x32_f16 v[112:115], v[174:177], v[182:185], v[112:115]
	v_mfma_f32_16x16x32_f16 v[104:107], v[154:157], v[212:215], v[104:107]
	v_mfma_f32_16x16x32_f16 v[96:99], v[174:177], v[212:215], v[96:99]
	v_mfma_f32_16x16x32_f16 v[88:91], v[154:157], v[220:223], v[88:91]
	v_mfma_f32_16x16x32_f16 v[80:83], v[174:177], v[220:223], v[80:83]
	v_mfma_f32_16x16x32_f16 v[72:75], v[154:157], v[228:231], v[72:75]
	v_mfma_f32_16x16x32_f16 v[64:67], v[174:177], v[228:231], v[64:67]
	v_mfma_f32_16x16x32_f16 v[120:123], v[162:165], v[190:193], v[120:123]
	v_mfma_f32_16x16x32_f16 v[112:115], v[178:181], v[190:193], v[112:115]
	v_mfma_f32_16x16x32_f16 v[104:107], v[162:165], v[216:219], v[104:107]
	v_mfma_f32_16x16x32_f16 v[96:99], v[178:181], v[216:219], v[96:99]
	v_mfma_f32_16x16x32_f16 v[88:91], v[162:165], v[224:227], v[88:91]
	v_mfma_f32_16x16x32_f16 v[80:83], v[178:181], v[224:227], v[80:83]
	v_mfma_f32_16x16x32_f16 v[72:75], v[162:165], v[232:235], v[72:75]
	v_mfma_f32_16x16x32_f16 v[64:67], v[178:181], v[232:235], v[64:67]
	s_barrier
; #define PG8_STAGE(bufoff, gbase, voff) do { _Pragma("unroll") for (int _i = 0; _i < 2; ++_i) \
;         __builtin_amdgcn_global_load_lds((const unsigned*)((const char*)(gbase) + (voff)[_i]), (LAS unsigned*)(lds + (bufoff) + ldsw + _i * 8192), 16, 0, 0); } while (0)
; #define PG8_LDA(dst, b, h) do { _Pragma("unroll") for (int m = 0; m < 4; ++m) _Pragma("unroll") for (int k = 0; k < 2; ++k) dst[m][k] = *(const LAS h16x8*)(lds + PG8_SA(b, h) + aoff + m * 2048 + k * 1024); } while (0)
; #define PG8_MMA(ai, bj, At, Bt) do { __builtin_amdgcn_s_setprio(1); _Pragma("unroll") for (int m = 0; m < 4; ++m) _Pragma("unroll") for (int n = 0; n < 2; ++n) _Pragma("unroll") for (int k = 0; k < 2; ++k) \
;         acc[ai][bj][m][n] = __builtin_amdgcn_mfma_f32_16x16x32_f16(Bt[n][k], At[m][k], acc[ai][bj][m][n], 0, 0, 0); __builtin_amdgcn_s_setprio(0); } while (0)
; #define PG8_WAIT_V(n) asm volatile("s_waitcnt vmcnt(" #n ")" ::: "memory")
; #define PG8_WAIT_L(n) asm volatile("s_waitcnt lgkmcnt(" #n ")" ::: "memory")
; #define PG8_BAR __builtin_amdgcn_s_barrier()
; #define PG8_SCHED __builtin_amdgcn_sched_barrier(0)
; template <class Epi>
; __device__ __forceinline__ void gemm_phase(LAS unsigned char* lds, const Gemm g, const StaticOrder& S, const Epi& E, const int tid) {
;     ...
;             PG8_LDA(At, 1, 1); PG8_STAGE(PG8_SB(1, 0), b3, voffB); PG8_STAGE(PG8_SB(1, 1), b3 + hstepB, voffB); PG8_STAGE(PG8_SA(1, 0), a3, voffA);
;             PG8_WAIT_V(8); PG8_WAIT_L(0); PG8_BAR; PG8_MMA(1, 0, At, B0); PG8_MMA(1, 1, At, B1); PG8_BAR; PG8_SCHED;
;         }
;         if (wr == 0) PG8_BAR;
	s_add_i32 s22, s31, s24
	v_lshl_add_u64 v[166:167], v[166:167], 0, s[0:1]
	s_mov_b32 m0, s22
	ds_read_b128 v[182:185], v211 offset:49152
	ds_read_b128 v[190:193], v211 offset:50176
	ds_read_b128 v[212:215], v211 offset:51200
	ds_read_b128 v[216:219], v211 offset:52224
	ds_read_b128 v[220:223], v211 offset:53248
	ds_read_b128 v[224:227], v211 offset:54272
	ds_read_b128 v[228:231], v211 offset:55296
	ds_read_b128 v[232:235], v211 offset:56320
	global_load_lds_dwordx4 v[166:167], off
	s_add_i32 m0, s22, 0x2000
	s_add_u32 s20, s20, 0x40080
	v_lshl_add_u64 v[166:167], v[186:187], 0, s[0:1]
	s_addc_u32 s21, s21, 0
	s_add_i32 s22, s42, s24
	global_load_lds_dwordx4 v[166:167], off
	v_lshl_add_u64 v[166:167], s[20:21], 0, v[152:153]
	s_mov_b32 m0, s22
	s_nop 0
	global_load_lds_dwordx4 v[166:167], off
	v_lshl_add_u64 v[166:167], s[20:21], 0, v[144:145]
	s_add_i32 m0, s22, 0x2000
	s_nop 0
	global_load_lds_dwordx4 v[166:167], off
	v_lshl_add_u64 v[166:167], v[204:205], 0, s[0:1]
	s_mov_b32 m0, s29
	s_nop 0
	global_load_lds_dwordx4 v[166:167], off
	v_lshl_add_u64 v[166:167], v[236:237], 0, s[0:1]
	s_mov_b32 m0, s35
	s_nop 0
	global_load_lds_dwordx4 v[166:167], off
	s_waitcnt vmcnt(8)
	s_waitcnt lgkmcnt(0)
	s_barrier
	s_waitcnt lgkmcnt(0)
	v_mfma_f32_16x16x32_f16 v[60:63], v[128:131], v[182:185], v[60:63]
	v_mfma_f32_16x16x32_f16 v[52:55], v[136:139], v[182:185], v[52:55]
	v_mfma_f32_16x16x32_f16 v[44:47], v[128:131], v[212:215], v[44:47]
	v_mfma_f32_16x16x32_f16 v[36:39], v[136:139], v[212:215], v[36:39]
	v_mfma_f32_16x16x32_f16 v[28:31], v[128:131], v[220:223], v[28:31]
	v_mfma_f32_16x16x32_f16 v[20:23], v[136:139], v[220:223], v[20:23]
	v_mfma_f32_16x16x32_f16 v[12:15], v[128:131], v[228:231], v[12:15]
	v_mfma_f32_16x16x32_f16 v[4:7], v[136:139], v[228:231], v[4:7]
	v_mfma_f32_16x16x32_f16 v[60:63], v[132:135], v[190:193], v[60:63]
	v_mfma_f32_16x16x32_f16 v[52:55], v[140:143], v[190:193], v[52:55]
	v_mfma_f32_16x16x32_f16 v[44:47], v[132:135], v[216:219], v[44:47]
	v_mfma_f32_16x16x32_f16 v[36:39], v[140:143], v[216:219], v[36:39]
	v_mfma_f32_16x16x32_f16 v[28:31], v[132:135], v[224:227], v[28:31]
	v_mfma_f32_16x16x32_f16 v[20:23], v[140:143], v[224:227], v[20:23]
	v_mfma_f32_16x16x32_f16 v[12:15], v[132:135], v[232:235], v[12:15]
	v_mfma_f32_16x16x32_f16 v[4:7], v[140:143], v[232:235], v[4:7]
	v_mfma_f32_16x16x32_f16 v[56:59], v[154:157], v[182:185], v[56:59]
	v_mfma_f32_16x16x32_f16 v[48:51], v[174:177], v[182:185], v[48:51]
	v_mfma_f32_16x16x32_f16 v[40:43], v[154:157], v[212:215], v[40:43]
	v_mfma_f32_16x16x32_f16 v[32:35], v[174:177], v[212:215], v[32:35]
	v_mfma_f32_16x16x32_f16 v[24:27], v[154:157], v[220:223], v[24:27]
	v_mfma_f32_16x16x32_f16 v[16:19], v[174:177], v[220:223], v[16:19]
	v_mfma_f32_16x16x32_f16 v[8:11], v[154:157], v[228:231], v[8:11]
	v_mfma_f32_16x16x32_f16 v[0:3], v[174:177], v[228:231], v[0:3]
	v_mfma_f32_16x16x32_f16 v[56:59], v[162:165], v[190:193], v[56:59]
	v_mfma_f32_16x16x32_f16 v[48:51], v[178:181], v[190:193], v[48:51]
	v_mfma_f32_16x16x32_f16 v[40:43], v[162:165], v[216:219], v[40:43]
	v_mfma_f32_16x16x32_f16 v[32:35], v[178:181], v[216:219], v[32:35]
	v_mfma_f32_16x16x32_f16 v[24:27], v[162:165], v[224:227], v[24:27]
	v_mfma_f32_16x16x32_f16 v[16:19], v[178:181], v[224:227], v[16:19]
	v_mfma_f32_16x16x32_f16 v[8:11], v[162:165], v[232:235], v[8:11]
	v_mfma_f32_16x16x32_f16 v[0:3], v[178:181], v[232:235], v[0:3]
	s_barrier
	s_add_i32 s41, s41, 2
	s_add_u32 s18, s18, 0x100
	s_addc_u32 s19, s19, 0
	s_add_u32 s2, s2, 0x100
	s_addc_u32 s3, s3, 0
	s_cmp_gt_u32 s41, 13
	s_cbranch_scc0 .LBB0_616
	s_and_b64 vcc, exec, s[8:9]
	s_cbranch_vccz .LBB0_619
	s_barrier

; template <int R>
; __device__ __forceinline__ void scan_item(const Args& a, int layer, int q, int rowhalf, LAS unsigned char* lds, int tid, int lane, int wave) {
;     ...
;         const int pw = wave - 4, j = lane, col = h * 64 + j;
;         const float* mu = a.in[I_MU] + l * 1920;
;         const float mu_r = mu[col], mu_k = mu[512 + col], mu_v = mu[1024 + col], mu_wl = mu[1536 + d * 64 + j], mu_al = mu[1536 + 128 + d * 64 + j];
;         const float k_k = a.in[I_KK][l * 512 + col], k_a = a.in[I_KA][l * 512 + col], r_k = a.in[I_RK][l * 512 + col];
;         const float w0 = a.in[I_W0][(l * 2 + d) * 512 + col], a0 = a.in[I_A0][(l * 2 + d) * 512 + col];
;         h16x8 bw[4][2], ba[4][2];
;         { const int n = lane & 15, kg = lane >> 4;
;           const float* wu = a.in[I_WUP] + ((l * 2 + d) * 64 + 8 * kg) * 512 + h * 64 + n; const float* au = a.in[I_AUP] + ((l * 2 + d) * 64 + 8 * kg) * 512 + h * 64 + n;
; #pragma unroll
;           for (int ks = 0; ks < 2; ++ks) {
; #pragma unroll
;               for (int e = 0; e < 8; ++e) {
;                   const float w_0 = wu[0], w_1 = wu[16], w_2 = wu[32], w_3 = wu[48], a_0 = au[0], a_1 = au[16], a_2 = au[32], a_3 = au[48];
;                   wu += 512; au += 512; asm volatile("" : "+v"(wu), "+v"(au));
;                   bw[0][ks][e] = (h16)w_0; bw[1][ks][e] = (h16)w_1; bw[2][ks][e] = (h16)w_2; bw[3][ks][e] = (h16)w_3;
;                   ba[0][ks][e] = (h16)a_0; ba[1][ks][e] = (h16)a_1; ba[2][ks][e] = (h16)a_2; ba[3][ks][e] = (h16)a_3; }
;               wu += 24 * 512; au += 24 * 512; asm volatile("" : "+v"(wu), "+v"(au)); } }
.LBB0_639:
	s_and_b64 vcc, exec, s[2:3]
	s_cbranch_vccz .LBB0_662
	s_setprio 0
	v_readlane_b32 s4, v248, 16
	v_and_b32_e32 v65, 63, v162
	s_mul_i32 s2, s74, 0x1e00
	v_readlane_b32 s10, v248, 22
	v_or_b32_e32 v64, s76, v65
	v_readlane_b32 s11, v248, 23
	s_add_u32 s2, s10, s2
	v_readlane_b32 s5, v248, 17
	s_addc_u32 s3, s11, 0
	v_lshlrev_b32_e32 v152, 2, v64
	v_lshl_add_u64 v[0:1], s[2:3], 0, v[152:153]
	s_movk_i32 s5, 0x1000
	v_add_co_u32_e32 v0, vcc, s5, v0
	v_readlane_b32 s4, v249, 39
	s_nop 0
	v_addc_co_u32_e32 v1, vcc, 0, v1, vcc
	global_load_dword v97, v152, s[2:3]
	global_load_dword v100, v152, s[2:3] offset:2048
	global_load_dword v101, v[0:1], off
	v_or_b32_e32 v0, s4, v65
	v_lshlrev_b32_e32 v0, 2, v0
	v_mov_b32_e32 v1, v153
	v_lshl_add_u64 v[0:1], s[2:3], 0, v[0:1]
	v_add_co_u32_e32 v0, vcc, s5, v0
	s_lshl_b64 s[2:3], s[74:75], 11
	s_nop 0
	v_addc_co_u32_e32 v1, vcc, 0, v1, vcc
	v_readlane_b32 s52, v248, 32
	v_readlane_b32 s4, v253, 16
	global_load_dword v102, v[0:1], off offset:2048
	global_load_dword v103, v[0:1], off offset:2560
	v_or_b32_e32 v0, s2, v152
	v_mov_b32_e32 v1, s3
	v_readlane_b32 s54, v248, 34
	v_readlane_b32 s55, v248, 35
	s_lshl_b64 s[2:3], s[74:75], 1
	v_readlane_b32 s5, v253, 17
	v_readlane_b32 s56, v248, 36
	v_readlane_b32 s57, v248, 37
	v_readlane_b32 s58, v248, 38
	v_readlane_b32 s59, v248, 39
	v_lshl_add_u64 v[2:3], s[54:55], 0, v[0:1]
	s_or_b64 s[2:3], s[2:3], s[4:5]
	global_load_dword v104, v[2:3], off
	v_lshl_add_u64 v[2:3], s[56:57], 0, v[0:1]
	v_lshl_add_u64 v[0:1], s[58:59], 0, v[0:1]
	s_lshl_b64 s[4:5], s[2:3], 11
	v_readlane_b32 s12, v248, 24
	v_readlane_b32 s13, v248, 25
	v_readlane_b32 s16, v248, 28
	v_readlane_b32 s17, v248, 29
	global_load_dword v106, v[0:1], off
	v_or_b32_e32 v0, s4, v152
	v_mov_b32_e32 v1, s5
	global_load_dword v105, v[2:3], off
	v_lshl_add_u64 v[2:3], s[12:13], 0, v[0:1]
	v_lshl_add_u64 v[0:1], s[16:17], 0, v[0:1]
	v_bfe_u32 v68, v162, 4, 2
	s_lshl_b64 s[2:3], s[2:3], 17
	global_load_dword v108, v[0:1], off
	v_lshl_or_b32 v0, v68, 14, s2
	v_mov_b32_e32 v1, s3
	v_readlane_b32 s2, v249, 40
	v_readlane_b32 s3, v249, 41
	global_load_dword v107, v[2:3], off
	v_lshlrev_b32_e32 v4, 2, v162
	v_lshl_add_u64 v[2:3], s[2:3], 0, v[0:1]
	v_readlane_b32 s2, v249, 42
	v_readlane_b32 s3, v249, 43
	v_and_b32_e32 v152, 60, v4
	v_lshl_add_u64 v[2:3], v[2:3], 0, v[152:153]
	v_lshl_add_u64 v[0:1], s[2:3], 0, v[0:1]
	v_lshl_add_u64 v[0:1], v[0:1], 0, v[152:153]
	s_mov_b64 s[2:3], 0x800
	global_load_dword v4, v[2:3], off
	global_load_dword v8, v[2:3], off offset:64
	global_load_dword v12, v[2:3], off offset:128
	global_load_dword v16, v[2:3], off offset:192
	global_load_dword v20, v[0:1], off
	global_load_dword v24, v[0:1], off offset:64
	global_load_dword v28, v[0:1], off offset:128
	global_load_dword v36, v[0:1], off offset:192
	v_lshl_add_u64 v[2:3], v[2:3], 0, s[2:3]
	v_lshl_add_u64 v[0:1], v[0:1], 0, s[2:3]
	flat_load_dword v5, v[2:3]
	flat_load_dword v9, v[2:3] offset:64
	flat_load_dword v13, v[2:3] offset:128
	flat_load_dword v17, v[2:3] offset:192
	flat_load_dword v21, v[0:1]
	flat_load_dword v25, v[0:1] offset:64
	flat_load_dword v29, v[0:1] offset:128
	flat_load_dword v37, v[0:1] offset:192
	v_lshl_add_u64 v[2:3], v[2:3], 0, s[2:3]
	v_lshl_add_u64 v[0:1], v[0:1], 0, s[2:3]
	flat_load_dword v6, v[2:3]
	flat_load_dword v10, v[2:3] offset:64
	flat_load_dword v14, v[2:3] offset:128
	flat_load_dword v18, v[2:3] offset:192
	flat_load_dword v22, v[0:1]
	flat_load_dword v26, v[0:1] offset:64
	flat_load_dword v30, v[0:1] offset:128
	flat_load_dword v38, v[0:1] offset:192
	v_lshl_add_u64 v[2:3], v[2:3], 0, s[2:3]
	v_lshl_add_u64 v[0:1], v[0:1], 0, s[2:3]
	flat_load_dword v7, v[2:3]
	flat_load_dword v11, v[2:3] offset:64
	flat_load_dword v15, v[2:3] offset:128
	flat_load_dword v19, v[2:3] offset:192
	flat_load_dword v23, v[0:1]
	flat_load_dword v27, v[0:1] offset:64
	flat_load_dword v31, v[0:1] offset:128
	flat_load_dword v39, v[0:1] offset:192
	v_lshl_add_u64 v[2:3], v[2:3], 0, s[2:3]
	v_lshl_add_u64 v[0:1], v[0:1], 0, s[2:3]
	flat_load_dword v40, v[2:3]
	flat_load_dword v41, v[2:3] offset:64
	flat_load_dword v42, v[2:3] offset:128
	flat_load_dword v43, v[2:3] offset:192
	flat_load_dword v44, v[0:1]
	flat_load_dword v45, v[0:1] offset:64
	flat_load_dword v46, v[0:1] offset:128
	flat_load_dword v47, v[0:1] offset:192
	v_lshl_add_u64 v[2:3], v[2:3], 0, s[2:3]
	v_lshl_add_u64 v[0:1], v[0:1], 0, s[2:3]
	flat_load_dword v48, v[2:3]
	flat_load_dword v49, v[2:3] offset:64
	flat_load_dword v50, v[2:3] offset:128
	flat_load_dword v51, v[2:3] offset:192
	flat_load_dword v52, v[0:1]
	flat_load_dword v53, v[0:1] offset:64
	flat_load_dword v54, v[0:1] offset:128
	flat_load_dword v55, v[0:1] offset:192
	v_lshl_add_u64 v[2:3], v[2:3], 0, s[2:3]
	v_lshl_add_u64 v[0:1], v[0:1], 0, s[2:3]
	flat_load_dword v56, v[2:3]
	flat_load_dword v57, v[2:3] offset:64
	flat_load_dword v58, v[2:3] offset:128
	flat_load_dword v59, v[2:3] offset:192
	flat_load_dword v60, v[0:1]
	flat_load_dword v61, v[0:1] offset:64
	flat_load_dword v62, v[0:1] offset:128
	flat_load_dword v63, v[0:1] offset:192
	v_lshl_add_u64 v[2:3], v[2:3], 0, s[2:3]
	v_lshl_add_u64 v[0:1], v[0:1], 0, s[2:3]
	flat_load_dword v66, v[2:3]
	flat_load_dword v67, v[2:3] offset:64
	flat_load_dword v69, v[2:3] offset:128
	flat_load_dword v70, v[2:3] offset:192
	flat_load_dword v71, v[0:1]
	flat_load_dword v72, v[0:1] offset:64
	flat_load_dword v73, v[0:1] offset:128
	flat_load_dword v74, v[0:1] offset:192
	v_lshl_add_u64 v[32:33], v[2:3], 0, s[2:3]
	v_lshl_add_u64 v[34:35], v[0:1], 0, s[2:3]
	s_mov_b64 s[4:5], 0xc000
	v_lshl_add_u64 v[32:33], v[32:33], 0, s[4:5]
	v_lshl_add_u64 v[34:35], v[34:35], 0, s[4:5]
	s_add_i32 s28, s34, -4
	v_readlane_b32 s8, v248, 20
	v_readlane_b32 s6, v248, 18
	v_readlane_b32 s7, v248, 19
	v_readlane_b32 s20, v250, 4
	v_readlane_b32 s9, v248, 21
	v_readlane_b32 s22, v250, 5
	v_readlane_b32 s23, v250, 6
	v_readlane_b32 s24, v250, 7
	v_readlane_b32 s36, v250, 9
	v_readlane_b32 s38, v253, 36
	v_readlane_b32 s25, v250, 8
	v_readlane_b32 s37, v250, 10
	v_readlane_b32 s39, v253, 37
	v_readlane_b32 s14, v248, 26
	v_readlane_b32 s15, v248, 27
	v_readlane_b32 s18, v248, 30
	v_readlane_b32 s19, v248, 31
	v_lshlrev_b32_e32 v68, 10, v68
	s_mov_b32 s26, 0
	s_mov_b32 s27, 1
	v_mov_b32_e32 v166, 0x3fff
	v_lshlrev_b32_e32 v236, 1, v64
	v_readlane_b32 s53, v248, 33
	v_readlane_b32 s60, v248, 40
	v_readlane_b32 s61, v248, 41
	v_readlane_b32 s62, v248, 42
	v_readlane_b32 s63, v248, 43
	v_readlane_b32 s64, v248, 44
	v_readlane_b32 s65, v248, 45
	v_readlane_b32 s66, v248, 46
	v_readlane_b32 s67, v248, 47
	s_waitcnt vmcnt(0) lgkmcnt(0)
; template <int R>
; __device__ __forceinline__ void scan_item(const Args& a, int layer, int q, int rowhalf, LAS unsigned char* lds, int tid, int lane, int wave) {
;     ...
;         { const int n = lane & 15, kg = lane >> 4;
;           const float* wu = a.in[I_WUP] + ((l * 2 + d) * 64 + 8 * kg) * 512 + h * 64 + n; const float* au = a.in[I_AUP] + ((l * 2 + d) * 64 + 8 * kg) * 512 + h * 64 + n;
; #pragma unroll
;           for (int ks = 0; ks < 2; ++ks) {
; #pragma unroll
;               for (int e = 0; e < 8; ++e) {
;                   const float w_0 = wu[0], w_1 = wu[16], w_2 = wu[32], w_3 = wu[48], a_0 = au[0], a_1 = au[16], a_2 = au[32], a_3 = au[48];
;                   wu += 512; au += 512; asm volatile("" : "+v"(wu), "+v"(au));
;                   bw[0][ks][e] = (h16)w_0; bw[1][ks][e] = (h16)w_1; bw[2][ks][e] = (h16)w_2; bw[3][ks][e] = (h16)w_3;
;                   ba[0][ks][e] = (h16)a_0; ba[1][ks][e] = (h16)a_1; ba[2][ks][e] = (h16)a_2; ba[3][ks][e] = (h16)a_3; }
;               wu += 24 * 512; au += 24 * 512; asm volatile("" : "+v"(wu), "+v"(au)); } }
	v_cvt_pk_f16_f32 v0, v4, v5
	v_cvt_pk_f16_f32 v4, v8, v9
	v_cvt_pk_f16_f32 v8, v12, v13
	v_cvt_pk_f16_f32 v12, v16, v17
	v_cvt_pk_f16_f32 v16, v20, v21
	v_cvt_pk_f16_f32 v20, v24, v25
	v_cvt_pk_f16_f32 v24, v28, v29
	v_cvt_pk_f16_f32 v28, v36, v37
	v_cvt_pk_f16_f32 v1, v6, v7
	v_cvt_pk_f16_f32 v5, v10, v11
	v_cvt_pk_f16_f32 v9, v14, v15
	v_cvt_pk_f16_f32 v13, v18, v19
	v_cvt_pk_f16_f32 v17, v22, v23
	v_cvt_pk_f16_f32 v21, v26, v27
	v_cvt_pk_f16_f32 v25, v30, v31
	v_cvt_pk_f16_f32 v29, v38, v39
	v_cvt_pk_f16_f32 v2, v40, v48
	v_cvt_pk_f16_f32 v6, v41, v49
	v_cvt_pk_f16_f32 v10, v42, v50
	v_cvt_pk_f16_f32 v14, v43, v51
	v_cvt_pk_f16_f32 v18, v44, v52
	v_cvt_pk_f16_f32 v22, v45, v53
	v_cvt_pk_f16_f32 v26, v46, v54
	v_cvt_pk_f16_f32 v30, v47, v55
	v_cvt_pk_f16_f32 v3, v56, v66
	v_cvt_pk_f16_f32 v7, v57, v67
	v_cvt_pk_f16_f32 v11, v58, v69
	v_cvt_pk_f16_f32 v15, v59, v70
	v_cvt_pk_f16_f32 v19, v60, v71
	flat_load_dword v36, v[32:33]
	flat_load_dword v40, v[32:33] offset:64
	flat_load_dword v44, v[32:33] offset:128
	flat_load_dword v48, v[32:33] offset:192
	flat_load_dword v52, v[34:35]
	flat_load_dword v56, v[34:35] offset:64
	flat_load_dword v60, v[34:35] offset:128
	flat_load_dword v69, v[34:35] offset:192
	v_lshl_add_u64 v[32:33], v[32:33], 0, s[2:3]
	v_lshl_add_u64 v[34:35], v[34:35], 0, s[2:3]
	v_cvt_pk_f16_f32 v23, v61, v72
	flat_load_dword v37, v[32:33]
	flat_load_dword v41, v[32:33] offset:64
	flat_load_dword v45, v[32:33] offset:128
	flat_load_dword v49, v[32:33] offset:192
	flat_load_dword v53, v[34:35]
	flat_load_dword v57, v[34:35] offset:64
	flat_load_dword v61, v[34:35] offset:128
	flat_load_dword v72, v[34:35] offset:192
	v_lshl_add_u64 v[32:33], v[32:33], 0, s[2:3]
	v_lshl_add_u64 v[34:35], v[34:35], 0, s[2:3]
	v_cvt_pk_f16_f32 v27, v62, v73
	flat_load_dword v38, v[32:33]
	flat_load_dword v42, v[32:33] offset:64
	flat_load_dword v46, v[32:33] offset:128
	flat_load_dword v50, v[32:33] offset:192
	flat_load_dword v54, v[34:35]
	flat_load_dword v58, v[34:35] offset:64
	flat_load_dword v62, v[34:35] offset:128
	flat_load_dword v73, v[34:35] offset:192
	v_lshl_add_u64 v[32:33], v[32:33], 0, s[2:3]
	v_lshl_add_u64 v[34:35], v[34:35], 0, s[2:3]
	v_cvt_pk_f16_f32 v31, v63, v74
	flat_load_dword v39, v[32:33]
	flat_load_dword v43, v[32:33] offset:64
	flat_load_dword v47, v[32:33] offset:128
	flat_load_dword v51, v[32:33] offset:192
	flat_load_dword v55, v[34:35]
	flat_load_dword v59, v[34:35] offset:64
	flat_load_dword v63, v[34:35] offset:128
	flat_load_dword v74, v[34:35] offset:192
	v_lshl_add_u64 v[32:33], v[32:33], 0, s[2:3]
	v_lshl_add_u64 v[34:35], v[34:35], 0, s[2:3]
	flat_load_dword v75, v[32:33]
	flat_load_dword v76, v[32:33] offset:64
	flat_load_dword v77, v[32:33] offset:128
	flat_load_dword v78, v[32:33] offset:192
	flat_load_dword v79, v[34:35]
	flat_load_dword v80, v[34:35] offset:64
	flat_load_dword v81, v[34:35] offset:128
	flat_load_dword v82, v[34:35] offset:192
	v_lshl_add_u64 v[32:33], v[32:33], 0, s[2:3]
	v_lshl_add_u64 v[34:35], v[34:35], 0, s[2:3]
	flat_load_dword v83, v[32:33]
	flat_load_dword v84, v[32:33] offset:64
	flat_load_dword v85, v[32:33] offset:128
	flat_load_dword v86, v[32:33] offset:192
	flat_load_dword v87, v[34:35]
	flat_load_dword v88, v[34:35] offset:64
	flat_load_dword v89, v[34:35] offset:128
	flat_load_dword v90, v[34:35] offset:192
	v_lshl_add_u64 v[32:33], v[32:33], 0, s[2:3]
	v_lshl_add_u64 v[34:35], v[34:35], 0, s[2:3]
	flat_load_dword v91, v[32:33]
	flat_load_dword v92, v[32:33] offset:64
	flat_load_dword v93, v[32:33] offset:128
	flat_load_dword v94, v[32:33] offset:192
	flat_load_dword v95, v[34:35]
	flat_load_dword v96, v[34:35] offset:64
	flat_load_dword v98, v[34:35] offset:128
	flat_load_dword v99, v[34:35] offset:192
	v_lshl_add_u64 v[32:33], v[32:33], 0, s[2:3]
	v_lshl_add_u64 v[34:35], v[34:35], 0, s[2:3]
	flat_load_dword v109, v[32:33]
	flat_load_dword v110, v[32:33] offset:64
	flat_load_dword v111, v[32:33] offset:128
	flat_load_dword v112, v[32:33] offset:192
	flat_load_dword v113, v[34:35]
	flat_load_dword v114, v[34:35] offset:64
	flat_load_dword v115, v[34:35] offset:128
	flat_load_dword v116, v[34:35] offset:192
	v_lshl_add_u64 v[66:67], v[32:33], 0, s[2:3]
	v_lshl_add_u64 v[70:71], v[34:35], 0, s[2:3]
	s_lshl_b32 s2, s28, 3
	v_lshl_add_u64 v[66:67], v[66:67], 0, s[4:5]
	v_lshl_add_u64 v[70:71], v[70:71], 0, s[4:5]
	s_lshl_b32 s4, s28, 12
	s_lshl_b32 s3, s28, 11
	s_add_i32 s5, s2, -1
	s_sub_i32 s8, 0x4000, s2
	s_and_b64 s[6:7], s[78:79], exec
	s_cselect_b32 s7, s5, s8
	s_mulk_i32 s28, 0x3000
	s_waitcnt vmcnt(0) lgkmcnt(0)
; template <int R>
; __device__ __forceinline__ void scan_item(const Args& a, int layer, int q, int rowhalf, LAS unsigned char* lds, int tid, int lane, int wave) {
;     ...
;               for (int e = 0; e < 8; ++e) {
;                   const float w_0 = wu[0], w_1 = wu[16], w_2 = wu[32], w_3 = wu[48], a_0 = au[0], a_1 = au[16], a_2 = au[32], a_3 = au[48];
;                   wu += 512; au += 512; asm volatile("" : "+v"(wu), "+v"(au));
;                   bw[0][ks][e] = (h16)w_0; bw[1][ks][e] = (h16)w_1; bw[2][ks][e] = (h16)w_2; bw[3][ks][e] = (h16)w_3;
;                   ba[0][ks][e] = (h16)a_0; ba[1][ks][e] = (h16)a_1; ba[2][ks][e] = (h16)a_2; ba[3][ks][e] = (h16)a_3; }
	v_cvt_pk_f16_f32 v32, v36, v37
	v_cvt_pk_f16_f32 v36, v40, v41
	v_cvt_pk_f16_f32 v40, v44, v45
	v_cvt_pk_f16_f32 v44, v48, v49
	v_cvt_pk_f16_f32 v48, v52, v53
	v_cvt_pk_f16_f32 v52, v56, v57
	v_cvt_pk_f16_f32 v56, v60, v61
	v_cvt_pk_f16_f32 v60, v69, v72
	v_lshlrev_b32_e32 v69, 1, v64
	v_cvt_pk_f16_f32 v33, v38, v39
	v_cvt_pk_f16_f32 v37, v42, v43
	v_cvt_pk_f16_f32 v41, v46, v47
	v_cvt_pk_f16_f32 v45, v50, v51
	v_cvt_pk_f16_f32 v49, v54, v55
	v_cvt_pk_f16_f32 v53, v58, v59
	v_cvt_pk_f16_f32 v57, v62, v63
	v_cvt_pk_f16_f32 v61, v73, v74
	v_mov_b32_e32 v74, 0x3fff
	v_med3_i32 v66, s7, 0, v74
	v_cvt_pk_f16_f32 v34, v75, v83
	v_readfirstlane_b32 s5, v66
	s_or_b32 s8, s5, s20
	s_ashr_i32 s9, s8, 31
	s_lshl_b64 s[10:11], s[8:9], 10
	v_or_b32_e32 v66, s10, v69
	v_mov_b32_e32 v67, s11
	s_mul_i32 s6, s8, 0x300
	v_lshl_add_u64 v[70:71], s[22:23], 0, v[66:67]
	s_mul_hi_i32 s5, s8, 0x300
	s_add_u32 s8, s38, s6
	v_cvt_pk_f16_f32 v35, v91, v109
	global_load_ushort v109, v[70:71], off
	v_lshl_add_u64 v[70:71], s[24:25], 0, v[66:67]
	v_lshl_add_u64 v[66:67], s[36:37], 0, v[66:67]
	s_addc_u32 s9, s39, s5
	s_or_b32 s29, s2, 1
	v_cvt_pk_f16_f32 v39, v92, v110
	v_cvt_pk_f16_f32 v43, v93, v111
	global_load_ushort v110, v[70:71], off
	global_load_ushort v111, v[66:67], off
	v_lshlrev_b32_e32 v66, 1, v65
	s_sub_i32 s5, 0x4000, s29
	v_cvt_pk_f16_f32 v47, v94, v112
	v_cvt_pk_f16_f32 v51, v95, v113
	global_load_ushort v112, v66, s[8:9]
	global_load_ushort v113, v66, s[8:9] offset:256
	s_and_b64 s[8:9], s[78:79], exec
	s_cselect_b32 s5, s2, s5
	v_med3_i32 v70, s5, 0, v74
	v_cvt_pk_f16_f32 v55, v96, v114
	v_readfirstlane_b32 s6, v70
	s_or_b32 s8, s6, s20
	s_ashr_i32 s9, s8, 31
	s_lshl_b64 s[10:11], s[8:9], 10
	s_mul_hi_i32 s6, s8, 0x300
	s_mulk_i32 s8, 0x300
	v_or_b32_e32 v70, s10, v69
	v_mov_b32_e32 v71, s11
	s_add_u32 s8, s38, s8
	v_lshl_add_u64 v[72:73], s[22:23], 0, v[70:71]
	s_addc_u32 s9, s39, s6
	s_or_b32 s12, s2, 2
	global_load_ushort v114, v[72:73], off
	v_lshl_add_u64 v[72:73], s[24:25], 0, v[70:71]
	v_lshl_add_u64 v[70:71], s[36:37], 0, v[70:71]
	s_sub_i32 s6, 0x4000, s12
	v_cvt_pk_f16_f32 v59, v98, v115
	v_cvt_pk_f16_f32 v63, v99, v116
	global_load_ushort v115, v[72:73], off
	global_load_ushort v116, v[70:71], off
	global_load_ushort v117, v66, s[8:9]
	global_load_ushort v118, v66, s[8:9] offset:256
	s_and_b64 s[8:9], s[78:79], exec
	s_cselect_b32 s6, s29, s6
	v_med3_i32 v70, s6, 0, v74
	v_mov_b32_e32 v67, v153
	v_readfirstlane_b32 s8, v70
	s_or_b32 s8, s8, s20
	s_ashr_i32 s9, s8, 31
	s_lshl_b64 s[10:11], s[8:9], 10
	s_mul_hi_i32 s9, s8, 0x300
	s_mulk_i32 s8, 0x300
	v_or_b32_e32 v70, s10, v69
	v_mov_b32_e32 v71, s11
	s_add_u32 s8, s38, s8
	v_lshl_add_u64 v[72:73], s[22:23], 0, v[70:71]
	s_addc_u32 s9, s39, s9
	s_or_b32 s14, s2, 3
	global_load_ushort v119, v[72:73], off
	v_lshl_add_u64 v[72:73], s[24:25], 0, v[70:71]
	v_lshl_add_u64 v[70:71], s[36:37], 0, v[70:71]
	s_sub_i32 s10, 0x4000, s14
	global_load_ushort v120, v[72:73], off
	global_load_ushort v121, v[70:71], off
	global_load_ushort v122, v66, s[8:9]
	global_load_ushort v123, v66, s[8:9] offset:256
	s_and_b64 s[8:9], s[78:79], exec
	s_cselect_b32 s8, s12, s10
	v_med3_i32 v70, s8, 0, v74
	v_lshl_add_u64 v[98:99], s[38:39], 0, v[66:67]
	v_readfirstlane_b32 s9, v70
	s_or_b32 s10, s9, s20
	s_ashr_i32 s11, s10, 31
	s_lshl_b64 s[12:13], s[10:11], 10
	s_mul_hi_i32 s9, s10, 0x300
	s_mulk_i32 s10, 0x300
	v_or_b32_e32 v70, s12, v69
	v_mov_b32_e32 v71, s13
	s_add_u32 s10, s38, s10
	v_lshl_add_u64 v[72:73], s[22:23], 0, v[70:71]
	s_addc_u32 s11, s39, s9
	s_or_b32 s15, s2, 4
	global_load_ushort v124, v[72:73], off
	v_lshl_add_u64 v[72:73], s[24:25], 0, v[70:71]
	v_lshl_add_u64 v[70:71], s[36:37], 0, v[70:71]
	s_sub_i32 s9, 0x4000, s15
	global_load_ushort v125, v[72:73], off
	global_load_ushort v126, v[70:71], off
	global_load_ushort v127, v66, s[10:11]
	global_load_ushort v128, v66, s[10:11] offset:256
	s_and_b64 s[10:11], s[78:79], exec
	s_cselect_b32 s9, s14, s9
	v_med3_i32 v70, s9, 0, v74
	v_cvt_pk_f16_f32 v38, v76, v84
	v_readfirstlane_b32 s10, v70
	s_or_b32 s10, s10, s20
	s_ashr_i32 s11, s10, 31
	s_lshl_b64 s[12:13], s[10:11], 10
	s_mul_hi_i32 s11, s10, 0x300
	s_mulk_i32 s10, 0x300
	v_or_b32_e32 v70, s12, v69
	v_mov_b32_e32 v71, s13
	s_add_u32 s10, s38, s10
	v_lshl_add_u64 v[72:73], s[22:23], 0, v[70:71]
	s_addc_u32 s11, s39, s11
	s_or_b32 s16, s2, 5
	global_load_ushort v129, v[72:73], off
	v_lshl_add_u64 v[72:73], s[24:25], 0, v[70:71]
	v_lshl_add_u64 v[70:71], s[36:37], 0, v[70:71]
	s_sub_i32 s12, 0x4000, s16
	global_load_ushort v130, v[72:73], off
	global_load_ushort v131, v[70:71], off
	global_load_ushort v132, v66, s[10:11]
	global_load_ushort v133, v66, s[10:11] offset:256
	s_and_b64 s[10:11], s[78:79], exec
	s_cselect_b32 s10, s15, s12
	v_med3_i32 v70, s10, 0, v74
	v_cvt_pk_f16_f32 v42, v77, v85
	v_readfirstlane_b32 s11, v70
	s_or_b32 s12, s11, s20
	s_ashr_i32 s13, s12, 31
	s_lshl_b64 s[14:15], s[12:13], 10
	s_mul_hi_i32 s11, s12, 0x300
	s_mulk_i32 s12, 0x300
	v_or_b32_e32 v70, s14, v69
	v_mov_b32_e32 v71, s15
	s_add_u32 s12, s38, s12
	v_lshl_add_u64 v[72:73], s[22:23], 0, v[70:71]
	s_addc_u32 s13, s39, s11
	s_or_b32 s17, s2, 6
	global_load_ushort v135, v[72:73], off
	v_lshl_add_u64 v[72:73], s[24:25], 0, v[70:71]
	v_lshl_add_u64 v[70:71], s[36:37], 0, v[70:71]
	s_sub_i32 s11, 0x4000, s17
	global_load_ushort v138, v[72:73], off
	global_load_ushort v139, v[70:71], off
	global_load_ushort v142, v66, s[12:13]
	global_load_ushort v143, v66, s[12:13] offset:256
	s_and_b64 s[12:13], s[78:79], exec
	s_cselect_b32 s11, s16, s11
	v_med3_i32 v70, s11, 0, v74
	v_cvt_pk_f16_f32 v46, v78, v86
	v_readfirstlane_b32 s12, v70
	s_or_b32 s12, s12, s20
	s_ashr_i32 s13, s12, 31
	s_lshl_b64 s[14:15], s[12:13], 10
	s_mul_hi_i32 s13, s12, 0x300
	s_mulk_i32 s12, 0x300
	v_or_b32_e32 v70, s14, v69
	v_mov_b32_e32 v71, s15
	s_add_u32 s12, s38, s12
	v_lshl_add_u64 v[72:73], s[22:23], 0, v[70:71]
	s_addc_u32 s13, s39, s13
	s_or_b32 s18, s2, 7
	global_load_ushort v147, v[72:73], off
	v_lshl_add_u64 v[72:73], s[24:25], 0, v[70:71]
	v_lshl_add_u64 v[70:71], s[36:37], 0, v[70:71]
	s_sub_i32 s14, 0x4000, s18
	global_load_ushort v150, v[72:73], off
	global_load_ushort v170, v[70:71], off
	global_load_ushort v173, v66, s[12:13]
	global_load_ushort v174, v66, s[12:13] offset:256
	s_and_b64 s[12:13], s[78:79], exec
	s_cselect_b32 s12, s17, s14
	v_med3_i32 v70, s12, 0, v74
	v_cvt_pk_f16_f32 v50, v79, v87
	v_readfirstlane_b32 s13, v70
	s_or_b32 s14, s13, s20
	s_ashr_i32 s15, s14, 31
	s_lshl_b64 s[16:17], s[14:15], 10
	v_or_b32_e32 v70, s16, v69
	v_mov_b32_e32 v71, s17
	s_mul_hi_i32 s13, s14, 0x300
	s_mulk_i32 s14, 0x300
	v_lshl_add_u64 v[72:73], s[22:23], 0, v[70:71]
	s_add_u32 s14, s38, s14
	global_load_ushort v179, v[72:73], off
	v_lshl_add_u64 v[72:73], s[24:25], 0, v[70:71]
	v_lshl_add_u64 v[70:71], s[36:37], 0, v[70:71]
	s_addc_u32 s15, s39, s13
	s_add_i32 s19, s2, 8
	s_sub_i32 s13, 0x3ff8, s2
	global_load_ushort v181, v[72:73], off
	global_load_ushort v184, v[70:71], off
	global_load_ushort v188, v66, s[14:15]
	global_load_ushort v189, v66, s[14:15] offset:256
	s_and_b64 s[14:15], s[78:79], exec
	s_cselect_b32 s13, s18, s13
	v_med3_i32 v70, s13, 0, v74
	v_cvt_pk_f16_f32 v54, v80, v88
	v_readfirstlane_b32 s14, v70
	s_or_b32 s14, s14, s20
	s_ashr_i32 s15, s14, 31
	s_lshl_b64 s[16:17], s[14:15], 10
	v_or_b32_e32 v70, s16, v69
	v_mov_b32_e32 v71, s17
	s_mul_hi_i32 s15, s14, 0x300
	s_mulk_i32 s14, 0x300
	v_lshl_add_u64 v[72:73], s[22:23], 0, v[70:71]
	s_add_u32 s14, s38, s14
	global_load_ushort v194, v[72:73], off
	v_lshl_add_u64 v[72:73], s[24:25], 0, v[70:71]
	v_lshl_add_u64 v[70:71], s[36:37], 0, v[70:71]
	s_addc_u32 s15, s39, s15
	s_sub_i32 s16, 0x3ff7, s2
	global_load_ushort v196, v[72:73], off
	global_load_ushort v197, v[70:71], off
	global_load_ushort v213, v66, s[14:15]
	global_load_ushort v214, v66, s[14:15] offset:256
	s_and_b64 s[14:15], s[78:79], exec
	s_cselect_b32 s14, s19, s16
	v_med3_i32 v70, s14, 0, v74
	v_cvt_pk_f16_f32 v58, v81, v89
	v_readfirstlane_b32 s15, v70
	s_or_b32 s16, s15, s20
	s_ashr_i32 s17, s16, 31
	s_lshl_b64 s[18:19], s[16:17], 10
	v_or_b32_e32 v70, s18, v69
	v_mov_b32_e32 v71, s19
	v_lshl_add_u64 v[72:73], s[22:23], 0, v[70:71]
	global_load_ushort v220, v[72:73], off
	v_lshl_add_u64 v[72:73], s[24:25], 0, v[70:71]
	v_lshl_add_u64 v[70:71], s[36:37], 0, v[70:71]
	global_load_ushort v226, v[72:73], off
	global_load_ushort v239, v[70:71], off
	s_mul_hi_i32 s15, s16, 0x300
	s_mulk_i32 s16, 0x300
	s_add_u32 s16, s38, s16
	s_addc_u32 s17, s39, s15
	global_load_ushort v242, v66, s[16:17]
	global_load_ushort v244, v66, s[16:17] offset:256
	s_add_i32 s4, s4, 0
	s_waitcnt vmcnt(49)
	v_cvt_f32_f16_e32 v69, v109
	s_waitcnt vmcnt(48)
	v_cvt_f32_f16_e32 v70, v110
	s_add_i32 s4, s4, 0x1e000
	s_cmpk_lt_u32 s7, 0x4000
	s_cselect_b64 vcc, -1, 0
	v_cndmask_b32_e32 v134, 0, v70, vcc
	v_cndmask_b32_e32 v136, 0, v69, vcc
	s_waitcnt vmcnt(46)
	v_cvt_f32_f16_e32 v69, v112
	s_waitcnt vmcnt(45)
	v_cvt_f32_f16_e32 v70, v113
	v_cvt_f32_f16_e32 v71, v111
	s_cmpk_lt_u32 s5, 0x4000
	v_cndmask_b32_e32 v140, 0, v69, vcc
	v_cndmask_b32_e32 v141, 0, v70, vcc
	s_waitcnt vmcnt(44)
	v_cvt_f32_f16_e32 v69, v114
	s_waitcnt vmcnt(43)
	v_cvt_f32_f16_e32 v70, v115
	v_cndmask_b32_e32 v137, 0, v71, vcc
	s_cselect_b64 vcc, -1, 0
	v_cndmask_b32_e32 v145, 0, v69, vcc
	v_cndmask_b32_e32 v144, 0, v70, vcc
	s_waitcnt vmcnt(41)
	v_cvt_f32_f16_e32 v69, v117
	s_waitcnt vmcnt(40)
	v_cvt_f32_f16_e32 v70, v118
	v_cvt_f32_f16_e32 v71, v116
	s_cmpk_lt_u32 s6, 0x4000
	v_cndmask_b32_e32 v148, 0, v69, vcc
	v_cndmask_b32_e32 v149, 0, v70, vcc
	s_waitcnt vmcnt(39)
	v_cvt_f32_f16_e32 v69, v119
	s_waitcnt vmcnt(38)
	v_cvt_f32_f16_e32 v70, v120
	v_cndmask_b32_e32 v146, 0, v71, vcc
	s_cselect_b64 vcc, -1, 0
	v_cndmask_b32_e32 v171, 0, v69, vcc
	v_cndmask_b32_e32 v151, 0, v70, vcc
	s_waitcnt vmcnt(36)
	v_cvt_f32_f16_e32 v69, v122
	s_waitcnt vmcnt(35)
	v_cvt_f32_f16_e32 v70, v123
	v_cvt_f32_f16_e32 v71, v121
	s_cmpk_lt_u32 s8, 0x4000
	v_cndmask_b32_e32 v175, 0, v69, vcc
	v_cndmask_b32_e32 v176, 0, v70, vcc
	s_waitcnt vmcnt(34)
	v_cvt_f32_f16_e32 v69, v124
	s_waitcnt vmcnt(33)
; #define LAS __attribute__((address_space(3)))
; __device__ __forceinline__ float sigmoidf_(float x) { return __builtin_amdgcn_rcpf(1.0f + __expf(-x)); }
; template <int R>
; __device__ __forceinline__ void scan_item(const Args& a, int layer, int q, int rowhalf, LAS unsigned char* lds, int tid, int lane, int wave) {
;     ...
;         SCAN_LOAD_RAW(0); SCAN_UNPACK(0);
;         for (int c = -1; c < nch; ++c) {
;     ...
;                     const int s = pw * 8 + s8; const int g = cp * SC_CH + s; const int t = d ? (T - 1 - g) : g; const size_t tok = (size_t)(tok0 + t);
;                     const float rr = mix3f(cur.r[s8], cur.r[s8 + 1], cur.r[s8 + 2], mu_r);
;                     const float kk0 = mix3f(cur.k[s8], cur.k[s8 + 1], cur.k[s8 + 2], mu_k);
;                     const float vv = mix3f(cur.v[s8], cur.v[s8 + 1], cur.v[s8 + 2], mu_v);
;                     const float z = w0 + zl[s8 * 64 + j], az = a0 + zl[512 + s8 * 64 + j];
;                     const float wdec = __expf(-0.606531f * sigmoidf_(z)); const float av = sigmoidf_(az);
;                     float kk = kk0 * k_k; const float n2 = wave_sum_fast(kk * kk); kk = kk * __builtin_amdgcn_rsqf(fmaxf(n2, 1e-24f));
;                     const float kd = kk0 * (1.0f + (av - 1.0f) * k_a); const float bb = kk * av;
;                     const float bs = wave_sum_fast(rr * kd * r_k);
;                     bsv = (lane == s8) ? bs : bsv;
;                     LAS float* o = op + s * 384 + j;
;                     o[0] = -kk; o[64] = wdec; o[128] = bb; o[192] = kd; o[256] = rr; o[320] = vv;
;                 }
;                 if (lane < 8 && rowhalf == 0) { const int gs = cp * SC_CH + pw * 8 + lane; const int t = d ? (T - 1 - gs) : gs; BSC[((size_t)(tok0 + t) * 8 + h) * 2 + d] = bsv; }
	v_cvt_f32_f16_e32 v70, v125
	v_cndmask_b32_e32 v172, 0, v71, vcc
	s_cselect_b64 vcc, -1, 0
	v_cndmask_b32_e32 v178, 0, v69, vcc
	v_cndmask_b32_e32 v177, 0, v70, vcc
	s_waitcnt vmcnt(31)
	v_cvt_f32_f16_e32 v69, v127
	s_waitcnt vmcnt(30)
	v_cvt_f32_f16_e32 v70, v128
	v_cvt_f32_f16_e32 v71, v126
	s_cmpk_lt_u32 s9, 0x4000
	v_cndmask_b32_e32 v182, 0, v69, vcc
	v_cndmask_b32_e32 v183, 0, v70, vcc
	s_waitcnt vmcnt(29)
	v_cvt_f32_f16_e32 v69, v129
	s_waitcnt vmcnt(28)
	v_cvt_f32_f16_e32 v70, v130
	v_cndmask_b32_e32 v180, 0, v71, vcc
	s_cselect_b64 vcc, -1, 0
	v_cndmask_b32_e32 v186, 0, v69, vcc
	v_cndmask_b32_e32 v185, 0, v70, vcc
	s_waitcnt vmcnt(26)
	v_cvt_f32_f16_e32 v69, v132
	s_waitcnt vmcnt(25)
	v_cvt_f32_f16_e32 v70, v133
	v_cvt_f32_f16_e32 v71, v131
	s_cmpk_lt_u32 s10, 0x4000
	v_cndmask_b32_e32 v190, 0, v69, vcc
	v_cndmask_b32_e32 v191, 0, v70, vcc
	s_waitcnt vmcnt(24)
	v_cvt_f32_f16_e32 v69, v135
	s_waitcnt vmcnt(23)
	v_cvt_f32_f16_e32 v70, v138
	v_cndmask_b32_e32 v187, 0, v71, vcc
	s_cselect_b64 vcc, -1, 0
	v_cndmask_b32_e32 v193, 0, v69, vcc
	v_cndmask_b32_e32 v192, 0, v70, vcc
	s_waitcnt vmcnt(21)
	v_cvt_f32_f16_e32 v69, v142
	s_waitcnt vmcnt(20)
	v_cvt_f32_f16_e32 v70, v143
	v_cvt_f32_f16_e32 v71, v139
	s_cmpk_lt_u32 s11, 0x4000
	v_cndmask_b32_e32 v198, 0, v69, vcc
	v_cndmask_b32_e32 v211, 0, v70, vcc
	s_waitcnt vmcnt(19)
	v_cvt_f32_f16_e32 v69, v147
	s_waitcnt vmcnt(18)
	v_cvt_f32_f16_e32 v70, v150
	v_cndmask_b32_e32 v195, 0, v71, vcc
	s_cselect_b64 vcc, -1, 0
	v_cndmask_b32_e32 v215, 0, v69, vcc
	v_cndmask_b32_e32 v212, 0, v70, vcc
	s_waitcnt vmcnt(16)
	v_cvt_f32_f16_e32 v69, v173
	s_waitcnt vmcnt(15)
	v_cvt_f32_f16_e32 v70, v174
	v_cvt_f32_f16_e32 v71, v170
	s_cmpk_lt_u32 s12, 0x4000
	v_cndmask_b32_e32 v218, 0, v69, vcc
	v_cndmask_b32_e32 v219, 0, v70, vcc
	s_waitcnt vmcnt(14)
	v_cvt_f32_f16_e32 v69, v179
	s_waitcnt vmcnt(13)
	v_cvt_f32_f16_e32 v70, v181
	v_cndmask_b32_e32 v216, 0, v71, vcc
	s_cselect_b64 vcc, -1, 0
	v_cndmask_b32_e32 v224, 0, v69, vcc
	v_cndmask_b32_e32 v222, 0, v70, vcc
	s_waitcnt vmcnt(11)
	v_cvt_f32_f16_e32 v69, v188
	s_waitcnt vmcnt(10)
	v_cvt_f32_f16_e32 v70, v189
	v_cvt_f32_f16_e32 v71, v184
	s_cmpk_lt_u32 s13, 0x4000
	v_cndmask_b32_e32 v231, 0, v69, vcc
	v_cndmask_b32_e32 v232, 0, v70, vcc
	s_waitcnt vmcnt(9)
	v_cvt_f32_f16_e32 v69, v194
	s_waitcnt vmcnt(8)
	v_cvt_f32_f16_e32 v70, v196
	v_cndmask_b32_e32 v227, 0, v71, vcc
	s_cselect_b64 vcc, -1, 0
	s_waitcnt vmcnt(7)
	v_cvt_f32_f16_e32 v71, v197
	v_cndmask_b32_e32 v240, 0, v70, vcc
	v_cndmask_b32_e32 v241, 0, v69, vcc
	s_waitcnt vmcnt(6)
	v_cvt_f32_f16_e32 v69, v213
	s_waitcnt vmcnt(5)
	v_cvt_f32_f16_e32 v70, v214
	v_cndmask_b32_e32 v243, 0, v71, vcc
	s_waitcnt vmcnt(2)
	v_cvt_f32_f16_e32 v71, v239
	v_cndmask_b32_e32 v245, 0, v69, vcc
	v_cndmask_b32_e32 v246, 0, v70, vcc
	v_cvt_f32_f16_e32 v69, v220
	v_cvt_f32_f16_e32 v70, v226
	s_cmpk_lt_u32 s14, 0x4000
	s_cselect_b64 vcc, -1, 0
	v_cndmask_b32_e32 v206, 0, v71, vcc
	v_bfe_u32 v71, v162, 3, 3
	v_lshlrev_b32_e32 v72, 3, v162
	v_cndmask_b32_e32 v205, 0, v70, vcc
	v_cndmask_b32_e32 v204, 0, v69, vcc
	s_waitcnt vmcnt(1)
	v_cvt_f32_f16_e32 v69, v242
	s_waitcnt vmcnt(0)
	v_cvt_f32_f16_e32 v70, v244
	v_or_b32_e32 v217, s2, v71
	v_and_b32_e32 v96, 56, v72
	v_lshlrev_b32_e32 v223, 8, v217
	s_add_i32 s2, 0, 0x18000
	v_lshlrev_b32_e32 v72, 2, v96
	s_add_i32 s3, s3, 0
	v_add3_u32 v225, s2, v223, v72
	v_lshlrev_b32_e32 v72, 8, v162
	v_readlane_b32 s2, v253, 48
	s_add_i32 s3, s3, 0x1c000
	v_and_b32_e32 v72, 0x700, v72
	v_add_u32_e32 v233, s2, v71
	s_lshl_b32 s34, s34, 3
	v_readlane_b32 s2, v253, 49
	v_cndmask_b32_e32 v210, 0, v69, vcc
	v_cndmask_b32_e32 v247, 0, v70, vcc
	v_add_u32_e32 v69, s4, v152
	v_lshlrev_b32_e32 v70, 2, v65
	v_add_u32_e32 v228, s3, v66
	v_add_u32_e32 v72, s3, v72
	v_and_b32_e32 v73, 48, v162
	v_subrev_co_u32_e64 v229, s[6:7], 32, v65
	v_cmp_gt_u32_e64 s[8:9], 8, v65
	v_cmp_eq_u32_e64 s[10:11], 7, v65
	v_cmp_eq_u32_e64 s[12:13], 6, v65
	v_cmp_eq_u32_e64 s[14:15], 5, v65
	v_cmp_eq_u32_e64 s[16:17], 4, v65
	v_cmp_eq_u32_e64 s[18:19], 3, v65
	v_cmp_eq_u32_e64 s[20:21], 2, v65
	v_cmp_eq_u32_e64 s[22:23], 1, v65
	v_cmp_eq_u32_e64 s[24:25], 0, v65
	v_sub_u32_e32 v66, s2, v71
	v_add_u32_e32 v65, s34, v65
	v_cvt_pk_f16_f32 v62, v82, v90
	v_add_u32_e32 v221, 0, v70
	v_add_u32_e32 v230, s4, v70
	s_mulk_i32 s29, 0x600
	v_subrev_u32_e32 v234, s34, v66
	s_sub_i32 s35, 0, s34
	v_sub_u32_e32 v235, 0x401f, v65
	s_movk_i32 s36, 0xc000
	v_add_u32_e32 v237, v72, v73
	v_add_u32_e32 v238, v69, v68
	s_branch .LBB0_642

; #define LAS __attribute__((address_space(3)))
; template <int R>
; __device__ __forceinline__ void scan_flush(LAS unsigned char* lds, int cf, int pw, int lane, int d, int T, int tok0, int h, int rowbase, h16* Yf, h16* Yb) {
;     const LAS float* yb = (const LAS float*)(lds + SC_YOFF + (cf & 1) * SC_YB);
;     const int s = pw * 8 + (lane >> 3); const int g = cf * SC_CH + s; const int t = d ? (T - 1 - g) : g;
;     if (R == 4) {
;         const int r8 = (lane & 7) * 8;
;         const f32x4 y0 = *(const LAS f32x4*)(yb + s * 64 + r8), y1 = *(const LAS f32x4*)(yb + s * 64 + r8 + 4);
;         u32x4 w4; w4.x = pk2h(y0.x, y0.y); w4.y = pk2h(y0.z, y0.w); w4.z = pk2h(y1.x, y1.y); w4.w = pk2h(y1.z, y1.w);
;         if (d == 0) *(u32x4*)(Yf + (size_t)(tok0 + t) * 1024 + 512 + h * 64 + r8) = w4; else *(u32x4*)(Yb + (size_t)(tok0 + t) * 512 + h * 64 + r8) = w4;
; template <int R>
; __device__ __forceinline__ void scan_item(const Args& a, int layer, int q, int rowhalf, LAS unsigned char* lds, int tid, int lane, int wave) {
;     ...
;         scan_flush<R>(lds, nch - 1, pw, lane, d, T, tok0, h, rowbase, Yf, Yb);
.LBB0_657:
	s_setprio 1
	s_add_i32 s2, 0, 0x1a000
	v_lshlrev_b32_e32 v0, 2, v96
	v_add3_u32 v0, s2, v223, v0
	ds_read_b128 v[4:7], v0
	ds_read_b128 v[0:3], v0 offset:16
	s_mov_b64 s[2:3], -1
	s_and_b64 vcc, exec, s[84:85]
	s_cbranch_vccz .LBB0_659
	v_readlane_b32 s2, v250, 13
	s_nop 1
	v_sub_u32_e32 v8, s2, v217
	v_ashrrev_i32_e32 v9, 31, v8
	v_readlane_b32 s2, v252, 16
	v_lshlrev_b64 v[8:9], 10, v[8:9]
	v_readlane_b32 s3, v252, 17
	s_nop 1
	v_lshl_add_u64 v[8:9], s[2:3], 0, v[8:9]
	s_mov_b64 s[2:3], 0

; #define PG8_STAGE(bufoff, gbase, voff) do { _Pragma("unroll") for (int _i = 0; _i < 2; ++_i) \
;         __builtin_amdgcn_global_load_lds((const unsigned*)((const char*)(gbase) + (voff)[_i]), (LAS unsigned*)(lds + (bufoff) + ldsw + _i * 8192), 16, 0, 0); } while (0)
; #define PG8_LDA(dst, b, h) do { _Pragma("unroll") for (int m = 0; m < 4; ++m) _Pragma("unroll") for (int k = 0; k < 2; ++k) dst[m][k] = *(const LAS h16x8*)(lds + PG8_SA(b, h) + aoff + m * 2048 + k * 1024); } while (0)
; #define PG8_LDB(dst, b, h) do { _Pragma("unroll") for (int n = 0; n < 2; ++n) _Pragma("unroll") for (int k = 0; k < 2; ++k) dst[n][k] = *(const LAS h16x8*)(lds + PG8_SB(b, h) + boff + n * 2048 + k * 1024); } while (0)
; #define PG8_MMA(ai, bj, At, Bt) do { __builtin_amdgcn_s_setprio(1); _Pragma("unroll") for (int m = 0; m < 4; ++m) _Pragma("unroll") for (int n = 0; n < 2; ++n) _Pragma("unroll") for (int k = 0; k < 2; ++k) \
;         acc[ai][bj][m][n] = __builtin_amdgcn_mfma_f32_16x16x32_f16(Bt[n][k], At[m][k], acc[ai][bj][m][n], 0, 0, 0); __builtin_amdgcn_s_setprio(0); } while (0)
; #define PG8_WAIT_V(n) asm volatile("s_waitcnt vmcnt(" #n ")" ::: "memory")
; #define PG8_BAR __builtin_amdgcn_s_barrier()
; template <class Epi>
; __device__ __forceinline__ void gemm_phase(LAS unsigned char* lds, const Gemm g, const StaticOrder& S, const Epi& E, const int tid) {
;     ...
;         const char* nA = has_next ? (const char*)g.A + (size_t)nxt.pm * tstepA : cA; const char* nB = has_next ? (const char*)g.Bt + (size_t)nxt.pn * tstepB : cB;
;         for (int t = 0; t < nt; t += 2) {
;             const bool last = (t == nt - 2);
;             const char* a1 = cA + (size_t)(t + 1) * kstep;
;             const char* a2 = last ? nA : cA + (size_t)(t + 2) * kstep; const char* b2 = last ? nB : cB + (size_t)(t + 2) * kstep;
;             const char* a3 = a2 + kstep; const char* b3 = b2 + kstep;
;             PG8_LDB(B0, 0, 0); PG8_LDB(B1, 0, 1); PG8_SCHED; PG8_LDA(At, 0, 0); PG8_STAGE(PG8_SA(1, 1), a1 + hstepA, voffA);
;             PG8_WAIT_V(8); PG8_WAIT_L(0); PG8_BAR; PG8_MMA(0, 0, At, B0); PG8_MMA(0, 1, At, B1); PG8_BAR; PG8_SCHED;
;             PG8_LDA(At, 0, 1); PG8_STAGE(PG8_SB(0, 0), b2, voffB); PG8_STAGE(PG8_SB(0, 1), b2 + hstepB, voffB); PG8_STAGE(PG8_SA(0, 0), a2, voffA);
;             PG8_WAIT_V(8); PG8_WAIT_L(0); PG8_BAR; PG8_MMA(1, 0, At, B0); PG8_MMA(1, 1, At, B1); PG8_BAR; PG8_SCHED;
.LBB0_745:
	s_add_u32 s20, s18, 0x100
	s_addc_u32 s21, s19, 0
	s_add_i32 s31, 0, 0x10000
	s_cmp_eq_u32 s44, 40
	s_cselect_b32 s25, s11, s21
	s_cselect_b32 s24, s10, s20
	s_cselect_b32 s23, s17, s3
	s_cselect_b32 s22, s16, s2
	s_add_i32 s45, 0, 0x14000
	v_add_u32_e32 v140, s31, v189
	v_add_u32_e32 v162, s45, v189
	ds_read_b128 v[128:131], v140
	ds_read_b128 v[132:135], v140 offset:1024
	ds_read_b128 v[136:139], v140 offset:2048
	ds_read_b128 v[140:143], v140 offset:3072
	ds_read_b128 v[144:147], v162
	ds_read_b128 v[148:151], v162 offset:1024
	ds_read_b128 v[154:157], v162 offset:2048
	ds_read_b128 v[162:165], v162 offset:3072
	v_lshl_add_u64 v[166:167], s[18:19], 0, v[172:173]
	s_add_i32 m0, s27, 0xc000
	ds_read_b128 v[176:179], v191
	ds_read_b128 v[180:183], v191 offset:1024
	ds_read_b128 v[184:187], v191 offset:2048
	ds_read_b128 v[192:195], v191 offset:3072
	ds_read_b128 v[210:213], v191 offset:4096
	ds_read_b128 v[214:217], v191 offset:5120
	ds_read_b128 v[218:221], v191 offset:6144
	ds_read_b128 v[222:225], v191 offset:7168
	global_load_lds_dwordx4 v[166:167], off
	v_lshl_add_u64 v[166:167], s[18:19], 0, v[174:175]
	s_add_i32 m0, s27, 0xe000
	s_nop 0
	global_load_lds_dwordx4 v[166:167], off
	s_waitcnt vmcnt(8)
	s_waitcnt lgkmcnt(0)
	s_barrier
	s_waitcnt lgkmcnt(0)
	v_mfma_f32_16x16x32_f16 v[124:127], v[128:131], v[176:179], v[124:127]
	v_mfma_f32_16x16x32_f16 v[120:123], v[136:139], v[176:179], v[120:123]
	v_mfma_f32_16x16x32_f16 v[108:111], v[128:131], v[184:187], v[108:111]
	v_mfma_f32_16x16x32_f16 v[104:107], v[136:139], v[184:187], v[104:107]
	v_mfma_f32_16x16x32_f16 v[92:95], v[128:131], v[210:213], v[92:95]
	v_mfma_f32_16x16x32_f16 v[88:91], v[136:139], v[210:213], v[88:91]
	v_mfma_f32_16x16x32_f16 v[76:79], v[128:131], v[218:221], v[76:79]
	v_mfma_f32_16x16x32_f16 v[72:75], v[136:139], v[218:221], v[72:75]
	v_mfma_f32_16x16x32_f16 v[124:127], v[132:135], v[180:183], v[124:127]
	v_mfma_f32_16x16x32_f16 v[120:123], v[140:143], v[180:183], v[120:123]
	v_mfma_f32_16x16x32_f16 v[108:111], v[132:135], v[192:195], v[108:111]
	v_mfma_f32_16x16x32_f16 v[104:107], v[140:143], v[192:195], v[104:107]
	v_mfma_f32_16x16x32_f16 v[92:95], v[132:135], v[214:217], v[92:95]
	v_mfma_f32_16x16x32_f16 v[88:91], v[140:143], v[214:217], v[88:91]
	v_mfma_f32_16x16x32_f16 v[76:79], v[132:135], v[222:225], v[76:79]
	v_mfma_f32_16x16x32_f16 v[72:75], v[140:143], v[222:225], v[72:75]
	v_mfma_f32_16x16x32_f16 v[116:119], v[144:147], v[176:179], v[116:119]
	v_mfma_f32_16x16x32_f16 v[112:115], v[154:157], v[176:179], v[112:115]
	v_mfma_f32_16x16x32_f16 v[100:103], v[144:147], v[184:187], v[100:103]
	v_mfma_f32_16x16x32_f16 v[96:99], v[154:157], v[184:187], v[96:99]
	v_mfma_f32_16x16x32_f16 v[84:87], v[144:147], v[210:213], v[84:87]
	v_mfma_f32_16x16x32_f16 v[80:83], v[154:157], v[210:213], v[80:83]
	v_mfma_f32_16x16x32_f16 v[68:71], v[144:147], v[218:221], v[68:71]
	v_mfma_f32_16x16x32_f16 v[64:67], v[154:157], v[218:221], v[64:67]
	v_mfma_f32_16x16x32_f16 v[116:119], v[148:151], v[180:183], v[116:119]
	v_mfma_f32_16x16x32_f16 v[112:115], v[162:165], v[180:183], v[112:115]
	v_mfma_f32_16x16x32_f16 v[100:103], v[148:151], v[192:195], v[100:103]
	v_mfma_f32_16x16x32_f16 v[96:99], v[162:165], v[192:195], v[96:99]
	v_mfma_f32_16x16x32_f16 v[84:87], v[148:151], v[214:217], v[84:87]
	v_mfma_f32_16x16x32_f16 v[80:83], v[162:165], v[214:217], v[80:83]
	v_mfma_f32_16x16x32_f16 v[68:71], v[148:151], v[222:225], v[68:71]
	v_mfma_f32_16x16x32_f16 v[64:67], v[162:165], v[222:225], v[64:67]
	s_barrier
	s_add_i32 s18, s31, s26
	v_lshl_add_u64 v[166:167], s[22:23], 0, v[152:153]
	s_mov_b32 m0, s18
	ds_read_b128 v[176:179], v191 offset:16384
	ds_read_b128 v[180:183], v191 offset:17408
	ds_read_b128 v[184:187], v191 offset:18432
	ds_read_b128 v[192:195], v191 offset:19456
	ds_read_b128 v[210:213], v191 offset:20480
	ds_read_b128 v[214:217], v191 offset:21504
	ds_read_b128 v[218:221], v191 offset:22528
	ds_read_b128 v[222:225], v191 offset:23552
	global_load_lds_dwordx4 v[166:167], off
	s_add_i32 m0, s18, 0x2000
	s_add_u32 s18, s22, 0xb0000
	v_lshl_add_u64 v[196:197], s[22:23], 0, v[170:171]
	s_addc_u32 s19, s23, 0
	s_add_i32 s31, s45, s26
	global_load_lds_dwordx4 v[196:197], off
	v_lshl_add_u64 v[204:205], s[18:19], 0, v[152:153]
	s_mov_b32 m0, s31
	v_lshl_add_u64 v[226:227], s[24:25], 0, v[170:171]
	global_load_lds_dwordx4 v[204:205], off
	v_lshl_add_u64 v[204:205], s[18:19], 0, v[170:171]
	s_add_i32 m0, s31, 0x2000
	s_nop 0
	global_load_lds_dwordx4 v[204:205], off
	v_lshl_add_u64 v[204:205], s[24:25], 0, v[152:153]
	s_mov_b32 m0, s27
	s_nop 0
	global_load_lds_dwordx4 v[204:205], off
	s_mov_b32 m0, s28
	s_nop 0
	global_load_lds_dwordx4 v[226:227], off
	s_waitcnt vmcnt(8)
	s_waitcnt lgkmcnt(0)
	s_barrier
; #define PG8_STAGE(bufoff, gbase, voff) do { _Pragma("unroll") for (int _i = 0; _i < 2; ++_i) \
;         __builtin_amdgcn_global_load_lds((const unsigned*)((const char*)(gbase) + (voff)[_i]), (LAS unsigned*)(lds + (bufoff) + ldsw + _i * 8192), 16, 0, 0); } while (0)
; #define PG8_LDA(dst, b, h) do { _Pragma("unroll") for (int m = 0; m < 4; ++m) _Pragma("unroll") for (int k = 0; k < 2; ++k) dst[m][k] = *(const LAS h16x8*)(lds + PG8_SA(b, h) + aoff + m * 2048 + k * 1024); } while (0)
; #define PG8_LDB(dst, b, h) do { _Pragma("unroll") for (int n = 0; n < 2; ++n) _Pragma("unroll") for (int k = 0; k < 2; ++k) dst[n][k] = *(const LAS h16x8*)(lds + PG8_SB(b, h) + boff + n * 2048 + k * 1024); } while (0)
; #define PG8_MMA(ai, bj, At, Bt) do { __builtin_amdgcn_s_setprio(1); _Pragma("unroll") for (int m = 0; m < 4; ++m) _Pragma("unroll") for (int n = 0; n < 2; ++n) _Pragma("unroll") for (int k = 0; k < 2; ++k) \
;         acc[ai][bj][m][n] = __builtin_amdgcn_mfma_f32_16x16x32_f16(Bt[n][k], At[m][k], acc[ai][bj][m][n], 0, 0, 0); __builtin_amdgcn_s_setprio(0); } while (0)
; #define PG8_WAIT_V(n) asm volatile("s_waitcnt vmcnt(" #n ")" ::: "memory")
; #define PG8_WAIT_L(n) asm volatile("s_waitcnt lgkmcnt(" #n ")" ::: "memory")
; #define PG8_BAR __builtin_amdgcn_s_barrier()
; #define PG8_SCHED __builtin_amdgcn_sched_barrier(0)
; template <class Epi>
; __device__ __forceinline__ void gemm_phase(LAS unsigned char* lds, const Gemm g, const StaticOrder& S, const Epi& E, const int tid) {
;     ...
;             PG8_WAIT_V(8); PG8_WAIT_L(0); PG8_BAR; PG8_MMA(1, 0, At, B0); PG8_MMA(1, 1, At, B1); PG8_BAR; PG8_SCHED;
;             PG8_LDB(B0, 1, 0); PG8_LDB(B1, 1, 1); PG8_SCHED; PG8_LDA(At, 1, 0); PG8_STAGE(PG8_SA(0, 1), a2 + hstepA, voffA);
;             PG8_WAIT_V(8); PG8_WAIT_L(0); PG8_BAR; PG8_MMA(0, 0, At, B0); PG8_MMA(0, 1, At, B1); PG8_BAR; PG8_SCHED;
;             PG8_LDA(At, 1, 1); PG8_STAGE(PG8_SB(1, 0), b3, voffB); PG8_STAGE(PG8_SB(1, 1), b3 + hstepB, voffB); PG8_STAGE(PG8_SA(1, 0), a3, voffA);
	s_waitcnt lgkmcnt(0)
	v_mfma_f32_16x16x32_f16 v[60:63], v[128:131], v[176:179], v[60:63]
	v_mfma_f32_16x16x32_f16 v[56:59], v[136:139], v[176:179], v[56:59]
	v_mfma_f32_16x16x32_f16 v[44:47], v[128:131], v[184:187], v[44:47]
	v_mfma_f32_16x16x32_f16 v[40:43], v[136:139], v[184:187], v[40:43]
	v_mfma_f32_16x16x32_f16 v[28:31], v[128:131], v[210:213], v[28:31]
	v_mfma_f32_16x16x32_f16 v[24:27], v[136:139], v[210:213], v[24:27]
	v_mfma_f32_16x16x32_f16 v[12:15], v[128:131], v[218:221], v[12:15]
	v_mfma_f32_16x16x32_f16 v[8:11], v[136:139], v[218:221], v[8:11]
	v_mfma_f32_16x16x32_f16 v[60:63], v[132:135], v[180:183], v[60:63]
	v_mfma_f32_16x16x32_f16 v[56:59], v[140:143], v[180:183], v[56:59]
	v_mfma_f32_16x16x32_f16 v[44:47], v[132:135], v[192:195], v[44:47]
	v_mfma_f32_16x16x32_f16 v[40:43], v[140:143], v[192:195], v[40:43]
	v_mfma_f32_16x16x32_f16 v[28:31], v[132:135], v[214:217], v[28:31]
	v_mfma_f32_16x16x32_f16 v[24:27], v[140:143], v[214:217], v[24:27]
	v_mfma_f32_16x16x32_f16 v[12:15], v[132:135], v[222:225], v[12:15]
	v_mfma_f32_16x16x32_f16 v[8:11], v[140:143], v[222:225], v[8:11]
	v_mfma_f32_16x16x32_f16 v[52:55], v[144:147], v[176:179], v[52:55]
	v_mfma_f32_16x16x32_f16 v[48:51], v[154:157], v[176:179], v[48:51]
	v_mfma_f32_16x16x32_f16 v[36:39], v[144:147], v[184:187], v[36:39]
	v_mfma_f32_16x16x32_f16 v[32:35], v[154:157], v[184:187], v[32:35]
	v_mfma_f32_16x16x32_f16 v[20:23], v[144:147], v[210:213], v[20:23]
	v_mfma_f32_16x16x32_f16 v[16:19], v[154:157], v[210:213], v[16:19]
	v_mfma_f32_16x16x32_f16 v[4:7], v[144:147], v[218:221], v[4:7]
	v_mfma_f32_16x16x32_f16 v[0:3], v[154:157], v[218:221], v[0:3]
	v_mfma_f32_16x16x32_f16 v[52:55], v[148:151], v[180:183], v[52:55]
	v_mfma_f32_16x16x32_f16 v[48:51], v[162:165], v[180:183], v[48:51]
	v_mfma_f32_16x16x32_f16 v[36:39], v[148:151], v[192:195], v[36:39]
	v_mfma_f32_16x16x32_f16 v[32:35], v[162:165], v[192:195], v[32:35]
	v_mfma_f32_16x16x32_f16 v[20:23], v[148:151], v[214:217], v[20:23]
	v_mfma_f32_16x16x32_f16 v[16:19], v[162:165], v[214:217], v[16:19]
	v_mfma_f32_16x16x32_f16 v[4:7], v[148:151], v[222:225], v[4:7]
	v_mfma_f32_16x16x32_f16 v[0:3], v[162:165], v[222:225], v[0:3]
	s_barrier
	s_add_i32 s31, 0, 0x18000
	s_add_i32 s45, 0, 0x1c000
	v_add_u32_e32 v140, s31, v189
	v_add_u32_e32 v162, s45, v189
	ds_read_b128 v[128:131], v140
	ds_read_b128 v[132:135], v140 offset:1024
	ds_read_b128 v[136:139], v140 offset:2048
	ds_read_b128 v[140:143], v140 offset:3072
	ds_read_b128 v[144:147], v162
	ds_read_b128 v[148:151], v162 offset:1024
	ds_read_b128 v[154:157], v162 offset:2048
	ds_read_b128 v[162:165], v162 offset:3072
	s_add_u32 s18, s24, 0xb0000
	s_addc_u32 s19, s25, 0
	s_mov_b32 m0, s29
	v_lshl_add_u64 v[228:229], s[18:19], 0, v[152:153]
	ds_read_b128 v[176:179], v191 offset:32768
	ds_read_b128 v[180:183], v191 offset:33792
	ds_read_b128 v[184:187], v191 offset:34816
	ds_read_b128 v[192:195], v191 offset:35840
	ds_read_b128 v[210:213], v191 offset:36864
	ds_read_b128 v[214:217], v191 offset:37888
	ds_read_b128 v[218:221], v191 offset:38912
	ds_read_b128 v[222:225], v191 offset:39936
	global_load_lds_dwordx4 v[228:229], off
	v_lshl_add_u64 v[228:229], s[18:19], 0, v[170:171]
	s_mov_b32 m0, s35
	s_nop 0
	global_load_lds_dwordx4 v[228:229], off
	s_waitcnt vmcnt(8)
	s_waitcnt lgkmcnt(0)
	s_barrier
	s_waitcnt lgkmcnt(0)
	v_mfma_f32_16x16x32_f16 v[124:127], v[128:131], v[176:179], v[124:127]
	v_mfma_f32_16x16x32_f16 v[120:123], v[136:139], v[176:179], v[120:123]
	v_mfma_f32_16x16x32_f16 v[108:111], v[128:131], v[184:187], v[108:111]
	v_mfma_f32_16x16x32_f16 v[104:107], v[136:139], v[184:187], v[104:107]
	v_mfma_f32_16x16x32_f16 v[92:95], v[128:131], v[210:213], v[92:95]
	v_mfma_f32_16x16x32_f16 v[88:91], v[136:139], v[210:213], v[88:91]
	v_mfma_f32_16x16x32_f16 v[76:79], v[128:131], v[218:221], v[76:79]
	v_mfma_f32_16x16x32_f16 v[72:75], v[136:139], v[218:221], v[72:75]
	v_mfma_f32_16x16x32_f16 v[124:127], v[132:135], v[180:183], v[124:127]
	v_mfma_f32_16x16x32_f16 v[120:123], v[140:143], v[180:183], v[120:123]
	v_mfma_f32_16x16x32_f16 v[108:111], v[132:135], v[192:195], v[108:111]
	v_mfma_f32_16x16x32_f16 v[104:107], v[140:143], v[192:195], v[104:107]
	v_mfma_f32_16x16x32_f16 v[92:95], v[132:135], v[214:217], v[92:95]
	v_mfma_f32_16x16x32_f16 v[88:91], v[140:143], v[214:217], v[88:91]
	v_mfma_f32_16x16x32_f16 v[76:79], v[132:135], v[222:225], v[76:79]
	v_mfma_f32_16x16x32_f16 v[72:75], v[140:143], v[222:225], v[72:75]
	v_mfma_f32_16x16x32_f16 v[116:119], v[144:147], v[176:179], v[116:119]
	v_mfma_f32_16x16x32_f16 v[112:115], v[154:157], v[176:179], v[112:115]
	v_mfma_f32_16x16x32_f16 v[100:103], v[144:147], v[184:187], v[100:103]
	v_mfma_f32_16x16x32_f16 v[96:99], v[154:157], v[184:187], v[96:99]
	v_mfma_f32_16x16x32_f16 v[84:87], v[144:147], v[210:213], v[84:87]
	v_mfma_f32_16x16x32_f16 v[80:83], v[154:157], v[210:213], v[80:83]
	v_mfma_f32_16x16x32_f16 v[68:71], v[144:147], v[218:221], v[68:71]
	v_mfma_f32_16x16x32_f16 v[64:67], v[154:157], v[218:221], v[64:67]
	v_mfma_f32_16x16x32_f16 v[116:119], v[148:151], v[180:183], v[116:119]
	v_mfma_f32_16x16x32_f16 v[112:115], v[162:165], v[180:183], v[112:115]
	v_mfma_f32_16x16x32_f16 v[100:103], v[148:151], v[192:195], v[100:103]
	v_mfma_f32_16x16x32_f16 v[96:99], v[162:165], v[192:195], v[96:99]
	v_mfma_f32_16x16x32_f16 v[84:87], v[148:151], v[214:217], v[84:87]
	v_mfma_f32_16x16x32_f16 v[80:83], v[162:165], v[214:217], v[80:83]
	v_mfma_f32_16x16x32_f16 v[68:71], v[148:151], v[222:225], v[68:71]
	v_mfma_f32_16x16x32_f16 v[64:67], v[162:165], v[222:225], v[64:67]
	s_barrier
; #define PG8_STAGE(bufoff, gbase, voff) do { _Pragma("unroll") for (int _i = 0; _i < 2; ++_i) \
;         __builtin_amdgcn_global_load_lds((const unsigned*)((const char*)(gbase) + (voff)[_i]), (LAS unsigned*)(lds + (bufoff) + ldsw + _i * 8192), 16, 0, 0); } while (0)
; #define PG8_LDA(dst, b, h) do { _Pragma("unroll") for (int m = 0; m < 4; ++m) _Pragma("unroll") for (int k = 0; k < 2; ++k) dst[m][k] = *(const LAS h16x8*)(lds + PG8_SA(b, h) + aoff + m * 2048 + k * 1024); } while (0)
; #define PG8_MMA(ai, bj, At, Bt) do { __builtin_amdgcn_s_setprio(1); _Pragma("unroll") for (int m = 0; m < 4; ++m) _Pragma("unroll") for (int n = 0; n < 2; ++n) _Pragma("unroll") for (int k = 0; k < 2; ++k) \
;         acc[ai][bj][m][n] = __builtin_amdgcn_mfma_f32_16x16x32_f16(Bt[n][k], At[m][k], acc[ai][bj][m][n], 0, 0, 0); __builtin_amdgcn_s_setprio(0); } while (0)
; #define PG8_WAIT_V(n) asm volatile("s_waitcnt vmcnt(" #n ")" ::: "memory")
; #define PG8_WAIT_L(n) asm volatile("s_waitcnt lgkmcnt(" #n ")" ::: "memory")
; #define PG8_BAR __builtin_amdgcn_s_barrier()
; #define PG8_SCHED __builtin_amdgcn_sched_barrier(0)
; template <class Epi>
; __device__ __forceinline__ void gemm_phase(LAS unsigned char* lds, const Gemm g, const StaticOrder& S, const Epi& E, const int tid) {
;     ...
;             PG8_LDA(At, 1, 1); PG8_STAGE(PG8_SB(1, 0), b3, voffB); PG8_STAGE(PG8_SB(1, 1), b3 + hstepB, voffB); PG8_STAGE(PG8_SA(1, 0), a3, voffA);
;             PG8_WAIT_V(8); PG8_WAIT_L(0); PG8_BAR; PG8_MMA(1, 0, At, B0); PG8_MMA(1, 1, At, B1); PG8_BAR; PG8_SCHED;
;         }
;         if (wr == 0) PG8_BAR;
	s_add_i32 s18, s31, s26
	v_lshl_add_u64 v[166:167], v[166:167], 0, s[0:1]
	s_mov_b32 m0, s18
	ds_read_b128 v[176:179], v191 offset:49152
	ds_read_b128 v[180:183], v191 offset:50176
	ds_read_b128 v[184:187], v191 offset:51200
	ds_read_b128 v[192:195], v191 offset:52224
	ds_read_b128 v[210:213], v191 offset:53248
	ds_read_b128 v[214:217], v191 offset:54272
	ds_read_b128 v[218:221], v191 offset:55296
	ds_read_b128 v[222:225], v191 offset:56320
	global_load_lds_dwordx4 v[166:167], off
	s_add_i32 m0, s18, 0x2000
	s_add_u32 s18, s22, 0xb0080
	v_lshl_add_u64 v[166:167], v[196:197], 0, s[0:1]
	s_addc_u32 s19, s23, 0
	s_add_i32 s22, s45, s26
	global_load_lds_dwordx4 v[166:167], off
	v_lshl_add_u64 v[166:167], s[18:19], 0, v[152:153]
	s_mov_b32 m0, s22
	s_nop 0
	global_load_lds_dwordx4 v[166:167], off
	v_lshl_add_u64 v[166:167], s[18:19], 0, v[170:171]
	s_add_i32 m0, s22, 0x2000
	s_nop 0
	global_load_lds_dwordx4 v[166:167], off
	v_lshl_add_u64 v[166:167], v[204:205], 0, s[0:1]
	s_mov_b32 m0, s36
	s_nop 0
	global_load_lds_dwordx4 v[166:167], off
	v_lshl_add_u64 v[166:167], v[226:227], 0, s[0:1]
	s_mov_b32 m0, s37
	s_nop 0
	global_load_lds_dwordx4 v[166:167], off
	s_waitcnt vmcnt(8)
	s_waitcnt lgkmcnt(0)
	s_barrier
	s_waitcnt lgkmcnt(0)
	v_mfma_f32_16x16x32_f16 v[60:63], v[128:131], v[176:179], v[60:63]
	v_mfma_f32_16x16x32_f16 v[56:59], v[136:139], v[176:179], v[56:59]
	v_mfma_f32_16x16x32_f16 v[44:47], v[128:131], v[184:187], v[44:47]
	v_mfma_f32_16x16x32_f16 v[40:43], v[136:139], v[184:187], v[40:43]
	v_mfma_f32_16x16x32_f16 v[28:31], v[128:131], v[210:213], v[28:31]
	v_mfma_f32_16x16x32_f16 v[24:27], v[136:139], v[210:213], v[24:27]
	v_mfma_f32_16x16x32_f16 v[12:15], v[128:131], v[218:221], v[12:15]
	v_mfma_f32_16x16x32_f16 v[8:11], v[136:139], v[218:221], v[8:11]
	v_mfma_f32_16x16x32_f16 v[60:63], v[132:135], v[180:183], v[60:63]
	v_mfma_f32_16x16x32_f16 v[56:59], v[140:143], v[180:183], v[56:59]
	v_mfma_f32_16x16x32_f16 v[44:47], v[132:135], v[192:195], v[44:47]
	v_mfma_f32_16x16x32_f16 v[40:43], v[140:143], v[192:195], v[40:43]
	v_mfma_f32_16x16x32_f16 v[28:31], v[132:135], v[214:217], v[28:31]
	v_mfma_f32_16x16x32_f16 v[24:27], v[140:143], v[214:217], v[24:27]
	v_mfma_f32_16x16x32_f16 v[12:15], v[132:135], v[222:225], v[12:15]
	v_mfma_f32_16x16x32_f16 v[8:11], v[140:143], v[222:225], v[8:11]
	v_mfma_f32_16x16x32_f16 v[52:55], v[144:147], v[176:179], v[52:55]
	v_mfma_f32_16x16x32_f16 v[48:51], v[154:157], v[176:179], v[48:51]
	v_mfma_f32_16x16x32_f16 v[36:39], v[144:147], v[184:187], v[36:39]
	v_mfma_f32_16x16x32_f16 v[32:35], v[154:157], v[184:187], v[32:35]
	v_mfma_f32_16x16x32_f16 v[20:23], v[144:147], v[210:213], v[20:23]
	v_mfma_f32_16x16x32_f16 v[16:19], v[154:157], v[210:213], v[16:19]
	v_mfma_f32_16x16x32_f16 v[4:7], v[144:147], v[218:221], v[4:7]
	v_mfma_f32_16x16x32_f16 v[0:3], v[154:157], v[218:221], v[0:3]
	v_mfma_f32_16x16x32_f16 v[52:55], v[148:151], v[180:183], v[52:55]
	v_mfma_f32_16x16x32_f16 v[48:51], v[162:165], v[180:183], v[48:51]
	v_mfma_f32_16x16x32_f16 v[36:39], v[148:151], v[192:195], v[36:39]
	v_mfma_f32_16x16x32_f16 v[32:35], v[162:165], v[192:195], v[32:35]
	v_mfma_f32_16x16x32_f16 v[20:23], v[148:151], v[214:217], v[20:23]
	v_mfma_f32_16x16x32_f16 v[16:19], v[162:165], v[214:217], v[16:19]
	v_mfma_f32_16x16x32_f16 v[4:7], v[148:151], v[222:225], v[4:7]
	v_mfma_f32_16x16x32_f16 v[0:3], v[162:165], v[222:225], v[0:3]
	s_barrier
	s_add_i32 s44, s44, 2
	s_add_u32 s2, s2, 0x100
	s_addc_u32 s3, s3, 0
	s_cmp_gt_u32 s44, 41
	s_mov_b64 s[18:19], s[20:21]
	s_cbranch_scc0 .LBB0_745
	s_and_b64 vcc, exec, s[14:15]
	s_cbranch_vccz .LBB0_748
	s_barrier

; #define PG8_STAGE(bufoff, gbase, voff) do { _Pragma("unroll") for (int _i = 0; _i < 2; ++_i) \
;         __builtin_amdgcn_global_load_lds((const unsigned*)((const char*)(gbase) + (voff)[_i]), (LAS unsigned*)(lds + (bufoff) + ldsw + _i * 8192), 16, 0, 0); } while (0)
; #define PG8_LDA(dst, b, h) do { _Pragma("unroll") for (int m = 0; m < 4; ++m) _Pragma("unroll") for (int k = 0; k < 2; ++k) dst[m][k] = *(const LAS h16x8*)(lds + PG8_SA(b, h) + aoff + m * 2048 + k * 1024); } while (0)
; #define PG8_LDB(dst, b, h) do { _Pragma("unroll") for (int n = 0; n < 2; ++n) _Pragma("unroll") for (int k = 0; k < 2; ++k) dst[n][k] = *(const LAS h16x8*)(lds + PG8_SB(b, h) + boff + n * 2048 + k * 1024); } while (0)
; #define PG8_MMA(ai, bj, At, Bt) do { __builtin_amdgcn_s_setprio(1); _Pragma("unroll") for (int m = 0; m < 4; ++m) _Pragma("unroll") for (int n = 0; n < 2; ++n) _Pragma("unroll") for (int k = 0; k < 2; ++k) \
;         acc[ai][bj][m][n] = __builtin_amdgcn_mfma_f32_16x16x32_f16(Bt[n][k], At[m][k], acc[ai][bj][m][n], 0, 0, 0); __builtin_amdgcn_s_setprio(0); } while (0)
; #define PG8_WAIT_V(n) asm volatile("s_waitcnt vmcnt(" #n ")" ::: "memory")
; #define PG8_BAR __builtin_amdgcn_s_barrier()
; template <class Epi>
; __device__ __forceinline__ void gemm_phase(LAS unsigned char* lds, const Gemm g, const StaticOrder& S, const Epi& E, const int tid) {
;     ...
;         const char* nA = has_next ? (const char*)g.A + (size_t)nxt.pm * tstepA : cA; const char* nB = has_next ? (const char*)g.Bt + (size_t)nxt.pn * tstepB : cB;
;         for (int t = 0; t < nt; t += 2) {
;             const bool last = (t == nt - 2);
;             const char* a1 = cA + (size_t)(t + 1) * kstep;
;             const char* a2 = last ? nA : cA + (size_t)(t + 2) * kstep; const char* b2 = last ? nB : cB + (size_t)(t + 2) * kstep;
;             const char* a3 = a2 + kstep; const char* b3 = b2 + kstep;
;             PG8_LDB(B0, 0, 0); PG8_LDB(B1, 0, 1); PG8_SCHED; PG8_LDA(At, 0, 0); PG8_STAGE(PG8_SA(1, 1), a1 + hstepA, voffA);
;             PG8_WAIT_V(8); PG8_WAIT_L(0); PG8_BAR; PG8_MMA(0, 0, At, B0); PG8_MMA(0, 1, At, B1); PG8_BAR; PG8_SCHED;
;             PG8_LDA(At, 0, 1); PG8_STAGE(PG8_SB(0, 0), b2, voffB); PG8_STAGE(PG8_SB(0, 1), b2 + hstepB, voffB); PG8_STAGE(PG8_SA(0, 0), a2, voffA);
;             PG8_WAIT_V(8); PG8_WAIT_L(0); PG8_BAR; PG8_MMA(1, 0, At, B0); PG8_MMA(1, 1, At, B1); PG8_BAR; PG8_SCHED;
.LBB0_794:
	s_add_u32 s24, s22, 0xfffc0080
	s_addc_u32 s25, s23, -1
	s_add_i32 s31, 0, 0x10000
	s_cmp_eq_u32 s46, 12
	s_cselect_b32 s27, s17, s25
	s_cselect_b32 s26, s44, s24
	s_cselect_b32 s25, s15, s3
	s_cselect_b32 s24, s45, s2
	s_add_i32 s47, 0, 0x14000
	v_add_u32_e32 v140, s31, v189
	v_add_u32_e32 v162, s47, v189
	ds_read_b128 v[128:131], v140
	ds_read_b128 v[132:135], v140 offset:1024
	ds_read_b128 v[136:139], v140 offset:2048
	ds_read_b128 v[140:143], v140 offset:3072
	ds_read_b128 v[144:147], v162
	ds_read_b128 v[148:151], v162 offset:1024
	ds_read_b128 v[154:157], v162 offset:2048
	ds_read_b128 v[162:165], v162 offset:3072
	v_lshl_add_u64 v[166:167], s[22:23], 0, v[172:173]
	s_add_i32 m0, s29, 0xc000
	ds_read_b128 v[176:179], v191
	ds_read_b128 v[180:183], v191 offset:1024
	ds_read_b128 v[184:187], v191 offset:2048
	ds_read_b128 v[192:195], v191 offset:3072
	ds_read_b128 v[210:213], v191 offset:4096
	ds_read_b128 v[214:217], v191 offset:5120
	ds_read_b128 v[218:221], v191 offset:6144
	ds_read_b128 v[222:225], v191 offset:7168
	global_load_lds_dwordx4 v[166:167], off
	v_lshl_add_u64 v[166:167], s[22:23], 0, v[174:175]
	s_add_i32 m0, s29, 0xe000
	s_nop 0
	global_load_lds_dwordx4 v[166:167], off
	s_waitcnt vmcnt(8)
	s_waitcnt lgkmcnt(0)
	s_barrier
	s_waitcnt lgkmcnt(0)
	v_mfma_f32_16x16x32_f16 v[124:127], v[128:131], v[176:179], v[124:127]
	v_mfma_f32_16x16x32_f16 v[120:123], v[136:139], v[176:179], v[120:123]
	v_mfma_f32_16x16x32_f16 v[108:111], v[128:131], v[184:187], v[108:111]
	v_mfma_f32_16x16x32_f16 v[104:107], v[136:139], v[184:187], v[104:107]
	v_mfma_f32_16x16x32_f16 v[92:95], v[128:131], v[210:213], v[92:95]
	v_mfma_f32_16x16x32_f16 v[88:91], v[136:139], v[210:213], v[88:91]
	v_mfma_f32_16x16x32_f16 v[76:79], v[128:131], v[218:221], v[76:79]
	v_mfma_f32_16x16x32_f16 v[72:75], v[136:139], v[218:221], v[72:75]
	v_mfma_f32_16x16x32_f16 v[124:127], v[132:135], v[180:183], v[124:127]
	v_mfma_f32_16x16x32_f16 v[120:123], v[140:143], v[180:183], v[120:123]
	v_mfma_f32_16x16x32_f16 v[108:111], v[132:135], v[192:195], v[108:111]
	v_mfma_f32_16x16x32_f16 v[104:107], v[140:143], v[192:195], v[104:107]
	v_mfma_f32_16x16x32_f16 v[92:95], v[132:135], v[214:217], v[92:95]
	v_mfma_f32_16x16x32_f16 v[88:91], v[140:143], v[214:217], v[88:91]
	v_mfma_f32_16x16x32_f16 v[76:79], v[132:135], v[222:225], v[76:79]
	v_mfma_f32_16x16x32_f16 v[72:75], v[140:143], v[222:225], v[72:75]
	v_mfma_f32_16x16x32_f16 v[116:119], v[144:147], v[176:179], v[116:119]
	v_mfma_f32_16x16x32_f16 v[112:115], v[154:157], v[176:179], v[112:115]
	v_mfma_f32_16x16x32_f16 v[100:103], v[144:147], v[184:187], v[100:103]
	v_mfma_f32_16x16x32_f16 v[96:99], v[154:157], v[184:187], v[96:99]
	v_mfma_f32_16x16x32_f16 v[84:87], v[144:147], v[210:213], v[84:87]
	v_mfma_f32_16x16x32_f16 v[80:83], v[154:157], v[210:213], v[80:83]
	v_mfma_f32_16x16x32_f16 v[68:71], v[144:147], v[218:221], v[68:71]
	v_mfma_f32_16x16x32_f16 v[64:67], v[154:157], v[218:221], v[64:67]
	v_mfma_f32_16x16x32_f16 v[116:119], v[148:151], v[180:183], v[116:119]
	v_mfma_f32_16x16x32_f16 v[112:115], v[162:165], v[180:183], v[112:115]
	v_mfma_f32_16x16x32_f16 v[100:103], v[148:151], v[192:195], v[100:103]
	v_mfma_f32_16x16x32_f16 v[96:99], v[162:165], v[192:195], v[96:99]
	v_mfma_f32_16x16x32_f16 v[84:87], v[148:151], v[214:217], v[84:87]
	v_mfma_f32_16x16x32_f16 v[80:83], v[162:165], v[214:217], v[80:83]
	v_mfma_f32_16x16x32_f16 v[68:71], v[148:151], v[222:225], v[68:71]
	v_mfma_f32_16x16x32_f16 v[64:67], v[162:165], v[222:225], v[64:67]
	s_barrier
	s_add_i32 s31, s31, s28
	v_lshl_add_u64 v[166:167], s[24:25], 0, v[152:153]
	s_mov_b32 m0, s31
	ds_read_b128 v[176:179], v191 offset:16384
	ds_read_b128 v[180:183], v191 offset:17408
	ds_read_b128 v[184:187], v191 offset:18432
	ds_read_b128 v[192:195], v191 offset:19456
	ds_read_b128 v[210:213], v191 offset:20480
	ds_read_b128 v[214:217], v191 offset:21504
	ds_read_b128 v[218:221], v191 offset:22528
	ds_read_b128 v[222:225], v191 offset:23552
	global_load_lds_dwordx4 v[166:167], off
	s_add_i32 m0, s31, 0x2000
	s_add_u32 s48, s24, 0x40000
	v_lshl_add_u64 v[196:197], s[24:25], 0, v[170:171]
	s_addc_u32 s49, s25, 0
	s_add_i32 s31, s47, s28
	global_load_lds_dwordx4 v[196:197], off
	v_lshl_add_u64 v[204:205], s[48:49], 0, v[152:153]
	s_mov_b32 m0, s31
	v_lshl_add_u64 v[226:227], s[26:27], 0, v[170:171]
	global_load_lds_dwordx4 v[204:205], off
	v_lshl_add_u64 v[204:205], s[48:49], 0, v[170:171]
	s_add_i32 m0, s31, 0x2000
	s_nop 0
	global_load_lds_dwordx4 v[204:205], off
	v_lshl_add_u64 v[204:205], s[26:27], 0, v[152:153]
	s_mov_b32 m0, s29
	s_nop 0
	global_load_lds_dwordx4 v[204:205], off
	s_mov_b32 m0, s35
	s_nop 0
	global_load_lds_dwordx4 v[226:227], off
	s_waitcnt vmcnt(8)
	s_waitcnt lgkmcnt(0)
	s_barrier
; #define PG8_STAGE(bufoff, gbase, voff) do { _Pragma("unroll") for (int _i = 0; _i < 2; ++_i) \
;         __builtin_amdgcn_global_load_lds((const unsigned*)((const char*)(gbase) + (voff)[_i]), (LAS unsigned*)(lds + (bufoff) + ldsw + _i * 8192), 16, 0, 0); } while (0)
; #define PG8_LDA(dst, b, h) do { _Pragma("unroll") for (int m = 0; m < 4; ++m) _Pragma("unroll") for (int k = 0; k < 2; ++k) dst[m][k] = *(const LAS h16x8*)(lds + PG8_SA(b, h) + aoff + m * 2048 + k * 1024); } while (0)
; #define PG8_LDB(dst, b, h) do { _Pragma("unroll") for (int n = 0; n < 2; ++n) _Pragma("unroll") for (int k = 0; k < 2; ++k) dst[n][k] = *(const LAS h16x8*)(lds + PG8_SB(b, h) + boff + n * 2048 + k * 1024); } while (0)
; #define PG8_MMA(ai, bj, At, Bt) do { __builtin_amdgcn_s_setprio(1); _Pragma("unroll") for (int m = 0; m < 4; ++m) _Pragma("unroll") for (int n = 0; n < 2; ++n) _Pragma("unroll") for (int k = 0; k < 2; ++k) \
;         acc[ai][bj][m][n] = __builtin_amdgcn_mfma_f32_16x16x32_f16(Bt[n][k], At[m][k], acc[ai][bj][m][n], 0, 0, 0); __builtin_amdgcn_s_setprio(0); } while (0)
; #define PG8_WAIT_V(n) asm volatile("s_waitcnt vmcnt(" #n ")" ::: "memory")
; #define PG8_WAIT_L(n) asm volatile("s_waitcnt lgkmcnt(" #n ")" ::: "memory")
; #define PG8_BAR __builtin_amdgcn_s_barrier()
; #define PG8_SCHED __builtin_amdgcn_sched_barrier(0)
; template <class Epi>
; __device__ __forceinline__ void gemm_phase(LAS unsigned char* lds, const Gemm g, const StaticOrder& S, const Epi& E, const int tid) {
;     ...
;             PG8_WAIT_V(8); PG8_WAIT_L(0); PG8_BAR; PG8_MMA(1, 0, At, B0); PG8_MMA(1, 1, At, B1); PG8_BAR; PG8_SCHED;
;             PG8_LDB(B0, 1, 0); PG8_LDB(B1, 1, 1); PG8_SCHED; PG8_LDA(At, 1, 0); PG8_STAGE(PG8_SA(0, 1), a2 + hstepA, voffA);
;             PG8_WAIT_V(8); PG8_WAIT_L(0); PG8_BAR; PG8_MMA(0, 0, At, B0); PG8_MMA(0, 1, At, B1); PG8_BAR; PG8_SCHED;
;             PG8_LDA(At, 1, 1); PG8_STAGE(PG8_SB(1, 0), b3, voffB); PG8_STAGE(PG8_SB(1, 1), b3 + hstepB, voffB); PG8_STAGE(PG8_SA(1, 0), a3, voffA);
	s_waitcnt lgkmcnt(0)
	v_mfma_f32_16x16x32_f16 v[60:63], v[128:131], v[176:179], v[60:63]
	v_mfma_f32_16x16x32_f16 v[56:59], v[136:139], v[176:179], v[56:59]
	v_mfma_f32_16x16x32_f16 v[44:47], v[128:131], v[184:187], v[44:47]
	v_mfma_f32_16x16x32_f16 v[40:43], v[136:139], v[184:187], v[40:43]
	v_mfma_f32_16x16x32_f16 v[28:31], v[128:131], v[210:213], v[28:31]
	v_mfma_f32_16x16x32_f16 v[24:27], v[136:139], v[210:213], v[24:27]
	v_mfma_f32_16x16x32_f16 v[12:15], v[128:131], v[218:221], v[12:15]
	v_mfma_f32_16x16x32_f16 v[8:11], v[136:139], v[218:221], v[8:11]
	v_mfma_f32_16x16x32_f16 v[60:63], v[132:135], v[180:183], v[60:63]
	v_mfma_f32_16x16x32_f16 v[56:59], v[140:143], v[180:183], v[56:59]
	v_mfma_f32_16x16x32_f16 v[44:47], v[132:135], v[192:195], v[44:47]
	v_mfma_f32_16x16x32_f16 v[40:43], v[140:143], v[192:195], v[40:43]
	v_mfma_f32_16x16x32_f16 v[28:31], v[132:135], v[214:217], v[28:31]
	v_mfma_f32_16x16x32_f16 v[24:27], v[140:143], v[214:217], v[24:27]
	v_mfma_f32_16x16x32_f16 v[12:15], v[132:135], v[222:225], v[12:15]
	v_mfma_f32_16x16x32_f16 v[8:11], v[140:143], v[222:225], v[8:11]
	v_mfma_f32_16x16x32_f16 v[52:55], v[144:147], v[176:179], v[52:55]
	v_mfma_f32_16x16x32_f16 v[48:51], v[154:157], v[176:179], v[48:51]
	v_mfma_f32_16x16x32_f16 v[36:39], v[144:147], v[184:187], v[36:39]
	v_mfma_f32_16x16x32_f16 v[32:35], v[154:157], v[184:187], v[32:35]
	v_mfma_f32_16x16x32_f16 v[20:23], v[144:147], v[210:213], v[20:23]
	v_mfma_f32_16x16x32_f16 v[16:19], v[154:157], v[210:213], v[16:19]
	v_mfma_f32_16x16x32_f16 v[4:7], v[144:147], v[218:221], v[4:7]
	v_mfma_f32_16x16x32_f16 v[0:3], v[154:157], v[218:221], v[0:3]
	v_mfma_f32_16x16x32_f16 v[52:55], v[148:151], v[180:183], v[52:55]
	v_mfma_f32_16x16x32_f16 v[48:51], v[162:165], v[180:183], v[48:51]
	v_mfma_f32_16x16x32_f16 v[36:39], v[148:151], v[192:195], v[36:39]
	v_mfma_f32_16x16x32_f16 v[32:35], v[162:165], v[192:195], v[32:35]
	v_mfma_f32_16x16x32_f16 v[20:23], v[148:151], v[214:217], v[20:23]
	v_mfma_f32_16x16x32_f16 v[16:19], v[162:165], v[214:217], v[16:19]
	v_mfma_f32_16x16x32_f16 v[4:7], v[148:151], v[222:225], v[4:7]
	v_mfma_f32_16x16x32_f16 v[0:3], v[162:165], v[222:225], v[0:3]
	s_barrier
	s_add_i32 s31, 0, 0x18000
	s_add_i32 s47, 0, 0x1c000
	v_add_u32_e32 v140, s31, v189
	v_add_u32_e32 v162, s47, v189
	ds_read_b128 v[128:131], v140
	ds_read_b128 v[132:135], v140 offset:1024
	ds_read_b128 v[136:139], v140 offset:2048
	ds_read_b128 v[140:143], v140 offset:3072
	ds_read_b128 v[144:147], v162
	ds_read_b128 v[148:151], v162 offset:1024
	ds_read_b128 v[154:157], v162 offset:2048
	ds_read_b128 v[162:165], v162 offset:3072
	s_add_u32 s26, s26, 0x40000
	s_addc_u32 s27, s27, 0
	s_mov_b32 m0, s36
	v_lshl_add_u64 v[228:229], s[26:27], 0, v[152:153]
	ds_read_b128 v[176:179], v191 offset:32768
	ds_read_b128 v[180:183], v191 offset:33792
	ds_read_b128 v[184:187], v191 offset:34816
	ds_read_b128 v[192:195], v191 offset:35840
	ds_read_b128 v[210:213], v191 offset:36864
	ds_read_b128 v[214:217], v191 offset:37888
	ds_read_b128 v[218:221], v191 offset:38912
	ds_read_b128 v[222:225], v191 offset:39936
	global_load_lds_dwordx4 v[228:229], off
	v_lshl_add_u64 v[228:229], s[26:27], 0, v[170:171]
	s_mov_b32 m0, s37
	s_nop 0
	global_load_lds_dwordx4 v[228:229], off
	s_waitcnt vmcnt(8)
	s_waitcnt lgkmcnt(0)
	s_barrier
	s_waitcnt lgkmcnt(0)
	v_mfma_f32_16x16x32_f16 v[124:127], v[128:131], v[176:179], v[124:127]
	v_mfma_f32_16x16x32_f16 v[120:123], v[136:139], v[176:179], v[120:123]
	v_mfma_f32_16x16x32_f16 v[108:111], v[128:131], v[184:187], v[108:111]
	v_mfma_f32_16x16x32_f16 v[104:107], v[136:139], v[184:187], v[104:107]
	v_mfma_f32_16x16x32_f16 v[92:95], v[128:131], v[210:213], v[92:95]
	v_mfma_f32_16x16x32_f16 v[88:91], v[136:139], v[210:213], v[88:91]
	v_mfma_f32_16x16x32_f16 v[76:79], v[128:131], v[218:221], v[76:79]
	v_mfma_f32_16x16x32_f16 v[72:75], v[136:139], v[218:221], v[72:75]
	v_mfma_f32_16x16x32_f16 v[124:127], v[132:135], v[180:183], v[124:127]
	v_mfma_f32_16x16x32_f16 v[120:123], v[140:143], v[180:183], v[120:123]
	v_mfma_f32_16x16x32_f16 v[108:111], v[132:135], v[192:195], v[108:111]
	v_mfma_f32_16x16x32_f16 v[104:107], v[140:143], v[192:195], v[104:107]
	v_mfma_f32_16x16x32_f16 v[92:95], v[132:135], v[214:217], v[92:95]
	v_mfma_f32_16x16x32_f16 v[88:91], v[140:143], v[214:217], v[88:91]
	v_mfma_f32_16x16x32_f16 v[76:79], v[132:135], v[222:225], v[76:79]
	v_mfma_f32_16x16x32_f16 v[72:75], v[140:143], v[222:225], v[72:75]
	v_mfma_f32_16x16x32_f16 v[116:119], v[144:147], v[176:179], v[116:119]
	v_mfma_f32_16x16x32_f16 v[112:115], v[154:157], v[176:179], v[112:115]
	v_mfma_f32_16x16x32_f16 v[100:103], v[144:147], v[184:187], v[100:103]
	v_mfma_f32_16x16x32_f16 v[96:99], v[154:157], v[184:187], v[96:99]
	v_mfma_f32_16x16x32_f16 v[84:87], v[144:147], v[210:213], v[84:87]
	v_mfma_f32_16x16x32_f16 v[80:83], v[154:157], v[210:213], v[80:83]
	v_mfma_f32_16x16x32_f16 v[68:71], v[144:147], v[218:221], v[68:71]
	v_mfma_f32_16x16x32_f16 v[64:67], v[154:157], v[218:221], v[64:67]
	v_mfma_f32_16x16x32_f16 v[116:119], v[148:151], v[180:183], v[116:119]
	v_mfma_f32_16x16x32_f16 v[112:115], v[162:165], v[180:183], v[112:115]
	v_mfma_f32_16x16x32_f16 v[100:103], v[148:151], v[192:195], v[100:103]
	v_mfma_f32_16x16x32_f16 v[96:99], v[162:165], v[192:195], v[96:99]
	v_mfma_f32_16x16x32_f16 v[84:87], v[148:151], v[214:217], v[84:87]
	v_mfma_f32_16x16x32_f16 v[80:83], v[162:165], v[214:217], v[80:83]
	v_mfma_f32_16x16x32_f16 v[68:71], v[148:151], v[222:225], v[68:71]
	v_mfma_f32_16x16x32_f16 v[64:67], v[162:165], v[222:225], v[64:67]
	s_barrier
; #define PG8_STAGE(bufoff, gbase, voff) do { _Pragma("unroll") for (int _i = 0; _i < 2; ++_i) \
;         __builtin_amdgcn_global_load_lds((const unsigned*)((const char*)(gbase) + (voff)[_i]), (LAS unsigned*)(lds + (bufoff) + ldsw + _i * 8192), 16, 0, 0); } while (0)
; #define PG8_LDA(dst, b, h) do { _Pragma("unroll") for (int m = 0; m < 4; ++m) _Pragma("unroll") for (int k = 0; k < 2; ++k) dst[m][k] = *(const LAS h16x8*)(lds + PG8_SA(b, h) + aoff + m * 2048 + k * 1024); } while (0)
; #define PG8_MMA(ai, bj, At, Bt) do { __builtin_amdgcn_s_setprio(1); _Pragma("unroll") for (int m = 0; m < 4; ++m) _Pragma("unroll") for (int n = 0; n < 2; ++n) _Pragma("unroll") for (int k = 0; k < 2; ++k) \
;         acc[ai][bj][m][n] = __builtin_amdgcn_mfma_f32_16x16x32_f16(Bt[n][k], At[m][k], acc[ai][bj][m][n], 0, 0, 0); __builtin_amdgcn_s_setprio(0); } while (0)
; #define PG8_WAIT_V(n) asm volatile("s_waitcnt vmcnt(" #n ")" ::: "memory")
; #define PG8_WAIT_L(n) asm volatile("s_waitcnt lgkmcnt(" #n ")" ::: "memory")
; #define PG8_BAR __builtin_amdgcn_s_barrier()
; #define PG8_SCHED __builtin_amdgcn_sched_barrier(0)
; template <class Epi>
; __device__ __forceinline__ void gemm_phase(LAS unsigned char* lds, const Gemm g, const StaticOrder& S, const Epi& E, const int tid) {
;     ...
;             PG8_LDA(At, 1, 1); PG8_STAGE(PG8_SB(1, 0), b3, voffB); PG8_STAGE(PG8_SB(1, 1), b3 + hstepB, voffB); PG8_STAGE(PG8_SA(1, 0), a3, voffA);
;             PG8_WAIT_V(8); PG8_WAIT_L(0); PG8_BAR; PG8_MMA(1, 0, At, B0); PG8_MMA(1, 1, At, B1); PG8_BAR; PG8_SCHED;
;         }
;         if (wr == 0) PG8_BAR;
	s_add_i32 s26, s31, s28
	v_lshl_add_u64 v[166:167], v[166:167], 0, s[0:1]
	s_mov_b32 m0, s26
	ds_read_b128 v[176:179], v191 offset:49152
	ds_read_b128 v[180:183], v191 offset:50176
	ds_read_b128 v[184:187], v191 offset:51200
	ds_read_b128 v[192:195], v191 offset:52224
	ds_read_b128 v[210:213], v191 offset:53248
	ds_read_b128 v[214:217], v191 offset:54272
	ds_read_b128 v[218:221], v191 offset:55296
	ds_read_b128 v[222:225], v191 offset:56320
	global_load_lds_dwordx4 v[166:167], off
	s_add_i32 m0, s26, 0x2000
	s_add_u32 s24, s24, 0x40080
	v_lshl_add_u64 v[166:167], v[196:197], 0, s[0:1]
	s_addc_u32 s25, s25, 0
	s_add_i32 s26, s47, s28
	global_load_lds_dwordx4 v[166:167], off
	v_lshl_add_u64 v[166:167], s[24:25], 0, v[152:153]
	s_mov_b32 m0, s26
	s_nop 0
	global_load_lds_dwordx4 v[166:167], off
	v_lshl_add_u64 v[166:167], s[24:25], 0, v[170:171]
	s_add_i32 m0, s26, 0x2000
	s_nop 0
	global_load_lds_dwordx4 v[166:167], off
	v_lshl_add_u64 v[166:167], v[204:205], 0, s[0:1]
	s_mov_b32 m0, s38
	s_nop 0
	global_load_lds_dwordx4 v[166:167], off
	v_lshl_add_u64 v[166:167], v[226:227], 0, s[0:1]
	s_mov_b32 m0, s39
	s_nop 0
	global_load_lds_dwordx4 v[166:167], off
	s_waitcnt vmcnt(8)
	s_waitcnt lgkmcnt(0)
	s_barrier
	s_waitcnt lgkmcnt(0)
	v_mfma_f32_16x16x32_f16 v[60:63], v[128:131], v[176:179], v[60:63]
	v_mfma_f32_16x16x32_f16 v[56:59], v[136:139], v[176:179], v[56:59]
	v_mfma_f32_16x16x32_f16 v[44:47], v[128:131], v[184:187], v[44:47]
	v_mfma_f32_16x16x32_f16 v[40:43], v[136:139], v[184:187], v[40:43]
	v_mfma_f32_16x16x32_f16 v[28:31], v[128:131], v[210:213], v[28:31]
	v_mfma_f32_16x16x32_f16 v[24:27], v[136:139], v[210:213], v[24:27]
	v_mfma_f32_16x16x32_f16 v[12:15], v[128:131], v[218:221], v[12:15]
	v_mfma_f32_16x16x32_f16 v[8:11], v[136:139], v[218:221], v[8:11]
	v_mfma_f32_16x16x32_f16 v[60:63], v[132:135], v[180:183], v[60:63]
	v_mfma_f32_16x16x32_f16 v[56:59], v[140:143], v[180:183], v[56:59]
	v_mfma_f32_16x16x32_f16 v[44:47], v[132:135], v[192:195], v[44:47]
	v_mfma_f32_16x16x32_f16 v[40:43], v[140:143], v[192:195], v[40:43]
	v_mfma_f32_16x16x32_f16 v[28:31], v[132:135], v[214:217], v[28:31]
	v_mfma_f32_16x16x32_f16 v[24:27], v[140:143], v[214:217], v[24:27]
	v_mfma_f32_16x16x32_f16 v[12:15], v[132:135], v[222:225], v[12:15]
	v_mfma_f32_16x16x32_f16 v[8:11], v[140:143], v[222:225], v[8:11]
	v_mfma_f32_16x16x32_f16 v[52:55], v[144:147], v[176:179], v[52:55]
	v_mfma_f32_16x16x32_f16 v[48:51], v[154:157], v[176:179], v[48:51]
	v_mfma_f32_16x16x32_f16 v[36:39], v[144:147], v[184:187], v[36:39]
	v_mfma_f32_16x16x32_f16 v[32:35], v[154:157], v[184:187], v[32:35]
	v_mfma_f32_16x16x32_f16 v[20:23], v[144:147], v[210:213], v[20:23]
	v_mfma_f32_16x16x32_f16 v[16:19], v[154:157], v[210:213], v[16:19]
	v_mfma_f32_16x16x32_f16 v[4:7], v[144:147], v[218:221], v[4:7]
	v_mfma_f32_16x16x32_f16 v[0:3], v[154:157], v[218:221], v[0:3]
	v_mfma_f32_16x16x32_f16 v[52:55], v[148:151], v[180:183], v[52:55]
	v_mfma_f32_16x16x32_f16 v[48:51], v[162:165], v[180:183], v[48:51]
	v_mfma_f32_16x16x32_f16 v[36:39], v[148:151], v[192:195], v[36:39]
	v_mfma_f32_16x16x32_f16 v[32:35], v[162:165], v[192:195], v[32:35]
	v_mfma_f32_16x16x32_f16 v[20:23], v[148:151], v[214:217], v[20:23]
	v_mfma_f32_16x16x32_f16 v[16:19], v[162:165], v[214:217], v[16:19]
	v_mfma_f32_16x16x32_f16 v[4:7], v[148:151], v[222:225], v[4:7]
	v_mfma_f32_16x16x32_f16 v[0:3], v[162:165], v[222:225], v[0:3]
	s_barrier
	s_add_i32 s46, s46, 2
	s_add_u32 s22, s22, 0x100
	s_addc_u32 s23, s23, 0
	s_add_u32 s2, s2, 0x100
	s_addc_u32 s3, s3, 0
	s_cmp_gt_u32 s46, 13
	s_cbranch_scc0 .LBB0_794
	s_and_b64 vcc, exec, s[10:11]
	s_cbranch_vccz .LBB0_797
	s_barrier

; #define PG8_STAGE(bufoff, gbase, voff) do { _Pragma("unroll") for (int _i = 0; _i < 2; ++_i) \
;         __builtin_amdgcn_global_load_lds((const unsigned*)((const char*)(gbase) + (voff)[_i]), (LAS unsigned*)(lds + (bufoff) + ldsw + _i * 8192), 16, 0, 0); } while (0)
; #define PG8_LDA(dst, b, h) do { _Pragma("unroll") for (int m = 0; m < 4; ++m) _Pragma("unroll") for (int k = 0; k < 2; ++k) dst[m][k] = *(const LAS h16x8*)(lds + PG8_SA(b, h) + aoff + m * 2048 + k * 1024); } while (0)
; #define PG8_LDB(dst, b, h) do { _Pragma("unroll") for (int n = 0; n < 2; ++n) _Pragma("unroll") for (int k = 0; k < 2; ++k) dst[n][k] = *(const LAS h16x8*)(lds + PG8_SB(b, h) + boff + n * 2048 + k * 1024); } while (0)
; #define PG8_MMA(ai, bj, At, Bt) do { __builtin_amdgcn_s_setprio(1); _Pragma("unroll") for (int m = 0; m < 4; ++m) _Pragma("unroll") for (int n = 0; n < 2; ++n) _Pragma("unroll") for (int k = 0; k < 2; ++k) \
;         acc[ai][bj][m][n] = __builtin_amdgcn_mfma_f32_16x16x32_f16(Bt[n][k], At[m][k], acc[ai][bj][m][n], 0, 0, 0); __builtin_amdgcn_s_setprio(0); } while (0)
; #define PG8_WAIT_V(n) asm volatile("s_waitcnt vmcnt(" #n ")" ::: "memory")
; #define PG8_BAR __builtin_amdgcn_s_barrier()
; template <class Epi>
; __device__ __forceinline__ void gemm_phase(LAS unsigned char* lds, const Gemm g, const StaticOrder& S, const Epi& E, const int tid) {
;     ...
;         const char* nA = has_next ? (const char*)g.A + (size_t)nxt.pm * tstepA : cA; const char* nB = has_next ? (const char*)g.Bt + (size_t)nxt.pn * tstepB : cB;
;         for (int t = 0; t < nt; t += 2) {
;             const bool last = (t == nt - 2);
;             const char* a1 = cA + (size_t)(t + 1) * kstep;
;             const char* a2 = last ? nA : cA + (size_t)(t + 2) * kstep; const char* b2 = last ? nB : cB + (size_t)(t + 2) * kstep;
;             const char* a3 = a2 + kstep; const char* b3 = b2 + kstep;
;             PG8_LDB(B0, 0, 0); PG8_LDB(B1, 0, 1); PG8_SCHED; PG8_LDA(At, 0, 0); PG8_STAGE(PG8_SA(1, 1), a1 + hstepA, voffA);
;             PG8_WAIT_V(8); PG8_WAIT_L(0); PG8_BAR; PG8_MMA(0, 0, At, B0); PG8_MMA(0, 1, At, B1); PG8_BAR; PG8_SCHED;
;             PG8_LDA(At, 0, 1); PG8_STAGE(PG8_SB(0, 0), b2, voffB); PG8_STAGE(PG8_SB(0, 1), b2 + hstepB, voffB); PG8_STAGE(PG8_SA(0, 0), a2, voffA);
;             PG8_WAIT_V(8); PG8_WAIT_L(0); PG8_BAR; PG8_MMA(1, 0, At, B0); PG8_MMA(1, 1, At, B1); PG8_BAR; PG8_SCHED;
.LBB0_835:
	s_add_i32 s45, s24, 2
	s_add_u32 s31, s22, 0x80
	s_addc_u32 s25, s23, 0
	s_add_i32 s48, 0, 0x10000
	s_cmp_eq_u32 s39, s24
	s_cselect_b32 s25, s9, s25
	s_cselect_b32 s24, s8, s31
	v_add_u32_e32 v150, s48, v139
	s_cselect_b32 s47, s21, s3
	s_cselect_b32 s46, s20, s2
	s_add_i32 s31, 0, 0x14000
	ds_read_b128 v[142:145], v150
	ds_read_b128 v[146:149], v150 offset:1024
	ds_read_b128 v[154:157], v150 offset:2048
	ds_read_b128 v[162:165], v150 offset:3072
	v_add_u32_e32 v150, s31, v139
	ds_read_b128 v[170:173], v150
	ds_read_b128 v[174:177], v150 offset:1024
	ds_read_b128 v[178:181], v150 offset:2048
	ds_read_b128 v[182:185], v150 offset:3072
	v_lshl_add_u64 v[150:151], s[22:23], 0, v[134:135]
	s_add_i32 m0, s27, 0xc000
	ds_read_b128 v[186:189], v141
	ds_read_b128 v[190:193], v141 offset:1024
	ds_read_b128 v[194:197], v141 offset:2048
	ds_read_b128 v[210:213], v141 offset:3072
	ds_read_b128 v[214:217], v141 offset:4096
	ds_read_b128 v[218:221], v141 offset:5120
	ds_read_b128 v[222:225], v141 offset:6144
	ds_read_b128 v[226:229], v141 offset:7168
	global_load_lds_dwordx4 v[150:151], off
	v_lshl_add_u64 v[150:151], s[22:23], 0, v[136:137]
	s_add_i32 m0, s27, 0xe000
	s_nop 0
	global_load_lds_dwordx4 v[150:151], off
	s_waitcnt vmcnt(8)
	s_waitcnt lgkmcnt(0)
	s_barrier
	s_waitcnt lgkmcnt(0)
	v_mfma_f32_16x16x32_f16 v[120:123], v[142:145], v[186:189], v[120:123]
	v_mfma_f32_16x16x32_f16 v[124:127], v[154:157], v[186:189], v[124:127]
	v_mfma_f32_16x16x32_f16 v[108:111], v[142:145], v[194:197], v[108:111]
	v_mfma_f32_16x16x32_f16 v[104:107], v[154:157], v[194:197], v[104:107]
	v_mfma_f32_16x16x32_f16 v[92:95], v[142:145], v[214:217], v[92:95]
	v_mfma_f32_16x16x32_f16 v[88:91], v[154:157], v[214:217], v[88:91]
	v_mfma_f32_16x16x32_f16 v[76:79], v[142:145], v[222:225], v[76:79]
	v_mfma_f32_16x16x32_f16 v[72:75], v[154:157], v[222:225], v[72:75]
	v_mfma_f32_16x16x32_f16 v[120:123], v[146:149], v[190:193], v[120:123]
	v_mfma_f32_16x16x32_f16 v[124:127], v[162:165], v[190:193], v[124:127]
	v_mfma_f32_16x16x32_f16 v[108:111], v[146:149], v[210:213], v[108:111]
	v_mfma_f32_16x16x32_f16 v[104:107], v[162:165], v[210:213], v[104:107]
	v_mfma_f32_16x16x32_f16 v[92:95], v[146:149], v[218:221], v[92:95]
	v_mfma_f32_16x16x32_f16 v[88:91], v[162:165], v[218:221], v[88:91]
	v_mfma_f32_16x16x32_f16 v[76:79], v[146:149], v[226:229], v[76:79]
	v_mfma_f32_16x16x32_f16 v[72:75], v[162:165], v[226:229], v[72:75]
	v_mfma_f32_16x16x32_f16 v[116:119], v[170:173], v[186:189], v[116:119]
	v_mfma_f32_16x16x32_f16 v[112:115], v[178:181], v[186:189], v[112:115]
	v_mfma_f32_16x16x32_f16 v[100:103], v[170:173], v[194:197], v[100:103]
	v_mfma_f32_16x16x32_f16 v[96:99], v[178:181], v[194:197], v[96:99]
	v_mfma_f32_16x16x32_f16 v[84:87], v[170:173], v[214:217], v[84:87]
	v_mfma_f32_16x16x32_f16 v[80:83], v[178:181], v[214:217], v[80:83]
	v_mfma_f32_16x16x32_f16 v[68:71], v[170:173], v[222:225], v[68:71]
	v_mfma_f32_16x16x32_f16 v[64:67], v[178:181], v[222:225], v[64:67]
	v_mfma_f32_16x16x32_f16 v[116:119], v[174:177], v[190:193], v[116:119]
	v_mfma_f32_16x16x32_f16 v[112:115], v[182:185], v[190:193], v[112:115]
	v_mfma_f32_16x16x32_f16 v[100:103], v[174:177], v[210:213], v[100:103]
	v_mfma_f32_16x16x32_f16 v[96:99], v[182:185], v[210:213], v[96:99]
	v_mfma_f32_16x16x32_f16 v[84:87], v[174:177], v[218:221], v[84:87]
	v_mfma_f32_16x16x32_f16 v[80:83], v[182:185], v[218:221], v[80:83]
	v_mfma_f32_16x16x32_f16 v[68:71], v[174:177], v[226:229], v[68:71]
	v_mfma_f32_16x16x32_f16 v[64:67], v[182:185], v[226:229], v[64:67]
	s_barrier
	s_add_i32 s48, s48, s26
	v_lshl_add_u64 v[150:151], s[46:47], 0, v[152:153]
	s_mov_b32 m0, s48
	ds_read_b128 v[186:189], v141 offset:16384
	ds_read_b128 v[190:193], v141 offset:17408
	ds_read_b128 v[194:197], v141 offset:18432
	ds_read_b128 v[210:213], v141 offset:19456
	ds_read_b128 v[214:217], v141 offset:20480
	ds_read_b128 v[218:221], v141 offset:21504
	ds_read_b128 v[222:225], v141 offset:22528
	ds_read_b128 v[226:229], v141 offset:23552
	global_load_lds_dwordx4 v[150:151], off
	s_add_i32 m0, s48, 0x2000
	v_lshl_add_u64 v[166:167], s[46:47], 0, v[128:129]
	s_add_u32 s46, s46, s4
	s_addc_u32 s47, s47, s5
	s_add_i32 s31, s31, s26
	global_load_lds_dwordx4 v[166:167], off
	v_lshl_add_u64 v[204:205], s[46:47], 0, v[152:153]
	s_mov_b32 m0, s31
	v_lshl_add_u64 v[230:231], s[46:47], 0, v[128:129]
	global_load_lds_dwordx4 v[204:205], off
	s_add_i32 m0, s31, 0x2000
	v_lshl_add_u64 v[232:233], s[24:25], 0, v[132:133]
	global_load_lds_dwordx4 v[230:231], off
	s_mov_b32 m0, s27
	v_lshl_add_u64 v[234:235], s[24:25], 0, v[130:131]
	global_load_lds_dwordx4 v[232:233], off
	s_mov_b32 m0, s28
	s_nop 0
	global_load_lds_dwordx4 v[234:235], off
	s_waitcnt vmcnt(8)
	s_waitcnt lgkmcnt(0)
	s_barrier
; #define PG8_STAGE(bufoff, gbase, voff) do { _Pragma("unroll") for (int _i = 0; _i < 2; ++_i) \
;         __builtin_amdgcn_global_load_lds((const unsigned*)((const char*)(gbase) + (voff)[_i]), (LAS unsigned*)(lds + (bufoff) + ldsw + _i * 8192), 16, 0, 0); } while (0)
; #define PG8_LDA(dst, b, h) do { _Pragma("unroll") for (int m = 0; m < 4; ++m) _Pragma("unroll") for (int k = 0; k < 2; ++k) dst[m][k] = *(const LAS h16x8*)(lds + PG8_SA(b, h) + aoff + m * 2048 + k * 1024); } while (0)
; #define PG8_LDB(dst, b, h) do { _Pragma("unroll") for (int n = 0; n < 2; ++n) _Pragma("unroll") for (int k = 0; k < 2; ++k) dst[n][k] = *(const LAS h16x8*)(lds + PG8_SB(b, h) + boff + n * 2048 + k * 1024); } while (0)
; #define PG8_MMA(ai, bj, At, Bt) do { __builtin_amdgcn_s_setprio(1); _Pragma("unroll") for (int m = 0; m < 4; ++m) _Pragma("unroll") for (int n = 0; n < 2; ++n) _Pragma("unroll") for (int k = 0; k < 2; ++k) \
;         acc[ai][bj][m][n] = __builtin_amdgcn_mfma_f32_16x16x32_f16(Bt[n][k], At[m][k], acc[ai][bj][m][n], 0, 0, 0); __builtin_amdgcn_s_setprio(0); } while (0)
; #define PG8_WAIT_V(n) asm volatile("s_waitcnt vmcnt(" #n ")" ::: "memory")
; #define PG8_WAIT_L(n) asm volatile("s_waitcnt lgkmcnt(" #n ")" ::: "memory")
; #define PG8_BAR __builtin_amdgcn_s_barrier()
; #define PG8_SCHED __builtin_amdgcn_sched_barrier(0)
; template <class Epi>
; __device__ __forceinline__ void gemm_phase(LAS unsigned char* lds, const Gemm g, const StaticOrder& S, const Epi& E, const int tid) {
;     ...
;             PG8_WAIT_V(8); PG8_WAIT_L(0); PG8_BAR; PG8_MMA(1, 0, At, B0); PG8_MMA(1, 1, At, B1); PG8_BAR; PG8_SCHED;
;             PG8_LDB(B0, 1, 0); PG8_LDB(B1, 1, 1); PG8_SCHED; PG8_LDA(At, 1, 0); PG8_STAGE(PG8_SA(0, 1), a2 + hstepA, voffA);
;             PG8_WAIT_V(8); PG8_WAIT_L(0); PG8_BAR; PG8_MMA(0, 0, At, B0); PG8_MMA(0, 1, At, B1); PG8_BAR; PG8_SCHED;
;             PG8_LDA(At, 1, 1); PG8_STAGE(PG8_SB(1, 0), b3, voffB); PG8_STAGE(PG8_SB(1, 1), b3 + hstepB, voffB); PG8_STAGE(PG8_SA(1, 0), a3, voffA);
	s_waitcnt lgkmcnt(0)
	v_mfma_f32_16x16x32_f16 v[60:63], v[142:145], v[186:189], v[60:63]
	v_mfma_f32_16x16x32_f16 v[56:59], v[154:157], v[186:189], v[56:59]
	v_mfma_f32_16x16x32_f16 v[44:47], v[142:145], v[194:197], v[44:47]
	v_mfma_f32_16x16x32_f16 v[40:43], v[154:157], v[194:197], v[40:43]
	v_mfma_f32_16x16x32_f16 v[28:31], v[142:145], v[214:217], v[28:31]
	v_mfma_f32_16x16x32_f16 v[24:27], v[154:157], v[214:217], v[24:27]
	v_mfma_f32_16x16x32_f16 v[12:15], v[142:145], v[222:225], v[12:15]
	v_mfma_f32_16x16x32_f16 v[8:11], v[154:157], v[222:225], v[8:11]
	v_mfma_f32_16x16x32_f16 v[60:63], v[146:149], v[190:193], v[60:63]
	v_mfma_f32_16x16x32_f16 v[56:59], v[162:165], v[190:193], v[56:59]
	v_mfma_f32_16x16x32_f16 v[44:47], v[146:149], v[210:213], v[44:47]
	v_mfma_f32_16x16x32_f16 v[40:43], v[162:165], v[210:213], v[40:43]
	v_mfma_f32_16x16x32_f16 v[28:31], v[146:149], v[218:221], v[28:31]
	v_mfma_f32_16x16x32_f16 v[24:27], v[162:165], v[218:221], v[24:27]
	v_mfma_f32_16x16x32_f16 v[12:15], v[146:149], v[226:229], v[12:15]
	v_mfma_f32_16x16x32_f16 v[8:11], v[162:165], v[226:229], v[8:11]
	v_mfma_f32_16x16x32_f16 v[52:55], v[170:173], v[186:189], v[52:55]
	v_mfma_f32_16x16x32_f16 v[48:51], v[178:181], v[186:189], v[48:51]
	v_mfma_f32_16x16x32_f16 v[36:39], v[170:173], v[194:197], v[36:39]
	v_mfma_f32_16x16x32_f16 v[32:35], v[178:181], v[194:197], v[32:35]
	v_mfma_f32_16x16x32_f16 v[20:23], v[170:173], v[214:217], v[20:23]
	v_mfma_f32_16x16x32_f16 v[16:19], v[178:181], v[214:217], v[16:19]
	v_mfma_f32_16x16x32_f16 v[4:7], v[170:173], v[222:225], v[4:7]
	v_mfma_f32_16x16x32_f16 v[0:3], v[178:181], v[222:225], v[0:3]
	v_mfma_f32_16x16x32_f16 v[52:55], v[174:177], v[190:193], v[52:55]
	v_mfma_f32_16x16x32_f16 v[48:51], v[182:185], v[190:193], v[48:51]
	v_mfma_f32_16x16x32_f16 v[36:39], v[174:177], v[210:213], v[36:39]
	v_mfma_f32_16x16x32_f16 v[32:35], v[182:185], v[210:213], v[32:35]
	v_mfma_f32_16x16x32_f16 v[20:23], v[174:177], v[218:221], v[20:23]
	v_mfma_f32_16x16x32_f16 v[16:19], v[182:185], v[218:221], v[16:19]
	v_mfma_f32_16x16x32_f16 v[4:7], v[174:177], v[226:229], v[4:7]
	v_mfma_f32_16x16x32_f16 v[0:3], v[182:185], v[226:229], v[0:3]
	s_barrier
	s_add_i32 s31, 0, 0x18000
	s_add_i32 s46, 0, 0x1c000
	v_add_u32_e32 v162, s31, v139
	v_add_u32_e32 v182, s46, v139
	ds_read_b128 v[142:145], v162
	ds_read_b128 v[146:149], v162 offset:1024
	ds_read_b128 v[154:157], v162 offset:2048
	ds_read_b128 v[162:165], v162 offset:3072
	ds_read_b128 v[170:173], v182
	ds_read_b128 v[174:177], v182 offset:1024
	ds_read_b128 v[178:181], v182 offset:2048
	ds_read_b128 v[182:185], v182 offset:3072
	s_add_u32 s24, s24, s4
	s_addc_u32 s25, s25, s5
	s_mov_b32 m0, s29
	v_lshl_add_u64 v[236:237], s[24:25], 0, v[132:133]
	ds_read_b128 v[186:189], v141 offset:32768
	ds_read_b128 v[190:193], v141 offset:33792
	ds_read_b128 v[194:197], v141 offset:34816
	ds_read_b128 v[210:213], v141 offset:35840
	ds_read_b128 v[214:217], v141 offset:36864
	ds_read_b128 v[218:221], v141 offset:37888
	ds_read_b128 v[222:225], v141 offset:38912
	ds_read_b128 v[226:229], v141 offset:39936
	global_load_lds_dwordx4 v[236:237], off
	v_lshl_add_u64 v[236:237], s[24:25], 0, v[130:131]
	s_mov_b32 m0, s35
	s_nop 0
	global_load_lds_dwordx4 v[236:237], off
	s_waitcnt vmcnt(8)
	s_waitcnt lgkmcnt(0)
	s_barrier
	s_waitcnt lgkmcnt(0)
	v_mfma_f32_16x16x32_f16 v[120:123], v[142:145], v[186:189], v[120:123]
	v_mfma_f32_16x16x32_f16 v[124:127], v[154:157], v[186:189], v[124:127]
	v_mfma_f32_16x16x32_f16 v[108:111], v[142:145], v[194:197], v[108:111]
	v_mfma_f32_16x16x32_f16 v[104:107], v[154:157], v[194:197], v[104:107]
	v_mfma_f32_16x16x32_f16 v[92:95], v[142:145], v[214:217], v[92:95]
	v_mfma_f32_16x16x32_f16 v[88:91], v[154:157], v[214:217], v[88:91]
	v_mfma_f32_16x16x32_f16 v[76:79], v[142:145], v[222:225], v[76:79]
	v_mfma_f32_16x16x32_f16 v[72:75], v[154:157], v[222:225], v[72:75]
	v_mfma_f32_16x16x32_f16 v[120:123], v[146:149], v[190:193], v[120:123]
	v_mfma_f32_16x16x32_f16 v[124:127], v[162:165], v[190:193], v[124:127]
	v_mfma_f32_16x16x32_f16 v[108:111], v[146:149], v[210:213], v[108:111]
	v_mfma_f32_16x16x32_f16 v[104:107], v[162:165], v[210:213], v[104:107]
	v_mfma_f32_16x16x32_f16 v[92:95], v[146:149], v[218:221], v[92:95]
	v_mfma_f32_16x16x32_f16 v[88:91], v[162:165], v[218:221], v[88:91]
	v_mfma_f32_16x16x32_f16 v[76:79], v[146:149], v[226:229], v[76:79]
	v_mfma_f32_16x16x32_f16 v[72:75], v[162:165], v[226:229], v[72:75]
	v_mfma_f32_16x16x32_f16 v[116:119], v[170:173], v[186:189], v[116:119]
	v_mfma_f32_16x16x32_f16 v[112:115], v[178:181], v[186:189], v[112:115]
	v_mfma_f32_16x16x32_f16 v[100:103], v[170:173], v[194:197], v[100:103]
	v_mfma_f32_16x16x32_f16 v[96:99], v[178:181], v[194:197], v[96:99]
	v_mfma_f32_16x16x32_f16 v[84:87], v[170:173], v[214:217], v[84:87]
	v_mfma_f32_16x16x32_f16 v[80:83], v[178:181], v[214:217], v[80:83]
	v_mfma_f32_16x16x32_f16 v[68:71], v[170:173], v[222:225], v[68:71]
	v_mfma_f32_16x16x32_f16 v[64:67], v[178:181], v[222:225], v[64:67]
	v_mfma_f32_16x16x32_f16 v[116:119], v[174:177], v[190:193], v[116:119]
	v_mfma_f32_16x16x32_f16 v[112:115], v[182:185], v[190:193], v[112:115]
	v_mfma_f32_16x16x32_f16 v[100:103], v[174:177], v[210:213], v[100:103]
	v_mfma_f32_16x16x32_f16 v[96:99], v[182:185], v[210:213], v[96:99]
	v_mfma_f32_16x16x32_f16 v[84:87], v[174:177], v[218:221], v[84:87]
	v_mfma_f32_16x16x32_f16 v[80:83], v[182:185], v[218:221], v[80:83]
	v_mfma_f32_16x16x32_f16 v[68:71], v[174:177], v[226:229], v[68:71]
	v_mfma_f32_16x16x32_f16 v[64:67], v[182:185], v[226:229], v[64:67]
	s_barrier
; #define PG8_STAGE(bufoff, gbase, voff) do { _Pragma("unroll") for (int _i = 0; _i < 2; ++_i) \
;         __builtin_amdgcn_global_load_lds((const unsigned*)((const char*)(gbase) + (voff)[_i]), (LAS unsigned*)(lds + (bufoff) + ldsw + _i * 8192), 16, 0, 0); } while (0)
; #define PG8_LDA(dst, b, h) do { _Pragma("unroll") for (int m = 0; m < 4; ++m) _Pragma("unroll") for (int k = 0; k < 2; ++k) dst[m][k] = *(const LAS h16x8*)(lds + PG8_SA(b, h) + aoff + m * 2048 + k * 1024); } while (0)
; #define PG8_MMA(ai, bj, At, Bt) do { __builtin_amdgcn_s_setprio(1); _Pragma("unroll") for (int m = 0; m < 4; ++m) _Pragma("unroll") for (int n = 0; n < 2; ++n) _Pragma("unroll") for (int k = 0; k < 2; ++k) \
;         acc[ai][bj][m][n] = __builtin_amdgcn_mfma_f32_16x16x32_f16(Bt[n][k], At[m][k], acc[ai][bj][m][n], 0, 0, 0); __builtin_amdgcn_s_setprio(0); } while (0)
; #define PG8_WAIT_V(n) asm volatile("s_waitcnt vmcnt(" #n ")" ::: "memory")
; #define PG8_WAIT_L(n) asm volatile("s_waitcnt lgkmcnt(" #n ")" ::: "memory")
; #define PG8_BAR __builtin_amdgcn_s_barrier()
; #define PG8_SCHED __builtin_amdgcn_sched_barrier(0)
; template <class Epi>
; __device__ __forceinline__ void gemm_phase(LAS unsigned char* lds, const Gemm g, const StaticOrder& S, const Epi& E, const int tid) {
;     ...
;             PG8_LDA(At, 1, 1); PG8_STAGE(PG8_SB(1, 0), b3, voffB); PG8_STAGE(PG8_SB(1, 1), b3 + hstepB, voffB); PG8_STAGE(PG8_SA(1, 0), a3, voffA);
;             PG8_WAIT_V(8); PG8_WAIT_L(0); PG8_BAR; PG8_MMA(1, 0, At, B0); PG8_MMA(1, 1, At, B1); PG8_BAR; PG8_SCHED;
;         }
;         if (wr == 0) PG8_BAR;
	s_add_i32 s24, s31, s26
	v_lshl_add_u64 v[150:151], v[150:151], 0, s[0:1]
	s_mov_b32 m0, s24
	ds_read_b128 v[186:189], v141 offset:49152
	ds_read_b128 v[190:193], v141 offset:50176
	ds_read_b128 v[194:197], v141 offset:51200
	ds_read_b128 v[210:213], v141 offset:52224
	ds_read_b128 v[214:217], v141 offset:53248
	ds_read_b128 v[218:221], v141 offset:54272
	ds_read_b128 v[222:225], v141 offset:55296
	ds_read_b128 v[226:229], v141 offset:56320
	global_load_lds_dwordx4 v[150:151], off
	v_lshl_add_u64 v[150:151], v[166:167], 0, s[0:1]
	s_add_i32 m0, s24, 0x2000
	s_add_i32 s24, s46, s26
	global_load_lds_dwordx4 v[150:151], off
	v_lshl_add_u64 v[150:151], v[204:205], 0, s[0:1]
	s_mov_b32 m0, s24
	s_nop 0
	global_load_lds_dwordx4 v[150:151], off
	v_lshl_add_u64 v[150:151], v[230:231], 0, s[0:1]
	s_add_i32 m0, s24, 0x2000
	s_nop 0
	global_load_lds_dwordx4 v[150:151], off
	v_lshl_add_u64 v[150:151], v[232:233], 0, s[0:1]
	s_mov_b32 m0, s36
	s_nop 0
	global_load_lds_dwordx4 v[150:151], off
	v_lshl_add_u64 v[150:151], v[234:235], 0, s[0:1]
	s_mov_b32 m0, s37
	s_nop 0
	global_load_lds_dwordx4 v[150:151], off
	s_waitcnt vmcnt(8)
	s_waitcnt lgkmcnt(0)
	s_barrier
	s_waitcnt lgkmcnt(0)
	v_mfma_f32_16x16x32_f16 v[60:63], v[142:145], v[186:189], v[60:63]
	v_mfma_f32_16x16x32_f16 v[56:59], v[154:157], v[186:189], v[56:59]
	v_mfma_f32_16x16x32_f16 v[44:47], v[142:145], v[194:197], v[44:47]
	v_mfma_f32_16x16x32_f16 v[40:43], v[154:157], v[194:197], v[40:43]
	v_mfma_f32_16x16x32_f16 v[28:31], v[142:145], v[214:217], v[28:31]
	v_mfma_f32_16x16x32_f16 v[24:27], v[154:157], v[214:217], v[24:27]
	v_mfma_f32_16x16x32_f16 v[12:15], v[142:145], v[222:225], v[12:15]
	v_mfma_f32_16x16x32_f16 v[8:11], v[154:157], v[222:225], v[8:11]
	v_mfma_f32_16x16x32_f16 v[60:63], v[146:149], v[190:193], v[60:63]
	v_mfma_f32_16x16x32_f16 v[56:59], v[162:165], v[190:193], v[56:59]
	v_mfma_f32_16x16x32_f16 v[44:47], v[146:149], v[210:213], v[44:47]
	v_mfma_f32_16x16x32_f16 v[40:43], v[162:165], v[210:213], v[40:43]
	v_mfma_f32_16x16x32_f16 v[28:31], v[146:149], v[218:221], v[28:31]
	v_mfma_f32_16x16x32_f16 v[24:27], v[162:165], v[218:221], v[24:27]
	v_mfma_f32_16x16x32_f16 v[12:15], v[146:149], v[226:229], v[12:15]
	v_mfma_f32_16x16x32_f16 v[8:11], v[162:165], v[226:229], v[8:11]
	v_mfma_f32_16x16x32_f16 v[52:55], v[170:173], v[186:189], v[52:55]
	v_mfma_f32_16x16x32_f16 v[48:51], v[178:181], v[186:189], v[48:51]
	v_mfma_f32_16x16x32_f16 v[36:39], v[170:173], v[194:197], v[36:39]
	v_mfma_f32_16x16x32_f16 v[32:35], v[178:181], v[194:197], v[32:35]
	v_mfma_f32_16x16x32_f16 v[20:23], v[170:173], v[214:217], v[20:23]
	v_mfma_f32_16x16x32_f16 v[16:19], v[178:181], v[214:217], v[16:19]
	v_mfma_f32_16x16x32_f16 v[4:7], v[170:173], v[222:225], v[4:7]
	v_mfma_f32_16x16x32_f16 v[0:3], v[178:181], v[222:225], v[0:3]
	v_mfma_f32_16x16x32_f16 v[52:55], v[174:177], v[190:193], v[52:55]
	v_mfma_f32_16x16x32_f16 v[48:51], v[182:185], v[190:193], v[48:51]
	v_mfma_f32_16x16x32_f16 v[36:39], v[174:177], v[210:213], v[36:39]
	v_mfma_f32_16x16x32_f16 v[32:35], v[182:185], v[210:213], v[32:35]
	v_mfma_f32_16x16x32_f16 v[20:23], v[174:177], v[218:221], v[20:23]
	v_mfma_f32_16x16x32_f16 v[16:19], v[182:185], v[218:221], v[16:19]
	v_mfma_f32_16x16x32_f16 v[4:7], v[174:177], v[226:229], v[4:7]
	v_mfma_f32_16x16x32_f16 v[0:3], v[182:185], v[226:229], v[0:3]
	s_barrier
	s_add_u32 s22, s22, 0x100
	s_addc_u32 s23, s23, 0
	s_add_u32 s2, s2, 0x100
	s_addc_u32 s3, s3, 0
	s_cmp_ge_i32 s45, s38
	s_mov_b32 s24, s45
	s_cbranch_scc0 .LBB0_835
	v_readlane_b32 s48, v254, 12
	v_readlane_b32 s46, v254, 16
	v_mov_b64_e32 v[154:155], v[158:159]
	v_readlane_b32 s49, v254, 13
	v_readlane_b32 s47, v254, 17
	v_mov_b64_e32 v[156:157], v[160:161]

; #define PG8_STAGE(bufoff, gbase, voff) do { _Pragma("unroll") for (int _i = 0; _i < 2; ++_i) \
;         __builtin_amdgcn_global_load_lds((const unsigned*)((const char*)(gbase) + (voff)[_i]), (LAS unsigned*)(lds + (bufoff) + ldsw + _i * 8192), 16, 0, 0); } while (0)
; #define PG8_LDA(dst, b, h) do { _Pragma("unroll") for (int m = 0; m < 4; ++m) _Pragma("unroll") for (int k = 0; k < 2; ++k) dst[m][k] = *(const LAS h16x8*)(lds + PG8_SA(b, h) + aoff + m * 2048 + k * 1024); } while (0)
; #define PG8_LDB(dst, b, h) do { _Pragma("unroll") for (int n = 0; n < 2; ++n) _Pragma("unroll") for (int k = 0; k < 2; ++k) dst[n][k] = *(const LAS h16x8*)(lds + PG8_SB(b, h) + boff + n * 2048 + k * 1024); } while (0)
; #define PG8_MMA(ai, bj, At, Bt) do { __builtin_amdgcn_s_setprio(1); _Pragma("unroll") for (int m = 0; m < 4; ++m) _Pragma("unroll") for (int n = 0; n < 2; ++n) _Pragma("unroll") for (int k = 0; k < 2; ++k) \
;         acc[ai][bj][m][n] = __builtin_amdgcn_mfma_f32_16x16x32_f16(Bt[n][k], At[m][k], acc[ai][bj][m][n], 0, 0, 0); __builtin_amdgcn_s_setprio(0); } while (0)
; #define PG8_WAIT_V(n) asm volatile("s_waitcnt vmcnt(" #n ")" ::: "memory")
; #define PG8_BAR __builtin_amdgcn_s_barrier()
; template <class Epi>
; __device__ __forceinline__ void gemm_phase(LAS unsigned char* lds, const Gemm g, const StaticOrder& S, const Epi& E, const int tid) {
;     ...
;         const char* nA = has_next ? (const char*)g.A + (size_t)nxt.pm * tstepA : cA; const char* nB = has_next ? (const char*)g.Bt + (size_t)nxt.pn * tstepB : cB;
;         for (int t = 0; t < nt; t += 2) {
;             const bool last = (t == nt - 2);
;             const char* a1 = cA + (size_t)(t + 1) * kstep;
;             const char* a2 = last ? nA : cA + (size_t)(t + 2) * kstep; const char* b2 = last ? nB : cB + (size_t)(t + 2) * kstep;
;             const char* a3 = a2 + kstep; const char* b3 = b2 + kstep;
;             PG8_LDB(B0, 0, 0); PG8_LDB(B1, 0, 1); PG8_SCHED; PG8_LDA(At, 0, 0); PG8_STAGE(PG8_SA(1, 1), a1 + hstepA, voffA);
;             PG8_WAIT_V(8); PG8_WAIT_L(0); PG8_BAR; PG8_MMA(0, 0, At, B0); PG8_MMA(0, 1, At, B1); PG8_BAR; PG8_SCHED;
;             PG8_LDA(At, 0, 1); PG8_STAGE(PG8_SB(0, 0), b2, voffB); PG8_STAGE(PG8_SB(0, 1), b2 + hstepB, voffB); PG8_STAGE(PG8_SA(0, 0), a2, voffA);
;             PG8_WAIT_V(8); PG8_WAIT_L(0); PG8_BAR; PG8_MMA(1, 0, At, B0); PG8_MMA(1, 1, At, B1); PG8_BAR; PG8_SCHED;
.LBB0_862:
	s_add_u32 s22, s20, 0xfffc0080
	s_addc_u32 s23, s21, -1
	s_add_i32 s31, 0, 0x10000
	s_cmp_eq_u32 s43, 12
	s_cselect_b32 s25, s15, s23
	s_cselect_b32 s24, s41, s22
	s_cselect_b32 s23, s11, s3
	s_cselect_b32 s22, s42, s2
	s_add_i32 s46, 0, 0x14000
	v_add_u32_e32 v140, s31, v195
	v_add_u32_e32 v166, s46, v195
	ds_read_b128 v[128:131], v140
	ds_read_b128 v[132:135], v140 offset:1024
	ds_read_b128 v[136:139], v140 offset:2048
	ds_read_b128 v[140:143], v140 offset:3072
	ds_read_b128 v[154:157], v166
	ds_read_b128 v[162:165], v166 offset:1024
	ds_read_b128 v[174:177], v166 offset:2048
	ds_read_b128 v[178:181], v166 offset:3072
	v_lshl_add_u64 v[166:167], s[20:21], 0, v[170:171]
	s_add_i32 m0, s27, 0xc000
	ds_read_b128 v[182:185], v211
	ds_read_b128 v[190:193], v211 offset:1024
	ds_read_b128 v[212:215], v211 offset:2048
	ds_read_b128 v[216:219], v211 offset:3072
	ds_read_b128 v[220:223], v211 offset:4096
	ds_read_b128 v[224:227], v211 offset:5120
	ds_read_b128 v[228:231], v211 offset:6144
	ds_read_b128 v[232:235], v211 offset:7168
	global_load_lds_dwordx4 v[166:167], off
	v_lshl_add_u64 v[166:167], s[20:21], 0, v[172:173]
	s_add_i32 m0, s27, 0xe000
	s_nop 0
	global_load_lds_dwordx4 v[166:167], off
	s_waitcnt vmcnt(8)
	s_waitcnt lgkmcnt(0)
	s_barrier
	s_waitcnt lgkmcnt(0)
	v_mfma_f32_16x16x32_f16 v[124:127], v[128:131], v[182:185], v[124:127]
	v_mfma_f32_16x16x32_f16 v[116:119], v[136:139], v[182:185], v[116:119]
	v_mfma_f32_16x16x32_f16 v[108:111], v[128:131], v[212:215], v[108:111]
	v_mfma_f32_16x16x32_f16 v[100:103], v[136:139], v[212:215], v[100:103]
	v_mfma_f32_16x16x32_f16 v[92:95], v[128:131], v[220:223], v[92:95]
	v_mfma_f32_16x16x32_f16 v[84:87], v[136:139], v[220:223], v[84:87]
	v_mfma_f32_16x16x32_f16 v[76:79], v[128:131], v[228:231], v[76:79]
	v_mfma_f32_16x16x32_f16 v[68:71], v[136:139], v[228:231], v[68:71]
	v_mfma_f32_16x16x32_f16 v[124:127], v[132:135], v[190:193], v[124:127]
	v_mfma_f32_16x16x32_f16 v[116:119], v[140:143], v[190:193], v[116:119]
	v_mfma_f32_16x16x32_f16 v[108:111], v[132:135], v[216:219], v[108:111]
	v_mfma_f32_16x16x32_f16 v[100:103], v[140:143], v[216:219], v[100:103]
	v_mfma_f32_16x16x32_f16 v[92:95], v[132:135], v[224:227], v[92:95]
	v_mfma_f32_16x16x32_f16 v[84:87], v[140:143], v[224:227], v[84:87]
	v_mfma_f32_16x16x32_f16 v[76:79], v[132:135], v[232:235], v[76:79]
	v_mfma_f32_16x16x32_f16 v[68:71], v[140:143], v[232:235], v[68:71]
	v_mfma_f32_16x16x32_f16 v[120:123], v[154:157], v[182:185], v[120:123]
	v_mfma_f32_16x16x32_f16 v[112:115], v[174:177], v[182:185], v[112:115]
	v_mfma_f32_16x16x32_f16 v[104:107], v[154:157], v[212:215], v[104:107]
	v_mfma_f32_16x16x32_f16 v[96:99], v[174:177], v[212:215], v[96:99]
	v_mfma_f32_16x16x32_f16 v[88:91], v[154:157], v[220:223], v[88:91]
	v_mfma_f32_16x16x32_f16 v[80:83], v[174:177], v[220:223], v[80:83]
	v_mfma_f32_16x16x32_f16 v[72:75], v[154:157], v[228:231], v[72:75]
	v_mfma_f32_16x16x32_f16 v[64:67], v[174:177], v[228:231], v[64:67]
	v_mfma_f32_16x16x32_f16 v[120:123], v[162:165], v[190:193], v[120:123]
	v_mfma_f32_16x16x32_f16 v[112:115], v[178:181], v[190:193], v[112:115]
	v_mfma_f32_16x16x32_f16 v[104:107], v[162:165], v[216:219], v[104:107]
	v_mfma_f32_16x16x32_f16 v[96:99], v[178:181], v[216:219], v[96:99]
	v_mfma_f32_16x16x32_f16 v[88:91], v[162:165], v[224:227], v[88:91]
	v_mfma_f32_16x16x32_f16 v[80:83], v[178:181], v[224:227], v[80:83]
	v_mfma_f32_16x16x32_f16 v[72:75], v[162:165], v[232:235], v[72:75]
	v_mfma_f32_16x16x32_f16 v[64:67], v[178:181], v[232:235], v[64:67]
	s_barrier
	s_add_i32 s31, s31, s26
	v_lshl_add_u64 v[166:167], s[22:23], 0, v[152:153]
	s_mov_b32 m0, s31
	ds_read_b128 v[182:185], v211 offset:16384
	ds_read_b128 v[190:193], v211 offset:17408
	ds_read_b128 v[212:215], v211 offset:18432
	ds_read_b128 v[216:219], v211 offset:19456
	ds_read_b128 v[220:223], v211 offset:20480
	ds_read_b128 v[224:227], v211 offset:21504
	ds_read_b128 v[228:231], v211 offset:22528
	ds_read_b128 v[232:235], v211 offset:23552
	global_load_lds_dwordx4 v[166:167], off
	s_add_i32 m0, s31, 0x2000
	s_add_u32 s44, s22, 0x40000
	v_lshl_add_u64 v[186:187], s[22:23], 0, v[144:145]
	s_addc_u32 s45, s23, 0
	s_add_i32 s31, s46, s26
	global_load_lds_dwordx4 v[186:187], off
	v_lshl_add_u64 v[204:205], s[44:45], 0, v[152:153]
	s_mov_b32 m0, s31
	v_lshl_add_u64 v[236:237], s[24:25], 0, v[146:147]
	global_load_lds_dwordx4 v[204:205], off
	v_lshl_add_u64 v[204:205], s[44:45], 0, v[144:145]
	s_add_i32 m0, s31, 0x2000
	s_nop 0
	global_load_lds_dwordx4 v[204:205], off
	v_lshl_add_u64 v[204:205], s[24:25], 0, v[148:149]
	s_mov_b32 m0, s27
	s_nop 0
	global_load_lds_dwordx4 v[204:205], off
	s_mov_b32 m0, s28
	s_nop 0
	global_load_lds_dwordx4 v[236:237], off
	s_waitcnt vmcnt(8)
	s_waitcnt lgkmcnt(0)
	s_barrier
; #define PG8_STAGE(bufoff, gbase, voff) do { _Pragma("unroll") for (int _i = 0; _i < 2; ++_i) \
;         __builtin_amdgcn_global_load_lds((const unsigned*)((const char*)(gbase) + (voff)[_i]), (LAS unsigned*)(lds + (bufoff) + ldsw + _i * 8192), 16, 0, 0); } while (0)
; #define PG8_LDA(dst, b, h) do { _Pragma("unroll") for (int m = 0; m < 4; ++m) _Pragma("unroll") for (int k = 0; k < 2; ++k) dst[m][k] = *(const LAS h16x8*)(lds + PG8_SA(b, h) + aoff + m * 2048 + k * 1024); } while (0)
; #define PG8_LDB(dst, b, h) do { _Pragma("unroll") for (int n = 0; n < 2; ++n) _Pragma("unroll") for (int k = 0; k < 2; ++k) dst[n][k] = *(const LAS h16x8*)(lds + PG8_SB(b, h) + boff + n * 2048 + k * 1024); } while (0)
; #define PG8_MMA(ai, bj, At, Bt) do { __builtin_amdgcn_s_setprio(1); _Pragma("unroll") for (int m = 0; m < 4; ++m) _Pragma("unroll") for (int n = 0; n < 2; ++n) _Pragma("unroll") for (int k = 0; k < 2; ++k) \
;         acc[ai][bj][m][n] = __builtin_amdgcn_mfma_f32_16x16x32_f16(Bt[n][k], At[m][k], acc[ai][bj][m][n], 0, 0, 0); __builtin_amdgcn_s_setprio(0); } while (0)
; #define PG8_WAIT_V(n) asm volatile("s_waitcnt vmcnt(" #n ")" ::: "memory")
; #define PG8_WAIT_L(n) asm volatile("s_waitcnt lgkmcnt(" #n ")" ::: "memory")
; #define PG8_BAR __builtin_amdgcn_s_barrier()
; #define PG8_SCHED __builtin_amdgcn_sched_barrier(0)
; template <class Epi>
; __device__ __forceinline__ void gemm_phase(LAS unsigned char* lds, const Gemm g, const StaticOrder& S, const Epi& E, const int tid) {
;     ...
;             PG8_WAIT_V(8); PG8_WAIT_L(0); PG8_BAR; PG8_MMA(1, 0, At, B0); PG8_MMA(1, 1, At, B1); PG8_BAR; PG8_SCHED;
;             PG8_LDB(B0, 1, 0); PG8_LDB(B1, 1, 1); PG8_SCHED; PG8_LDA(At, 1, 0); PG8_STAGE(PG8_SA(0, 1), a2 + hstepA, voffA);
;             PG8_WAIT_V(8); PG8_WAIT_L(0); PG8_BAR; PG8_MMA(0, 0, At, B0); PG8_MMA(0, 1, At, B1); PG8_BAR; PG8_SCHED;
;             PG8_LDA(At, 1, 1); PG8_STAGE(PG8_SB(1, 0), b3, voffB); PG8_STAGE(PG8_SB(1, 1), b3 + hstepB, voffB); PG8_STAGE(PG8_SA(1, 0), a3, voffA);
	s_waitcnt lgkmcnt(0)
	v_mfma_f32_16x16x32_f16 v[60:63], v[128:131], v[182:185], v[60:63]
	v_mfma_f32_16x16x32_f16 v[52:55], v[136:139], v[182:185], v[52:55]
	v_mfma_f32_16x16x32_f16 v[44:47], v[128:131], v[212:215], v[44:47]
	v_mfma_f32_16x16x32_f16 v[36:39], v[136:139], v[212:215], v[36:39]
	v_mfma_f32_16x16x32_f16 v[28:31], v[128:131], v[220:223], v[28:31]
	v_mfma_f32_16x16x32_f16 v[20:23], v[136:139], v[220:223], v[20:23]
	v_mfma_f32_16x16x32_f16 v[12:15], v[128:131], v[228:231], v[12:15]
	v_mfma_f32_16x16x32_f16 v[4:7], v[136:139], v[228:231], v[4:7]
	v_mfma_f32_16x16x32_f16 v[60:63], v[132:135], v[190:193], v[60:63]
	v_mfma_f32_16x16x32_f16 v[52:55], v[140:143], v[190:193], v[52:55]
	v_mfma_f32_16x16x32_f16 v[44:47], v[132:135], v[216:219], v[44:47]
	v_mfma_f32_16x16x32_f16 v[36:39], v[140:143], v[216:219], v[36:39]
	v_mfma_f32_16x16x32_f16 v[28:31], v[132:135], v[224:227], v[28:31]
	v_mfma_f32_16x16x32_f16 v[20:23], v[140:143], v[224:227], v[20:23]
	v_mfma_f32_16x16x32_f16 v[12:15], v[132:135], v[232:235], v[12:15]
	v_mfma_f32_16x16x32_f16 v[4:7], v[140:143], v[232:235], v[4:7]
	v_mfma_f32_16x16x32_f16 v[56:59], v[154:157], v[182:185], v[56:59]
	v_mfma_f32_16x16x32_f16 v[48:51], v[174:177], v[182:185], v[48:51]
	v_mfma_f32_16x16x32_f16 v[40:43], v[154:157], v[212:215], v[40:43]
	v_mfma_f32_16x16x32_f16 v[32:35], v[174:177], v[212:215], v[32:35]
	v_mfma_f32_16x16x32_f16 v[24:27], v[154:157], v[220:223], v[24:27]
	v_mfma_f32_16x16x32_f16 v[16:19], v[174:177], v[220:223], v[16:19]
	v_mfma_f32_16x16x32_f16 v[8:11], v[154:157], v[228:231], v[8:11]
	v_mfma_f32_16x16x32_f16 v[0:3], v[174:177], v[228:231], v[0:3]
	v_mfma_f32_16x16x32_f16 v[56:59], v[162:165], v[190:193], v[56:59]
	v_mfma_f32_16x16x32_f16 v[48:51], v[178:181], v[190:193], v[48:51]
	v_mfma_f32_16x16x32_f16 v[40:43], v[162:165], v[216:219], v[40:43]
	v_mfma_f32_16x16x32_f16 v[32:35], v[178:181], v[216:219], v[32:35]
	v_mfma_f32_16x16x32_f16 v[24:27], v[162:165], v[224:227], v[24:27]
	v_mfma_f32_16x16x32_f16 v[16:19], v[178:181], v[224:227], v[16:19]
	v_mfma_f32_16x16x32_f16 v[8:11], v[162:165], v[232:235], v[8:11]
	v_mfma_f32_16x16x32_f16 v[0:3], v[178:181], v[232:235], v[0:3]
	s_barrier
	s_add_i32 s31, 0, 0x18000
	s_add_i32 s44, 0, 0x1c000
	v_add_u32_e32 v140, s31, v195
	v_add_u32_e32 v178, s44, v195
	ds_read_b128 v[128:131], v140
	ds_read_b128 v[132:135], v140 offset:1024
	ds_read_b128 v[136:139], v140 offset:2048
	ds_read_b128 v[140:143], v140 offset:3072
	ds_read_b128 v[154:157], v178
	ds_read_b128 v[162:165], v178 offset:1024
	ds_read_b128 v[174:177], v178 offset:2048
	ds_read_b128 v[178:181], v178 offset:3072
	s_add_u32 s24, s24, 0x40000
	s_addc_u32 s25, s25, 0
	s_mov_b32 m0, s29
	v_lshl_add_u64 v[238:239], s[24:25], 0, v[148:149]
	ds_read_b128 v[182:185], v211 offset:32768
	ds_read_b128 v[190:193], v211 offset:33792
	ds_read_b128 v[212:215], v211 offset:34816
	ds_read_b128 v[216:219], v211 offset:35840
	ds_read_b128 v[220:223], v211 offset:36864
	ds_read_b128 v[224:227], v211 offset:37888
	ds_read_b128 v[228:231], v211 offset:38912
	ds_read_b128 v[232:235], v211 offset:39936
	global_load_lds_dwordx4 v[238:239], off
	v_lshl_add_u64 v[238:239], s[24:25], 0, v[146:147]
	s_mov_b32 m0, s35
	s_nop 0
	global_load_lds_dwordx4 v[238:239], off
	s_waitcnt vmcnt(8)
	s_waitcnt lgkmcnt(0)
	s_barrier
	s_waitcnt lgkmcnt(0)
	v_mfma_f32_16x16x32_f16 v[124:127], v[128:131], v[182:185], v[124:127]
	v_mfma_f32_16x16x32_f16 v[116:119], v[136:139], v[182:185], v[116:119]
	v_mfma_f32_16x16x32_f16 v[108:111], v[128:131], v[212:215], v[108:111]
	v_mfma_f32_16x16x32_f16 v[100:103], v[136:139], v[212:215], v[100:103]
	v_mfma_f32_16x16x32_f16 v[92:95], v[128:131], v[220:223], v[92:95]
	v_mfma_f32_16x16x32_f16 v[84:87], v[136:139], v[220:223], v[84:87]
	v_mfma_f32_16x16x32_f16 v[76:79], v[128:131], v[228:231], v[76:79]
	v_mfma_f32_16x16x32_f16 v[68:71], v[136:139], v[228:231], v[68:71]
	v_mfma_f32_16x16x32_f16 v[124:127], v[132:135], v[190:193], v[124:127]
	v_mfma_f32_16x16x32_f16 v[116:119], v[140:143], v[190:193], v[116:119]
	v_mfma_f32_16x16x32_f16 v[108:111], v[132:135], v[216:219], v[108:111]
	v_mfma_f32_16x16x32_f16 v[100:103], v[140:143], v[216:219], v[100:103]
	v_mfma_f32_16x16x32_f16 v[92:95], v[132:135], v[224:227], v[92:95]
	v_mfma_f32_16x16x32_f16 v[84:87], v[140:143], v[224:227], v[84:87]
	v_mfma_f32_16x16x32_f16 v[76:79], v[132:135], v[232:235], v[76:79]
	v_mfma_f32_16x16x32_f16 v[68:71], v[140:143], v[232:235], v[68:71]
	v_mfma_f32_16x16x32_f16 v[120:123], v[154:157], v[182:185], v[120:123]
	v_mfma_f32_16x16x32_f16 v[112:115], v[174:177], v[182:185], v[112:115]
	v_mfma_f32_16x16x32_f16 v[104:107], v[154:157], v[212:215], v[104:107]
	v_mfma_f32_16x16x32_f16 v[96:99], v[174:177], v[212:215], v[96:99]
	v_mfma_f32_16x16x32_f16 v[88:91], v[154:157], v[220:223], v[88:91]
	v_mfma_f32_16x16x32_f16 v[80:83], v[174:177], v[220:223], v[80:83]
	v_mfma_f32_16x16x32_f16 v[72:75], v[154:157], v[228:231], v[72:75]
	v_mfma_f32_16x16x32_f16 v[64:67], v[174:177], v[228:231], v[64:67]
	v_mfma_f32_16x16x32_f16 v[120:123], v[162:165], v[190:193], v[120:123]
	v_mfma_f32_16x16x32_f16 v[112:115], v[178:181], v[190:193], v[112:115]
	v_mfma_f32_16x16x32_f16 v[104:107], v[162:165], v[216:219], v[104:107]
	v_mfma_f32_16x16x32_f16 v[96:99], v[178:181], v[216:219], v[96:99]
	v_mfma_f32_16x16x32_f16 v[88:91], v[162:165], v[224:227], v[88:91]
	v_mfma_f32_16x16x32_f16 v[80:83], v[178:181], v[224:227], v[80:83]
	v_mfma_f32_16x16x32_f16 v[72:75], v[162:165], v[232:235], v[72:75]
	v_mfma_f32_16x16x32_f16 v[64:67], v[178:181], v[232:235], v[64:67]
	s_barrier
; #define PG8_STAGE(bufoff, gbase, voff) do { _Pragma("unroll") for (int _i = 0; _i < 2; ++_i) \
;         __builtin_amdgcn_global_load_lds((const unsigned*)((const char*)(gbase) + (voff)[_i]), (LAS unsigned*)(lds + (bufoff) + ldsw + _i * 8192), 16, 0, 0); } while (0)
; #define PG8_LDA(dst, b, h) do { _Pragma("unroll") for (int m = 0; m < 4; ++m) _Pragma("unroll") for (int k = 0; k < 2; ++k) dst[m][k] = *(const LAS h16x8*)(lds + PG8_SA(b, h) + aoff + m * 2048 + k * 1024); } while (0)
; #define PG8_MMA(ai, bj, At, Bt) do { __builtin_amdgcn_s_setprio(1); _Pragma("unroll") for (int m = 0; m < 4; ++m) _Pragma("unroll") for (int n = 0; n < 2; ++n) _Pragma("unroll") for (int k = 0; k < 2; ++k) \
;         acc[ai][bj][m][n] = __builtin_amdgcn_mfma_f32_16x16x32_f16(Bt[n][k], At[m][k], acc[ai][bj][m][n], 0, 0, 0); __builtin_amdgcn_s_setprio(0); } while (0)
; #define PG8_WAIT_V(n) asm volatile("s_waitcnt vmcnt(" #n ")" ::: "memory")
; #define PG8_WAIT_L(n) asm volatile("s_waitcnt lgkmcnt(" #n ")" ::: "memory")
; #define PG8_BAR __builtin_amdgcn_s_barrier()
; #define PG8_SCHED __builtin_amdgcn_sched_barrier(0)
; template <class Epi>
; __device__ __forceinline__ void gemm_phase(LAS unsigned char* lds, const Gemm g, const StaticOrder& S, const Epi& E, const int tid) {
;     ...
;             PG8_LDA(At, 1, 1); PG8_STAGE(PG8_SB(1, 0), b3, voffB); PG8_STAGE(PG8_SB(1, 1), b3 + hstepB, voffB); PG8_STAGE(PG8_SA(1, 0), a3, voffA);
;             PG8_WAIT_V(8); PG8_WAIT_L(0); PG8_BAR; PG8_MMA(1, 0, At, B0); PG8_MMA(1, 1, At, B1); PG8_BAR; PG8_SCHED;
;         }
;         if (wr == 0) PG8_BAR;
	s_add_i32 s24, s31, s26
	v_lshl_add_u64 v[166:167], v[166:167], 0, s[0:1]
	s_mov_b32 m0, s24
	ds_read_b128 v[182:185], v211 offset:49152
	ds_read_b128 v[190:193], v211 offset:50176
	ds_read_b128 v[212:215], v211 offset:51200
	ds_read_b128 v[216:219], v211 offset:52224
	ds_read_b128 v[220:223], v211 offset:53248
	ds_read_b128 v[224:227], v211 offset:54272
	ds_read_b128 v[228:231], v211 offset:55296
	ds_read_b128 v[232:235], v211 offset:56320
	global_load_lds_dwordx4 v[166:167], off
	s_add_i32 m0, s24, 0x2000
	s_add_u32 s22, s22, 0x40080
	v_lshl_add_u64 v[166:167], v[186:187], 0, s[0:1]
	s_addc_u32 s23, s23, 0
	s_add_i32 s24, s44, s26
	global_load_lds_dwordx4 v[166:167], off
	v_lshl_add_u64 v[166:167], s[22:23], 0, v[152:153]
	s_mov_b32 m0, s24
	s_nop 0
	global_load_lds_dwordx4 v[166:167], off
	v_lshl_add_u64 v[166:167], s[22:23], 0, v[144:145]
	s_add_i32 m0, s24, 0x2000
	s_nop 0
	global_load_lds_dwordx4 v[166:167], off
	v_lshl_add_u64 v[166:167], v[204:205], 0, s[0:1]
	s_mov_b32 m0, s36
	s_nop 0
	global_load_lds_dwordx4 v[166:167], off
	v_lshl_add_u64 v[166:167], v[236:237], 0, s[0:1]
	s_mov_b32 m0, s37
	s_nop 0
	global_load_lds_dwordx4 v[166:167], off
	s_waitcnt vmcnt(8)
	s_waitcnt lgkmcnt(0)
	s_barrier
	s_waitcnt lgkmcnt(0)
	v_mfma_f32_16x16x32_f16 v[60:63], v[128:131], v[182:185], v[60:63]
	v_mfma_f32_16x16x32_f16 v[52:55], v[136:139], v[182:185], v[52:55]
	v_mfma_f32_16x16x32_f16 v[44:47], v[128:131], v[212:215], v[44:47]
	v_mfma_f32_16x16x32_f16 v[36:39], v[136:139], v[212:215], v[36:39]
	v_mfma_f32_16x16x32_f16 v[28:31], v[128:131], v[220:223], v[28:31]
	v_mfma_f32_16x16x32_f16 v[20:23], v[136:139], v[220:223], v[20:23]
	v_mfma_f32_16x16x32_f16 v[12:15], v[128:131], v[228:231], v[12:15]
	v_mfma_f32_16x16x32_f16 v[4:7], v[136:139], v[228:231], v[4:7]
	v_mfma_f32_16x16x32_f16 v[60:63], v[132:135], v[190:193], v[60:63]
	v_mfma_f32_16x16x32_f16 v[52:55], v[140:143], v[190:193], v[52:55]
	v_mfma_f32_16x16x32_f16 v[44:47], v[132:135], v[216:219], v[44:47]
	v_mfma_f32_16x16x32_f16 v[36:39], v[140:143], v[216:219], v[36:39]
	v_mfma_f32_16x16x32_f16 v[28:31], v[132:135], v[224:227], v[28:31]
	v_mfma_f32_16x16x32_f16 v[20:23], v[140:143], v[224:227], v[20:23]
	v_mfma_f32_16x16x32_f16 v[12:15], v[132:135], v[232:235], v[12:15]
	v_mfma_f32_16x16x32_f16 v[4:7], v[140:143], v[232:235], v[4:7]
	v_mfma_f32_16x16x32_f16 v[56:59], v[154:157], v[182:185], v[56:59]
	v_mfma_f32_16x16x32_f16 v[48:51], v[174:177], v[182:185], v[48:51]
	v_mfma_f32_16x16x32_f16 v[40:43], v[154:157], v[212:215], v[40:43]
	v_mfma_f32_16x16x32_f16 v[32:35], v[174:177], v[212:215], v[32:35]
	v_mfma_f32_16x16x32_f16 v[24:27], v[154:157], v[220:223], v[24:27]
	v_mfma_f32_16x16x32_f16 v[16:19], v[174:177], v[220:223], v[16:19]
	v_mfma_f32_16x16x32_f16 v[8:11], v[154:157], v[228:231], v[8:11]
	v_mfma_f32_16x16x32_f16 v[0:3], v[174:177], v[228:231], v[0:3]
	v_mfma_f32_16x16x32_f16 v[56:59], v[162:165], v[190:193], v[56:59]
	v_mfma_f32_16x16x32_f16 v[48:51], v[178:181], v[190:193], v[48:51]
	v_mfma_f32_16x16x32_f16 v[40:43], v[162:165], v[216:219], v[40:43]
	v_mfma_f32_16x16x32_f16 v[32:35], v[178:181], v[216:219], v[32:35]
	v_mfma_f32_16x16x32_f16 v[24:27], v[162:165], v[224:227], v[24:27]
	v_mfma_f32_16x16x32_f16 v[16:19], v[178:181], v[224:227], v[16:19]
	v_mfma_f32_16x16x32_f16 v[8:11], v[162:165], v[232:235], v[8:11]
	v_mfma_f32_16x16x32_f16 v[0:3], v[178:181], v[232:235], v[0:3]
	s_barrier
	s_add_i32 s43, s43, 2
	s_add_u32 s20, s20, 0x100
	s_addc_u32 s21, s21, 0
	s_add_u32 s2, s2, 0x100
	s_addc_u32 s3, s3, 0
	s_cmp_gt_u32 s43, 13
	s_cbranch_scc0 .LBB0_862
	s_and_b64 vcc, exec, s[8:9]
	s_cbranch_vccz .LBB0_865
	s_barrier

; #define PG8_STAGE(bufoff, gbase, voff) do { _Pragma("unroll") for (int _i = 0; _i < 2; ++_i) \
;         __builtin_amdgcn_global_load_lds((const unsigned*)((const char*)(gbase) + (voff)[_i]), (LAS unsigned*)(lds + (bufoff) + ldsw + _i * 8192), 16, 0, 0); } while (0)
; #define PG8_LDA(dst, b, h) do { _Pragma("unroll") for (int m = 0; m < 4; ++m) _Pragma("unroll") for (int k = 0; k < 2; ++k) dst[m][k] = *(const LAS h16x8*)(lds + PG8_SA(b, h) + aoff + m * 2048 + k * 1024); } while (0)
; #define PG8_LDB(dst, b, h) do { _Pragma("unroll") for (int n = 0; n < 2; ++n) _Pragma("unroll") for (int k = 0; k < 2; ++k) dst[n][k] = *(const LAS h16x8*)(lds + PG8_SB(b, h) + boff + n * 2048 + k * 1024); } while (0)
; #define PG8_MMA(ai, bj, At, Bt) do { __builtin_amdgcn_s_setprio(1); _Pragma("unroll") for (int m = 0; m < 4; ++m) _Pragma("unroll") for (int n = 0; n < 2; ++n) _Pragma("unroll") for (int k = 0; k < 2; ++k) \
;         acc[ai][bj][m][n] = __builtin_amdgcn_mfma_f32_16x16x32_f16(Bt[n][k], At[m][k], acc[ai][bj][m][n], 0, 0, 0); __builtin_amdgcn_s_setprio(0); } while (0)
; #define PG8_WAIT_V(n) asm volatile("s_waitcnt vmcnt(" #n ")" ::: "memory")
; #define PG8_BAR __builtin_amdgcn_s_barrier()
; template <class Epi>
; __device__ __forceinline__ void gemm_phase(LAS unsigned char* lds, const Gemm g, const StaticOrder& S, const Epi& E, const int tid) {
;     ...
;         const char* nA = has_next ? (const char*)g.A + (size_t)nxt.pm * tstepA : cA; const char* nB = has_next ? (const char*)g.Bt + (size_t)nxt.pn * tstepB : cB;
;         for (int t = 0; t < nt; t += 2) {
;             const bool last = (t == nt - 2);
;             const char* a1 = cA + (size_t)(t + 1) * kstep;
;             const char* a2 = last ? nA : cA + (size_t)(t + 2) * kstep; const char* b2 = last ? nB : cB + (size_t)(t + 2) * kstep;
;             const char* a3 = a2 + kstep; const char* b3 = b2 + kstep;
;             PG8_LDB(B0, 0, 0); PG8_LDB(B1, 0, 1); PG8_SCHED; PG8_LDA(At, 0, 0); PG8_STAGE(PG8_SA(1, 1), a1 + hstepA, voffA);
;             PG8_WAIT_V(8); PG8_WAIT_L(0); PG8_BAR; PG8_MMA(0, 0, At, B0); PG8_MMA(0, 1, At, B1); PG8_BAR; PG8_SCHED;
;             PG8_LDA(At, 0, 1); PG8_STAGE(PG8_SB(0, 0), b2, voffB); PG8_STAGE(PG8_SB(0, 1), b2 + hstepB, voffB); PG8_STAGE(PG8_SA(0, 0), a2, voffA);
;             PG8_WAIT_V(8); PG8_WAIT_L(0); PG8_BAR; PG8_MMA(1, 0, At, B0); PG8_MMA(1, 1, At, B1); PG8_BAR; PG8_SCHED;
.LBB0_882:
	s_add_u32 s22, s4, 0xfffc0080
	s_addc_u32 s23, s5, -1
	s_add_i32 s31, 0, 0x10000
	s_cmp_eq_u32 s44, 12
	s_cselect_b32 s25, s17, s23
	s_cselect_b32 s24, s42, s22
	s_cselect_b32 s23, s15, s3
	s_cselect_b32 s22, s43, s2
	s_add_i32 s45, 0, 0x14000
	v_add_u32_e32 v148, s31, v198
	v_add_u32_e32 v166, s45, v198
	ds_read_b128 v[136:139], v148
	ds_read_b128 v[140:143], v148 offset:1024
	ds_read_b128 v[144:147], v148 offset:2048
	ds_read_b128 v[148:151], v148 offset:3072
	ds_read_b128 v[154:157], v166
	ds_read_b128 v[162:165], v166 offset:1024
	ds_read_b128 v[170:173], v166 offset:2048
	ds_read_b128 v[174:177], v166 offset:3072
	v_lshl_add_u64 v[166:167], s[4:5], 0, v[132:133]
	s_add_i32 m0, s27, 0xc000
	ds_read_b128 v[178:181], v212
	ds_read_b128 v[182:185], v212 offset:1024
	ds_read_b128 v[188:191], v212 offset:2048
	ds_read_b128 v[192:195], v212 offset:3072
	ds_read_b128 v[214:217], v212 offset:4096
	ds_read_b128 v[218:221], v212 offset:5120
	ds_read_b128 v[222:225], v212 offset:6144
	ds_read_b128 v[226:229], v212 offset:7168
	global_load_lds_dwordx4 v[166:167], off
	v_lshl_add_u64 v[166:167], s[4:5], 0, v[134:135]
	s_add_i32 m0, s27, 0xe000
	s_nop 0
	global_load_lds_dwordx4 v[166:167], off
	s_waitcnt vmcnt(8)
	s_waitcnt lgkmcnt(0)
	s_barrier
	s_waitcnt lgkmcnt(0)
	v_mfma_f32_16x16x32_f16 v[124:127], v[136:139], v[178:181], v[124:127]
	v_mfma_f32_16x16x32_f16 v[120:123], v[144:147], v[178:181], v[120:123]
	v_mfma_f32_16x16x32_f16 v[108:111], v[136:139], v[188:191], v[108:111]
	v_mfma_f32_16x16x32_f16 v[104:107], v[144:147], v[188:191], v[104:107]
	v_mfma_f32_16x16x32_f16 v[92:95], v[136:139], v[214:217], v[92:95]
	v_mfma_f32_16x16x32_f16 v[88:91], v[144:147], v[214:217], v[88:91]
	v_mfma_f32_16x16x32_f16 v[76:79], v[136:139], v[222:225], v[76:79]
	v_mfma_f32_16x16x32_f16 v[72:75], v[144:147], v[222:225], v[72:75]
	v_mfma_f32_16x16x32_f16 v[124:127], v[140:143], v[182:185], v[124:127]
	v_mfma_f32_16x16x32_f16 v[120:123], v[148:151], v[182:185], v[120:123]
	v_mfma_f32_16x16x32_f16 v[108:111], v[140:143], v[192:195], v[108:111]
	v_mfma_f32_16x16x32_f16 v[104:107], v[148:151], v[192:195], v[104:107]
	v_mfma_f32_16x16x32_f16 v[92:95], v[140:143], v[218:221], v[92:95]
	v_mfma_f32_16x16x32_f16 v[88:91], v[148:151], v[218:221], v[88:91]
	v_mfma_f32_16x16x32_f16 v[76:79], v[140:143], v[226:229], v[76:79]
	v_mfma_f32_16x16x32_f16 v[72:75], v[148:151], v[226:229], v[72:75]
	v_mfma_f32_16x16x32_f16 v[116:119], v[154:157], v[178:181], v[116:119]
	v_mfma_f32_16x16x32_f16 v[112:115], v[170:173], v[178:181], v[112:115]
	v_mfma_f32_16x16x32_f16 v[100:103], v[154:157], v[188:191], v[100:103]
	v_mfma_f32_16x16x32_f16 v[96:99], v[170:173], v[188:191], v[96:99]
	v_mfma_f32_16x16x32_f16 v[84:87], v[154:157], v[214:217], v[84:87]
	v_mfma_f32_16x16x32_f16 v[80:83], v[170:173], v[214:217], v[80:83]
	v_mfma_f32_16x16x32_f16 v[68:71], v[154:157], v[222:225], v[68:71]
	v_mfma_f32_16x16x32_f16 v[64:67], v[170:173], v[222:225], v[64:67]
	v_mfma_f32_16x16x32_f16 v[116:119], v[162:165], v[182:185], v[116:119]
	v_mfma_f32_16x16x32_f16 v[112:115], v[174:177], v[182:185], v[112:115]
	v_mfma_f32_16x16x32_f16 v[100:103], v[162:165], v[192:195], v[100:103]
	v_mfma_f32_16x16x32_f16 v[96:99], v[174:177], v[192:195], v[96:99]
	v_mfma_f32_16x16x32_f16 v[84:87], v[162:165], v[218:221], v[84:87]
	v_mfma_f32_16x16x32_f16 v[80:83], v[174:177], v[218:221], v[80:83]
	v_mfma_f32_16x16x32_f16 v[68:71], v[162:165], v[226:229], v[68:71]
	v_mfma_f32_16x16x32_f16 v[64:67], v[174:177], v[226:229], v[64:67]
	s_barrier
	s_add_i32 s31, s31, s26
	v_lshl_add_u64 v[166:167], s[22:23], 0, v[152:153]
	s_mov_b32 m0, s31
	ds_read_b128 v[178:181], v212 offset:16384
	ds_read_b128 v[182:185], v212 offset:17408
	ds_read_b128 v[188:191], v212 offset:18432
	ds_read_b128 v[192:195], v212 offset:19456
	ds_read_b128 v[214:217], v212 offset:20480
	ds_read_b128 v[218:221], v212 offset:21504
	ds_read_b128 v[222:225], v212 offset:22528
	ds_read_b128 v[226:229], v212 offset:23552
	global_load_lds_dwordx4 v[166:167], off
	s_add_i32 m0, s31, 0x2000
	s_add_u32 s46, s22, 0x40000
	v_lshl_add_u64 v[196:197], s[22:23], 0, v[128:129]
	s_addc_u32 s47, s23, 0
	s_add_i32 s31, s45, s26
	global_load_lds_dwordx4 v[196:197], off
	v_lshl_add_u64 v[204:205], s[46:47], 0, v[152:153]
	s_mov_b32 m0, s31
	v_lshl_add_u64 v[230:231], s[24:25], 0, v[128:129]
	global_load_lds_dwordx4 v[204:205], off
	v_lshl_add_u64 v[204:205], s[46:47], 0, v[128:129]
	s_add_i32 m0, s31, 0x2000
	s_nop 0
	global_load_lds_dwordx4 v[204:205], off
	v_lshl_add_u64 v[204:205], s[24:25], 0, v[152:153]
	s_mov_b32 m0, s27
	s_nop 0
	global_load_lds_dwordx4 v[204:205], off
	s_mov_b32 m0, s28
	s_nop 0
	global_load_lds_dwordx4 v[230:231], off
	s_waitcnt vmcnt(8)
	s_waitcnt lgkmcnt(0)
	s_barrier
; #define PG8_STAGE(bufoff, gbase, voff) do { _Pragma("unroll") for (int _i = 0; _i < 2; ++_i) \
;         __builtin_amdgcn_global_load_lds((const unsigned*)((const char*)(gbase) + (voff)[_i]), (LAS unsigned*)(lds + (bufoff) + ldsw + _i * 8192), 16, 0, 0); } while (0)
; #define PG8_LDA(dst, b, h) do { _Pragma("unroll") for (int m = 0; m < 4; ++m) _Pragma("unroll") for (int k = 0; k < 2; ++k) dst[m][k] = *(const LAS h16x8*)(lds + PG8_SA(b, h) + aoff + m * 2048 + k * 1024); } while (0)
; #define PG8_LDB(dst, b, h) do { _Pragma("unroll") for (int n = 0; n < 2; ++n) _Pragma("unroll") for (int k = 0; k < 2; ++k) dst[n][k] = *(const LAS h16x8*)(lds + PG8_SB(b, h) + boff + n * 2048 + k * 1024); } while (0)
; #define PG8_MMA(ai, bj, At, Bt) do { __builtin_amdgcn_s_setprio(1); _Pragma("unroll") for (int m = 0; m < 4; ++m) _Pragma("unroll") for (int n = 0; n < 2; ++n) _Pragma("unroll") for (int k = 0; k < 2; ++k) \
;         acc[ai][bj][m][n] = __builtin_amdgcn_mfma_f32_16x16x32_f16(Bt[n][k], At[m][k], acc[ai][bj][m][n], 0, 0, 0); __builtin_amdgcn_s_setprio(0); } while (0)
; #define PG8_WAIT_V(n) asm volatile("s_waitcnt vmcnt(" #n ")" ::: "memory")
; #define PG8_WAIT_L(n) asm volatile("s_waitcnt lgkmcnt(" #n ")" ::: "memory")
; #define PG8_BAR __builtin_amdgcn_s_barrier()
; #define PG8_SCHED __builtin_amdgcn_sched_barrier(0)
; template <class Epi>
; __device__ __forceinline__ void gemm_phase(LAS unsigned char* lds, const Gemm g, const StaticOrder& S, const Epi& E, const int tid) {
;     ...
;             PG8_WAIT_V(8); PG8_WAIT_L(0); PG8_BAR; PG8_MMA(1, 0, At, B0); PG8_MMA(1, 1, At, B1); PG8_BAR; PG8_SCHED;
;             PG8_LDB(B0, 1, 0); PG8_LDB(B1, 1, 1); PG8_SCHED; PG8_LDA(At, 1, 0); PG8_STAGE(PG8_SA(0, 1), a2 + hstepA, voffA);
;             PG8_WAIT_V(8); PG8_WAIT_L(0); PG8_BAR; PG8_MMA(0, 0, At, B0); PG8_MMA(0, 1, At, B1); PG8_BAR; PG8_SCHED;
;             PG8_LDA(At, 1, 1); PG8_STAGE(PG8_SB(1, 0), b3, voffB); PG8_STAGE(PG8_SB(1, 1), b3 + hstepB, voffB); PG8_STAGE(PG8_SA(1, 0), a3, voffA);
	s_waitcnt lgkmcnt(0)
	v_mfma_f32_16x16x32_f16 v[60:63], v[136:139], v[178:181], v[60:63]
	v_mfma_f32_16x16x32_f16 v[56:59], v[144:147], v[178:181], v[56:59]
	v_mfma_f32_16x16x32_f16 v[44:47], v[136:139], v[188:191], v[44:47]
	v_mfma_f32_16x16x32_f16 v[40:43], v[144:147], v[188:191], v[40:43]
	v_mfma_f32_16x16x32_f16 v[28:31], v[136:139], v[214:217], v[28:31]
	v_mfma_f32_16x16x32_f16 v[24:27], v[144:147], v[214:217], v[24:27]
	v_mfma_f32_16x16x32_f16 v[12:15], v[136:139], v[222:225], v[12:15]
	v_mfma_f32_16x16x32_f16 v[8:11], v[144:147], v[222:225], v[8:11]
	v_mfma_f32_16x16x32_f16 v[60:63], v[140:143], v[182:185], v[60:63]
	v_mfma_f32_16x16x32_f16 v[56:59], v[148:151], v[182:185], v[56:59]
	v_mfma_f32_16x16x32_f16 v[44:47], v[140:143], v[192:195], v[44:47]
	v_mfma_f32_16x16x32_f16 v[40:43], v[148:151], v[192:195], v[40:43]
	v_mfma_f32_16x16x32_f16 v[28:31], v[140:143], v[218:221], v[28:31]
	v_mfma_f32_16x16x32_f16 v[24:27], v[148:151], v[218:221], v[24:27]
	v_mfma_f32_16x16x32_f16 v[12:15], v[140:143], v[226:229], v[12:15]
	v_mfma_f32_16x16x32_f16 v[8:11], v[148:151], v[226:229], v[8:11]
	v_mfma_f32_16x16x32_f16 v[52:55], v[154:157], v[178:181], v[52:55]
	v_mfma_f32_16x16x32_f16 v[48:51], v[170:173], v[178:181], v[48:51]
	v_mfma_f32_16x16x32_f16 v[36:39], v[154:157], v[188:191], v[36:39]
	v_mfma_f32_16x16x32_f16 v[32:35], v[170:173], v[188:191], v[32:35]
	v_mfma_f32_16x16x32_f16 v[20:23], v[154:157], v[214:217], v[20:23]
	v_mfma_f32_16x16x32_f16 v[16:19], v[170:173], v[214:217], v[16:19]
	v_mfma_f32_16x16x32_f16 v[4:7], v[154:157], v[222:225], v[4:7]
	v_mfma_f32_16x16x32_f16 v[0:3], v[170:173], v[222:225], v[0:3]
	v_mfma_f32_16x16x32_f16 v[52:55], v[162:165], v[182:185], v[52:55]
	v_mfma_f32_16x16x32_f16 v[48:51], v[174:177], v[182:185], v[48:51]
	v_mfma_f32_16x16x32_f16 v[36:39], v[162:165], v[192:195], v[36:39]
	v_mfma_f32_16x16x32_f16 v[32:35], v[174:177], v[192:195], v[32:35]
	v_mfma_f32_16x16x32_f16 v[20:23], v[162:165], v[218:221], v[20:23]
	v_mfma_f32_16x16x32_f16 v[16:19], v[174:177], v[218:221], v[16:19]
	v_mfma_f32_16x16x32_f16 v[4:7], v[162:165], v[226:229], v[4:7]
	v_mfma_f32_16x16x32_f16 v[0:3], v[174:177], v[226:229], v[0:3]
	s_barrier
	s_add_i32 s31, 0, 0x18000
	s_add_i32 s45, 0, 0x1c000
	v_add_u32_e32 v148, s31, v198
	v_add_u32_e32 v174, s45, v198
	ds_read_b128 v[136:139], v148
	ds_read_b128 v[140:143], v148 offset:1024
	ds_read_b128 v[144:147], v148 offset:2048
	ds_read_b128 v[148:151], v148 offset:3072
	ds_read_b128 v[154:157], v174
	ds_read_b128 v[162:165], v174 offset:1024
	ds_read_b128 v[170:173], v174 offset:2048
	ds_read_b128 v[174:177], v174 offset:3072
	s_add_u32 s24, s24, 0x40000
	s_addc_u32 s25, s25, 0
	s_mov_b32 m0, s29
	v_lshl_add_u64 v[232:233], s[24:25], 0, v[152:153]
	ds_read_b128 v[178:181], v212 offset:32768
	ds_read_b128 v[182:185], v212 offset:33792
	ds_read_b128 v[188:191], v212 offset:34816
	ds_read_b128 v[192:195], v212 offset:35840
	ds_read_b128 v[214:217], v212 offset:36864
	ds_read_b128 v[218:221], v212 offset:37888
	ds_read_b128 v[222:225], v212 offset:38912
	ds_read_b128 v[226:229], v212 offset:39936
	global_load_lds_dwordx4 v[232:233], off
	v_lshl_add_u64 v[232:233], s[24:25], 0, v[128:129]
	s_mov_b32 m0, s35
	s_nop 0
	global_load_lds_dwordx4 v[232:233], off
	s_waitcnt vmcnt(8)
	s_waitcnt lgkmcnt(0)
	s_barrier
	s_waitcnt lgkmcnt(0)
	v_mfma_f32_16x16x32_f16 v[124:127], v[136:139], v[178:181], v[124:127]
	v_mfma_f32_16x16x32_f16 v[120:123], v[144:147], v[178:181], v[120:123]
	v_mfma_f32_16x16x32_f16 v[108:111], v[136:139], v[188:191], v[108:111]
	v_mfma_f32_16x16x32_f16 v[104:107], v[144:147], v[188:191], v[104:107]
	v_mfma_f32_16x16x32_f16 v[92:95], v[136:139], v[214:217], v[92:95]
	v_mfma_f32_16x16x32_f16 v[88:91], v[144:147], v[214:217], v[88:91]
	v_mfma_f32_16x16x32_f16 v[76:79], v[136:139], v[222:225], v[76:79]
	v_mfma_f32_16x16x32_f16 v[72:75], v[144:147], v[222:225], v[72:75]
	v_mfma_f32_16x16x32_f16 v[124:127], v[140:143], v[182:185], v[124:127]
	v_mfma_f32_16x16x32_f16 v[120:123], v[148:151], v[182:185], v[120:123]
	v_mfma_f32_16x16x32_f16 v[108:111], v[140:143], v[192:195], v[108:111]
	v_mfma_f32_16x16x32_f16 v[104:107], v[148:151], v[192:195], v[104:107]
	v_mfma_f32_16x16x32_f16 v[92:95], v[140:143], v[218:221], v[92:95]
	v_mfma_f32_16x16x32_f16 v[88:91], v[148:151], v[218:221], v[88:91]
	v_mfma_f32_16x16x32_f16 v[76:79], v[140:143], v[226:229], v[76:79]
	v_mfma_f32_16x16x32_f16 v[72:75], v[148:151], v[226:229], v[72:75]
	v_mfma_f32_16x16x32_f16 v[116:119], v[154:157], v[178:181], v[116:119]
	v_mfma_f32_16x16x32_f16 v[112:115], v[170:173], v[178:181], v[112:115]
	v_mfma_f32_16x16x32_f16 v[100:103], v[154:157], v[188:191], v[100:103]
	v_mfma_f32_16x16x32_f16 v[96:99], v[170:173], v[188:191], v[96:99]
	v_mfma_f32_16x16x32_f16 v[84:87], v[154:157], v[214:217], v[84:87]
	v_mfma_f32_16x16x32_f16 v[80:83], v[170:173], v[214:217], v[80:83]
	v_mfma_f32_16x16x32_f16 v[68:71], v[154:157], v[222:225], v[68:71]
	v_mfma_f32_16x16x32_f16 v[64:67], v[170:173], v[222:225], v[64:67]
	v_mfma_f32_16x16x32_f16 v[116:119], v[162:165], v[182:185], v[116:119]
	v_mfma_f32_16x16x32_f16 v[112:115], v[174:177], v[182:185], v[112:115]
	v_mfma_f32_16x16x32_f16 v[100:103], v[162:165], v[192:195], v[100:103]
	v_mfma_f32_16x16x32_f16 v[96:99], v[174:177], v[192:195], v[96:99]
	v_mfma_f32_16x16x32_f16 v[84:87], v[162:165], v[218:221], v[84:87]
	v_mfma_f32_16x16x32_f16 v[80:83], v[174:177], v[218:221], v[80:83]
	v_mfma_f32_16x16x32_f16 v[68:71], v[162:165], v[226:229], v[68:71]
	v_mfma_f32_16x16x32_f16 v[64:67], v[174:177], v[226:229], v[64:67]
	s_barrier
; #define PG8_STAGE(bufoff, gbase, voff) do { _Pragma("unroll") for (int _i = 0; _i < 2; ++_i) \
;         __builtin_amdgcn_global_load_lds((const unsigned*)((const char*)(gbase) + (voff)[_i]), (LAS unsigned*)(lds + (bufoff) + ldsw + _i * 8192), 16, 0, 0); } while (0)
; #define PG8_LDA(dst, b, h) do { _Pragma("unroll") for (int m = 0; m < 4; ++m) _Pragma("unroll") for (int k = 0; k < 2; ++k) dst[m][k] = *(const LAS h16x8*)(lds + PG8_SA(b, h) + aoff + m * 2048 + k * 1024); } while (0)
; #define PG8_MMA(ai, bj, At, Bt) do { __builtin_amdgcn_s_setprio(1); _Pragma("unroll") for (int m = 0; m < 4; ++m) _Pragma("unroll") for (int n = 0; n < 2; ++n) _Pragma("unroll") for (int k = 0; k < 2; ++k) \
;         acc[ai][bj][m][n] = __builtin_amdgcn_mfma_f32_16x16x32_f16(Bt[n][k], At[m][k], acc[ai][bj][m][n], 0, 0, 0); __builtin_amdgcn_s_setprio(0); } while (0)
; #define PG8_WAIT_V(n) asm volatile("s_waitcnt vmcnt(" #n ")" ::: "memory")
; #define PG8_WAIT_L(n) asm volatile("s_waitcnt lgkmcnt(" #n ")" ::: "memory")
; #define PG8_BAR __builtin_amdgcn_s_barrier()
; #define PG8_SCHED __builtin_amdgcn_sched_barrier(0)
; template <class Epi>
; __device__ __forceinline__ void gemm_phase(LAS unsigned char* lds, const Gemm g, const StaticOrder& S, const Epi& E, const int tid) {
;     ...
;             PG8_LDA(At, 1, 1); PG8_STAGE(PG8_SB(1, 0), b3, voffB); PG8_STAGE(PG8_SB(1, 1), b3 + hstepB, voffB); PG8_STAGE(PG8_SA(1, 0), a3, voffA);
;             PG8_WAIT_V(8); PG8_WAIT_L(0); PG8_BAR; PG8_MMA(1, 0, At, B0); PG8_MMA(1, 1, At, B1); PG8_BAR; PG8_SCHED;
;         }
;         if (wr == 0) PG8_BAR;
	s_add_i32 s24, s31, s26
	v_lshl_add_u64 v[166:167], v[166:167], 0, s[0:1]
	s_mov_b32 m0, s24
	ds_read_b128 v[178:181], v212 offset:49152
	ds_read_b128 v[182:185], v212 offset:50176
	ds_read_b128 v[188:191], v212 offset:51200
	ds_read_b128 v[192:195], v212 offset:52224
	ds_read_b128 v[214:217], v212 offset:53248
	ds_read_b128 v[218:221], v212 offset:54272
	ds_read_b128 v[222:225], v212 offset:55296
	ds_read_b128 v[226:229], v212 offset:56320
	global_load_lds_dwordx4 v[166:167], off
	s_add_i32 m0, s24, 0x2000
	s_add_u32 s22, s22, 0x40080
	v_lshl_add_u64 v[166:167], v[196:197], 0, s[0:1]
	s_addc_u32 s23, s23, 0
	s_add_i32 s24, s45, s26
	global_load_lds_dwordx4 v[166:167], off
	v_lshl_add_u64 v[166:167], s[22:23], 0, v[152:153]
	s_mov_b32 m0, s24
	s_nop 0
	global_load_lds_dwordx4 v[166:167], off
	v_lshl_add_u64 v[166:167], s[22:23], 0, v[128:129]
	s_add_i32 m0, s24, 0x2000
	s_nop 0
	global_load_lds_dwordx4 v[166:167], off
	v_lshl_add_u64 v[166:167], v[204:205], 0, s[0:1]
	s_mov_b32 m0, s36
	s_nop 0
	global_load_lds_dwordx4 v[166:167], off
	v_lshl_add_u64 v[166:167], v[230:231], 0, s[0:1]
	s_mov_b32 m0, s37
	s_nop 0
	global_load_lds_dwordx4 v[166:167], off
	s_waitcnt vmcnt(8)
	s_waitcnt lgkmcnt(0)
	s_barrier
	s_waitcnt lgkmcnt(0)
	v_mfma_f32_16x16x32_f16 v[60:63], v[136:139], v[178:181], v[60:63]
	v_mfma_f32_16x16x32_f16 v[56:59], v[144:147], v[178:181], v[56:59]
	v_mfma_f32_16x16x32_f16 v[44:47], v[136:139], v[188:191], v[44:47]
	v_mfma_f32_16x16x32_f16 v[40:43], v[144:147], v[188:191], v[40:43]
	v_mfma_f32_16x16x32_f16 v[28:31], v[136:139], v[214:217], v[28:31]
	v_mfma_f32_16x16x32_f16 v[24:27], v[144:147], v[214:217], v[24:27]
	v_mfma_f32_16x16x32_f16 v[12:15], v[136:139], v[222:225], v[12:15]
	v_mfma_f32_16x16x32_f16 v[8:11], v[144:147], v[222:225], v[8:11]
	v_mfma_f32_16x16x32_f16 v[60:63], v[140:143], v[182:185], v[60:63]
	v_mfma_f32_16x16x32_f16 v[56:59], v[148:151], v[182:185], v[56:59]
	v_mfma_f32_16x16x32_f16 v[44:47], v[140:143], v[192:195], v[44:47]
	v_mfma_f32_16x16x32_f16 v[40:43], v[148:151], v[192:195], v[40:43]
	v_mfma_f32_16x16x32_f16 v[28:31], v[140:143], v[218:221], v[28:31]
	v_mfma_f32_16x16x32_f16 v[24:27], v[148:151], v[218:221], v[24:27]
	v_mfma_f32_16x16x32_f16 v[12:15], v[140:143], v[226:229], v[12:15]
	v_mfma_f32_16x16x32_f16 v[8:11], v[148:151], v[226:229], v[8:11]
	v_mfma_f32_16x16x32_f16 v[52:55], v[154:157], v[178:181], v[52:55]
	v_mfma_f32_16x16x32_f16 v[48:51], v[170:173], v[178:181], v[48:51]
	v_mfma_f32_16x16x32_f16 v[36:39], v[154:157], v[188:191], v[36:39]
	v_mfma_f32_16x16x32_f16 v[32:35], v[170:173], v[188:191], v[32:35]
	v_mfma_f32_16x16x32_f16 v[20:23], v[154:157], v[214:217], v[20:23]
	v_mfma_f32_16x16x32_f16 v[16:19], v[170:173], v[214:217], v[16:19]
	v_mfma_f32_16x16x32_f16 v[4:7], v[154:157], v[222:225], v[4:7]
	v_mfma_f32_16x16x32_f16 v[0:3], v[170:173], v[222:225], v[0:3]
	v_mfma_f32_16x16x32_f16 v[52:55], v[162:165], v[182:185], v[52:55]
	v_mfma_f32_16x16x32_f16 v[48:51], v[174:177], v[182:185], v[48:51]
	v_mfma_f32_16x16x32_f16 v[36:39], v[162:165], v[192:195], v[36:39]
	v_mfma_f32_16x16x32_f16 v[32:35], v[174:177], v[192:195], v[32:35]
	v_mfma_f32_16x16x32_f16 v[20:23], v[162:165], v[218:221], v[20:23]
	v_mfma_f32_16x16x32_f16 v[16:19], v[174:177], v[218:221], v[16:19]
	v_mfma_f32_16x16x32_f16 v[4:7], v[162:165], v[226:229], v[4:7]
	v_mfma_f32_16x16x32_f16 v[0:3], v[174:177], v[226:229], v[0:3]
	s_barrier
	s_add_i32 s44, s44, 2
	s_add_u32 s4, s4, 0x100
	s_addc_u32 s5, s5, 0
	s_add_u32 s2, s2, 0x100
	s_addc_u32 s3, s3, 0
	s_cmp_gt_u32 s44, 13
	s_cbranch_scc0 .LBB0_882
	s_and_b64 vcc, exec, s[8:9]
	s_cbranch_vccz .LBB0_885
	s_barrier

; #define PG8_STAGE(bufoff, gbase, voff) do { _Pragma("unroll") for (int _i = 0; _i < 2; ++_i) \
;         __builtin_amdgcn_global_load_lds((const unsigned*)((const char*)(gbase) + (voff)[_i]), (LAS unsigned*)(lds + (bufoff) + ldsw + _i * 8192), 16, 0, 0); } while (0)
; #define PG8_LDA(dst, b, h) do { _Pragma("unroll") for (int m = 0; m < 4; ++m) _Pragma("unroll") for (int k = 0; k < 2; ++k) dst[m][k] = *(const LAS h16x8*)(lds + PG8_SA(b, h) + aoff + m * 2048 + k * 1024); } while (0)
; #define PG8_LDB(dst, b, h) do { _Pragma("unroll") for (int n = 0; n < 2; ++n) _Pragma("unroll") for (int k = 0; k < 2; ++k) dst[n][k] = *(const LAS h16x8*)(lds + PG8_SB(b, h) + boff + n * 2048 + k * 1024); } while (0)
; #define PG8_MMA(ai, bj, At, Bt) do { __builtin_amdgcn_s_setprio(1); _Pragma("unroll") for (int m = 0; m < 4; ++m) _Pragma("unroll") for (int n = 0; n < 2; ++n) _Pragma("unroll") for (int k = 0; k < 2; ++k) \
;         acc[ai][bj][m][n] = __builtin_amdgcn_mfma_f32_16x16x32_f16(Bt[n][k], At[m][k], acc[ai][bj][m][n], 0, 0, 0); __builtin_amdgcn_s_setprio(0); } while (0)
; #define PG8_WAIT_V(n) asm volatile("s_waitcnt vmcnt(" #n ")" ::: "memory")
; #define PG8_BAR __builtin_amdgcn_s_barrier()
; template <class Epi>
; __device__ __forceinline__ void gemm_phase(LAS unsigned char* lds, const Gemm g, const StaticOrder& S, const Epi& E, const int tid) {
;     ...
;         const char* nA = has_next ? (const char*)g.A + (size_t)nxt.pm * tstepA : cA; const char* nB = has_next ? (const char*)g.Bt + (size_t)nxt.pn * tstepB : cB;
;         for (int t = 0; t < nt; t += 2) {
;             const bool last = (t == nt - 2);
;             const char* a1 = cA + (size_t)(t + 1) * kstep;
;             const char* a2 = last ? nA : cA + (size_t)(t + 2) * kstep; const char* b2 = last ? nB : cB + (size_t)(t + 2) * kstep;
;             const char* a3 = a2 + kstep; const char* b3 = b2 + kstep;
;             PG8_LDB(B0, 0, 0); PG8_LDB(B1, 0, 1); PG8_SCHED; PG8_LDA(At, 0, 0); PG8_STAGE(PG8_SA(1, 1), a1 + hstepA, voffA);
;             PG8_WAIT_V(8); PG8_WAIT_L(0); PG8_BAR; PG8_MMA(0, 0, At, B0); PG8_MMA(0, 1, At, B1); PG8_BAR; PG8_SCHED;
;             PG8_LDA(At, 0, 1); PG8_STAGE(PG8_SB(0, 0), b2, voffB); PG8_STAGE(PG8_SB(0, 1), b2 + hstepB, voffB); PG8_STAGE(PG8_SA(0, 0), a2, voffA);
;             PG8_WAIT_V(8); PG8_WAIT_L(0); PG8_BAR; PG8_MMA(1, 0, At, B0); PG8_MMA(1, 1, At, B1); PG8_BAR; PG8_SCHED;
.LBB0_932:
	s_add_u32 s18, s16, 0x100
	s_addc_u32 s19, s17, 0
	s_add_i32 s31, 0, 0x10000
	s_cmp_eq_u32 s42, 40
	s_cselect_b32 s23, s11, s19
	s_cselect_b32 s22, s10, s18
	s_cselect_b32 s21, s15, s3
	s_cselect_b32 s20, s14, s2
	s_add_i32 s43, 0, 0x14000
	v_add_u32_e32 v140, s31, v189
	v_add_u32_e32 v162, s43, v189
	ds_read_b128 v[128:131], v140
	ds_read_b128 v[132:135], v140 offset:1024
	ds_read_b128 v[136:139], v140 offset:2048
	ds_read_b128 v[140:143], v140 offset:3072
	ds_read_b128 v[144:147], v162
	ds_read_b128 v[148:151], v162 offset:1024
	ds_read_b128 v[154:157], v162 offset:2048
	ds_read_b128 v[162:165], v162 offset:3072
	v_lshl_add_u64 v[166:167], s[16:17], 0, v[172:173]
	s_add_i32 m0, s25, 0xc000
	ds_read_b128 v[176:179], v191
	ds_read_b128 v[180:183], v191 offset:1024
	ds_read_b128 v[184:187], v191 offset:2048
	ds_read_b128 v[192:195], v191 offset:3072
	ds_read_b128 v[210:213], v191 offset:4096
	ds_read_b128 v[214:217], v191 offset:5120
	ds_read_b128 v[218:221], v191 offset:6144
	ds_read_b128 v[222:225], v191 offset:7168
	global_load_lds_dwordx4 v[166:167], off
	v_lshl_add_u64 v[166:167], s[16:17], 0, v[174:175]
	s_add_i32 m0, s25, 0xe000
	s_nop 0
	global_load_lds_dwordx4 v[166:167], off
	s_waitcnt vmcnt(8)
	s_waitcnt lgkmcnt(0)
	s_barrier
	s_waitcnt lgkmcnt(0)
	v_mfma_f32_16x16x32_f16 v[124:127], v[128:131], v[176:179], v[124:127]
	v_mfma_f32_16x16x32_f16 v[120:123], v[136:139], v[176:179], v[120:123]
	v_mfma_f32_16x16x32_f16 v[108:111], v[128:131], v[184:187], v[108:111]
	v_mfma_f32_16x16x32_f16 v[104:107], v[136:139], v[184:187], v[104:107]
	v_mfma_f32_16x16x32_f16 v[92:95], v[128:131], v[210:213], v[92:95]
	v_mfma_f32_16x16x32_f16 v[88:91], v[136:139], v[210:213], v[88:91]
	v_mfma_f32_16x16x32_f16 v[76:79], v[128:131], v[218:221], v[76:79]
	v_mfma_f32_16x16x32_f16 v[72:75], v[136:139], v[218:221], v[72:75]
	v_mfma_f32_16x16x32_f16 v[124:127], v[132:135], v[180:183], v[124:127]
	v_mfma_f32_16x16x32_f16 v[120:123], v[140:143], v[180:183], v[120:123]
	v_mfma_f32_16x16x32_f16 v[108:111], v[132:135], v[192:195], v[108:111]
	v_mfma_f32_16x16x32_f16 v[104:107], v[140:143], v[192:195], v[104:107]
	v_mfma_f32_16x16x32_f16 v[92:95], v[132:135], v[214:217], v[92:95]
	v_mfma_f32_16x16x32_f16 v[88:91], v[140:143], v[214:217], v[88:91]
	v_mfma_f32_16x16x32_f16 v[76:79], v[132:135], v[222:225], v[76:79]
	v_mfma_f32_16x16x32_f16 v[72:75], v[140:143], v[222:225], v[72:75]
	v_mfma_f32_16x16x32_f16 v[116:119], v[144:147], v[176:179], v[116:119]
	v_mfma_f32_16x16x32_f16 v[112:115], v[154:157], v[176:179], v[112:115]
	v_mfma_f32_16x16x32_f16 v[100:103], v[144:147], v[184:187], v[100:103]
	v_mfma_f32_16x16x32_f16 v[96:99], v[154:157], v[184:187], v[96:99]
	v_mfma_f32_16x16x32_f16 v[84:87], v[144:147], v[210:213], v[84:87]
	v_mfma_f32_16x16x32_f16 v[80:83], v[154:157], v[210:213], v[80:83]
	v_mfma_f32_16x16x32_f16 v[68:71], v[144:147], v[218:221], v[68:71]
	v_mfma_f32_16x16x32_f16 v[64:67], v[154:157], v[218:221], v[64:67]
	v_mfma_f32_16x16x32_f16 v[116:119], v[148:151], v[180:183], v[116:119]
	v_mfma_f32_16x16x32_f16 v[112:115], v[162:165], v[180:183], v[112:115]
	v_mfma_f32_16x16x32_f16 v[100:103], v[148:151], v[192:195], v[100:103]
	v_mfma_f32_16x16x32_f16 v[96:99], v[162:165], v[192:195], v[96:99]
	v_mfma_f32_16x16x32_f16 v[84:87], v[148:151], v[214:217], v[84:87]
	v_mfma_f32_16x16x32_f16 v[80:83], v[162:165], v[214:217], v[80:83]
	v_mfma_f32_16x16x32_f16 v[68:71], v[148:151], v[222:225], v[68:71]
	v_mfma_f32_16x16x32_f16 v[64:67], v[162:165], v[222:225], v[64:67]
	s_barrier
	s_add_i32 s16, s31, s24
	v_lshl_add_u64 v[166:167], s[20:21], 0, v[152:153]
	s_mov_b32 m0, s16
	ds_read_b128 v[176:179], v191 offset:16384
	ds_read_b128 v[180:183], v191 offset:17408
	ds_read_b128 v[184:187], v191 offset:18432
	ds_read_b128 v[192:195], v191 offset:19456
	ds_read_b128 v[210:213], v191 offset:20480
	ds_read_b128 v[214:217], v191 offset:21504
	ds_read_b128 v[218:221], v191 offset:22528
	ds_read_b128 v[222:225], v191 offset:23552
	global_load_lds_dwordx4 v[166:167], off
	s_add_i32 m0, s16, 0x2000
	s_add_u32 s16, s20, 0xb0000
	v_lshl_add_u64 v[196:197], s[20:21], 0, v[170:171]
	s_addc_u32 s17, s21, 0
	s_add_i32 s31, s43, s24
	global_load_lds_dwordx4 v[196:197], off
	v_lshl_add_u64 v[204:205], s[16:17], 0, v[152:153]
	s_mov_b32 m0, s31
	v_lshl_add_u64 v[226:227], s[22:23], 0, v[170:171]
	global_load_lds_dwordx4 v[204:205], off
	v_lshl_add_u64 v[204:205], s[16:17], 0, v[170:171]
	s_add_i32 m0, s31, 0x2000
	s_nop 0
	global_load_lds_dwordx4 v[204:205], off
	v_lshl_add_u64 v[204:205], s[22:23], 0, v[152:153]
	s_mov_b32 m0, s25
	s_nop 0
	global_load_lds_dwordx4 v[204:205], off
	s_mov_b32 m0, s26
	s_nop 0
	global_load_lds_dwordx4 v[226:227], off
	s_waitcnt vmcnt(8)
	s_waitcnt lgkmcnt(0)
	s_barrier
; #define PG8_STAGE(bufoff, gbase, voff) do { _Pragma("unroll") for (int _i = 0; _i < 2; ++_i) \
;         __builtin_amdgcn_global_load_lds((const unsigned*)((const char*)(gbase) + (voff)[_i]), (LAS unsigned*)(lds + (bufoff) + ldsw + _i * 8192), 16, 0, 0); } while (0)
; #define PG8_LDA(dst, b, h) do { _Pragma("unroll") for (int m = 0; m < 4; ++m) _Pragma("unroll") for (int k = 0; k < 2; ++k) dst[m][k] = *(const LAS h16x8*)(lds + PG8_SA(b, h) + aoff + m * 2048 + k * 1024); } while (0)
; #define PG8_LDB(dst, b, h) do { _Pragma("unroll") for (int n = 0; n < 2; ++n) _Pragma("unroll") for (int k = 0; k < 2; ++k) dst[n][k] = *(const LAS h16x8*)(lds + PG8_SB(b, h) + boff + n * 2048 + k * 1024); } while (0)
; #define PG8_MMA(ai, bj, At, Bt) do { __builtin_amdgcn_s_setprio(1); _Pragma("unroll") for (int m = 0; m < 4; ++m) _Pragma("unroll") for (int n = 0; n < 2; ++n) _Pragma("unroll") for (int k = 0; k < 2; ++k) \
;         acc[ai][bj][m][n] = __builtin_amdgcn_mfma_f32_16x16x32_f16(Bt[n][k], At[m][k], acc[ai][bj][m][n], 0, 0, 0); __builtin_amdgcn_s_setprio(0); } while (0)
; #define PG8_WAIT_V(n) asm volatile("s_waitcnt vmcnt(" #n ")" ::: "memory")
; #define PG8_WAIT_L(n) asm volatile("s_waitcnt lgkmcnt(" #n ")" ::: "memory")
; #define PG8_BAR __builtin_amdgcn_s_barrier()
; #define PG8_SCHED __builtin_amdgcn_sched_barrier(0)
; template <class Epi>
; __device__ __forceinline__ void gemm_phase(LAS unsigned char* lds, const Gemm g, const StaticOrder& S, const Epi& E, const int tid) {
;     ...
;             PG8_WAIT_V(8); PG8_WAIT_L(0); PG8_BAR; PG8_MMA(1, 0, At, B0); PG8_MMA(1, 1, At, B1); PG8_BAR; PG8_SCHED;
;             PG8_LDB(B0, 1, 0); PG8_LDB(B1, 1, 1); PG8_SCHED; PG8_LDA(At, 1, 0); PG8_STAGE(PG8_SA(0, 1), a2 + hstepA, voffA);
;             PG8_WAIT_V(8); PG8_WAIT_L(0); PG8_BAR; PG8_MMA(0, 0, At, B0); PG8_MMA(0, 1, At, B1); PG8_BAR; PG8_SCHED;
	s_waitcnt lgkmcnt(0)
	v_mfma_f32_16x16x32_f16 v[60:63], v[128:131], v[176:179], v[60:63]
	v_mfma_f32_16x16x32_f16 v[56:59], v[136:139], v[176:179], v[56:59]
	v_mfma_f32_16x16x32_f16 v[44:47], v[128:131], v[184:187], v[44:47]
	v_mfma_f32_16x16x32_f16 v[40:43], v[136:139], v[184:187], v[40:43]
	v_mfma_f32_16x16x32_f16 v[28:31], v[128:131], v[210:213], v[28:31]
	v_mfma_f32_16x16x32_f16 v[24:27], v[136:139], v[210:213], v[24:27]
	v_mfma_f32_16x16x32_f16 v[12:15], v[128:131], v[218:221], v[12:15]
	v_mfma_f32_16x16x32_f16 v[8:11], v[136:139], v[218:221], v[8:11]
	v_mfma_f32_16x16x32_f16 v[60:63], v[132:135], v[180:183], v[60:63]
	v_mfma_f32_16x16x32_f16 v[56:59], v[140:143], v[180:183], v[56:59]
	v_mfma_f32_16x16x32_f16 v[44:47], v[132:135], v[192:195], v[44:47]
	v_mfma_f32_16x16x32_f16 v[40:43], v[140:143], v[192:195], v[40:43]
	v_mfma_f32_16x16x32_f16 v[28:31], v[132:135], v[214:217], v[28:31]
	v_mfma_f32_16x16x32_f16 v[24:27], v[140:143], v[214:217], v[24:27]
	v_mfma_f32_16x16x32_f16 v[12:15], v[132:135], v[222:225], v[12:15]
	v_mfma_f32_16x16x32_f16 v[8:11], v[140:143], v[222:225], v[8:11]
	v_mfma_f32_16x16x32_f16 v[52:55], v[144:147], v[176:179], v[52:55]
	v_mfma_f32_16x16x32_f16 v[48:51], v[154:157], v[176:179], v[48:51]
	v_mfma_f32_16x16x32_f16 v[36:39], v[144:147], v[184:187], v[36:39]
	v_mfma_f32_16x16x32_f16 v[32:35], v[154:157], v[184:187], v[32:35]
	v_mfma_f32_16x16x32_f16 v[20:23], v[144:147], v[210:213], v[20:23]
	v_mfma_f32_16x16x32_f16 v[16:19], v[154:157], v[210:213], v[16:19]
	v_mfma_f32_16x16x32_f16 v[4:7], v[144:147], v[218:221], v[4:7]
	v_mfma_f32_16x16x32_f16 v[0:3], v[154:157], v[218:221], v[0:3]
	v_mfma_f32_16x16x32_f16 v[52:55], v[148:151], v[180:183], v[52:55]
	v_mfma_f32_16x16x32_f16 v[48:51], v[162:165], v[180:183], v[48:51]
	v_mfma_f32_16x16x32_f16 v[36:39], v[148:151], v[192:195], v[36:39]
	v_mfma_f32_16x16x32_f16 v[32:35], v[162:165], v[192:195], v[32:35]
	v_mfma_f32_16x16x32_f16 v[20:23], v[148:151], v[214:217], v[20:23]
	v_mfma_f32_16x16x32_f16 v[16:19], v[162:165], v[214:217], v[16:19]
	v_mfma_f32_16x16x32_f16 v[4:7], v[148:151], v[222:225], v[4:7]
	v_mfma_f32_16x16x32_f16 v[0:3], v[162:165], v[222:225], v[0:3]
	s_barrier
	s_add_i32 s31, 0, 0x18000
	s_add_i32 s43, 0, 0x1c000
	v_add_u32_e32 v140, s31, v189
	v_add_u32_e32 v162, s43, v189
	ds_read_b128 v[128:131], v140
	ds_read_b128 v[132:135], v140 offset:1024
	ds_read_b128 v[136:139], v140 offset:2048
	ds_read_b128 v[140:143], v140 offset:3072
	ds_read_b128 v[144:147], v162
	ds_read_b128 v[148:151], v162 offset:1024
	ds_read_b128 v[154:157], v162 offset:2048
	ds_read_b128 v[162:165], v162 offset:3072
	s_add_u32 s16, s22, 0xb0000
	s_addc_u32 s17, s23, 0
	s_mov_b32 m0, s27
	v_lshl_add_u64 v[228:229], s[16:17], 0, v[152:153]
	ds_read_b128 v[176:179], v191 offset:32768
	ds_read_b128 v[180:183], v191 offset:33792
	ds_read_b128 v[184:187], v191 offset:34816
	ds_read_b128 v[192:195], v191 offset:35840
	ds_read_b128 v[210:213], v191 offset:36864
	ds_read_b128 v[214:217], v191 offset:37888
	ds_read_b128 v[218:221], v191 offset:38912
	ds_read_b128 v[222:225], v191 offset:39936
	global_load_lds_dwordx4 v[228:229], off
	v_lshl_add_u64 v[228:229], s[16:17], 0, v[170:171]
	s_mov_b32 m0, s28
	s_nop 0
	global_load_lds_dwordx4 v[228:229], off
	s_waitcnt vmcnt(8)
	s_waitcnt lgkmcnt(0)
	s_barrier
	s_waitcnt lgkmcnt(0)
	v_mfma_f32_16x16x32_f16 v[124:127], v[128:131], v[176:179], v[124:127]
	v_mfma_f32_16x16x32_f16 v[120:123], v[136:139], v[176:179], v[120:123]
	v_mfma_f32_16x16x32_f16 v[108:111], v[128:131], v[184:187], v[108:111]
	v_mfma_f32_16x16x32_f16 v[104:107], v[136:139], v[184:187], v[104:107]
	v_mfma_f32_16x16x32_f16 v[92:95], v[128:131], v[210:213], v[92:95]
	v_mfma_f32_16x16x32_f16 v[88:91], v[136:139], v[210:213], v[88:91]
	v_mfma_f32_16x16x32_f16 v[76:79], v[128:131], v[218:221], v[76:79]
	v_mfma_f32_16x16x32_f16 v[72:75], v[136:139], v[218:221], v[72:75]
	v_mfma_f32_16x16x32_f16 v[124:127], v[132:135], v[180:183], v[124:127]
	v_mfma_f32_16x16x32_f16 v[120:123], v[140:143], v[180:183], v[120:123]
	v_mfma_f32_16x16x32_f16 v[108:111], v[132:135], v[192:195], v[108:111]
	v_mfma_f32_16x16x32_f16 v[104:107], v[140:143], v[192:195], v[104:107]
	v_mfma_f32_16x16x32_f16 v[92:95], v[132:135], v[214:217], v[92:95]
	v_mfma_f32_16x16x32_f16 v[88:91], v[140:143], v[214:217], v[88:91]
	v_mfma_f32_16x16x32_f16 v[76:79], v[132:135], v[222:225], v[76:79]
	v_mfma_f32_16x16x32_f16 v[72:75], v[140:143], v[222:225], v[72:75]
	v_mfma_f32_16x16x32_f16 v[116:119], v[144:147], v[176:179], v[116:119]
	v_mfma_f32_16x16x32_f16 v[112:115], v[154:157], v[176:179], v[112:115]
	v_mfma_f32_16x16x32_f16 v[100:103], v[144:147], v[184:187], v[100:103]
	v_mfma_f32_16x16x32_f16 v[96:99], v[154:157], v[184:187], v[96:99]
	v_mfma_f32_16x16x32_f16 v[84:87], v[144:147], v[210:213], v[84:87]
	v_mfma_f32_16x16x32_f16 v[80:83], v[154:157], v[210:213], v[80:83]
	v_mfma_f32_16x16x32_f16 v[68:71], v[144:147], v[218:221], v[68:71]
	v_mfma_f32_16x16x32_f16 v[64:67], v[154:157], v[218:221], v[64:67]
	v_mfma_f32_16x16x32_f16 v[116:119], v[148:151], v[180:183], v[116:119]
	v_mfma_f32_16x16x32_f16 v[112:115], v[162:165], v[180:183], v[112:115]
	v_mfma_f32_16x16x32_f16 v[100:103], v[148:151], v[192:195], v[100:103]
	v_mfma_f32_16x16x32_f16 v[96:99], v[162:165], v[192:195], v[96:99]
	v_mfma_f32_16x16x32_f16 v[84:87], v[148:151], v[214:217], v[84:87]
	v_mfma_f32_16x16x32_f16 v[80:83], v[162:165], v[214:217], v[80:83]
	v_mfma_f32_16x16x32_f16 v[68:71], v[148:151], v[222:225], v[68:71]
	v_mfma_f32_16x16x32_f16 v[64:67], v[162:165], v[222:225], v[64:67]
	s_barrier
; #define PG8_STAGE(bufoff, gbase, voff) do { _Pragma("unroll") for (int _i = 0; _i < 2; ++_i) \
;         __builtin_amdgcn_global_load_lds((const unsigned*)((const char*)(gbase) + (voff)[_i]), (LAS unsigned*)(lds + (bufoff) + ldsw + _i * 8192), 16, 0, 0); } while (0)
; #define PG8_LDA(dst, b, h) do { _Pragma("unroll") for (int m = 0; m < 4; ++m) _Pragma("unroll") for (int k = 0; k < 2; ++k) dst[m][k] = *(const LAS h16x8*)(lds + PG8_SA(b, h) + aoff + m * 2048 + k * 1024); } while (0)
; #define PG8_MMA(ai, bj, At, Bt) do { __builtin_amdgcn_s_setprio(1); _Pragma("unroll") for (int m = 0; m < 4; ++m) _Pragma("unroll") for (int n = 0; n < 2; ++n) _Pragma("unroll") for (int k = 0; k < 2; ++k) \
;         acc[ai][bj][m][n] = __builtin_amdgcn_mfma_f32_16x16x32_f16(Bt[n][k], At[m][k], acc[ai][bj][m][n], 0, 0, 0); __builtin_amdgcn_s_setprio(0); } while (0)
; #define PG8_WAIT_V(n) asm volatile("s_waitcnt vmcnt(" #n ")" ::: "memory")
; #define PG8_WAIT_L(n) asm volatile("s_waitcnt lgkmcnt(" #n ")" ::: "memory")
; #define PG8_BAR __builtin_amdgcn_s_barrier()
; #define PG8_SCHED __builtin_amdgcn_sched_barrier(0)
; template <class Epi>
; __device__ __forceinline__ void gemm_phase(LAS unsigned char* lds, const Gemm g, const StaticOrder& S, const Epi& E, const int tid) {
;     ...
;             PG8_LDA(At, 1, 1); PG8_STAGE(PG8_SB(1, 0), b3, voffB); PG8_STAGE(PG8_SB(1, 1), b3 + hstepB, voffB); PG8_STAGE(PG8_SA(1, 0), a3, voffA);
;             PG8_WAIT_V(8); PG8_WAIT_L(0); PG8_BAR; PG8_MMA(1, 0, At, B0); PG8_MMA(1, 1, At, B1); PG8_BAR; PG8_SCHED;
;         }
	s_add_i32 s16, s31, s24
	v_lshl_add_u64 v[166:167], v[166:167], 0, s[0:1]
	s_mov_b32 m0, s16
	ds_read_b128 v[176:179], v191 offset:49152
	ds_read_b128 v[180:183], v191 offset:50176
	ds_read_b128 v[184:187], v191 offset:51200
	ds_read_b128 v[192:195], v191 offset:52224
	ds_read_b128 v[210:213], v191 offset:53248
	ds_read_b128 v[214:217], v191 offset:54272
	ds_read_b128 v[218:221], v191 offset:55296
	ds_read_b128 v[222:225], v191 offset:56320
	global_load_lds_dwordx4 v[166:167], off
	s_add_i32 m0, s16, 0x2000
	s_add_u32 s16, s20, 0xb0080
	v_lshl_add_u64 v[166:167], v[196:197], 0, s[0:1]
	s_addc_u32 s17, s21, 0
	s_add_i32 s20, s43, s24
	global_load_lds_dwordx4 v[166:167], off
	v_lshl_add_u64 v[166:167], s[16:17], 0, v[152:153]
	s_mov_b32 m0, s20
	s_nop 0
	global_load_lds_dwordx4 v[166:167], off
	v_lshl_add_u64 v[166:167], s[16:17], 0, v[170:171]
	s_add_i32 m0, s20, 0x2000
	s_nop 0
	global_load_lds_dwordx4 v[166:167], off
	v_lshl_add_u64 v[166:167], v[204:205], 0, s[0:1]
	s_mov_b32 m0, s29
	s_nop 0
	global_load_lds_dwordx4 v[166:167], off
	v_lshl_add_u64 v[166:167], v[226:227], 0, s[0:1]
	s_mov_b32 m0, s35
	s_nop 0
	global_load_lds_dwordx4 v[166:167], off
	s_waitcnt vmcnt(8)
	s_waitcnt lgkmcnt(0)
	s_barrier
	s_waitcnt lgkmcnt(0)
	v_mfma_f32_16x16x32_f16 v[60:63], v[128:131], v[176:179], v[60:63]
	v_mfma_f32_16x16x32_f16 v[56:59], v[136:139], v[176:179], v[56:59]
	v_mfma_f32_16x16x32_f16 v[44:47], v[128:131], v[184:187], v[44:47]
	v_mfma_f32_16x16x32_f16 v[40:43], v[136:139], v[184:187], v[40:43]
	v_mfma_f32_16x16x32_f16 v[28:31], v[128:131], v[210:213], v[28:31]
	v_mfma_f32_16x16x32_f16 v[24:27], v[136:139], v[210:213], v[24:27]
	v_mfma_f32_16x16x32_f16 v[12:15], v[128:131], v[218:221], v[12:15]
	v_mfma_f32_16x16x32_f16 v[8:11], v[136:139], v[218:221], v[8:11]
	v_mfma_f32_16x16x32_f16 v[60:63], v[132:135], v[180:183], v[60:63]
	v_mfma_f32_16x16x32_f16 v[56:59], v[140:143], v[180:183], v[56:59]
	v_mfma_f32_16x16x32_f16 v[44:47], v[132:135], v[192:195], v[44:47]
	v_mfma_f32_16x16x32_f16 v[40:43], v[140:143], v[192:195], v[40:43]
	v_mfma_f32_16x16x32_f16 v[28:31], v[132:135], v[214:217], v[28:31]
	v_mfma_f32_16x16x32_f16 v[24:27], v[140:143], v[214:217], v[24:27]
	v_mfma_f32_16x16x32_f16 v[12:15], v[132:135], v[222:225], v[12:15]
	v_mfma_f32_16x16x32_f16 v[8:11], v[140:143], v[222:225], v[8:11]
	v_mfma_f32_16x16x32_f16 v[52:55], v[144:147], v[176:179], v[52:55]
	v_mfma_f32_16x16x32_f16 v[48:51], v[154:157], v[176:179], v[48:51]
	v_mfma_f32_16x16x32_f16 v[36:39], v[144:147], v[184:187], v[36:39]
	v_mfma_f32_16x16x32_f16 v[32:35], v[154:157], v[184:187], v[32:35]
	v_mfma_f32_16x16x32_f16 v[20:23], v[144:147], v[210:213], v[20:23]
	v_mfma_f32_16x16x32_f16 v[16:19], v[154:157], v[210:213], v[16:19]
	v_mfma_f32_16x16x32_f16 v[4:7], v[144:147], v[218:221], v[4:7]
	v_mfma_f32_16x16x32_f16 v[0:3], v[154:157], v[218:221], v[0:3]
	v_mfma_f32_16x16x32_f16 v[52:55], v[148:151], v[180:183], v[52:55]
	v_mfma_f32_16x16x32_f16 v[48:51], v[162:165], v[180:183], v[48:51]
	v_mfma_f32_16x16x32_f16 v[36:39], v[148:151], v[192:195], v[36:39]
	v_mfma_f32_16x16x32_f16 v[32:35], v[162:165], v[192:195], v[32:35]
	v_mfma_f32_16x16x32_f16 v[20:23], v[148:151], v[214:217], v[20:23]
	v_mfma_f32_16x16x32_f16 v[16:19], v[162:165], v[214:217], v[16:19]
	v_mfma_f32_16x16x32_f16 v[4:7], v[148:151], v[222:225], v[4:7]
	v_mfma_f32_16x16x32_f16 v[0:3], v[162:165], v[222:225], v[0:3]
	s_barrier
	s_add_i32 s42, s42, 2
	s_add_u32 s2, s2, 0x100
	s_addc_u32 s3, s3, 0
	s_cmp_gt_u32 s42, 41
	s_mov_b64 s[16:17], s[18:19]
	s_cbranch_scc0 .LBB0_932
	s_and_b64 vcc, exec, s[12:13]
	s_cbranch_vccz .LBB0_935
	s_barrier

; #define PG8_STAGE(bufoff, gbase, voff) do { _Pragma("unroll") for (int _i = 0; _i < 2; ++_i) \
;         __builtin_amdgcn_global_load_lds((const unsigned*)((const char*)(gbase) + (voff)[_i]), (LAS unsigned*)(lds + (bufoff) + ldsw + _i * 8192), 16, 0, 0); } while (0)
; #define PG8_LDA(dst, b, h) do { _Pragma("unroll") for (int m = 0; m < 4; ++m) _Pragma("unroll") for (int k = 0; k < 2; ++k) dst[m][k] = *(const LAS h16x8*)(lds + PG8_SA(b, h) + aoff + m * 2048 + k * 1024); } while (0)
; #define PG8_LDB(dst, b, h) do { _Pragma("unroll") for (int n = 0; n < 2; ++n) _Pragma("unroll") for (int k = 0; k < 2; ++k) dst[n][k] = *(const LAS h16x8*)(lds + PG8_SB(b, h) + boff + n * 2048 + k * 1024); } while (0)
; #define PG8_MMA(ai, bj, At, Bt) do { __builtin_amdgcn_s_setprio(1); _Pragma("unroll") for (int m = 0; m < 4; ++m) _Pragma("unroll") for (int n = 0; n < 2; ++n) _Pragma("unroll") for (int k = 0; k < 2; ++k) \
;         acc[ai][bj][m][n] = __builtin_amdgcn_mfma_f32_16x16x32_f16(Bt[n][k], At[m][k], acc[ai][bj][m][n], 0, 0, 0); __builtin_amdgcn_s_setprio(0); } while (0)
; #define PG8_WAIT_V(n) asm volatile("s_waitcnt vmcnt(" #n ")" ::: "memory")
; #define PG8_WAIT_L(n) asm volatile("s_waitcnt lgkmcnt(" #n ")" ::: "memory")
; #define PG8_BAR __builtin_amdgcn_s_barrier()
; template <class Epi>
; __device__ __forceinline__ void gemm_phase(LAS unsigned char* lds, const Gemm g, const StaticOrder& S, const Epi& E, const int tid) {
;     ...
;         const char* nA = has_next ? (const char*)g.A + (size_t)nxt.pm * tstepA : cA; const char* nB = has_next ? (const char*)g.Bt + (size_t)nxt.pn * tstepB : cB;
;         for (int t = 0; t < nt; t += 2) {
;             const bool last = (t == nt - 2);
;             const char* a1 = cA + (size_t)(t + 1) * kstep;
;             const char* a2 = last ? nA : cA + (size_t)(t + 2) * kstep; const char* b2 = last ? nB : cB + (size_t)(t + 2) * kstep;
;             const char* a3 = a2 + kstep; const char* b3 = b2 + kstep;
;             PG8_LDB(B0, 0, 0); PG8_LDB(B1, 0, 1); PG8_SCHED; PG8_LDA(At, 0, 0); PG8_STAGE(PG8_SA(1, 1), a1 + hstepA, voffA);
;             PG8_WAIT_V(8); PG8_WAIT_L(0); PG8_BAR; PG8_MMA(0, 0, At, B0); PG8_MMA(0, 1, At, B1); PG8_BAR; PG8_SCHED;
;             PG8_LDA(At, 0, 1); PG8_STAGE(PG8_SB(0, 0), b2, voffB); PG8_STAGE(PG8_SB(0, 1), b2 + hstepB, voffB); PG8_STAGE(PG8_SA(0, 0), a2, voffA);
.LBB0_986:
	s_add_i32 s43, s22, 2
	s_add_u32 s31, s20, 0x80
	s_addc_u32 s23, s21, 0
	s_add_i32 s46, 0, 0x10000
	s_cmp_eq_u32 s37, s22
	s_cselect_b32 s23, s9, s23
	s_cselect_b32 s22, s8, s31
	v_add_u32_e32 v150, s46, v139
	s_cselect_b32 s45, s19, s3
	s_cselect_b32 s44, s18, s2
	s_add_i32 s31, 0, 0x14000
	ds_read_b128 v[142:145], v150
	ds_read_b128 v[146:149], v150 offset:1024
	ds_read_b128 v[154:157], v150 offset:2048
	ds_read_b128 v[162:165], v150 offset:3072
	v_add_u32_e32 v150, s31, v139
	ds_read_b128 v[170:173], v150
	ds_read_b128 v[174:177], v150 offset:1024
	ds_read_b128 v[178:181], v150 offset:2048
	ds_read_b128 v[182:185], v150 offset:3072
	v_lshl_add_u64 v[150:151], s[20:21], 0, v[134:135]
	s_add_i32 m0, s25, 0xc000
	ds_read_b128 v[186:189], v141
	ds_read_b128 v[190:193], v141 offset:1024
	ds_read_b128 v[194:197], v141 offset:2048
	ds_read_b128 v[210:213], v141 offset:3072
	ds_read_b128 v[214:217], v141 offset:4096
	ds_read_b128 v[218:221], v141 offset:5120
	ds_read_b128 v[222:225], v141 offset:6144
	ds_read_b128 v[226:229], v141 offset:7168
	global_load_lds_dwordx4 v[150:151], off
	v_lshl_add_u64 v[150:151], s[20:21], 0, v[136:137]
	s_add_i32 m0, s25, 0xe000
	s_nop 0
	global_load_lds_dwordx4 v[150:151], off
	s_waitcnt vmcnt(8)
	s_waitcnt lgkmcnt(0)
	s_barrier
	s_waitcnt lgkmcnt(0)
	v_mfma_f32_16x16x32_f16 v[120:123], v[142:145], v[186:189], v[120:123]
	v_mfma_f32_16x16x32_f16 v[124:127], v[154:157], v[186:189], v[124:127]
	v_mfma_f32_16x16x32_f16 v[108:111], v[142:145], v[194:197], v[108:111]
	v_mfma_f32_16x16x32_f16 v[104:107], v[154:157], v[194:197], v[104:107]
	v_mfma_f32_16x16x32_f16 v[92:95], v[142:145], v[214:217], v[92:95]
	v_mfma_f32_16x16x32_f16 v[88:91], v[154:157], v[214:217], v[88:91]
	v_mfma_f32_16x16x32_f16 v[76:79], v[142:145], v[222:225], v[76:79]
	v_mfma_f32_16x16x32_f16 v[72:75], v[154:157], v[222:225], v[72:75]
	v_mfma_f32_16x16x32_f16 v[120:123], v[146:149], v[190:193], v[120:123]
	v_mfma_f32_16x16x32_f16 v[124:127], v[162:165], v[190:193], v[124:127]
	v_mfma_f32_16x16x32_f16 v[108:111], v[146:149], v[210:213], v[108:111]
	v_mfma_f32_16x16x32_f16 v[104:107], v[162:165], v[210:213], v[104:107]
	v_mfma_f32_16x16x32_f16 v[92:95], v[146:149], v[218:221], v[92:95]
	v_mfma_f32_16x16x32_f16 v[88:91], v[162:165], v[218:221], v[88:91]
	v_mfma_f32_16x16x32_f16 v[76:79], v[146:149], v[226:229], v[76:79]
	v_mfma_f32_16x16x32_f16 v[72:75], v[162:165], v[226:229], v[72:75]
	v_mfma_f32_16x16x32_f16 v[116:119], v[170:173], v[186:189], v[116:119]
	v_mfma_f32_16x16x32_f16 v[112:115], v[178:181], v[186:189], v[112:115]
	v_mfma_f32_16x16x32_f16 v[100:103], v[170:173], v[194:197], v[100:103]
	v_mfma_f32_16x16x32_f16 v[96:99], v[178:181], v[194:197], v[96:99]
	v_mfma_f32_16x16x32_f16 v[84:87], v[170:173], v[214:217], v[84:87]
	v_mfma_f32_16x16x32_f16 v[80:83], v[178:181], v[214:217], v[80:83]
	v_mfma_f32_16x16x32_f16 v[68:71], v[170:173], v[222:225], v[68:71]
	v_mfma_f32_16x16x32_f16 v[64:67], v[178:181], v[222:225], v[64:67]
	v_mfma_f32_16x16x32_f16 v[116:119], v[174:177], v[190:193], v[116:119]
	v_mfma_f32_16x16x32_f16 v[112:115], v[182:185], v[190:193], v[112:115]
	v_mfma_f32_16x16x32_f16 v[100:103], v[174:177], v[210:213], v[100:103]
	v_mfma_f32_16x16x32_f16 v[96:99], v[182:185], v[210:213], v[96:99]
	v_mfma_f32_16x16x32_f16 v[84:87], v[174:177], v[218:221], v[84:87]
	v_mfma_f32_16x16x32_f16 v[80:83], v[182:185], v[218:221], v[80:83]
	v_mfma_f32_16x16x32_f16 v[68:71], v[174:177], v[226:229], v[68:71]
	v_mfma_f32_16x16x32_f16 v[64:67], v[182:185], v[226:229], v[64:67]
	s_barrier
	s_add_i32 s46, s46, s24
	v_lshl_add_u64 v[150:151], s[44:45], 0, v[152:153]
	s_mov_b32 m0, s46
	ds_read_b128 v[186:189], v141 offset:16384
	ds_read_b128 v[190:193], v141 offset:17408
	ds_read_b128 v[194:197], v141 offset:18432
	ds_read_b128 v[210:213], v141 offset:19456
	ds_read_b128 v[214:217], v141 offset:20480
	ds_read_b128 v[218:221], v141 offset:21504
	ds_read_b128 v[222:225], v141 offset:22528
	ds_read_b128 v[226:229], v141 offset:23552
	global_load_lds_dwordx4 v[150:151], off
	s_add_i32 m0, s46, 0x2000
	v_lshl_add_u64 v[166:167], s[44:45], 0, v[128:129]
	s_add_u32 s44, s44, s4
	s_addc_u32 s45, s45, s5
	s_add_i32 s31, s31, s24
	global_load_lds_dwordx4 v[166:167], off
	v_lshl_add_u64 v[204:205], s[44:45], 0, v[152:153]
	s_mov_b32 m0, s31
	v_lshl_add_u64 v[230:231], s[44:45], 0, v[128:129]
	global_load_lds_dwordx4 v[204:205], off
	s_add_i32 m0, s31, 0x2000
	v_lshl_add_u64 v[232:233], s[22:23], 0, v[132:133]
	global_load_lds_dwordx4 v[230:231], off
	s_mov_b32 m0, s25
	v_lshl_add_u64 v[234:235], s[22:23], 0, v[130:131]
	global_load_lds_dwordx4 v[232:233], off
	s_mov_b32 m0, s26
	s_nop 0
	global_load_lds_dwordx4 v[234:235], off
	s_waitcnt vmcnt(8)
	s_waitcnt lgkmcnt(0)
	s_barrier
; #define PG8_STAGE(bufoff, gbase, voff) do { _Pragma("unroll") for (int _i = 0; _i < 2; ++_i) \
;         __builtin_amdgcn_global_load_lds((const unsigned*)((const char*)(gbase) + (voff)[_i]), (LAS unsigned*)(lds + (bufoff) + ldsw + _i * 8192), 16, 0, 0); } while (0)
; #define PG8_LDA(dst, b, h) do { _Pragma("unroll") for (int m = 0; m < 4; ++m) _Pragma("unroll") for (int k = 0; k < 2; ++k) dst[m][k] = *(const LAS h16x8*)(lds + PG8_SA(b, h) + aoff + m * 2048 + k * 1024); } while (0)
; #define PG8_LDB(dst, b, h) do { _Pragma("unroll") for (int n = 0; n < 2; ++n) _Pragma("unroll") for (int k = 0; k < 2; ++k) dst[n][k] = *(const LAS h16x8*)(lds + PG8_SB(b, h) + boff + n * 2048 + k * 1024); } while (0)
; #define PG8_MMA(ai, bj, At, Bt) do { __builtin_amdgcn_s_setprio(1); _Pragma("unroll") for (int m = 0; m < 4; ++m) _Pragma("unroll") for (int n = 0; n < 2; ++n) _Pragma("unroll") for (int k = 0; k < 2; ++k) \
;         acc[ai][bj][m][n] = __builtin_amdgcn_mfma_f32_16x16x32_f16(Bt[n][k], At[m][k], acc[ai][bj][m][n], 0, 0, 0); __builtin_amdgcn_s_setprio(0); } while (0)
; #define PG8_WAIT_V(n) asm volatile("s_waitcnt vmcnt(" #n ")" ::: "memory")
; #define PG8_WAIT_L(n) asm volatile("s_waitcnt lgkmcnt(" #n ")" ::: "memory")
; #define PG8_BAR __builtin_amdgcn_s_barrier()
; #define PG8_SCHED __builtin_amdgcn_sched_barrier(0)
; template <class Epi>
; __device__ __forceinline__ void gemm_phase(LAS unsigned char* lds, const Gemm g, const StaticOrder& S, const Epi& E, const int tid) {
;     ...
;             PG8_WAIT_V(8); PG8_WAIT_L(0); PG8_BAR; PG8_MMA(1, 0, At, B0); PG8_MMA(1, 1, At, B1); PG8_BAR; PG8_SCHED;
;             PG8_LDB(B0, 1, 0); PG8_LDB(B1, 1, 1); PG8_SCHED; PG8_LDA(At, 1, 0); PG8_STAGE(PG8_SA(0, 1), a2 + hstepA, voffA);
;             PG8_WAIT_V(8); PG8_WAIT_L(0); PG8_BAR; PG8_MMA(0, 0, At, B0); PG8_MMA(0, 1, At, B1); PG8_BAR; PG8_SCHED;
	s_waitcnt lgkmcnt(0)
	v_mfma_f32_16x16x32_f16 v[60:63], v[142:145], v[186:189], v[60:63]
	v_mfma_f32_16x16x32_f16 v[56:59], v[154:157], v[186:189], v[56:59]
	v_mfma_f32_16x16x32_f16 v[44:47], v[142:145], v[194:197], v[44:47]
	v_mfma_f32_16x16x32_f16 v[40:43], v[154:157], v[194:197], v[40:43]
	v_mfma_f32_16x16x32_f16 v[28:31], v[142:145], v[214:217], v[28:31]
	v_mfma_f32_16x16x32_f16 v[24:27], v[154:157], v[214:217], v[24:27]
	v_mfma_f32_16x16x32_f16 v[12:15], v[142:145], v[222:225], v[12:15]
	v_mfma_f32_16x16x32_f16 v[8:11], v[154:157], v[222:225], v[8:11]
	v_mfma_f32_16x16x32_f16 v[60:63], v[146:149], v[190:193], v[60:63]
	v_mfma_f32_16x16x32_f16 v[56:59], v[162:165], v[190:193], v[56:59]
	v_mfma_f32_16x16x32_f16 v[44:47], v[146:149], v[210:213], v[44:47]
	v_mfma_f32_16x16x32_f16 v[40:43], v[162:165], v[210:213], v[40:43]
	v_mfma_f32_16x16x32_f16 v[28:31], v[146:149], v[218:221], v[28:31]
	v_mfma_f32_16x16x32_f16 v[24:27], v[162:165], v[218:221], v[24:27]
	v_mfma_f32_16x16x32_f16 v[12:15], v[146:149], v[226:229], v[12:15]
	v_mfma_f32_16x16x32_f16 v[8:11], v[162:165], v[226:229], v[8:11]
	v_mfma_f32_16x16x32_f16 v[52:55], v[170:173], v[186:189], v[52:55]
	v_mfma_f32_16x16x32_f16 v[48:51], v[178:181], v[186:189], v[48:51]
	v_mfma_f32_16x16x32_f16 v[36:39], v[170:173], v[194:197], v[36:39]
	v_mfma_f32_16x16x32_f16 v[32:35], v[178:181], v[194:197], v[32:35]
	v_mfma_f32_16x16x32_f16 v[20:23], v[170:173], v[214:217], v[20:23]
	v_mfma_f32_16x16x32_f16 v[16:19], v[178:181], v[214:217], v[16:19]
	v_mfma_f32_16x16x32_f16 v[4:7], v[170:173], v[222:225], v[4:7]
	v_mfma_f32_16x16x32_f16 v[0:3], v[178:181], v[222:225], v[0:3]
	v_mfma_f32_16x16x32_f16 v[52:55], v[174:177], v[190:193], v[52:55]
	v_mfma_f32_16x16x32_f16 v[48:51], v[182:185], v[190:193], v[48:51]
	v_mfma_f32_16x16x32_f16 v[36:39], v[174:177], v[210:213], v[36:39]
	v_mfma_f32_16x16x32_f16 v[32:35], v[182:185], v[210:213], v[32:35]
	v_mfma_f32_16x16x32_f16 v[20:23], v[174:177], v[218:221], v[20:23]
	v_mfma_f32_16x16x32_f16 v[16:19], v[182:185], v[218:221], v[16:19]
	v_mfma_f32_16x16x32_f16 v[4:7], v[174:177], v[226:229], v[4:7]
	v_mfma_f32_16x16x32_f16 v[0:3], v[182:185], v[226:229], v[0:3]
	s_barrier
	s_add_i32 s31, 0, 0x18000
	s_add_i32 s44, 0, 0x1c000
	v_add_u32_e32 v162, s31, v139
	v_add_u32_e32 v182, s44, v139
	ds_read_b128 v[142:145], v162
	ds_read_b128 v[146:149], v162 offset:1024
	ds_read_b128 v[154:157], v162 offset:2048
	ds_read_b128 v[162:165], v162 offset:3072
	ds_read_b128 v[170:173], v182
	ds_read_b128 v[174:177], v182 offset:1024
	ds_read_b128 v[178:181], v182 offset:2048
	ds_read_b128 v[182:185], v182 offset:3072
	s_add_u32 s22, s22, s4
	s_addc_u32 s23, s23, s5
	s_mov_b32 m0, s27
	v_lshl_add_u64 v[236:237], s[22:23], 0, v[132:133]
	ds_read_b128 v[186:189], v141 offset:32768
	ds_read_b128 v[190:193], v141 offset:33792
	ds_read_b128 v[194:197], v141 offset:34816
	ds_read_b128 v[210:213], v141 offset:35840
	ds_read_b128 v[214:217], v141 offset:36864
	ds_read_b128 v[218:221], v141 offset:37888
	ds_read_b128 v[222:225], v141 offset:38912
	ds_read_b128 v[226:229], v141 offset:39936
	global_load_lds_dwordx4 v[236:237], off
	v_lshl_add_u64 v[236:237], s[22:23], 0, v[130:131]
	s_mov_b32 m0, s28
	s_nop 0
	global_load_lds_dwordx4 v[236:237], off
	s_waitcnt vmcnt(8)
	s_waitcnt lgkmcnt(0)
	s_barrier
	s_waitcnt lgkmcnt(0)
	v_mfma_f32_16x16x32_f16 v[120:123], v[142:145], v[186:189], v[120:123]
	v_mfma_f32_16x16x32_f16 v[124:127], v[154:157], v[186:189], v[124:127]
	v_mfma_f32_16x16x32_f16 v[108:111], v[142:145], v[194:197], v[108:111]
	v_mfma_f32_16x16x32_f16 v[104:107], v[154:157], v[194:197], v[104:107]
	v_mfma_f32_16x16x32_f16 v[92:95], v[142:145], v[214:217], v[92:95]
	v_mfma_f32_16x16x32_f16 v[88:91], v[154:157], v[214:217], v[88:91]
	v_mfma_f32_16x16x32_f16 v[76:79], v[142:145], v[222:225], v[76:79]
	v_mfma_f32_16x16x32_f16 v[72:75], v[154:157], v[222:225], v[72:75]
	v_mfma_f32_16x16x32_f16 v[120:123], v[146:149], v[190:193], v[120:123]
	v_mfma_f32_16x16x32_f16 v[124:127], v[162:165], v[190:193], v[124:127]
	v_mfma_f32_16x16x32_f16 v[108:111], v[146:149], v[210:213], v[108:111]
	v_mfma_f32_16x16x32_f16 v[104:107], v[162:165], v[210:213], v[104:107]
	v_mfma_f32_16x16x32_f16 v[92:95], v[146:149], v[218:221], v[92:95]
	v_mfma_f32_16x16x32_f16 v[88:91], v[162:165], v[218:221], v[88:91]
	v_mfma_f32_16x16x32_f16 v[76:79], v[146:149], v[226:229], v[76:79]
	v_mfma_f32_16x16x32_f16 v[72:75], v[162:165], v[226:229], v[72:75]
	v_mfma_f32_16x16x32_f16 v[116:119], v[170:173], v[186:189], v[116:119]
	v_mfma_f32_16x16x32_f16 v[112:115], v[178:181], v[186:189], v[112:115]
	v_mfma_f32_16x16x32_f16 v[100:103], v[170:173], v[194:197], v[100:103]
	v_mfma_f32_16x16x32_f16 v[96:99], v[178:181], v[194:197], v[96:99]
	v_mfma_f32_16x16x32_f16 v[84:87], v[170:173], v[214:217], v[84:87]
	v_mfma_f32_16x16x32_f16 v[80:83], v[178:181], v[214:217], v[80:83]
	v_mfma_f32_16x16x32_f16 v[68:71], v[170:173], v[222:225], v[68:71]
	v_mfma_f32_16x16x32_f16 v[64:67], v[178:181], v[222:225], v[64:67]
	v_mfma_f32_16x16x32_f16 v[116:119], v[174:177], v[190:193], v[116:119]
	v_mfma_f32_16x16x32_f16 v[112:115], v[182:185], v[190:193], v[112:115]
	v_mfma_f32_16x16x32_f16 v[100:103], v[174:177], v[210:213], v[100:103]
	v_mfma_f32_16x16x32_f16 v[96:99], v[182:185], v[210:213], v[96:99]
	v_mfma_f32_16x16x32_f16 v[84:87], v[174:177], v[218:221], v[84:87]
	v_mfma_f32_16x16x32_f16 v[80:83], v[182:185], v[218:221], v[80:83]
	v_mfma_f32_16x16x32_f16 v[68:71], v[174:177], v[226:229], v[68:71]
	v_mfma_f32_16x16x32_f16 v[64:67], v[182:185], v[226:229], v[64:67]
	s_barrier
; #define PG8_STAGE(bufoff, gbase, voff) do { _Pragma("unroll") for (int _i = 0; _i < 2; ++_i) \
;         __builtin_amdgcn_global_load_lds((const unsigned*)((const char*)(gbase) + (voff)[_i]), (LAS unsigned*)(lds + (bufoff) + ldsw + _i * 8192), 16, 0, 0); } while (0)
; #define PG8_LDA(dst, b, h) do { _Pragma("unroll") for (int m = 0; m < 4; ++m) _Pragma("unroll") for (int k = 0; k < 2; ++k) dst[m][k] = *(const LAS h16x8*)(lds + PG8_SA(b, h) + aoff + m * 2048 + k * 1024); } while (0)
; #define PG8_MMA(ai, bj, At, Bt) do { __builtin_amdgcn_s_setprio(1); _Pragma("unroll") for (int m = 0; m < 4; ++m) _Pragma("unroll") for (int n = 0; n < 2; ++n) _Pragma("unroll") for (int k = 0; k < 2; ++k) \
;         acc[ai][bj][m][n] = __builtin_amdgcn_mfma_f32_16x16x32_f16(Bt[n][k], At[m][k], acc[ai][bj][m][n], 0, 0, 0); __builtin_amdgcn_s_setprio(0); } while (0)
; #define PG8_WAIT_V(n) asm volatile("s_waitcnt vmcnt(" #n ")" ::: "memory")
; #define PG8_WAIT_L(n) asm volatile("s_waitcnt lgkmcnt(" #n ")" ::: "memory")
; #define PG8_BAR __builtin_amdgcn_s_barrier()
; #define PG8_SCHED __builtin_amdgcn_sched_barrier(0)
; template <class Epi>
; __device__ __forceinline__ void gemm_phase(LAS unsigned char* lds, const Gemm g, const StaticOrder& S, const Epi& E, const int tid) {
;     ...
;             PG8_LDA(At, 1, 1); PG8_STAGE(PG8_SB(1, 0), b3, voffB); PG8_STAGE(PG8_SB(1, 1), b3 + hstepB, voffB); PG8_STAGE(PG8_SA(1, 0), a3, voffA);
;             PG8_WAIT_V(8); PG8_WAIT_L(0); PG8_BAR; PG8_MMA(1, 0, At, B0); PG8_MMA(1, 1, At, B1); PG8_BAR; PG8_SCHED;
;         }
	s_add_i32 s22, s31, s24
	v_lshl_add_u64 v[150:151], v[150:151], 0, s[0:1]
	s_mov_b32 m0, s22
	ds_read_b128 v[186:189], v141 offset:49152
	ds_read_b128 v[190:193], v141 offset:50176
	ds_read_b128 v[194:197], v141 offset:51200
	ds_read_b128 v[210:213], v141 offset:52224
	ds_read_b128 v[214:217], v141 offset:53248
	ds_read_b128 v[218:221], v141 offset:54272
	ds_read_b128 v[222:225], v141 offset:55296
	ds_read_b128 v[226:229], v141 offset:56320
	global_load_lds_dwordx4 v[150:151], off
	v_lshl_add_u64 v[150:151], v[166:167], 0, s[0:1]
	s_add_i32 m0, s22, 0x2000
	s_add_i32 s22, s44, s24
	global_load_lds_dwordx4 v[150:151], off
	v_lshl_add_u64 v[150:151], v[204:205], 0, s[0:1]
	s_mov_b32 m0, s22
	s_nop 0
	global_load_lds_dwordx4 v[150:151], off
	v_lshl_add_u64 v[150:151], v[230:231], 0, s[0:1]
	s_add_i32 m0, s22, 0x2000
	s_nop 0
	global_load_lds_dwordx4 v[150:151], off
	v_lshl_add_u64 v[150:151], v[232:233], 0, s[0:1]
	s_mov_b32 m0, s29
	s_nop 0
	global_load_lds_dwordx4 v[150:151], off
	v_lshl_add_u64 v[150:151], v[234:235], 0, s[0:1]
	s_mov_b32 m0, s35
	s_nop 0
	global_load_lds_dwordx4 v[150:151], off
	s_waitcnt vmcnt(8)
	s_waitcnt lgkmcnt(0)
	s_barrier
	s_waitcnt lgkmcnt(0)
	v_mfma_f32_16x16x32_f16 v[60:63], v[142:145], v[186:189], v[60:63]
	v_mfma_f32_16x16x32_f16 v[56:59], v[154:157], v[186:189], v[56:59]
	v_mfma_f32_16x16x32_f16 v[44:47], v[142:145], v[194:197], v[44:47]
	v_mfma_f32_16x16x32_f16 v[40:43], v[154:157], v[194:197], v[40:43]
	v_mfma_f32_16x16x32_f16 v[28:31], v[142:145], v[214:217], v[28:31]
	v_mfma_f32_16x16x32_f16 v[24:27], v[154:157], v[214:217], v[24:27]
	v_mfma_f32_16x16x32_f16 v[12:15], v[142:145], v[222:225], v[12:15]
	v_mfma_f32_16x16x32_f16 v[8:11], v[154:157], v[222:225], v[8:11]
	v_mfma_f32_16x16x32_f16 v[60:63], v[146:149], v[190:193], v[60:63]
	v_mfma_f32_16x16x32_f16 v[56:59], v[162:165], v[190:193], v[56:59]
	v_mfma_f32_16x16x32_f16 v[44:47], v[146:149], v[210:213], v[44:47]
	v_mfma_f32_16x16x32_f16 v[40:43], v[162:165], v[210:213], v[40:43]
	v_mfma_f32_16x16x32_f16 v[28:31], v[146:149], v[218:221], v[28:31]
	v_mfma_f32_16x16x32_f16 v[24:27], v[162:165], v[218:221], v[24:27]
	v_mfma_f32_16x16x32_f16 v[12:15], v[146:149], v[226:229], v[12:15]
	v_mfma_f32_16x16x32_f16 v[8:11], v[162:165], v[226:229], v[8:11]
	v_mfma_f32_16x16x32_f16 v[52:55], v[170:173], v[186:189], v[52:55]
	v_mfma_f32_16x16x32_f16 v[48:51], v[178:181], v[186:189], v[48:51]
	v_mfma_f32_16x16x32_f16 v[36:39], v[170:173], v[194:197], v[36:39]
	v_mfma_f32_16x16x32_f16 v[32:35], v[178:181], v[194:197], v[32:35]
	v_mfma_f32_16x16x32_f16 v[20:23], v[170:173], v[214:217], v[20:23]
	v_mfma_f32_16x16x32_f16 v[16:19], v[178:181], v[214:217], v[16:19]
	v_mfma_f32_16x16x32_f16 v[4:7], v[170:173], v[222:225], v[4:7]
	v_mfma_f32_16x16x32_f16 v[0:3], v[178:181], v[222:225], v[0:3]
	v_mfma_f32_16x16x32_f16 v[52:55], v[174:177], v[190:193], v[52:55]
	v_mfma_f32_16x16x32_f16 v[48:51], v[182:185], v[190:193], v[48:51]
	v_mfma_f32_16x16x32_f16 v[36:39], v[174:177], v[210:213], v[36:39]
	v_mfma_f32_16x16x32_f16 v[32:35], v[182:185], v[210:213], v[32:35]
	v_mfma_f32_16x16x32_f16 v[20:23], v[174:177], v[218:221], v[20:23]
	v_mfma_f32_16x16x32_f16 v[16:19], v[182:185], v[218:221], v[16:19]
	v_mfma_f32_16x16x32_f16 v[4:7], v[174:177], v[226:229], v[4:7]
	v_mfma_f32_16x16x32_f16 v[0:3], v[182:185], v[226:229], v[0:3]
	s_barrier
	s_add_u32 s20, s20, 0x100
	s_addc_u32 s21, s21, 0
	s_add_u32 s2, s2, 0x100
	s_addc_u32 s3, s3, 0
	s_cmp_ge_i32 s43, s36
	s_mov_b32 s22, s43
	s_cbranch_scc0 .LBB0_986
	v_readlane_b32 s46, v254, 16
	v_mov_b64_e32 v[154:155], v[158:159]
	v_readlane_b32 s47, v254, 17
	v_mov_b64_e32 v[156:157], v[160:161]

; #define PG8_STAGE(bufoff, gbase, voff) do { _Pragma("unroll") for (int _i = 0; _i < 2; ++_i) \
;         __builtin_amdgcn_global_load_lds((const unsigned*)((const char*)(gbase) + (voff)[_i]), (LAS unsigned*)(lds + (bufoff) + ldsw + _i * 8192), 16, 0, 0); } while (0)
; #define PG8_LDA(dst, b, h) do { _Pragma("unroll") for (int m = 0; m < 4; ++m) _Pragma("unroll") for (int k = 0; k < 2; ++k) dst[m][k] = *(const LAS h16x8*)(lds + PG8_SA(b, h) + aoff + m * 2048 + k * 1024); } while (0)
; #define PG8_LDB(dst, b, h) do { _Pragma("unroll") for (int n = 0; n < 2; ++n) _Pragma("unroll") for (int k = 0; k < 2; ++k) dst[n][k] = *(const LAS h16x8*)(lds + PG8_SB(b, h) + boff + n * 2048 + k * 1024); } while (0)
; #define PG8_MMA(ai, bj, At, Bt) do { __builtin_amdgcn_s_setprio(1); _Pragma("unroll") for (int m = 0; m < 4; ++m) _Pragma("unroll") for (int n = 0; n < 2; ++n) _Pragma("unroll") for (int k = 0; k < 2; ++k) \
;         acc[ai][bj][m][n] = __builtin_amdgcn_mfma_f32_16x16x32_f16(Bt[n][k], At[m][k], acc[ai][bj][m][n], 0, 0, 0); __builtin_amdgcn_s_setprio(0); } while (0)
; #define PG8_WAIT_V(n) asm volatile("s_waitcnt vmcnt(" #n ")" ::: "memory")
; #define PG8_WAIT_L(n) asm volatile("s_waitcnt lgkmcnt(" #n ")" ::: "memory")
; #define PG8_BAR __builtin_amdgcn_s_barrier()
; template <class Epi>
; __device__ __forceinline__ void gemm_phase(LAS unsigned char* lds, const Gemm g, const StaticOrder& S, const Epi& E, const int tid) {
;     ...
;         const char* nA = has_next ? (const char*)g.A + (size_t)nxt.pm * tstepA : cA; const char* nB = has_next ? (const char*)g.Bt + (size_t)nxt.pn * tstepB : cB;
;         for (int t = 0; t < nt; t += 2) {
;             const bool last = (t == nt - 2);
;             const char* a1 = cA + (size_t)(t + 1) * kstep;
;             const char* a2 = last ? nA : cA + (size_t)(t + 2) * kstep; const char* b2 = last ? nB : cB + (size_t)(t + 2) * kstep;
;             const char* a3 = a2 + kstep; const char* b3 = b2 + kstep;
;             PG8_LDB(B0, 0, 0); PG8_LDB(B1, 0, 1); PG8_SCHED; PG8_LDA(At, 0, 0); PG8_STAGE(PG8_SA(1, 1), a1 + hstepA, voffA);
;             PG8_WAIT_V(8); PG8_WAIT_L(0); PG8_BAR; PG8_MMA(0, 0, At, B0); PG8_MMA(0, 1, At, B1); PG8_BAR; PG8_SCHED;
;             PG8_LDA(At, 0, 1); PG8_STAGE(PG8_SB(0, 0), b2, voffB); PG8_STAGE(PG8_SB(0, 1), b2 + hstepB, voffB); PG8_STAGE(PG8_SA(0, 0), a2, voffA);
.LBB0_1017:
	s_add_u32 s22, s4, 0xfffc0080
	s_addc_u32 s23, s5, -1
	s_add_i32 s31, 0, 0x10000
	s_cmp_eq_u32 s44, 12
	s_cselect_b32 s25, s17, s23
	s_cselect_b32 s24, s42, s22
	s_cselect_b32 s23, s15, s3
	s_cselect_b32 s22, s43, s2
	s_add_i32 s45, 0, 0x14000
	v_add_u32_e32 v148, s31, v198
	v_add_u32_e32 v166, s45, v198
	ds_read_b128 v[136:139], v148
	ds_read_b128 v[140:143], v148 offset:1024
	ds_read_b128 v[144:147], v148 offset:2048
	ds_read_b128 v[148:151], v148 offset:3072
	ds_read_b128 v[154:157], v166
	ds_read_b128 v[162:165], v166 offset:1024
	ds_read_b128 v[170:173], v166 offset:2048
	ds_read_b128 v[174:177], v166 offset:3072
	v_lshl_add_u64 v[166:167], s[4:5], 0, v[132:133]
	s_add_i32 m0, s27, 0xc000
	ds_read_b128 v[178:181], v212
	ds_read_b128 v[182:185], v212 offset:1024
	ds_read_b128 v[188:191], v212 offset:2048
	ds_read_b128 v[192:195], v212 offset:3072
	ds_read_b128 v[214:217], v212 offset:4096
	ds_read_b128 v[218:221], v212 offset:5120
	ds_read_b128 v[222:225], v212 offset:6144
	ds_read_b128 v[226:229], v212 offset:7168
	global_load_lds_dwordx4 v[166:167], off
	v_lshl_add_u64 v[166:167], s[4:5], 0, v[134:135]
	s_add_i32 m0, s27, 0xe000
	s_nop 0
	global_load_lds_dwordx4 v[166:167], off
	s_waitcnt vmcnt(8)
	s_waitcnt lgkmcnt(0)
	s_barrier
	s_waitcnt lgkmcnt(0)
	v_mfma_f32_16x16x32_f16 v[124:127], v[136:139], v[178:181], v[124:127]
	v_mfma_f32_16x16x32_f16 v[120:123], v[144:147], v[178:181], v[120:123]
	v_mfma_f32_16x16x32_f16 v[108:111], v[136:139], v[188:191], v[108:111]
	v_mfma_f32_16x16x32_f16 v[104:107], v[144:147], v[188:191], v[104:107]
	v_mfma_f32_16x16x32_f16 v[92:95], v[136:139], v[214:217], v[92:95]
	v_mfma_f32_16x16x32_f16 v[88:91], v[144:147], v[214:217], v[88:91]
	v_mfma_f32_16x16x32_f16 v[76:79], v[136:139], v[222:225], v[76:79]
	v_mfma_f32_16x16x32_f16 v[72:75], v[144:147], v[222:225], v[72:75]
	v_mfma_f32_16x16x32_f16 v[124:127], v[140:143], v[182:185], v[124:127]
	v_mfma_f32_16x16x32_f16 v[120:123], v[148:151], v[182:185], v[120:123]
	v_mfma_f32_16x16x32_f16 v[108:111], v[140:143], v[192:195], v[108:111]
	v_mfma_f32_16x16x32_f16 v[104:107], v[148:151], v[192:195], v[104:107]
	v_mfma_f32_16x16x32_f16 v[92:95], v[140:143], v[218:221], v[92:95]
	v_mfma_f32_16x16x32_f16 v[88:91], v[148:151], v[218:221], v[88:91]
	v_mfma_f32_16x16x32_f16 v[76:79], v[140:143], v[226:229], v[76:79]
	v_mfma_f32_16x16x32_f16 v[72:75], v[148:151], v[226:229], v[72:75]
	v_mfma_f32_16x16x32_f16 v[116:119], v[154:157], v[178:181], v[116:119]
	v_mfma_f32_16x16x32_f16 v[112:115], v[170:173], v[178:181], v[112:115]
	v_mfma_f32_16x16x32_f16 v[100:103], v[154:157], v[188:191], v[100:103]
	v_mfma_f32_16x16x32_f16 v[96:99], v[170:173], v[188:191], v[96:99]
	v_mfma_f32_16x16x32_f16 v[84:87], v[154:157], v[214:217], v[84:87]
	v_mfma_f32_16x16x32_f16 v[80:83], v[170:173], v[214:217], v[80:83]
	v_mfma_f32_16x16x32_f16 v[68:71], v[154:157], v[222:225], v[68:71]
	v_mfma_f32_16x16x32_f16 v[64:67], v[170:173], v[222:225], v[64:67]
	v_mfma_f32_16x16x32_f16 v[116:119], v[162:165], v[182:185], v[116:119]
	v_mfma_f32_16x16x32_f16 v[112:115], v[174:177], v[182:185], v[112:115]
	v_mfma_f32_16x16x32_f16 v[100:103], v[162:165], v[192:195], v[100:103]
	v_mfma_f32_16x16x32_f16 v[96:99], v[174:177], v[192:195], v[96:99]
	v_mfma_f32_16x16x32_f16 v[84:87], v[162:165], v[218:221], v[84:87]
	v_mfma_f32_16x16x32_f16 v[80:83], v[174:177], v[218:221], v[80:83]
	v_mfma_f32_16x16x32_f16 v[68:71], v[162:165], v[226:229], v[68:71]
	v_mfma_f32_16x16x32_f16 v[64:67], v[174:177], v[226:229], v[64:67]
	s_barrier
	s_add_i32 s31, s31, s26
	v_lshl_add_u64 v[166:167], s[22:23], 0, v[152:153]
	s_mov_b32 m0, s31
	ds_read_b128 v[178:181], v212 offset:16384
	ds_read_b128 v[182:185], v212 offset:17408
	ds_read_b128 v[188:191], v212 offset:18432
	ds_read_b128 v[192:195], v212 offset:19456
	ds_read_b128 v[214:217], v212 offset:20480
	ds_read_b128 v[218:221], v212 offset:21504
	ds_read_b128 v[222:225], v212 offset:22528
	ds_read_b128 v[226:229], v212 offset:23552
	global_load_lds_dwordx4 v[166:167], off
	s_add_i32 m0, s31, 0x2000
	s_add_u32 s46, s22, 0x40000
	v_lshl_add_u64 v[196:197], s[22:23], 0, v[128:129]
	s_addc_u32 s47, s23, 0
	s_add_i32 s31, s45, s26
	global_load_lds_dwordx4 v[196:197], off
	v_lshl_add_u64 v[204:205], s[46:47], 0, v[152:153]
	s_mov_b32 m0, s31
	v_lshl_add_u64 v[230:231], s[24:25], 0, v[128:129]
	global_load_lds_dwordx4 v[204:205], off
	v_lshl_add_u64 v[204:205], s[46:47], 0, v[128:129]
	s_add_i32 m0, s31, 0x2000
	s_nop 0
	global_load_lds_dwordx4 v[204:205], off
	v_lshl_add_u64 v[204:205], s[24:25], 0, v[152:153]
	s_mov_b32 m0, s27
	s_nop 0
	global_load_lds_dwordx4 v[204:205], off
	s_mov_b32 m0, s28
	s_nop 0
	global_load_lds_dwordx4 v[230:231], off
	s_waitcnt vmcnt(8)
	s_waitcnt lgkmcnt(0)
	s_barrier
; #define PG8_STAGE(bufoff, gbase, voff) do { _Pragma("unroll") for (int _i = 0; _i < 2; ++_i) \
;         __builtin_amdgcn_global_load_lds((const unsigned*)((const char*)(gbase) + (voff)[_i]), (LAS unsigned*)(lds + (bufoff) + ldsw + _i * 8192), 16, 0, 0); } while (0)
; #define PG8_LDA(dst, b, h) do { _Pragma("unroll") for (int m = 0; m < 4; ++m) _Pragma("unroll") for (int k = 0; k < 2; ++k) dst[m][k] = *(const LAS h16x8*)(lds + PG8_SA(b, h) + aoff + m * 2048 + k * 1024); } while (0)
; #define PG8_LDB(dst, b, h) do { _Pragma("unroll") for (int n = 0; n < 2; ++n) _Pragma("unroll") for (int k = 0; k < 2; ++k) dst[n][k] = *(const LAS h16x8*)(lds + PG8_SB(b, h) + boff + n * 2048 + k * 1024); } while (0)
; #define PG8_MMA(ai, bj, At, Bt) do { __builtin_amdgcn_s_setprio(1); _Pragma("unroll") for (int m = 0; m < 4; ++m) _Pragma("unroll") for (int n = 0; n < 2; ++n) _Pragma("unroll") for (int k = 0; k < 2; ++k) \
;         acc[ai][bj][m][n] = __builtin_amdgcn_mfma_f32_16x16x32_f16(Bt[n][k], At[m][k], acc[ai][bj][m][n], 0, 0, 0); __builtin_amdgcn_s_setprio(0); } while (0)
; #define PG8_WAIT_V(n) asm volatile("s_waitcnt vmcnt(" #n ")" ::: "memory")
; #define PG8_WAIT_L(n) asm volatile("s_waitcnt lgkmcnt(" #n ")" ::: "memory")
; #define PG8_BAR __builtin_amdgcn_s_barrier()
; #define PG8_SCHED __builtin_amdgcn_sched_barrier(0)
; template <class Epi>
; __device__ __forceinline__ void gemm_phase(LAS unsigned char* lds, const Gemm g, const StaticOrder& S, const Epi& E, const int tid) {
;     ...
;             PG8_WAIT_V(8); PG8_WAIT_L(0); PG8_BAR; PG8_MMA(1, 0, At, B0); PG8_MMA(1, 1, At, B1); PG8_BAR; PG8_SCHED;
;             PG8_LDB(B0, 1, 0); PG8_LDB(B1, 1, 1); PG8_SCHED; PG8_LDA(At, 1, 0); PG8_STAGE(PG8_SA(0, 1), a2 + hstepA, voffA);
;             PG8_WAIT_V(8); PG8_WAIT_L(0); PG8_BAR; PG8_MMA(0, 0, At, B0); PG8_MMA(0, 1, At, B1); PG8_BAR; PG8_SCHED;
	s_waitcnt lgkmcnt(0)
	v_mfma_f32_16x16x32_f16 v[60:63], v[136:139], v[178:181], v[60:63]
	v_mfma_f32_16x16x32_f16 v[56:59], v[144:147], v[178:181], v[56:59]
	v_mfma_f32_16x16x32_f16 v[44:47], v[136:139], v[188:191], v[44:47]
	v_mfma_f32_16x16x32_f16 v[40:43], v[144:147], v[188:191], v[40:43]
	v_mfma_f32_16x16x32_f16 v[28:31], v[136:139], v[214:217], v[28:31]
	v_mfma_f32_16x16x32_f16 v[24:27], v[144:147], v[214:217], v[24:27]
	v_mfma_f32_16x16x32_f16 v[12:15], v[136:139], v[222:225], v[12:15]
	v_mfma_f32_16x16x32_f16 v[8:11], v[144:147], v[222:225], v[8:11]
	v_mfma_f32_16x16x32_f16 v[60:63], v[140:143], v[182:185], v[60:63]
	v_mfma_f32_16x16x32_f16 v[56:59], v[148:151], v[182:185], v[56:59]
	v_mfma_f32_16x16x32_f16 v[44:47], v[140:143], v[192:195], v[44:47]
	v_mfma_f32_16x16x32_f16 v[40:43], v[148:151], v[192:195], v[40:43]
	v_mfma_f32_16x16x32_f16 v[28:31], v[140:143], v[218:221], v[28:31]
	v_mfma_f32_16x16x32_f16 v[24:27], v[148:151], v[218:221], v[24:27]
	v_mfma_f32_16x16x32_f16 v[12:15], v[140:143], v[226:229], v[12:15]
	v_mfma_f32_16x16x32_f16 v[8:11], v[148:151], v[226:229], v[8:11]
	v_mfma_f32_16x16x32_f16 v[52:55], v[154:157], v[178:181], v[52:55]
	v_mfma_f32_16x16x32_f16 v[48:51], v[170:173], v[178:181], v[48:51]
	v_mfma_f32_16x16x32_f16 v[36:39], v[154:157], v[188:191], v[36:39]
	v_mfma_f32_16x16x32_f16 v[32:35], v[170:173], v[188:191], v[32:35]
	v_mfma_f32_16x16x32_f16 v[20:23], v[154:157], v[214:217], v[20:23]
	v_mfma_f32_16x16x32_f16 v[16:19], v[170:173], v[214:217], v[16:19]
	v_mfma_f32_16x16x32_f16 v[4:7], v[154:157], v[222:225], v[4:7]
	v_mfma_f32_16x16x32_f16 v[0:3], v[170:173], v[222:225], v[0:3]
	v_mfma_f32_16x16x32_f16 v[52:55], v[162:165], v[182:185], v[52:55]
	v_mfma_f32_16x16x32_f16 v[48:51], v[174:177], v[182:185], v[48:51]
	v_mfma_f32_16x16x32_f16 v[36:39], v[162:165], v[192:195], v[36:39]
	v_mfma_f32_16x16x32_f16 v[32:35], v[174:177], v[192:195], v[32:35]
	v_mfma_f32_16x16x32_f16 v[20:23], v[162:165], v[218:221], v[20:23]
	v_mfma_f32_16x16x32_f16 v[16:19], v[174:177], v[218:221], v[16:19]
	v_mfma_f32_16x16x32_f16 v[4:7], v[162:165], v[226:229], v[4:7]
	v_mfma_f32_16x16x32_f16 v[0:3], v[174:177], v[226:229], v[0:3]
	s_barrier
	s_add_i32 s31, 0, 0x18000
	s_add_i32 s45, 0, 0x1c000
	v_add_u32_e32 v148, s31, v198
	v_add_u32_e32 v174, s45, v198
	ds_read_b128 v[136:139], v148
	ds_read_b128 v[140:143], v148 offset:1024
	ds_read_b128 v[144:147], v148 offset:2048
	ds_read_b128 v[148:151], v148 offset:3072
	ds_read_b128 v[154:157], v174
	ds_read_b128 v[162:165], v174 offset:1024
	ds_read_b128 v[170:173], v174 offset:2048
	ds_read_b128 v[174:177], v174 offset:3072
	s_add_u32 s24, s24, 0x40000
	s_addc_u32 s25, s25, 0
	s_mov_b32 m0, s29
	v_lshl_add_u64 v[232:233], s[24:25], 0, v[152:153]
	ds_read_b128 v[178:181], v212 offset:32768
	ds_read_b128 v[182:185], v212 offset:33792
	ds_read_b128 v[188:191], v212 offset:34816
	ds_read_b128 v[192:195], v212 offset:35840
	ds_read_b128 v[214:217], v212 offset:36864
	ds_read_b128 v[218:221], v212 offset:37888
	ds_read_b128 v[222:225], v212 offset:38912
	ds_read_b128 v[226:229], v212 offset:39936
	global_load_lds_dwordx4 v[232:233], off
	v_lshl_add_u64 v[232:233], s[24:25], 0, v[128:129]
	s_mov_b32 m0, s35
	s_nop 0
	global_load_lds_dwordx4 v[232:233], off
	s_waitcnt vmcnt(8)
	s_waitcnt lgkmcnt(0)
	s_barrier
	s_waitcnt lgkmcnt(0)
	v_mfma_f32_16x16x32_f16 v[124:127], v[136:139], v[178:181], v[124:127]
	v_mfma_f32_16x16x32_f16 v[120:123], v[144:147], v[178:181], v[120:123]
	v_mfma_f32_16x16x32_f16 v[108:111], v[136:139], v[188:191], v[108:111]
	v_mfma_f32_16x16x32_f16 v[104:107], v[144:147], v[188:191], v[104:107]
	v_mfma_f32_16x16x32_f16 v[92:95], v[136:139], v[214:217], v[92:95]
	v_mfma_f32_16x16x32_f16 v[88:91], v[144:147], v[214:217], v[88:91]
	v_mfma_f32_16x16x32_f16 v[76:79], v[136:139], v[222:225], v[76:79]
	v_mfma_f32_16x16x32_f16 v[72:75], v[144:147], v[222:225], v[72:75]
	v_mfma_f32_16x16x32_f16 v[124:127], v[140:143], v[182:185], v[124:127]
	v_mfma_f32_16x16x32_f16 v[120:123], v[148:151], v[182:185], v[120:123]
	v_mfma_f32_16x16x32_f16 v[108:111], v[140:143], v[192:195], v[108:111]
	v_mfma_f32_16x16x32_f16 v[104:107], v[148:151], v[192:195], v[104:107]
	v_mfma_f32_16x16x32_f16 v[92:95], v[140:143], v[218:221], v[92:95]
	v_mfma_f32_16x16x32_f16 v[88:91], v[148:151], v[218:221], v[88:91]
	v_mfma_f32_16x16x32_f16 v[76:79], v[140:143], v[226:229], v[76:79]
	v_mfma_f32_16x16x32_f16 v[72:75], v[148:151], v[226:229], v[72:75]
	v_mfma_f32_16x16x32_f16 v[116:119], v[154:157], v[178:181], v[116:119]
	v_mfma_f32_16x16x32_f16 v[112:115], v[170:173], v[178:181], v[112:115]
	v_mfma_f32_16x16x32_f16 v[100:103], v[154:157], v[188:191], v[100:103]
	v_mfma_f32_16x16x32_f16 v[96:99], v[170:173], v[188:191], v[96:99]
	v_mfma_f32_16x16x32_f16 v[84:87], v[154:157], v[214:217], v[84:87]
	v_mfma_f32_16x16x32_f16 v[80:83], v[170:173], v[214:217], v[80:83]
	v_mfma_f32_16x16x32_f16 v[68:71], v[154:157], v[222:225], v[68:71]
	v_mfma_f32_16x16x32_f16 v[64:67], v[170:173], v[222:225], v[64:67]
	v_mfma_f32_16x16x32_f16 v[116:119], v[162:165], v[182:185], v[116:119]
	v_mfma_f32_16x16x32_f16 v[112:115], v[174:177], v[182:185], v[112:115]
	v_mfma_f32_16x16x32_f16 v[100:103], v[162:165], v[192:195], v[100:103]
	v_mfma_f32_16x16x32_f16 v[96:99], v[174:177], v[192:195], v[96:99]
	v_mfma_f32_16x16x32_f16 v[84:87], v[162:165], v[218:221], v[84:87]
	v_mfma_f32_16x16x32_f16 v[80:83], v[174:177], v[218:221], v[80:83]
	v_mfma_f32_16x16x32_f16 v[68:71], v[162:165], v[226:229], v[68:71]
	v_mfma_f32_16x16x32_f16 v[64:67], v[174:177], v[226:229], v[64:67]
	s_barrier
; #define PG8_STAGE(bufoff, gbase, voff) do { _Pragma("unroll") for (int _i = 0; _i < 2; ++_i) \
;         __builtin_amdgcn_global_load_lds((const unsigned*)((const char*)(gbase) + (voff)[_i]), (LAS unsigned*)(lds + (bufoff) + ldsw + _i * 8192), 16, 0, 0); } while (0)
; #define PG8_LDA(dst, b, h) do { _Pragma("unroll") for (int m = 0; m < 4; ++m) _Pragma("unroll") for (int k = 0; k < 2; ++k) dst[m][k] = *(const LAS h16x8*)(lds + PG8_SA(b, h) + aoff + m * 2048 + k * 1024); } while (0)
; #define PG8_MMA(ai, bj, At, Bt) do { __builtin_amdgcn_s_setprio(1); _Pragma("unroll") for (int m = 0; m < 4; ++m) _Pragma("unroll") for (int n = 0; n < 2; ++n) _Pragma("unroll") for (int k = 0; k < 2; ++k) \
;         acc[ai][bj][m][n] = __builtin_amdgcn_mfma_f32_16x16x32_f16(Bt[n][k], At[m][k], acc[ai][bj][m][n], 0, 0, 0); __builtin_amdgcn_s_setprio(0); } while (0)
; #define PG8_WAIT_V(n) asm volatile("s_waitcnt vmcnt(" #n ")" ::: "memory")
; #define PG8_WAIT_L(n) asm volatile("s_waitcnt lgkmcnt(" #n ")" ::: "memory")
; #define PG8_BAR __builtin_amdgcn_s_barrier()
; #define PG8_SCHED __builtin_amdgcn_sched_barrier(0)
; template <class Epi>
; __device__ __forceinline__ void gemm_phase(LAS unsigned char* lds, const Gemm g, const StaticOrder& S, const Epi& E, const int tid) {
;     ...
;             PG8_LDA(At, 1, 1); PG8_STAGE(PG8_SB(1, 0), b3, voffB); PG8_STAGE(PG8_SB(1, 1), b3 + hstepB, voffB); PG8_STAGE(PG8_SA(1, 0), a3, voffA);
;             PG8_WAIT_V(8); PG8_WAIT_L(0); PG8_BAR; PG8_MMA(1, 0, At, B0); PG8_MMA(1, 1, At, B1); PG8_BAR; PG8_SCHED;
;         }
	s_add_i32 s24, s31, s26
	v_lshl_add_u64 v[166:167], v[166:167], 0, s[0:1]
	s_mov_b32 m0, s24
	ds_read_b128 v[178:181], v212 offset:49152
	ds_read_b128 v[182:185], v212 offset:50176
	ds_read_b128 v[188:191], v212 offset:51200
	ds_read_b128 v[192:195], v212 offset:52224
	ds_read_b128 v[214:217], v212 offset:53248
	ds_read_b128 v[218:221], v212 offset:54272
	ds_read_b128 v[222:225], v212 offset:55296
	ds_read_b128 v[226:229], v212 offset:56320
	global_load_lds_dwordx4 v[166:167], off
	s_add_i32 m0, s24, 0x2000
	s_add_u32 s22, s22, 0x40080
	v_lshl_add_u64 v[166:167], v[196:197], 0, s[0:1]
	s_addc_u32 s23, s23, 0
	s_add_i32 s24, s45, s26
	global_load_lds_dwordx4 v[166:167], off
	v_lshl_add_u64 v[166:167], s[22:23], 0, v[152:153]
	s_mov_b32 m0, s24
	s_nop 0
	global_load_lds_dwordx4 v[166:167], off
	v_lshl_add_u64 v[166:167], s[22:23], 0, v[128:129]
	s_add_i32 m0, s24, 0x2000
	s_nop 0
	global_load_lds_dwordx4 v[166:167], off
	v_lshl_add_u64 v[166:167], v[204:205], 0, s[0:1]
	s_mov_b32 m0, s36
	s_nop 0
	global_load_lds_dwordx4 v[166:167], off
	v_lshl_add_u64 v[166:167], v[230:231], 0, s[0:1]
	s_mov_b32 m0, s37
	s_nop 0
	global_load_lds_dwordx4 v[166:167], off
	s_waitcnt vmcnt(8)
	s_waitcnt lgkmcnt(0)
	s_barrier
	s_waitcnt lgkmcnt(0)
	v_mfma_f32_16x16x32_f16 v[60:63], v[136:139], v[178:181], v[60:63]
	v_mfma_f32_16x16x32_f16 v[56:59], v[144:147], v[178:181], v[56:59]
	v_mfma_f32_16x16x32_f16 v[44:47], v[136:139], v[188:191], v[44:47]
	v_mfma_f32_16x16x32_f16 v[40:43], v[144:147], v[188:191], v[40:43]
	v_mfma_f32_16x16x32_f16 v[28:31], v[136:139], v[214:217], v[28:31]
	v_mfma_f32_16x16x32_f16 v[24:27], v[144:147], v[214:217], v[24:27]
	v_mfma_f32_16x16x32_f16 v[12:15], v[136:139], v[222:225], v[12:15]
	v_mfma_f32_16x16x32_f16 v[8:11], v[144:147], v[222:225], v[8:11]
	v_mfma_f32_16x16x32_f16 v[60:63], v[140:143], v[182:185], v[60:63]
	v_mfma_f32_16x16x32_f16 v[56:59], v[148:151], v[182:185], v[56:59]
	v_mfma_f32_16x16x32_f16 v[44:47], v[140:143], v[192:195], v[44:47]
	v_mfma_f32_16x16x32_f16 v[40:43], v[148:151], v[192:195], v[40:43]
	v_mfma_f32_16x16x32_f16 v[28:31], v[140:143], v[218:221], v[28:31]
	v_mfma_f32_16x16x32_f16 v[24:27], v[148:151], v[218:221], v[24:27]
	v_mfma_f32_16x16x32_f16 v[12:15], v[140:143], v[226:229], v[12:15]
	v_mfma_f32_16x16x32_f16 v[8:11], v[148:151], v[226:229], v[8:11]
	v_mfma_f32_16x16x32_f16 v[52:55], v[154:157], v[178:181], v[52:55]
	v_mfma_f32_16x16x32_f16 v[48:51], v[170:173], v[178:181], v[48:51]
	v_mfma_f32_16x16x32_f16 v[36:39], v[154:157], v[188:191], v[36:39]
	v_mfma_f32_16x16x32_f16 v[32:35], v[170:173], v[188:191], v[32:35]
	v_mfma_f32_16x16x32_f16 v[20:23], v[154:157], v[214:217], v[20:23]
	v_mfma_f32_16x16x32_f16 v[16:19], v[170:173], v[214:217], v[16:19]
	v_mfma_f32_16x16x32_f16 v[4:7], v[154:157], v[222:225], v[4:7]
	v_mfma_f32_16x16x32_f16 v[0:3], v[170:173], v[222:225], v[0:3]
	v_mfma_f32_16x16x32_f16 v[52:55], v[162:165], v[182:185], v[52:55]
	v_mfma_f32_16x16x32_f16 v[48:51], v[174:177], v[182:185], v[48:51]
	v_mfma_f32_16x16x32_f16 v[36:39], v[162:165], v[192:195], v[36:39]
	v_mfma_f32_16x16x32_f16 v[32:35], v[174:177], v[192:195], v[32:35]
	v_mfma_f32_16x16x32_f16 v[20:23], v[162:165], v[218:221], v[20:23]
	v_mfma_f32_16x16x32_f16 v[16:19], v[174:177], v[218:221], v[16:19]
	v_mfma_f32_16x16x32_f16 v[4:7], v[162:165], v[226:229], v[4:7]
	v_mfma_f32_16x16x32_f16 v[0:3], v[174:177], v[226:229], v[0:3]
	s_barrier
	s_add_i32 s44, s44, 2
	s_add_u32 s4, s4, 0x100
	s_addc_u32 s5, s5, 0
	s_add_u32 s2, s2, 0x100
	s_addc_u32 s3, s3, 0
	s_cmp_gt_u32 s44, 13
	s_cbranch_scc0 .LBB0_1017
	s_and_b64 vcc, exec, s[12:13]
	s_cbranch_vccz .LBB0_1020
	s_barrier
